# GEMM MFMA blocks: redundant post-barrier lgkmcnt(0) removed (the pre-barrier wait already covers the fragment reads)
# speedup vs baseline: 1.0001x; 1.0001x over previous
; #define PG8_STAGE(bufoff, gbase, voff) do { _Pragma("unroll") for (int _i = 0; _i < 2; ++_i) \
;         __builtin_amdgcn_global_load_lds((const unsigned*)((const char*)(gbase) + (voff)[_i]), (PG8_LAS unsigned*)(lds + (bufoff) + ldsw + _i * 8192), 16, 0, 0); } while (0)
; #define PG8_LDA(dst, b, h) do { _Pragma("unroll") for (int m = 0; m < 4; ++m) _Pragma("unroll") for (int k = 0; k < 2; ++k) dst[m][k] = *(const PG8_LAS bf16x8*)(lds + PG8_SA(b, h) + aoff + m * 2048 + k * 1024); } while (0)
; #define PG8_LDB(dst, b, h) do { _Pragma("unroll") for (int n = 0; n < 2; ++n) _Pragma("unroll") for (int k = 0; k < 2; ++k) dst[n][k] = *(const PG8_LAS bf16x8*)(lds + PG8_SB(b, h) + boff + n * 2048 + k * 1024); } while (0)
; #define PG8_WAIT_V(n) asm volatile("s_waitcnt vmcnt(" #n ")" ::: "memory")
; #define PG8_WAIT_L(n) asm volatile("s_waitcnt lgkmcnt(" #n ")" ::: "memory")
; #define PG8_BAR __builtin_amdgcn_s_barrier()
; #define PG8_SCHED __builtin_amdgcn_sched_barrier(0)
; template <class Epi, class Sched, bool ALIGN_EPI = false, bool SP2 = false>
; __device__ __forceinline__ void gemm_phase(PG8_LAS unsigned char* lds, const Gemm g, const Sched& S, const Epi& E) {
;     ...
;         const bool has_next = S.next(ui + 1, nxt);
;         const char* nA = has_next ? (const char*)g.A + (size_t)nxt.pm * tstep : cA; const char* nB = has_next ? (const char*)g.Bt + (size_t)nxt.pn * tstep : cB;
;         for (int t = 0; t < nt; t += 2) {
;             const bool last = (t == nt - 2);
;             const char* a1 = cA + (size_t)(t + 1) * kstep;
;             const char* a2 = last ? nA : cA + (size_t)(t + 2) * kstep; const char* b2 = last ? nB : cB + (size_t)(t + 2) * kstep;
;             const char* a3 = a2 + kstep; const char* b3 = b2 + kstep;
;             if (last && has_next) S.a_ready(nxt);
;             if constexpr (SP2) {
;             PG8_LDB(B0, 0, 0); PG8_LDB(B1, 0, 1); PG8_SCHED; PG8_LDA(At, 0, 0); PG8_STAGE(PG8_SA(1, 1), a1 + hstep, voffA);
;             PG8_WAIT_V(8); PG8_WAIT_L(0); PG8_BAR; PG8_MMA(0, 0, At, B0); PG8_MMA(0, 1, At, B1); PG8_BAR; PG8_SCHED;
;             PG8_LDA(At, 0, 1); PG8_STAGE(PG8_SB(0, 0), b2, voffB); PG8_STAGE(PG8_SB(0, 1), b2 + hstep, voffB); PG8_STAGE(PG8_SA(0, 0), a2, voffA);
;             PG8_WAIT_V(8); PG8_WAIT_L(0); PG8_BAR; PG8_MMA(1, 0, At, B0); PG8_MMA(1, 1, At, B1); PG8_BAR; PG8_SCHED;
.LBB0_170:
	s_ashr_i32 s29, s28, 31
	s_lshl_b64 s[30:31], s[28:29], 20
	s_add_u32 s30, s13, s30
	s_addc_u32 s31, s47, s31
	s_and_b64 s[34:35], s[38:39], exec
	s_cselect_b32 s29, s31, s41
	s_cselect_b32 s37, s30, s40
	s_ashr_i32 s27, s26, 31
	s_lshl_b64 s[34:35], s[26:27], 20
	s_add_u32 s34, s48, s34
	s_addc_u32 s35, s49, s35
	s_and_b64 s[44:45], s[38:39], exec
	s_cselect_b32 s27, s35, s43
	s_cselect_b32 s65, s34, s42
	s_add_u32 s40, s40, 0x80080
	s_addc_u32 s41, s41, 0
	s_add_u32 s67, s42, 0x100
	s_addc_u32 s68, s43, 0
	s_mov_b32 s69, -2
	ds_read_b128 v[128:131], v175
	ds_read_b128 v[132:135], v175 offset:1024
	ds_read_b128 v[136:139], v175 offset:2048
	ds_read_b128 v[140:143], v175 offset:3072
	ds_read_b128 v[164:167], v176
	ds_read_b128 v[168:171], v176 offset:1024
	ds_read_b128 v[178:181], v176 offset:2048
	ds_read_b128 v[182:185], v176 offset:3072
	s_add_u32 s42, s40, 0xfff80080
	s_addc_u32 s43, s41, -1
	s_cmp_eq_u32 s69, 28
	s_cselect_b32 s45, s29, s43
	s_cselect_b32 s44, s37, s42
	s_cselect_b32 s43, s27, s68
	s_cselect_b32 s42, s65, s67
	v_lshl_add_u64 v[190:191], s[40:41], 0, v[156:157]
	s_add_i32 m0, s52, 0xc000
	ds_read_b128 v[186:189], v177
	ds_read_b128 v[194:197], v177 offset:1024
	ds_read_b128 v[198:201], v177 offset:2048
	ds_read_b128 v[202:205], v177 offset:3072
	ds_read_b128 v[206:209], v177 offset:4096
	ds_read_b128 v[210:213], v177 offset:5120
	ds_read_b128 v[218:221], v177 offset:6144
	ds_read_b128 v[222:225], v177 offset:7168
	global_load_lds_dwordx4 v[190:191], off
	v_lshl_add_u64 v[190:191], s[40:41], 0, v[158:159]
	s_add_i32 m0, s52, 0xe000
	s_nop 0
	global_load_lds_dwordx4 v[190:191], off
	s_waitcnt vmcnt(8)
	s_waitcnt lgkmcnt(0)
	s_barrier
	s_setprio 1
	v_mfma_f32_16x16x32_bf16 v[124:127], v[128:131], v[186:189], 0
	v_mfma_f32_16x16x32_bf16 v[120:123], v[136:139], v[186:189], 0
	v_mfma_f32_16x16x32_bf16 v[116:119], v[128:131], v[198:201], 0
	v_mfma_f32_16x16x32_bf16 v[112:115], v[136:139], v[198:201], 0
	v_mfma_f32_16x16x32_bf16 v[100:103], v[128:131], v[206:209], 0
	v_mfma_f32_16x16x32_bf16 v[96:99], v[136:139], v[206:209], 0
	v_mfma_f32_16x16x32_bf16 v[84:87], v[128:131], v[218:221], 0
	v_mfma_f32_16x16x32_bf16 v[80:83], v[136:139], v[218:221], 0
	v_mfma_f32_16x16x32_bf16 v[124:127], v[132:135], v[194:197], v[124:127]
	v_mfma_f32_16x16x32_bf16 v[120:123], v[140:143], v[194:197], v[120:123]
	v_mfma_f32_16x16x32_bf16 v[116:119], v[132:135], v[202:205], v[116:119]
	v_mfma_f32_16x16x32_bf16 v[112:115], v[140:143], v[202:205], v[112:115]
	v_mfma_f32_16x16x32_bf16 v[100:103], v[132:135], v[210:213], v[100:103]
	v_mfma_f32_16x16x32_bf16 v[96:99], v[140:143], v[210:213], v[96:99]
	v_mfma_f32_16x16x32_bf16 v[84:87], v[132:135], v[222:225], v[84:87]
	v_mfma_f32_16x16x32_bf16 v[80:83], v[140:143], v[222:225], v[80:83]
	v_mfma_f32_16x16x32_bf16 v[108:111], v[164:167], v[186:189], 0
	v_mfma_f32_16x16x32_bf16 v[104:107], v[178:181], v[186:189], 0
	v_mfma_f32_16x16x32_bf16 v[92:95], v[164:167], v[198:201], 0
	v_mfma_f32_16x16x32_bf16 v[88:91], v[178:181], v[198:201], 0
	v_mfma_f32_16x16x32_bf16 v[76:79], v[164:167], v[206:209], 0
	v_mfma_f32_16x16x32_bf16 v[72:75], v[178:181], v[206:209], 0
	v_mfma_f32_16x16x32_bf16 v[68:71], v[164:167], v[218:221], 0
	v_mfma_f32_16x16x32_bf16 v[64:67], v[178:181], v[218:221], 0
	v_mfma_f32_16x16x32_bf16 v[108:111], v[168:171], v[194:197], v[108:111]
	v_mfma_f32_16x16x32_bf16 v[104:107], v[182:185], v[194:197], v[104:107]
	v_mfma_f32_16x16x32_bf16 v[92:95], v[168:171], v[202:205], v[92:95]
	v_mfma_f32_16x16x32_bf16 v[88:91], v[182:185], v[202:205], v[88:91]
	v_mfma_f32_16x16x32_bf16 v[76:79], v[168:171], v[210:213], v[76:79]
	v_mfma_f32_16x16x32_bf16 v[72:75], v[182:185], v[210:213], v[72:75]
	v_mfma_f32_16x16x32_bf16 v[68:71], v[168:171], v[222:225], v[68:71]
	v_mfma_f32_16x16x32_bf16 v[64:67], v[182:185], v[222:225], v[64:67]
	s_setprio 0
	s_barrier
	s_add_i32 s70, s61, s50
	v_lshl_add_u64 v[190:191], s[42:43], 0, v[148:149]
	s_mov_b32 m0, s70
	ds_read_b128 v[186:189], v177 offset:16384
	ds_read_b128 v[194:197], v177 offset:17408
	ds_read_b128 v[198:201], v177 offset:18432
	ds_read_b128 v[202:205], v177 offset:19456
	ds_read_b128 v[206:209], v177 offset:20480
	ds_read_b128 v[210:213], v177 offset:21504
	ds_read_b128 v[218:221], v177 offset:22528
	ds_read_b128 v[222:225], v177 offset:23552
	global_load_lds_dwordx4 v[190:191], off
	s_add_i32 m0, s70, 0x2000
	s_add_u32 s70, s42, 0x80000
	v_lshl_add_u64 v[214:215], s[42:43], 0, v[144:145]
	s_addc_u32 s71, s43, 0
	s_add_i32 s72, s62, s50
	global_load_lds_dwordx4 v[214:215], off
	v_lshl_add_u64 v[226:227], s[70:71], 0, v[148:149]
	s_mov_b32 m0, s72
	v_lshl_add_u64 v[228:229], s[44:45], 0, v[146:147]
	global_load_lds_dwordx4 v[226:227], off
	v_lshl_add_u64 v[226:227], s[70:71], 0, v[144:145]
	s_add_i32 m0, s72, 0x2000
	s_nop 0
	global_load_lds_dwordx4 v[226:227], off
	v_lshl_add_u64 v[226:227], s[44:45], 0, v[150:151]
	s_mov_b32 m0, s52
	s_nop 0
	global_load_lds_dwordx4 v[226:227], off
	s_mov_b32 m0, s53
	s_nop 0
	global_load_lds_dwordx4 v[228:229], off
	s_waitcnt vmcnt(8)
	s_waitcnt lgkmcnt(0)
	s_barrier
; #define PG8_STAGE(bufoff, gbase, voff) do { _Pragma("unroll") for (int _i = 0; _i < 2; ++_i) \
;         __builtin_amdgcn_global_load_lds((const unsigned*)((const char*)(gbase) + (voff)[_i]), (PG8_LAS unsigned*)(lds + (bufoff) + ldsw + _i * 8192), 16, 0, 0); } while (0)
; #define PG8_LDA(dst, b, h) do { _Pragma("unroll") for (int m = 0; m < 4; ++m) _Pragma("unroll") for (int k = 0; k < 2; ++k) dst[m][k] = *(const PG8_LAS bf16x8*)(lds + PG8_SA(b, h) + aoff + m * 2048 + k * 1024); } while (0)
; #define PG8_LDB(dst, b, h) do { _Pragma("unroll") for (int n = 0; n < 2; ++n) _Pragma("unroll") for (int k = 0; k < 2; ++k) dst[n][k] = *(const PG8_LAS bf16x8*)(lds + PG8_SB(b, h) + boff + n * 2048 + k * 1024); } while (0)
; #define PG8_MMA(ai, bj, At, Bt) do { __builtin_amdgcn_s_setprio(1); _Pragma("unroll") for (int m = 0; m < 4; ++m) _Pragma("unroll") for (int n = 0; n < 2; ++n) _Pragma("unroll") for (int k = 0; k < 2; ++k) \
;         acc[ai][bj][m][n] = __builtin_amdgcn_mfma_f32_16x16x32_bf16(Bt[n][k], At[m][k], acc[ai][bj][m][n], 0, 0, 0); __builtin_amdgcn_s_setprio(0); } while (0)
; #define PG8_WAIT_V(n) asm volatile("s_waitcnt vmcnt(" #n ")" ::: "memory")
; #define PG8_WAIT_L(n) asm volatile("s_waitcnt lgkmcnt(" #n ")" ::: "memory")
; #define PG8_BAR __builtin_amdgcn_s_barrier()
; #define PG8_SCHED __builtin_amdgcn_sched_barrier(0)
; template <class Epi, class Sched, bool ALIGN_EPI = false, bool SP2 = false>
; __device__ __forceinline__ void gemm_phase(PG8_LAS unsigned char* lds, const Gemm g, const Sched& S, const Epi& E) {
;     ...
;             PG8_WAIT_V(8); PG8_WAIT_L(0); PG8_BAR; PG8_MMA(1, 0, At, B0); PG8_MMA(1, 1, At, B1); PG8_BAR; PG8_SCHED;
;             PG8_LDB(B0, 1, 0); PG8_LDB(B1, 1, 1); PG8_SCHED; PG8_LDA(At, 1, 0); PG8_STAGE(PG8_SA(0, 1), a2 + hstep, voffA);
;             PG8_WAIT_V(8); PG8_WAIT_L(0); PG8_BAR; PG8_MMA(0, 0, At, B0); PG8_MMA(0, 1, At, B1); PG8_BAR; PG8_SCHED;
	s_setprio 1
	v_mfma_f32_16x16x32_bf16 v[60:63], v[128:131], v[186:189], 0
	v_mfma_f32_16x16x32_bf16 v[56:59], v[136:139], v[186:189], 0
	v_mfma_f32_16x16x32_bf16 v[52:55], v[128:131], v[198:201], 0
	v_mfma_f32_16x16x32_bf16 v[48:51], v[136:139], v[198:201], 0
	v_mfma_f32_16x16x32_bf16 v[36:39], v[128:131], v[206:209], 0
	v_mfma_f32_16x16x32_bf16 v[32:35], v[136:139], v[206:209], 0
	v_mfma_f32_16x16x32_bf16 v[20:23], v[128:131], v[218:221], 0
	v_mfma_f32_16x16x32_bf16 v[16:19], v[136:139], v[218:221], 0
	v_mfma_f32_16x16x32_bf16 v[60:63], v[132:135], v[194:197], v[60:63]
	v_mfma_f32_16x16x32_bf16 v[56:59], v[140:143], v[194:197], v[56:59]
	v_mfma_f32_16x16x32_bf16 v[52:55], v[132:135], v[202:205], v[52:55]
	v_mfma_f32_16x16x32_bf16 v[48:51], v[140:143], v[202:205], v[48:51]
	v_mfma_f32_16x16x32_bf16 v[36:39], v[132:135], v[210:213], v[36:39]
	v_mfma_f32_16x16x32_bf16 v[32:35], v[140:143], v[210:213], v[32:35]
	v_mfma_f32_16x16x32_bf16 v[20:23], v[132:135], v[222:225], v[20:23]
	v_mfma_f32_16x16x32_bf16 v[16:19], v[140:143], v[222:225], v[16:19]
	v_mfma_f32_16x16x32_bf16 v[44:47], v[164:167], v[186:189], 0
	v_mfma_f32_16x16x32_bf16 v[40:43], v[178:181], v[186:189], 0
	v_mfma_f32_16x16x32_bf16 v[28:31], v[164:167], v[198:201], 0
	v_mfma_f32_16x16x32_bf16 v[24:27], v[178:181], v[198:201], 0
	v_mfma_f32_16x16x32_bf16 v[12:15], v[164:167], v[206:209], 0
	v_mfma_f32_16x16x32_bf16 v[8:11], v[178:181], v[206:209], 0
	v_mfma_f32_16x16x32_bf16 v[4:7], v[164:167], v[218:221], 0
	v_mfma_f32_16x16x32_bf16 v[0:3], v[178:181], v[218:221], 0
	v_mfma_f32_16x16x32_bf16 v[44:47], v[168:171], v[194:197], v[44:47]
	v_mfma_f32_16x16x32_bf16 v[40:43], v[182:185], v[194:197], v[40:43]
	v_mfma_f32_16x16x32_bf16 v[28:31], v[168:171], v[202:205], v[28:31]
	v_mfma_f32_16x16x32_bf16 v[24:27], v[182:185], v[202:205], v[24:27]
	v_mfma_f32_16x16x32_bf16 v[12:15], v[168:171], v[210:213], v[12:15]
	v_mfma_f32_16x16x32_bf16 v[8:11], v[182:185], v[210:213], v[8:11]
	v_mfma_f32_16x16x32_bf16 v[4:7], v[168:171], v[222:225], v[4:7]
	v_mfma_f32_16x16x32_bf16 v[0:3], v[182:185], v[222:225], v[0:3]
	s_setprio 0
	s_barrier
	s_add_i32 s70, 0, 0x18000
	s_add_i32 s71, 0, 0x1c000
	v_add_u32_e32 v140, s70, v173
	v_add_u32_e32 v182, s71, v173
	ds_read_b128 v[128:131], v140
	ds_read_b128 v[132:135], v140 offset:1024
	ds_read_b128 v[136:139], v140 offset:2048
	ds_read_b128 v[140:143], v140 offset:3072
	ds_read_b128 v[164:167], v182
	ds_read_b128 v[168:171], v182 offset:1024
	ds_read_b128 v[178:181], v182 offset:2048
	ds_read_b128 v[182:185], v182 offset:3072
	s_add_u32 s44, s44, 0x80000
	s_addc_u32 s45, s45, 0
	s_mov_b32 m0, s54
	v_lshl_add_u64 v[230:231], s[44:45], 0, v[150:151]
	ds_read_b128 v[186:189], v177 offset:32768
	ds_read_b128 v[194:197], v177 offset:33792
	ds_read_b128 v[198:201], v177 offset:34816
	ds_read_b128 v[202:205], v177 offset:35840
	ds_read_b128 v[206:209], v177 offset:36864
	ds_read_b128 v[210:213], v177 offset:37888
	ds_read_b128 v[218:221], v177 offset:38912
	ds_read_b128 v[222:225], v177 offset:39936
	global_load_lds_dwordx4 v[230:231], off
	v_lshl_add_u64 v[230:231], s[44:45], 0, v[146:147]
	s_mov_b32 m0, s55
	s_nop 0
	global_load_lds_dwordx4 v[230:231], off
	s_waitcnt vmcnt(8)
	s_waitcnt lgkmcnt(0)
	s_barrier
	s_setprio 1
	v_mfma_f32_16x16x32_bf16 v[124:127], v[128:131], v[186:189], v[124:127]
	v_mfma_f32_16x16x32_bf16 v[120:123], v[136:139], v[186:189], v[120:123]
	v_mfma_f32_16x16x32_bf16 v[116:119], v[128:131], v[198:201], v[116:119]
	v_mfma_f32_16x16x32_bf16 v[112:115], v[136:139], v[198:201], v[112:115]
	v_mfma_f32_16x16x32_bf16 v[100:103], v[128:131], v[206:209], v[100:103]
	v_mfma_f32_16x16x32_bf16 v[96:99], v[136:139], v[206:209], v[96:99]
	v_mfma_f32_16x16x32_bf16 v[84:87], v[128:131], v[218:221], v[84:87]
	v_mfma_f32_16x16x32_bf16 v[80:83], v[136:139], v[218:221], v[80:83]
	v_mfma_f32_16x16x32_bf16 v[124:127], v[132:135], v[194:197], v[124:127]
	v_mfma_f32_16x16x32_bf16 v[120:123], v[140:143], v[194:197], v[120:123]
	v_mfma_f32_16x16x32_bf16 v[116:119], v[132:135], v[202:205], v[116:119]
	v_mfma_f32_16x16x32_bf16 v[112:115], v[140:143], v[202:205], v[112:115]
	v_mfma_f32_16x16x32_bf16 v[100:103], v[132:135], v[210:213], v[100:103]
	v_mfma_f32_16x16x32_bf16 v[96:99], v[140:143], v[210:213], v[96:99]
	v_mfma_f32_16x16x32_bf16 v[84:87], v[132:135], v[222:225], v[84:87]
	v_mfma_f32_16x16x32_bf16 v[80:83], v[140:143], v[222:225], v[80:83]
	v_mfma_f32_16x16x32_bf16 v[108:111], v[164:167], v[186:189], v[108:111]
	v_mfma_f32_16x16x32_bf16 v[104:107], v[178:181], v[186:189], v[104:107]
	v_mfma_f32_16x16x32_bf16 v[92:95], v[164:167], v[198:201], v[92:95]
	v_mfma_f32_16x16x32_bf16 v[88:91], v[178:181], v[198:201], v[88:91]
	v_mfma_f32_16x16x32_bf16 v[76:79], v[164:167], v[206:209], v[76:79]
	v_mfma_f32_16x16x32_bf16 v[72:75], v[178:181], v[206:209], v[72:75]
	v_mfma_f32_16x16x32_bf16 v[68:71], v[164:167], v[218:221], v[68:71]
	v_mfma_f32_16x16x32_bf16 v[64:67], v[178:181], v[218:221], v[64:67]
	v_mfma_f32_16x16x32_bf16 v[108:111], v[168:171], v[194:197], v[108:111]
	v_mfma_f32_16x16x32_bf16 v[104:107], v[182:185], v[194:197], v[104:107]
	v_mfma_f32_16x16x32_bf16 v[92:95], v[168:171], v[202:205], v[92:95]
	v_mfma_f32_16x16x32_bf16 v[88:91], v[182:185], v[202:205], v[88:91]
	v_mfma_f32_16x16x32_bf16 v[76:79], v[168:171], v[210:213], v[76:79]
	v_mfma_f32_16x16x32_bf16 v[72:75], v[182:185], v[210:213], v[72:75]
	v_mfma_f32_16x16x32_bf16 v[68:71], v[168:171], v[222:225], v[68:71]
	v_mfma_f32_16x16x32_bf16 v[64:67], v[182:185], v[222:225], v[64:67]
	s_setprio 0
	s_barrier
; #define PG8_STAGE(bufoff, gbase, voff) do { _Pragma("unroll") for (int _i = 0; _i < 2; ++_i) \
;         __builtin_amdgcn_global_load_lds((const unsigned*)((const char*)(gbase) + (voff)[_i]), (PG8_LAS unsigned*)(lds + (bufoff) + ldsw + _i * 8192), 16, 0, 0); } while (0)
; #define PG8_LDA(dst, b, h) do { _Pragma("unroll") for (int m = 0; m < 4; ++m) _Pragma("unroll") for (int k = 0; k < 2; ++k) dst[m][k] = *(const PG8_LAS bf16x8*)(lds + PG8_SA(b, h) + aoff + m * 2048 + k * 1024); } while (0)
; #define PG8_LDB(dst, b, h) do { _Pragma("unroll") for (int n = 0; n < 2; ++n) _Pragma("unroll") for (int k = 0; k < 2; ++k) dst[n][k] = *(const PG8_LAS bf16x8*)(lds + PG8_SB(b, h) + boff + n * 2048 + k * 1024); } while (0)
; #define PG8_MMA(ai, bj, At, Bt) do { __builtin_amdgcn_s_setprio(1); _Pragma("unroll") for (int m = 0; m < 4; ++m) _Pragma("unroll") for (int n = 0; n < 2; ++n) _Pragma("unroll") for (int k = 0; k < 2; ++k) \
;         acc[ai][bj][m][n] = __builtin_amdgcn_mfma_f32_16x16x32_bf16(Bt[n][k], At[m][k], acc[ai][bj][m][n], 0, 0, 0); __builtin_amdgcn_s_setprio(0); } while (0)
; #define PG8_WAIT_V(n) asm volatile("s_waitcnt vmcnt(" #n ")" ::: "memory")
; #define PG8_BAR __builtin_amdgcn_s_barrier()
; template <class Epi, class Sched, bool ALIGN_EPI = false, bool SP2 = false>
; __device__ __forceinline__ void gemm_phase(PG8_LAS unsigned char* lds, const Gemm g, const Sched& S, const Epi& E) {
;     ...
;         for (int t = 0; t < nt; t += 2) {
;             const bool last = (t == nt - 2);
;             const char* a1 = cA + (size_t)(t + 1) * kstep;
;             const char* a2 = last ? nA : cA + (size_t)(t + 2) * kstep; const char* b2 = last ? nB : cB + (size_t)(t + 2) * kstep;
;             const char* a3 = a2 + kstep; const char* b3 = b2 + kstep;
;             if (last && has_next) S.a_ready(nxt);
;             if constexpr (SP2) {
;             PG8_LDB(B0, 0, 0); PG8_LDB(B1, 0, 1); PG8_SCHED; PG8_LDA(At, 0, 0); PG8_STAGE(PG8_SA(1, 1), a1 + hstep, voffA);
;             PG8_WAIT_V(8); PG8_WAIT_L(0); PG8_BAR; PG8_MMA(0, 0, At, B0); PG8_MMA(0, 1, At, B1); PG8_BAR; PG8_SCHED;
;     ...
;             PG8_LDA(At, 1, 1); PG8_STAGE(PG8_SB(1, 0), b3, voffB); PG8_STAGE(PG8_SB(1, 1), b3 + hstep, voffB); PG8_STAGE(PG8_SA(1, 0), a3, voffA);
;             PG8_WAIT_V(8); PG8_WAIT_L(0); PG8_BAR; PG8_MMA(1, 0, At, B0); PG8_MMA(1, 1, At, B1); PG8_BAR; PG8_SCHED;
	s_add_i32 s44, s70, s50
	v_lshl_add_u64 v[190:191], v[190:191], 0, s[22:23]
	s_mov_b32 m0, s44
	ds_read_b128 v[186:189], v177 offset:49152
	ds_read_b128 v[194:197], v177 offset:50176
	ds_read_b128 v[198:201], v177 offset:51200
	ds_read_b128 v[202:205], v177 offset:52224
	ds_read_b128 v[206:209], v177 offset:53248
	ds_read_b128 v[210:213], v177 offset:54272
	ds_read_b128 v[218:221], v177 offset:55296
	ds_read_b128 v[222:225], v177 offset:56320
	global_load_lds_dwordx4 v[190:191], off
	s_add_i32 m0, s44, 0x2000
	s_add_u32 s42, s42, 0x80080
	v_lshl_add_u64 v[190:191], v[214:215], 0, s[22:23]
	s_addc_u32 s43, s43, 0
	s_add_i32 s44, s71, s50
	global_load_lds_dwordx4 v[190:191], off
	v_lshl_add_u64 v[190:191], s[42:43], 0, v[148:149]
	s_mov_b32 m0, s44
	s_nop 0
	global_load_lds_dwordx4 v[190:191], off
	v_lshl_add_u64 v[190:191], s[42:43], 0, v[144:145]
	s_add_i32 m0, s44, 0x2000
	s_nop 0
	global_load_lds_dwordx4 v[190:191], off
	v_lshl_add_u64 v[190:191], v[226:227], 0, s[22:23]
	s_mov_b32 m0, s59
	s_nop 0
	global_load_lds_dwordx4 v[190:191], off
	v_lshl_add_u64 v[190:191], v[228:229], 0, s[22:23]
	s_mov_b32 m0, s60
	s_nop 0
	global_load_lds_dwordx4 v[190:191], off
	s_waitcnt vmcnt(8)
	s_waitcnt lgkmcnt(0)
	s_barrier
	s_setprio 1
	v_mfma_f32_16x16x32_bf16 v[60:63], v[128:131], v[186:189], v[60:63]
	v_mfma_f32_16x16x32_bf16 v[56:59], v[136:139], v[186:189], v[56:59]
	v_mfma_f32_16x16x32_bf16 v[52:55], v[128:131], v[198:201], v[52:55]
	v_mfma_f32_16x16x32_bf16 v[48:51], v[136:139], v[198:201], v[48:51]
	v_mfma_f32_16x16x32_bf16 v[36:39], v[128:131], v[206:209], v[36:39]
	v_mfma_f32_16x16x32_bf16 v[32:35], v[136:139], v[206:209], v[32:35]
	v_mfma_f32_16x16x32_bf16 v[20:23], v[128:131], v[218:221], v[20:23]
	v_mfma_f32_16x16x32_bf16 v[16:19], v[136:139], v[218:221], v[16:19]
	v_mfma_f32_16x16x32_bf16 v[60:63], v[132:135], v[194:197], v[60:63]
	v_mfma_f32_16x16x32_bf16 v[56:59], v[140:143], v[194:197], v[56:59]
	v_mfma_f32_16x16x32_bf16 v[52:55], v[132:135], v[202:205], v[52:55]
	v_mfma_f32_16x16x32_bf16 v[48:51], v[140:143], v[202:205], v[48:51]
	v_mfma_f32_16x16x32_bf16 v[36:39], v[132:135], v[210:213], v[36:39]
	v_mfma_f32_16x16x32_bf16 v[32:35], v[140:143], v[210:213], v[32:35]
	v_mfma_f32_16x16x32_bf16 v[20:23], v[132:135], v[222:225], v[20:23]
	v_mfma_f32_16x16x32_bf16 v[16:19], v[140:143], v[222:225], v[16:19]
	v_mfma_f32_16x16x32_bf16 v[44:47], v[164:167], v[186:189], v[44:47]
	v_mfma_f32_16x16x32_bf16 v[40:43], v[178:181], v[186:189], v[40:43]
	v_mfma_f32_16x16x32_bf16 v[28:31], v[164:167], v[198:201], v[28:31]
	v_mfma_f32_16x16x32_bf16 v[24:27], v[178:181], v[198:201], v[24:27]
	v_mfma_f32_16x16x32_bf16 v[12:15], v[164:167], v[206:209], v[12:15]
	v_mfma_f32_16x16x32_bf16 v[8:11], v[178:181], v[206:209], v[8:11]
	v_mfma_f32_16x16x32_bf16 v[4:7], v[164:167], v[218:221], v[4:7]
	v_mfma_f32_16x16x32_bf16 v[0:3], v[178:181], v[218:221], v[0:3]
	v_mfma_f32_16x16x32_bf16 v[44:47], v[168:171], v[194:197], v[44:47]
	v_mfma_f32_16x16x32_bf16 v[40:43], v[182:185], v[194:197], v[40:43]
	v_mfma_f32_16x16x32_bf16 v[28:31], v[168:171], v[202:205], v[28:31]
	v_mfma_f32_16x16x32_bf16 v[24:27], v[182:185], v[202:205], v[24:27]
	v_mfma_f32_16x16x32_bf16 v[12:15], v[168:171], v[210:213], v[12:15]
	v_mfma_f32_16x16x32_bf16 v[8:11], v[182:185], v[210:213], v[8:11]
	v_mfma_f32_16x16x32_bf16 v[4:7], v[168:171], v[222:225], v[4:7]
	v_mfma_f32_16x16x32_bf16 v[0:3], v[182:185], v[222:225], v[0:3]
	s_setprio 0
	s_barrier
	s_add_i32 s69, s69, 2
	s_add_u32 s40, s40, 0x100
	s_addc_u32 s41, s41, 0
	s_add_u32 s67, s67, 0x100
	s_addc_u32 s68, s68, 0
	s_cmp_gt_u32 s69, 29
.LBB0_171:
	ds_read_b128 v[128:131], v175
	ds_read_b128 v[132:135], v175 offset:1024
	ds_read_b128 v[136:139], v175 offset:2048
	ds_read_b128 v[140:143], v175 offset:3072
	ds_read_b128 v[164:167], v176
	ds_read_b128 v[168:171], v176 offset:1024
	ds_read_b128 v[178:181], v176 offset:2048
	ds_read_b128 v[182:185], v176 offset:3072
	s_add_u32 s42, s40, 0xfff80080
	s_addc_u32 s43, s41, -1
	s_cmp_eq_u32 s69, 28
	s_cselect_b32 s45, s29, s43
	s_cselect_b32 s44, s37, s42
	s_cselect_b32 s43, s27, s68
	s_cselect_b32 s42, s65, s67
	v_lshl_add_u64 v[190:191], s[40:41], 0, v[156:157]
	s_add_i32 m0, s52, 0xc000
	ds_read_b128 v[186:189], v177
	ds_read_b128 v[194:197], v177 offset:1024
	ds_read_b128 v[198:201], v177 offset:2048
	ds_read_b128 v[202:205], v177 offset:3072
	ds_read_b128 v[206:209], v177 offset:4096
	ds_read_b128 v[210:213], v177 offset:5120
	ds_read_b128 v[218:221], v177 offset:6144
	ds_read_b128 v[222:225], v177 offset:7168
	global_load_lds_dwordx4 v[190:191], off
	v_lshl_add_u64 v[190:191], s[40:41], 0, v[158:159]
	s_add_i32 m0, s52, 0xe000
	s_nop 0
	global_load_lds_dwordx4 v[190:191], off
	s_waitcnt vmcnt(8)
	s_waitcnt lgkmcnt(0)
	s_barrier
; #define PG8_STAGE(bufoff, gbase, voff) do { _Pragma("unroll") for (int _i = 0; _i < 2; ++_i) \
;         __builtin_amdgcn_global_load_lds((const unsigned*)((const char*)(gbase) + (voff)[_i]), (PG8_LAS unsigned*)(lds + (bufoff) + ldsw + _i * 8192), 16, 0, 0); } while (0)
; #define PG8_LDA(dst, b, h) do { _Pragma("unroll") for (int m = 0; m < 4; ++m) _Pragma("unroll") for (int k = 0; k < 2; ++k) dst[m][k] = *(const PG8_LAS bf16x8*)(lds + PG8_SA(b, h) + aoff + m * 2048 + k * 1024); } while (0)
; #define PG8_MMA(ai, bj, At, Bt) do { __builtin_amdgcn_s_setprio(1); _Pragma("unroll") for (int m = 0; m < 4; ++m) _Pragma("unroll") for (int n = 0; n < 2; ++n) _Pragma("unroll") for (int k = 0; k < 2; ++k) \
;         acc[ai][bj][m][n] = __builtin_amdgcn_mfma_f32_16x16x32_bf16(Bt[n][k], At[m][k], acc[ai][bj][m][n], 0, 0, 0); __builtin_amdgcn_s_setprio(0); } while (0)
; #define PG8_WAIT_V(n) asm volatile("s_waitcnt vmcnt(" #n ")" ::: "memory")
; #define PG8_WAIT_L(n) asm volatile("s_waitcnt lgkmcnt(" #n ")" ::: "memory")
; #define PG8_BAR __builtin_amdgcn_s_barrier()
; #define PG8_SCHED __builtin_amdgcn_sched_barrier(0)
; template <class Epi, class Sched, bool ALIGN_EPI = false, bool SP2 = false>
; __device__ __forceinline__ void gemm_phase(PG8_LAS unsigned char* lds, const Gemm g, const Sched& S, const Epi& E) {
;     ...
;             PG8_WAIT_V(8); PG8_WAIT_L(0); PG8_BAR; PG8_MMA(0, 0, At, B0); PG8_MMA(0, 1, At, B1); PG8_BAR; PG8_SCHED;
;             PG8_LDA(At, 0, 1); PG8_STAGE(PG8_SB(0, 0), b2, voffB); PG8_STAGE(PG8_SB(0, 1), b2 + hstep, voffB); PG8_STAGE(PG8_SA(0, 0), a2, voffA);
;             PG8_WAIT_V(8); PG8_WAIT_L(0); PG8_BAR; PG8_MMA(1, 0, At, B0); PG8_MMA(1, 1, At, B1); PG8_BAR; PG8_SCHED;
	s_setprio 1
	v_mfma_f32_16x16x32_bf16 v[124:127], v[128:131], v[186:189], v[124:127]
	v_mfma_f32_16x16x32_bf16 v[120:123], v[136:139], v[186:189], v[120:123]
	v_mfma_f32_16x16x32_bf16 v[116:119], v[128:131], v[198:201], v[116:119]
	v_mfma_f32_16x16x32_bf16 v[112:115], v[136:139], v[198:201], v[112:115]
	v_mfma_f32_16x16x32_bf16 v[100:103], v[128:131], v[206:209], v[100:103]
	v_mfma_f32_16x16x32_bf16 v[96:99], v[136:139], v[206:209], v[96:99]
	v_mfma_f32_16x16x32_bf16 v[84:87], v[128:131], v[218:221], v[84:87]
	v_mfma_f32_16x16x32_bf16 v[80:83], v[136:139], v[218:221], v[80:83]
	v_mfma_f32_16x16x32_bf16 v[124:127], v[132:135], v[194:197], v[124:127]
	v_mfma_f32_16x16x32_bf16 v[120:123], v[140:143], v[194:197], v[120:123]
	v_mfma_f32_16x16x32_bf16 v[116:119], v[132:135], v[202:205], v[116:119]
	v_mfma_f32_16x16x32_bf16 v[112:115], v[140:143], v[202:205], v[112:115]
	v_mfma_f32_16x16x32_bf16 v[100:103], v[132:135], v[210:213], v[100:103]
	v_mfma_f32_16x16x32_bf16 v[96:99], v[140:143], v[210:213], v[96:99]
	v_mfma_f32_16x16x32_bf16 v[84:87], v[132:135], v[222:225], v[84:87]
	v_mfma_f32_16x16x32_bf16 v[80:83], v[140:143], v[222:225], v[80:83]
	v_mfma_f32_16x16x32_bf16 v[108:111], v[164:167], v[186:189], v[108:111]
	v_mfma_f32_16x16x32_bf16 v[104:107], v[178:181], v[186:189], v[104:107]
	v_mfma_f32_16x16x32_bf16 v[92:95], v[164:167], v[198:201], v[92:95]
	v_mfma_f32_16x16x32_bf16 v[88:91], v[178:181], v[198:201], v[88:91]
	v_mfma_f32_16x16x32_bf16 v[76:79], v[164:167], v[206:209], v[76:79]
	v_mfma_f32_16x16x32_bf16 v[72:75], v[178:181], v[206:209], v[72:75]
	v_mfma_f32_16x16x32_bf16 v[68:71], v[164:167], v[218:221], v[68:71]
	v_mfma_f32_16x16x32_bf16 v[64:67], v[178:181], v[218:221], v[64:67]
	v_mfma_f32_16x16x32_bf16 v[108:111], v[168:171], v[194:197], v[108:111]
	v_mfma_f32_16x16x32_bf16 v[104:107], v[182:185], v[194:197], v[104:107]
	v_mfma_f32_16x16x32_bf16 v[92:95], v[168:171], v[202:205], v[92:95]
	v_mfma_f32_16x16x32_bf16 v[88:91], v[182:185], v[202:205], v[88:91]
	v_mfma_f32_16x16x32_bf16 v[76:79], v[168:171], v[210:213], v[76:79]
	v_mfma_f32_16x16x32_bf16 v[72:75], v[182:185], v[210:213], v[72:75]
	v_mfma_f32_16x16x32_bf16 v[68:71], v[168:171], v[222:225], v[68:71]
	v_mfma_f32_16x16x32_bf16 v[64:67], v[182:185], v[222:225], v[64:67]
	s_setprio 0
	s_barrier
	s_add_i32 s70, s61, s50
	v_lshl_add_u64 v[190:191], s[42:43], 0, v[148:149]
	s_mov_b32 m0, s70
	ds_read_b128 v[186:189], v177 offset:16384
	ds_read_b128 v[194:197], v177 offset:17408
	ds_read_b128 v[198:201], v177 offset:18432
	ds_read_b128 v[202:205], v177 offset:19456
	ds_read_b128 v[206:209], v177 offset:20480
	ds_read_b128 v[210:213], v177 offset:21504
	ds_read_b128 v[218:221], v177 offset:22528
	ds_read_b128 v[222:225], v177 offset:23552
	global_load_lds_dwordx4 v[190:191], off
	s_add_i32 m0, s70, 0x2000
	s_add_u32 s70, s42, 0x80000
	v_lshl_add_u64 v[214:215], s[42:43], 0, v[144:145]
	s_addc_u32 s71, s43, 0
	s_add_i32 s72, s62, s50
	global_load_lds_dwordx4 v[214:215], off
	v_lshl_add_u64 v[226:227], s[70:71], 0, v[148:149]
	s_mov_b32 m0, s72
	v_lshl_add_u64 v[228:229], s[44:45], 0, v[146:147]
	global_load_lds_dwordx4 v[226:227], off
	v_lshl_add_u64 v[226:227], s[70:71], 0, v[144:145]
	s_add_i32 m0, s72, 0x2000
	s_nop 0
	global_load_lds_dwordx4 v[226:227], off
	v_lshl_add_u64 v[226:227], s[44:45], 0, v[150:151]
	s_mov_b32 m0, s52
	s_nop 0
	global_load_lds_dwordx4 v[226:227], off
	s_mov_b32 m0, s53
	s_nop 0
	global_load_lds_dwordx4 v[228:229], off
	s_waitcnt vmcnt(8)
	s_waitcnt lgkmcnt(0)
	s_barrier
	s_setprio 1
	v_mfma_f32_16x16x32_bf16 v[60:63], v[128:131], v[186:189], v[60:63]
	v_mfma_f32_16x16x32_bf16 v[56:59], v[136:139], v[186:189], v[56:59]
	v_mfma_f32_16x16x32_bf16 v[52:55], v[128:131], v[198:201], v[52:55]
	v_mfma_f32_16x16x32_bf16 v[48:51], v[136:139], v[198:201], v[48:51]
	v_mfma_f32_16x16x32_bf16 v[36:39], v[128:131], v[206:209], v[36:39]
	v_mfma_f32_16x16x32_bf16 v[32:35], v[136:139], v[206:209], v[32:35]
	v_mfma_f32_16x16x32_bf16 v[20:23], v[128:131], v[218:221], v[20:23]
	v_mfma_f32_16x16x32_bf16 v[16:19], v[136:139], v[218:221], v[16:19]
	v_mfma_f32_16x16x32_bf16 v[60:63], v[132:135], v[194:197], v[60:63]
	v_mfma_f32_16x16x32_bf16 v[56:59], v[140:143], v[194:197], v[56:59]
	v_mfma_f32_16x16x32_bf16 v[52:55], v[132:135], v[202:205], v[52:55]
	v_mfma_f32_16x16x32_bf16 v[48:51], v[140:143], v[202:205], v[48:51]
	v_mfma_f32_16x16x32_bf16 v[36:39], v[132:135], v[210:213], v[36:39]
	v_mfma_f32_16x16x32_bf16 v[32:35], v[140:143], v[210:213], v[32:35]
	v_mfma_f32_16x16x32_bf16 v[20:23], v[132:135], v[222:225], v[20:23]
	v_mfma_f32_16x16x32_bf16 v[16:19], v[140:143], v[222:225], v[16:19]
	v_mfma_f32_16x16x32_bf16 v[44:47], v[164:167], v[186:189], v[44:47]
	v_mfma_f32_16x16x32_bf16 v[40:43], v[178:181], v[186:189], v[40:43]
	v_mfma_f32_16x16x32_bf16 v[28:31], v[164:167], v[198:201], v[28:31]
	v_mfma_f32_16x16x32_bf16 v[24:27], v[178:181], v[198:201], v[24:27]
	v_mfma_f32_16x16x32_bf16 v[12:15], v[164:167], v[206:209], v[12:15]
	v_mfma_f32_16x16x32_bf16 v[8:11], v[178:181], v[206:209], v[8:11]
	v_mfma_f32_16x16x32_bf16 v[4:7], v[164:167], v[218:221], v[4:7]
	v_mfma_f32_16x16x32_bf16 v[0:3], v[178:181], v[218:221], v[0:3]
	v_mfma_f32_16x16x32_bf16 v[44:47], v[168:171], v[194:197], v[44:47]
	v_mfma_f32_16x16x32_bf16 v[40:43], v[182:185], v[194:197], v[40:43]
	v_mfma_f32_16x16x32_bf16 v[28:31], v[168:171], v[202:205], v[28:31]
	v_mfma_f32_16x16x32_bf16 v[24:27], v[182:185], v[202:205], v[24:27]
	v_mfma_f32_16x16x32_bf16 v[12:15], v[168:171], v[210:213], v[12:15]
	v_mfma_f32_16x16x32_bf16 v[8:11], v[182:185], v[210:213], v[8:11]
	v_mfma_f32_16x16x32_bf16 v[4:7], v[168:171], v[222:225], v[4:7]
	v_mfma_f32_16x16x32_bf16 v[0:3], v[182:185], v[222:225], v[0:3]
	s_setprio 0
	s_barrier
; #define PG8_STAGE(bufoff, gbase, voff) do { _Pragma("unroll") for (int _i = 0; _i < 2; ++_i) \
;         __builtin_amdgcn_global_load_lds((const unsigned*)((const char*)(gbase) + (voff)[_i]), (PG8_LAS unsigned*)(lds + (bufoff) + ldsw + _i * 8192), 16, 0, 0); } while (0)
; #define PG8_LDA(dst, b, h) do { _Pragma("unroll") for (int m = 0; m < 4; ++m) _Pragma("unroll") for (int k = 0; k < 2; ++k) dst[m][k] = *(const PG8_LAS bf16x8*)(lds + PG8_SA(b, h) + aoff + m * 2048 + k * 1024); } while (0)
; #define PG8_LDB(dst, b, h) do { _Pragma("unroll") for (int n = 0; n < 2; ++n) _Pragma("unroll") for (int k = 0; k < 2; ++k) dst[n][k] = *(const PG8_LAS bf16x8*)(lds + PG8_SB(b, h) + boff + n * 2048 + k * 1024); } while (0)
; #define PG8_MMA(ai, bj, At, Bt) do { __builtin_amdgcn_s_setprio(1); _Pragma("unroll") for (int m = 0; m < 4; ++m) _Pragma("unroll") for (int n = 0; n < 2; ++n) _Pragma("unroll") for (int k = 0; k < 2; ++k) \
;         acc[ai][bj][m][n] = __builtin_amdgcn_mfma_f32_16x16x32_bf16(Bt[n][k], At[m][k], acc[ai][bj][m][n], 0, 0, 0); __builtin_amdgcn_s_setprio(0); } while (0)
; #define PG8_WAIT_V(n) asm volatile("s_waitcnt vmcnt(" #n ")" ::: "memory")
; #define PG8_WAIT_L(n) asm volatile("s_waitcnt lgkmcnt(" #n ")" ::: "memory")
; #define PG8_BAR __builtin_amdgcn_s_barrier()
; #define PG8_SCHED __builtin_amdgcn_sched_barrier(0)
; template <class Epi, class Sched, bool ALIGN_EPI = false, bool SP2 = false>
; __device__ __forceinline__ void gemm_phase(PG8_LAS unsigned char* lds, const Gemm g, const Sched& S, const Epi& E) {
;     ...
;             PG8_LDB(B0, 1, 0); PG8_LDB(B1, 1, 1); PG8_SCHED; PG8_LDA(At, 1, 0); PG8_STAGE(PG8_SA(0, 1), a2 + hstep, voffA);
;             PG8_WAIT_V(8); PG8_WAIT_L(0); PG8_BAR; PG8_MMA(0, 0, At, B0); PG8_MMA(0, 1, At, B1); PG8_BAR; PG8_SCHED;
	s_add_i32 s70, 0, 0x18000
	s_add_i32 s71, 0, 0x1c000
	v_add_u32_e32 v140, s70, v173
	v_add_u32_e32 v182, s71, v173
	ds_read_b128 v[128:131], v140
	ds_read_b128 v[132:135], v140 offset:1024
	ds_read_b128 v[136:139], v140 offset:2048
	ds_read_b128 v[140:143], v140 offset:3072
	ds_read_b128 v[164:167], v182
	ds_read_b128 v[168:171], v182 offset:1024
	ds_read_b128 v[178:181], v182 offset:2048
	ds_read_b128 v[182:185], v182 offset:3072
	s_add_u32 s44, s44, 0x80000
	s_addc_u32 s45, s45, 0
	s_mov_b32 m0, s54
	v_lshl_add_u64 v[230:231], s[44:45], 0, v[150:151]
	ds_read_b128 v[186:189], v177 offset:32768
	ds_read_b128 v[194:197], v177 offset:33792
	ds_read_b128 v[198:201], v177 offset:34816
	ds_read_b128 v[202:205], v177 offset:35840
	ds_read_b128 v[206:209], v177 offset:36864
	ds_read_b128 v[210:213], v177 offset:37888
	ds_read_b128 v[218:221], v177 offset:38912
	ds_read_b128 v[222:225], v177 offset:39936
	global_load_lds_dwordx4 v[230:231], off
	v_lshl_add_u64 v[230:231], s[44:45], 0, v[146:147]
	s_mov_b32 m0, s55
	s_nop 0
	global_load_lds_dwordx4 v[230:231], off
	s_waitcnt vmcnt(8)
	s_waitcnt lgkmcnt(0)
	s_barrier
	s_setprio 1
	v_mfma_f32_16x16x32_bf16 v[124:127], v[128:131], v[186:189], v[124:127]
	v_mfma_f32_16x16x32_bf16 v[120:123], v[136:139], v[186:189], v[120:123]
	v_mfma_f32_16x16x32_bf16 v[116:119], v[128:131], v[198:201], v[116:119]
	v_mfma_f32_16x16x32_bf16 v[112:115], v[136:139], v[198:201], v[112:115]
	v_mfma_f32_16x16x32_bf16 v[100:103], v[128:131], v[206:209], v[100:103]
	v_mfma_f32_16x16x32_bf16 v[96:99], v[136:139], v[206:209], v[96:99]
	v_mfma_f32_16x16x32_bf16 v[84:87], v[128:131], v[218:221], v[84:87]
	v_mfma_f32_16x16x32_bf16 v[80:83], v[136:139], v[218:221], v[80:83]
	v_mfma_f32_16x16x32_bf16 v[124:127], v[132:135], v[194:197], v[124:127]
	v_mfma_f32_16x16x32_bf16 v[120:123], v[140:143], v[194:197], v[120:123]
	v_mfma_f32_16x16x32_bf16 v[116:119], v[132:135], v[202:205], v[116:119]
	v_mfma_f32_16x16x32_bf16 v[112:115], v[140:143], v[202:205], v[112:115]
	v_mfma_f32_16x16x32_bf16 v[100:103], v[132:135], v[210:213], v[100:103]
	v_mfma_f32_16x16x32_bf16 v[96:99], v[140:143], v[210:213], v[96:99]
	v_mfma_f32_16x16x32_bf16 v[84:87], v[132:135], v[222:225], v[84:87]
	v_mfma_f32_16x16x32_bf16 v[80:83], v[140:143], v[222:225], v[80:83]
	v_mfma_f32_16x16x32_bf16 v[108:111], v[164:167], v[186:189], v[108:111]
	v_mfma_f32_16x16x32_bf16 v[104:107], v[178:181], v[186:189], v[104:107]
	v_mfma_f32_16x16x32_bf16 v[92:95], v[164:167], v[198:201], v[92:95]
	v_mfma_f32_16x16x32_bf16 v[88:91], v[178:181], v[198:201], v[88:91]
	v_mfma_f32_16x16x32_bf16 v[76:79], v[164:167], v[206:209], v[76:79]
	v_mfma_f32_16x16x32_bf16 v[72:75], v[178:181], v[206:209], v[72:75]
	v_mfma_f32_16x16x32_bf16 v[68:71], v[164:167], v[218:221], v[68:71]
	v_mfma_f32_16x16x32_bf16 v[64:67], v[178:181], v[218:221], v[64:67]
	v_mfma_f32_16x16x32_bf16 v[108:111], v[168:171], v[194:197], v[108:111]
	v_mfma_f32_16x16x32_bf16 v[104:107], v[182:185], v[194:197], v[104:107]
	v_mfma_f32_16x16x32_bf16 v[92:95], v[168:171], v[202:205], v[92:95]
	v_mfma_f32_16x16x32_bf16 v[88:91], v[182:185], v[202:205], v[88:91]
	v_mfma_f32_16x16x32_bf16 v[76:79], v[168:171], v[210:213], v[76:79]
	v_mfma_f32_16x16x32_bf16 v[72:75], v[182:185], v[210:213], v[72:75]
	v_mfma_f32_16x16x32_bf16 v[68:71], v[168:171], v[222:225], v[68:71]
	v_mfma_f32_16x16x32_bf16 v[64:67], v[182:185], v[222:225], v[64:67]
	s_setprio 0
	s_barrier
; #define PG8_STAGE(bufoff, gbase, voff) do { _Pragma("unroll") for (int _i = 0; _i < 2; ++_i) \
;         __builtin_amdgcn_global_load_lds((const unsigned*)((const char*)(gbase) + (voff)[_i]), (PG8_LAS unsigned*)(lds + (bufoff) + ldsw + _i * 8192), 16, 0, 0); } while (0)
; #define PG8_LDA(dst, b, h) do { _Pragma("unroll") for (int m = 0; m < 4; ++m) _Pragma("unroll") for (int k = 0; k < 2; ++k) dst[m][k] = *(const PG8_LAS bf16x8*)(lds + PG8_SA(b, h) + aoff + m * 2048 + k * 1024); } while (0)
; #define PG8_MMA(ai, bj, At, Bt) do { __builtin_amdgcn_s_setprio(1); _Pragma("unroll") for (int m = 0; m < 4; ++m) _Pragma("unroll") for (int n = 0; n < 2; ++n) _Pragma("unroll") for (int k = 0; k < 2; ++k) \
;         acc[ai][bj][m][n] = __builtin_amdgcn_mfma_f32_16x16x32_bf16(Bt[n][k], At[m][k], acc[ai][bj][m][n], 0, 0, 0); __builtin_amdgcn_s_setprio(0); } while (0)
; #define PG8_WAIT_V(n) asm volatile("s_waitcnt vmcnt(" #n ")" ::: "memory")
; #define PG8_WAIT_L(n) asm volatile("s_waitcnt lgkmcnt(" #n ")" ::: "memory")
; #define PG8_BAR __builtin_amdgcn_s_barrier()
; #define PG8_SCHED __builtin_amdgcn_sched_barrier(0)
; template <class Epi, class Sched, bool ALIGN_EPI = false, bool SP2 = false>
; __device__ __forceinline__ void gemm_phase(PG8_LAS unsigned char* lds, const Gemm g, const Sched& S, const Epi& E) {
;     ...
;             PG8_LDA(At, 1, 1); PG8_STAGE(PG8_SB(1, 0), b3, voffB); PG8_STAGE(PG8_SB(1, 1), b3 + hstep, voffB); PG8_STAGE(PG8_SA(1, 0), a3, voffA);
;             PG8_WAIT_V(8); PG8_WAIT_L(0); PG8_BAR; PG8_MMA(1, 0, At, B0); PG8_MMA(1, 1, At, B1); PG8_BAR; PG8_SCHED;
;     ...
;         }
;         if constexpr (ALIGN_EPI) { if (wr == 0) PG8_BAR; }
	s_add_i32 s44, s70, s50
	v_lshl_add_u64 v[190:191], v[190:191], 0, s[22:23]
	s_mov_b32 m0, s44
	ds_read_b128 v[186:189], v177 offset:49152
	ds_read_b128 v[194:197], v177 offset:50176
	ds_read_b128 v[198:201], v177 offset:51200
	ds_read_b128 v[202:205], v177 offset:52224
	ds_read_b128 v[206:209], v177 offset:53248
	ds_read_b128 v[210:213], v177 offset:54272
	ds_read_b128 v[218:221], v177 offset:55296
	ds_read_b128 v[222:225], v177 offset:56320
	global_load_lds_dwordx4 v[190:191], off
	s_add_i32 m0, s44, 0x2000
	s_add_u32 s42, s42, 0x80080
	v_lshl_add_u64 v[190:191], v[214:215], 0, s[22:23]
	s_addc_u32 s43, s43, 0
	s_add_i32 s44, s71, s50
	global_load_lds_dwordx4 v[190:191], off
	v_lshl_add_u64 v[190:191], s[42:43], 0, v[148:149]
	s_mov_b32 m0, s44
	s_nop 0
	global_load_lds_dwordx4 v[190:191], off
	v_lshl_add_u64 v[190:191], s[42:43], 0, v[144:145]
	s_add_i32 m0, s44, 0x2000
	s_nop 0
	global_load_lds_dwordx4 v[190:191], off
	v_lshl_add_u64 v[190:191], v[226:227], 0, s[22:23]
	s_mov_b32 m0, s59
	s_nop 0
	global_load_lds_dwordx4 v[190:191], off
	v_lshl_add_u64 v[190:191], v[228:229], 0, s[22:23]
	s_mov_b32 m0, s60
	s_nop 0
	global_load_lds_dwordx4 v[190:191], off
	s_waitcnt vmcnt(8)
	s_waitcnt lgkmcnt(0)
	s_barrier
	s_setprio 1
	v_mfma_f32_16x16x32_bf16 v[60:63], v[128:131], v[186:189], v[60:63]
	v_mfma_f32_16x16x32_bf16 v[56:59], v[136:139], v[186:189], v[56:59]
	v_mfma_f32_16x16x32_bf16 v[52:55], v[128:131], v[198:201], v[52:55]
	v_mfma_f32_16x16x32_bf16 v[48:51], v[136:139], v[198:201], v[48:51]
	v_mfma_f32_16x16x32_bf16 v[36:39], v[128:131], v[206:209], v[36:39]
	v_mfma_f32_16x16x32_bf16 v[32:35], v[136:139], v[206:209], v[32:35]
	v_mfma_f32_16x16x32_bf16 v[20:23], v[128:131], v[218:221], v[20:23]
	v_mfma_f32_16x16x32_bf16 v[16:19], v[136:139], v[218:221], v[16:19]
	v_mfma_f32_16x16x32_bf16 v[60:63], v[132:135], v[194:197], v[60:63]
	v_mfma_f32_16x16x32_bf16 v[56:59], v[140:143], v[194:197], v[56:59]
	v_mfma_f32_16x16x32_bf16 v[52:55], v[132:135], v[202:205], v[52:55]
	v_mfma_f32_16x16x32_bf16 v[48:51], v[140:143], v[202:205], v[48:51]
	v_mfma_f32_16x16x32_bf16 v[36:39], v[132:135], v[210:213], v[36:39]
	v_mfma_f32_16x16x32_bf16 v[32:35], v[140:143], v[210:213], v[32:35]
	v_mfma_f32_16x16x32_bf16 v[20:23], v[132:135], v[222:225], v[20:23]
	v_mfma_f32_16x16x32_bf16 v[16:19], v[140:143], v[222:225], v[16:19]
	v_mfma_f32_16x16x32_bf16 v[44:47], v[164:167], v[186:189], v[44:47]
	v_mfma_f32_16x16x32_bf16 v[40:43], v[178:181], v[186:189], v[40:43]
	v_mfma_f32_16x16x32_bf16 v[28:31], v[164:167], v[198:201], v[28:31]
	v_mfma_f32_16x16x32_bf16 v[24:27], v[178:181], v[198:201], v[24:27]
	v_mfma_f32_16x16x32_bf16 v[12:15], v[164:167], v[206:209], v[12:15]
	v_mfma_f32_16x16x32_bf16 v[8:11], v[178:181], v[206:209], v[8:11]
	v_mfma_f32_16x16x32_bf16 v[4:7], v[164:167], v[218:221], v[4:7]
	v_mfma_f32_16x16x32_bf16 v[0:3], v[178:181], v[218:221], v[0:3]
	v_mfma_f32_16x16x32_bf16 v[44:47], v[168:171], v[194:197], v[44:47]
	v_mfma_f32_16x16x32_bf16 v[40:43], v[182:185], v[194:197], v[40:43]
	v_mfma_f32_16x16x32_bf16 v[28:31], v[168:171], v[202:205], v[28:31]
	v_mfma_f32_16x16x32_bf16 v[24:27], v[182:185], v[202:205], v[24:27]
	v_mfma_f32_16x16x32_bf16 v[12:15], v[168:171], v[210:213], v[12:15]
	v_mfma_f32_16x16x32_bf16 v[8:11], v[182:185], v[210:213], v[8:11]
	v_mfma_f32_16x16x32_bf16 v[4:7], v[168:171], v[222:225], v[4:7]
	v_mfma_f32_16x16x32_bf16 v[0:3], v[182:185], v[222:225], v[0:3]
	s_setprio 0
	s_barrier
	s_add_i32 s69, s69, 2
	s_add_u32 s40, s40, 0x100
	s_addc_u32 s41, s41, 0
	s_add_u32 s67, s67, 0x100
	s_addc_u32 s68, s68, 0
	s_cmp_gt_u32 s69, 29
	s_cbranch_scc0 .LBB0_171
	s_and_b64 vcc, exec, s[24:25]
	s_cbranch_vccz .LBB0_174
	s_barrier

; #define VMW() asm volatile("s_waitcnt vmcnt(0)" ::: "memory")
; #define SLOAD_H(Kp, Vp, k0) do { S.st_v0 = load8(ROW(Vp, k0, sr)); S.st_v1 = load8(ROW(Vp, k0, 32 + sr)); S.st_k0 = load8(ROW(Kp, k0, sr)); S.st_k1 = load8(ROW(Kp, k0, 32 + sr)); } while (0)
; #define SWRITE_HK(bf) do { *(bf16x8*)(K_lds + (bf) * SHM_K + kws) = S.st_k0; *(bf16x8*)(K_lds + (bf) * SHM_K + kws + 32 * 256) = S.st_k1; } while (0)
; #define WSP(off) ((bf16*)((unsigned char*)kargp(25) + (off)))
; __device__ __forceinline__ void attn_prime(const BlockRef& cur, char* lds, Seam& S) {
;     int tid_ = threadIdx.x; asm volatile("" : "+v"(tid_));
;     const int tid = tid_, wid = __builtin_amdgcn_readfirstlane(tid >> 6), lane = tid & 63, r32 = lane & 31, hi = lane >> 5;
;     const int sr = tid >> 4, sc = (tid & 15) * 8, kws = KSWZ(sr, sc * 2); char* K_lds = lds + 2 * SHM_V;
;     for (int d0 = 0; d0 < 8; ++d0) S.qr[d0] = load8(cur.Q + (size_t)(wid * QBLK + r32) * D + d0 * 16 + hi * 8);
;     SLOAD_H(cur.K, cur.V, 0); VMW(); SWRITE_HK(0);
;     __syncthreads();
; }
; __global__ void __launch_bounds__(NTHR, 2) mega_fwd(Args args) {
;     ...
;         bf16* QH = WSP(WS_QH); bf16* KH = WSP(WS_KH); bf16* VH = WSP(WS_VH); bf16* O16 = WSP(WS_O16); bf16* OA = WSP(WS_OA);
;         att::Seam S;
;         const int NSI = BATCH * 4 * 16;
;         if (vcu < NSI) {
;             int si = vcu, sub = 0;
;     ...
;             att::BlockRef cur, nxt; MKREF(cur, si, sub);
;             att::attn_prime(cur, (char*)lds, S);
.LBB0_314:
	s_or_b64 exec, exec, s[14:15]
	s_nop 0
	s_nop 0
	s_nop 0
	s_nop 0
	s_nop 0
	s_nop 0
	s_nop 0
	s_nop 0
	s_waitcnt lgkmcnt(0)
	s_barrier
	s_movk_i32 s13, 0x100
	s_cmpk_lt_i32 s66, 0x100
	s_mov_b64 s[22:23], s[0:1]
	v_readfirstlane_b32 s24, v192
	s_mov_b64 s[20:21], s[0:1]
	s_mov_b64 s[18:19], s[0:1]
	s_mov_b64 s[14:15], s[0:1]
	s_mov_b64 s[16:17], s[0:1]
	s_cbranch_scc0 .LBB0_488
	s_load_dwordx2 s[22:23], s[22:23], 0xc8
	v_mov_b32_e32 v1, v216
	s_load_dwordx2 s[20:21], s[20:21], 0xc8
	v_mov_b32_e32 v195, 0
	s_load_dwordx2 s[18:19], s[18:19], 0xc8
	s_waitcnt lgkmcnt(0)
	s_add_u32 s25, s22, 0x2f800000
	s_addc_u32 s26, s23, 0
	s_load_dwordx2 s[14:15], s[14:15], 0xc8
	s_add_u32 s27, s20, 0x33800000
	s_addc_u32 s28, s21, 0
	s_add_u32 s30, s18, 0x37800000
	s_addc_u32 s31, s19, 0
	s_waitcnt lgkmcnt(0)
	s_add_u32 s14, s14, 0xf800000
	s_addc_u32 s15, s15, 0
	s_bfe_u32 s20, s66, 0x20004
	s_ashr_i32 s21, s66, 6
	s_lshl_b32 s18, s20, 15
	s_lshl_b32 s19, s21, 17
	s_or_b32 s18, s18, s19
	s_lshl_b32 s19, s66, 8
	s_and_b32 s19, s19, 0xf00
	s_lshl_b32 s20, s20, 14
	s_lshl_b32 s21, s21, 16
	s_xor_b32 s29, s19, 0x1f00
	s_or_b32 s20, s20, s21
	s_or_b32 s18, s18, s29
	s_or_b32 s22, s20, s29
	s_ashr_i32 s19, s18, 31
	s_ashr_i32 s23, s22, 31
	s_lshl_b64 s[18:19], s[18:19], 8
	s_ashr_i32 s21, s20, 31
	s_lshl_b64 s[22:23], s[22:23], 8
	s_add_u32 s36, s25, s22
	s_addc_u32 s37, s26, s23
	s_lshl_b64 s[20:21], s[20:21], 8
	s_add_u32 s70, s27, s20
	s_addc_u32 s71, s28, s21
	s_add_u32 s72, s30, s20
	s_addc_u32 s73, s31, s21
	s_load_dwordx2 s[16:17], s[16:17], 0xc8
	s_add_u32 s22, s14, s18
	s_addc_u32 s23, s15, s19
	v_readfirstlane_b32 s18, v1
	s_ashr_i32 s18, s18, 1
	s_movk_i32 s19, 0xffe0
	v_mov_b32_e32 v2, s18
	v_bfi_b32 v2, s19, v2, v1
	v_ashrrev_i32_e32 v3, 31, v2
	v_lshlrev_b64 v[2:3], 8, v[2:3]
	s_waitcnt vmcnt(32)
	v_lshrrev_b32_e32 v4, 1, v1
	v_lshl_add_u64 v[2:3], s[36:37], 0, v[2:3]
	v_and_b32_e32 v194, 16, v4
	v_lshl_add_u64 v[2:3], v[2:3], 0, v[194:195]
	global_load_dwordx4 v[156:159], v[2:3], off
	global_load_dwordx4 v[152:155], v[2:3], off offset:32
	global_load_dwordx4 v[148:151], v[2:3], off offset:64
	global_load_dwordx4 v[144:147], v[2:3], off offset:96
	global_load_dwordx4 v[140:143], v[2:3], off offset:128
	global_load_dwordx4 v[136:139], v[2:3], off offset:160
	global_load_dwordx4 v[132:135], v[2:3], off offset:192
	global_load_dwordx4 v[128:131], v[2:3], off offset:224
	v_ashrrev_i32_e32 v2, 4, v1
	v_lshlrev_b32_e32 v3, 4, v1
	s_movk_i32 s18, 0xf0
	v_and_b32_e32 v1, 0x70, v1
	v_and_b32_e32 v194, 0xf0, v3
	v_bitop3_b32 v1, v3, v1, s18 bitop3:0x6c
	v_ashrrev_i32_e32 v3, 31, v2
	s_waitcnt vmcnt(37)
	v_lshlrev_b32_e32 v10, 8, v2
	v_lshlrev_b64 v[2:3], 8, v[2:3]
	v_lshl_add_u64 v[4:5], s[72:73], 0, v[2:3]
	s_mov_b64 s[18:19], 0x2000
	v_lshl_add_u64 v[4:5], v[4:5], 0, v[194:195]
	v_lshl_add_u64 v[6:7], v[2:3], 0, s[18:19]
	global_load_dwordx4 v[96:99], v[4:5], off
	v_lshl_add_u64 v[4:5], s[72:73], 0, v[6:7]
	v_lshl_add_u64 v[2:3], s[70:71], 0, v[2:3]
	v_lshl_add_u64 v[4:5], v[4:5], 0, v[194:195]
	v_lshl_add_u64 v[2:3], v[2:3], 0, v[194:195]
	v_lshl_add_u64 v[6:7], s[70:71], 0, v[6:7]
	global_load_dwordx4 v[100:103], v[4:5], off
	v_lshl_add_u64 v[6:7], v[6:7], 0, v[194:195]
	global_load_dwordx4 v[2:5], v[2:3], off
	v_writelane_b32 v254, s25, 53
	global_load_dwordx4 v[6:9], v[6:7], off
	v_add3_u32 v1, 0, v10, v1
	v_and_b32_e32 v255, 0x800, v10
	v_lshrrev_b32_e32 v255, 4, v255
	v_xor_b32_e32 v1, v1, v255
	v_writelane_b32 v254, s26, 54
	s_waitcnt vmcnt(0)
	v_writelane_b32 v254, s27, 55
	s_ashr_i32 s18, s24, 3
	v_writelane_b32 v254, s28, 56
	s_and_b32 s18, s18, -8
	v_and_b32_e32 v0, 63, v192
	v_writelane_b32 v254, s30, 57
	s_cmpk_lt_i32 s18, 0x200
	v_writelane_b32 v254, s31, 58
	s_mov_b32 s48, 0
	v_bfe_u32 v193, v192, 4, 2
	s_cselect_b64 s[24:25], -1, 0
	s_mov_b32 s67, 0x41000000
	s_mov_b32 s26, 0x3e0293ee
	v_mbcnt_hi_u32_b32 v205, -1, v217
	v_lshlrev_b32_e32 v214, 2, v0
	s_mov_b32 s28, 0x3f4ccccd
	s_mov_b32 s64, 0x200000
	s_mov_b32 s65, 0x400000
	s_mov_b32 s27, 0x600000
	v_mov_b32_e32 v218, 0x358637bd
	s_mov_b32 s47, 0xf800000
	v_mov_b32_e32 v219, 0x260
	v_mov_b32_e32 v220, 0xff800000
	v_mov_b32_e32 v221, 0xf149f2ca
	s_mov_b32 s77, 0
	v_writelane_b32 v254, s18, 59
	s_waitcnt vmcnt(1)
	ds_write_b128 v1, v[2:5] offset:32768
	s_waitcnt vmcnt(0)
	ds_write_b128 v1, v[6:9] offset:40960
	v_lshlrev_b32_e32 v1, 3, v192
	v_and_b32_e32 v2, 0x78, v1
	v_lshlrev_b32_e32 v194, 1, v2
	s_waitcnt lgkmcnt(0)
	v_lshl_add_u64 v[4:5], s[16:17], 0, v[194:195]
	s_mov_b64 s[16:17], 0x17800000
	v_lshl_add_u64 v[196:197], s[14:15], 0, v[194:195]
	v_lshl_add_u64 v[198:199], v[4:5], 0, s[16:17]
	v_lshlrev_b32_e32 v215, 2, v2
	s_barrier
	s_branch .LBB0_317

; #define PG8_WAIT_V(n) asm volatile("s_waitcnt vmcnt(" #n ")" ::: "memory")
; #define PG8_BAR __builtin_amdgcn_s_barrier()
; template <class Epi, class Sched, bool ALIGN_EPI = false, bool SP2 = false>
; __device__ __forceinline__ void gemm_phase(PG8_LAS unsigned char* lds, const Gemm g, const Sched& S, const Epi& E) {
;     int tid_ = threadIdx.x; asm volatile("" : "+v"(tid_));
;     const int tid = tid_, wid = __builtin_amdgcn_readfirstlane(tid >> 6), lane = tid & 63, wr = wid >> 2, wc = wid & 3, fr = lane & 15, fq = lane >> 4;
;     const int K = g.K, nt = K / BK;
;     unsigned voffA[2], voffB[2];
; #pragma unroll
;     for (int i = 0; i < 2; ++i) { int R, C; stage_rc(tid * 16 + i * 8192, R, C); const int Rb = Epi::PERM ? ((R & ~31) + perm32(R & 31)) : R;
;         voffA[i] = (unsigned)(R * K + C) * 2u; voffB[i] = (unsigned)(Rb * K + C) * 2u; }
;     const size_t kstep = (size_t)(BK * 2);
;     const size_t hstep = (size_t)HALF * K * 2;
;     const size_t tstep = 2 * hstep;
;     const unsigned ldsw = (unsigned)wid * 1024u;
;     const int aoff = lds_byte(wr * 64 + fr, fq * 8), boff = lds_byte(wc * 32 + fr, fq * 8);
;     ...
;     Unit cur, nxt; int ui = 0;
;     if (!S.next(0, cur)) return;
;     f32x4 acc[2][2][4][2];
; #pragma unroll
;     for (int a = 0; a < 2; ++a)
; #pragma unroll
;         for (int b = 0; b < 2; ++b)
; #pragma unroll
;             for (int m = 0; m < 4; ++m)
; #pragma unroll
;                 for (int n = 0; n < 2; ++n) acc[a][b][m][n] = (f32x4){0.f, 0.f, 0.f, 0.f};
;     bf16x8 At[4][2], B0[2][2], B1[2][2];
;     const char* cA = (const char*)g.A + (size_t)cur.pm * tstep; const char* cB = (const char*)g.Bt + (size_t)cur.pn * tstep;
;     S.a_ready(cur);
;     if constexpr (SP2) {
;         PG8_STAGE(PG8_SB(0, 0), cB, voffB); PG8_STAGE(PG8_SB(0, 1), cB + hstep, voffB); PG8_STAGE(PG8_SA(0, 0), cA, voffA); PG8_STAGE(PG8_SA(0, 1), cA + hstep, voffA);
;         if (wr == 1) PG8_BAR;
;         PG8_WAIT_V(2); PG8_BAR;
;         PG8_STAGE(PG8_SB(1, 0), cB + kstep, voffB); PG8_STAGE(PG8_SA(1, 0), cA + kstep, voffA); PG8_STAGE(PG8_SB(1, 1), cB + hstep + kstep, voffB);
;         PG8_WAIT_V(6); PG8_BAR;
;     } else {
;         PG8_STAGE(PG8_SB(0, 0), cB, voffB); PG8_STAGE(PG8_SA(0, 0), cA, voffA); PG8_STAGE(PG8_SB(0, 1), cB + hstep, voffB); PG8_STAGE(PG8_SA(0, 1), cA + hstep, voffA);
;         if (wr == 1) PG8_BAR;
.LBB0_540:
	s_or_b64 exec, exec, s[14:15]
	s_nop 0
	s_nop 0
	s_nop 0
	s_nop 0
	s_nop 0
	s_nop 0
	s_nop 0
	s_nop 0
	s_nop 0
	s_nop 0
	s_nop 0
	s_nop 0
	s_cmpk_lt_i32 s2, 0x400
	s_mov_b64 s[22:23], s[0:1]
	s_mov_b64 s[16:17], s[0:1]
	s_mov_b64 s[24:25], s[0:1]
	s_mov_b64 s[18:19], s[0:1]
	s_mov_b64 s[14:15], s[0:1]
	s_waitcnt lgkmcnt(0)
	s_barrier
	s_cselect_b64 s[48:49], -1, 0
	s_lshr_b32 s13, s33, 29
	s_add_i32 s13, s2, s13
	s_load_dwordx2 s[14:15], s[14:15], 0xc8
	s_ashr_i32 s56, s13, 3
	s_and_b32 s13, s13, -8
	s_load_dwordx2 s[20:21], s[16:17], 0xc8
	s_nop 0
	s_load_dwordx2 s[18:19], s[18:19], 0xc8
	s_mov_b64 s[16:17], s[0:1]
	s_sub_i32 s59, s2, s13
	s_cmp_lt_i32 s59, 0
	s_load_dwordx2 s[16:17], s[16:17], 0xc8
	s_cselect_b64 s[42:43], -1, 0
	s_lshl_b32 s57, s59, 7
	s_waitcnt lgkmcnt(0)
	s_add_u32 s14, s14, 0x2f800000
	s_addc_u32 s15, s15, 0
	s_waitcnt vmcnt(27)
	v_mov_b32_e32 v14, v216
	s_cmpk_gt_i32 s2, 0x3ff
	s_mul_i32 s58, s59, 0x81
	s_nop 0
	v_readfirstlane_b32 s28, v14
	s_cbranch_scc1 .LBB0_560
	v_lshlrev_b32_e32 v0, 4, v14
	v_add_u32_e32 v1, 0x2000, v0
	v_ashrrev_i32_e32 v2, 31, v1
	v_lshrrev_b32_e32 v2, 22, v2
	v_add_u32_e32 v2, v1, v2
	v_ashrrev_i32_e32 v8, 10, v2
	v_mul_i32_i24_e32 v2, 0x400, v8
	v_sub_u32_e32 v1, v1, v2
	v_lshrrev_b32_e32 v2, 4, v1
	v_bitop3_b32 v1, v2, v1, 32 bitop3:0x6c
	v_ashrrev_i32_e32 v2, 31, v1
	s_load_dwordx2 s[22:23], s[22:23], 0xc8
	s_nop 0
	s_load_dwordx2 s[24:25], s[24:25], 0xc8
	v_lshrrev_b32_e32 v2, 26, v2
	v_add_u32_e32 v2, v1, v2
	v_lshlrev_b32_e32 v3, 3, v8
	v_ashrrev_i32_e32 v9, 6, v2
	v_and_b32_e32 v3, -16, v3
	v_add_u32_e32 v3, v9, v3
	s_waitcnt lgkmcnt(0)
	s_add_u32 s13, s22, 0x3b800000
	v_and_b32_e32 v4, 3, v9
	s_mov_b32 s22, 0x1fffe0
	v_lshrrev_b32_e32 v5, 2, v3
	v_lshlrev_b32_e32 v6, 1, v3
	v_and_b32_e32 v2, 0xc0, v2
	v_and_or_b32 v4, v3, s22, v4
	v_and_b32_e32 v5, 4, v5
	v_and_b32_e32 v6, 24, v6
	v_sub_u32_e32 v1, v1, v2
	v_mov_b32_e32 v2, 1
	v_or3_b32 v4, v4, v5, v6
	v_lshlrev_b32_e32 v5, 5, v8
	v_ashrrev_i16_sdwa v1, v2, sext(v1) dst_sel:DWORD dst_unused:UNUSED_PAD src0_sel:DWORD src1_sel:BYTE_0
	v_and_b32_e32 v5, 32, v5
	v_bfe_i32 v10, v1, 0, 16
	v_add_lshl_u32 v1, v5, v10, 1
	s_waitcnt vmcnt(6)
	v_lshl_add_u32 v152, v4, 11, v1
	v_lshl_add_u32 v154, v3, 11, v1
	v_bfe_i32 v1, v14, 27, 1
	v_lshrrev_b32_e32 v1, 22, v1
	v_add_u32_e32 v1, v0, v1
	v_and_b32_e32 v1, 0xfffffc00, v1
	v_sub_u32_e32 v0, v0, v1
	v_lshrrev_b32_e32 v1, 4, v0
	v_ashrrev_i32_e32 v3, 31, v14
	v_bitop3_b32 v0, v1, v0, 32 bitop3:0x6c
	v_lshrrev_b32_e32 v3, 26, v3
	v_ashrrev_i32_e32 v1, 31, v0
	v_add_u32_e32 v3, v14, v3
	s_addc_u32 s47, s23, 0
	v_lshrrev_b32_e32 v1, 26, v1
	v_ashrrev_i32_e32 v12, 6, v3
	s_add_u32 s60, s24, 0x2600000
	v_add_u32_e32 v1, v0, v1
	v_lshlrev_b32_e32 v3, 3, v12
	s_addc_u32 s61, s25, 0
	s_ashr_i32 s26, s28, 6
	v_ashrrev_i32_e32 v11, 6, v1
	v_and_b32_e32 v3, -16, v3
	s_ashr_i32 s27, s28, 8
	s_lshl_b32 s62, s26, 10
	v_add_u32_e32 v3, v11, v3
	v_and_b32_e32 v4, 3, v11
	v_and_or_b32 v4, v3, s22, v4
	s_and_b64 s[22:23], s[42:43], exec
	s_cselect_b32 s22, s58, s57
	s_add_i32 s22, s22, s56
	s_ashr_i32 s23, s22, 31
	s_lshr_b32 s23, s23, 27
	s_add_i32 s23, s22, s23
	s_ashr_i32 s24, s23, 5
	s_and_b32 s23, s23, 0xffe0
	s_sub_i32 s22, s22, s23
	s_bfe_i32 s23, s22, 0x80000
	s_bfe_u32 s23, s23, 0x2000d
	s_add_i32 s23, s22, s23
	s_lshl_b32 s25, s24, 2
	s_bfe_i32 s24, s23, 0x80000
	s_and_b32 s23, s23, 0xfc
	s_sub_i32 s22, s22, s23
	s_sext_i32_i16 s24, s24
	s_sext_i32_i8 s22, s22
	v_lshrrev_b32_e32 v5, 2, v3
	v_lshlrev_b32_e32 v6, 1, v3
	v_and_b32_e32 v1, 0xc0, v1
	s_lshr_b32 s24, s24, 2
	s_add_i32 s44, s25, s22
	v_and_b32_e32 v5, 4, v5
	v_and_b32_e32 v6, 24, v6
	v_sub_u32_e32 v0, v0, v1
	s_ashr_i32 s45, s44, 31
	s_bfe_i64 s[30:31], s[24:25], 0x100000
	v_or3_b32 v4, v4, v5, v6
	v_lshlrev_b32_e32 v5, 5, v12
	v_ashrrev_i16_sdwa v0, v2, sext(v0) dst_sel:DWORD dst_unused:UNUSED_PAD src0_sel:DWORD src1_sel:BYTE_0
	s_lshl_b64 s[22:23], s[44:45], 19
	s_lshl_b64 s[30:31], s[30:31], 19
	v_and_b32_e32 v5, 32, v5
	v_bfe_i32 v13, v0, 0, 16
	s_add_u32 s52, s60, s30
	v_add_lshl_u32 v0, v5, v13, 1
	s_addc_u32 s53, s61, s31
	s_add_i32 s63, s62, 0
	v_lshl_add_u32 v156, v4, 11, v0
	s_add_i32 m0, s63, 0x10000
	v_lshl_add_u32 v158, v3, 11, v0
	global_load_lds_dwordx4 v156, s[52:53]
	s_add_i32 m0, s63, 0x12000
	s_add_u32 s30, s52, 0x40000
	global_load_lds_dwordx4 v152, s[52:53]
	s_addc_u32 s31, s53, 0
	s_add_i32 m0, s63, 0x14000
	v_mov_b32_e32 v157, 0
	global_load_lds_dwordx4 v156, s[30:31]
	s_add_i32 m0, s63, 0x16000
	s_add_u32 s50, s13, s22
	s_addc_u32 s51, s47, s23
	s_add_i32 s64, s63, 0x2000
	global_load_lds_dwordx4 v152, s[30:31]
	s_mov_b32 m0, s63
	s_add_u32 s22, s50, 0x40000
	global_load_lds_dwordx4 v158, s[50:51]
	s_mov_b32 m0, s64
	s_addc_u32 s23, s51, 0
	s_add_i32 s65, s63, 0x4000
	global_load_lds_dwordx4 v154, s[50:51]
	s_mov_b32 m0, s65
	s_add_i32 s66, s63, 0x6000
	global_load_lds_dwordx4 v158, s[22:23]
	s_mov_b32 m0, s66
	v_mov_b32_e32 v153, v157
	global_load_lds_dwordx4 v154, s[22:23]
	v_mov_b32_e32 v159, v157
	v_mov_b32_e32 v155, v157
	s_cmp_eq_u32 s27, 1
	v_lshl_add_u64 v[6:7], s[52:53], 0, v[156:157]
	v_lshl_add_u64 v[4:5], s[52:53], 0, v[152:153]
	v_lshl_add_u64 v[0:1], s[50:51], 0, v[158:159]
	s_cselect_b64 s[22:23], -1, 0
	s_cmp_lg_u32 s27, 1
	v_lshl_add_u64 v[2:3], s[50:51], 0, v[154:155]
	s_cbranch_scc1 .LBB0_543
	s_barrier

; #define PG8_STAGE(bufoff, gbase, voff) do { _Pragma("unroll") for (int _i = 0; _i < 2; ++_i) \
;         __builtin_amdgcn_global_load_lds((const unsigned*)((const char*)(gbase) + (voff)[_i]), (PG8_LAS unsigned*)(lds + (bufoff) + ldsw + _i * 8192), 16, 0, 0); } while (0)
; #define PG8_LDA(dst, b, h) do { _Pragma("unroll") for (int m = 0; m < 4; ++m) _Pragma("unroll") for (int k = 0; k < 2; ++k) dst[m][k] = *(const PG8_LAS bf16x8*)(lds + PG8_SA(b, h) + aoff + m * 2048 + k * 1024); } while (0)
; #define PG8_LDB(dst, b, h) do { _Pragma("unroll") for (int n = 0; n < 2; ++n) _Pragma("unroll") for (int k = 0; k < 2; ++k) dst[n][k] = *(const PG8_LAS bf16x8*)(lds + PG8_SB(b, h) + boff + n * 2048 + k * 1024); } while (0)
; #define PG8_WAIT_V(n) asm volatile("s_waitcnt vmcnt(" #n ")" ::: "memory")
; #define PG8_WAIT_L(n) asm volatile("s_waitcnt lgkmcnt(" #n ")" ::: "memory")
; #define PG8_BAR __builtin_amdgcn_s_barrier()
; #define PG8_SCHED __builtin_amdgcn_sched_barrier(0)
; template <class Epi, class Sched, bool ALIGN_EPI = false, bool SP2 = false>
; __device__ __forceinline__ void gemm_phase(PG8_LAS unsigned char* lds, const Gemm g, const Sched& S, const Epi& E) {
;     ...
;         const bool has_next = S.next(ui + 1, nxt);
;         const char* nA = has_next ? (const char*)g.A + (size_t)nxt.pm * tstep : cA; const char* nB = has_next ? (const char*)g.Bt + (size_t)nxt.pn * tstep : cB;
;         for (int t = 0; t < nt; t += 2) {
;             const bool last = (t == nt - 2);
;             const char* a1 = cA + (size_t)(t + 1) * kstep;
;             const char* a2 = last ? nA : cA + (size_t)(t + 2) * kstep; const char* b2 = last ? nB : cB + (size_t)(t + 2) * kstep;
;             const char* a3 = a2 + kstep; const char* b3 = b2 + kstep;
;             if (last && has_next) S.a_ready(nxt);
;             if constexpr (SP2) {
;             PG8_LDB(B0, 0, 0); PG8_LDB(B1, 0, 1); PG8_SCHED; PG8_LDA(At, 0, 0); PG8_STAGE(PG8_SA(1, 1), a1 + hstep, voffA);
;             PG8_WAIT_V(8); PG8_WAIT_L(0); PG8_BAR; PG8_MMA(0, 0, At, B0); PG8_MMA(0, 1, At, B1); PG8_BAR; PG8_SCHED;
;             PG8_LDA(At, 0, 1); PG8_STAGE(PG8_SB(0, 0), b2, voffB); PG8_STAGE(PG8_SB(0, 1), b2 + hstep, voffB); PG8_STAGE(PG8_SA(0, 0), a2, voffA);
;             PG8_WAIT_V(8); PG8_WAIT_L(0); PG8_BAR; PG8_MMA(1, 0, At, B0); PG8_MMA(1, 1, At, B1); PG8_BAR; PG8_SCHED;
.LBB0_552:
	s_ashr_i32 s35, s34, 31
	s_lshl_b64 s[36:37], s[34:35], 19
	s_add_u32 s36, s13, s36
	s_addc_u32 s37, s47, s37
	s_and_b64 s[40:41], s[38:39], exec
	s_cselect_b32 s35, s37, s51
	s_cselect_b32 s72, s36, s50
	s_ashr_i32 s31, s30, 31
	s_lshl_b64 s[40:41], s[30:31], 19
	s_add_u32 s40, s60, s40
	s_addc_u32 s41, s61, s41
	s_and_b64 s[54:55], s[38:39], exec
	s_cselect_b32 s31, s41, s53
	s_cselect_b32 s73, s40, s52
	s_add_u32 s50, s50, 0x40080
	s_addc_u32 s51, s51, 0
	s_add_u32 s74, s52, 0x100
	s_addc_u32 s75, s53, 0
	s_mov_b32 s76, -2
	s_waitcnt vmcnt(0)
	ds_read_b128 v[128:131], v181
	ds_read_b128 v[132:135], v181 offset:1024
	ds_read_b128 v[136:139], v181 offset:2048
	ds_read_b128 v[140:143], v181 offset:3072
	ds_read_b128 v[144:147], v182
	ds_read_b128 v[148:151], v182 offset:1024
	ds_read_b128 v[168:171], v182 offset:2048
	ds_read_b128 v[172:175], v182 offset:3072
	s_add_u32 s52, s50, 0xfffc0080
	s_addc_u32 s53, s51, -1
	s_cmp_eq_u32 s76, 12
	s_cselect_b32 s55, s35, s53
	s_cselect_b32 s54, s72, s52
	s_cselect_b32 s53, s31, s75
	s_cselect_b32 s52, s73, s74
	v_lshl_add_u64 v[176:177], s[50:51], 0, v[160:161]
	s_add_i32 m0, s63, 0xc000
	ds_read_b128 v[184:187], v183
	ds_read_b128 v[188:191], v183 offset:1024
	ds_read_b128 v[194:197], v183 offset:2048
	ds_read_b128 v[198:201], v183 offset:3072
	ds_read_b128 v[202:205], v183 offset:4096
	ds_read_b128 v[206:209], v183 offset:5120
	ds_read_b128 v[210:213], v183 offset:6144
	ds_read_b128 v[218:221], v183 offset:7168
	global_load_lds_dwordx4 v[176:177], off
	v_lshl_add_u64 v[176:177], s[50:51], 0, v[162:163]
	s_add_i32 m0, s63, 0xe000
	s_nop 0
	global_load_lds_dwordx4 v[176:177], off
	s_waitcnt vmcnt(8)
	s_waitcnt lgkmcnt(0)
	s_barrier
	s_setprio 1
	v_mfma_f32_16x16x32_bf16 v[124:127], v[128:131], v[184:187], 0
	v_mfma_f32_16x16x32_bf16 v[120:123], v[136:139], v[184:187], 0
	v_mfma_f32_16x16x32_bf16 v[108:111], v[128:131], v[194:197], 0
	v_mfma_f32_16x16x32_bf16 v[104:107], v[136:139], v[194:197], 0
	v_mfma_f32_16x16x32_bf16 v[96:99], v[128:131], v[202:205], 0
	v_mfma_f32_16x16x32_bf16 v[88:91], v[136:139], v[202:205], 0
	v_mfma_f32_16x16x32_bf16 v[80:83], v[128:131], v[210:213], 0
	v_mfma_f32_16x16x32_bf16 v[72:75], v[136:139], v[210:213], 0
	v_mfma_f32_16x16x32_bf16 v[124:127], v[132:135], v[188:191], v[124:127]
	v_mfma_f32_16x16x32_bf16 v[120:123], v[140:143], v[188:191], v[120:123]
	v_mfma_f32_16x16x32_bf16 v[108:111], v[132:135], v[198:201], v[108:111]
	v_mfma_f32_16x16x32_bf16 v[104:107], v[140:143], v[198:201], v[104:107]
	v_mfma_f32_16x16x32_bf16 v[96:99], v[132:135], v[206:209], v[96:99]
	v_mfma_f32_16x16x32_bf16 v[88:91], v[140:143], v[206:209], v[88:91]
	v_mfma_f32_16x16x32_bf16 v[80:83], v[132:135], v[218:221], v[80:83]
	v_mfma_f32_16x16x32_bf16 v[72:75], v[140:143], v[218:221], v[72:75]
	v_mfma_f32_16x16x32_bf16 v[116:119], v[144:147], v[184:187], 0
	v_mfma_f32_16x16x32_bf16 v[112:115], v[168:171], v[184:187], 0
	v_mfma_f32_16x16x32_bf16 v[100:103], v[144:147], v[194:197], 0
	v_mfma_f32_16x16x32_bf16 v[92:95], v[168:171], v[194:197], 0
	v_mfma_f32_16x16x32_bf16 v[84:87], v[144:147], v[202:205], 0
	v_mfma_f32_16x16x32_bf16 v[76:79], v[168:171], v[202:205], 0
	v_mfma_f32_16x16x32_bf16 v[68:71], v[144:147], v[210:213], 0
	v_mfma_f32_16x16x32_bf16 v[64:67], v[168:171], v[210:213], 0
	v_mfma_f32_16x16x32_bf16 v[116:119], v[148:151], v[188:191], v[116:119]
	v_mfma_f32_16x16x32_bf16 v[112:115], v[172:175], v[188:191], v[112:115]
	v_mfma_f32_16x16x32_bf16 v[100:103], v[148:151], v[198:201], v[100:103]
	v_mfma_f32_16x16x32_bf16 v[92:95], v[172:175], v[198:201], v[92:95]
	v_mfma_f32_16x16x32_bf16 v[84:87], v[148:151], v[206:209], v[84:87]
	v_mfma_f32_16x16x32_bf16 v[76:79], v[172:175], v[206:209], v[76:79]
	v_mfma_f32_16x16x32_bf16 v[68:71], v[148:151], v[218:221], v[68:71]
	v_mfma_f32_16x16x32_bf16 v[64:67], v[172:175], v[218:221], v[64:67]
	s_setprio 0
	s_barrier
	s_add_i32 s77, s70, s62
	v_lshl_add_u64 v[176:177], s[52:53], 0, v[156:157]
	s_mov_b32 m0, s77
	ds_read_b128 v[184:187], v183 offset:16384
	ds_read_b128 v[188:191], v183 offset:17408
	ds_read_b128 v[194:197], v183 offset:18432
	ds_read_b128 v[198:201], v183 offset:19456
	ds_read_b128 v[202:205], v183 offset:20480
	ds_read_b128 v[206:209], v183 offset:21504
	ds_read_b128 v[210:213], v183 offset:22528
	ds_read_b128 v[218:221], v183 offset:23552
	global_load_lds_dwordx4 v[176:177], off
	s_add_i32 m0, s77, 0x2000
	s_add_u32 s78, s52, 0x40000
	v_lshl_add_u64 v[214:215], s[52:53], 0, v[152:153]
	s_addc_u32 s79, s53, 0
	s_add_i32 s77, s71, s62
	global_load_lds_dwordx4 v[214:215], off
	v_lshl_add_u64 v[222:223], s[78:79], 0, v[156:157]
	s_mov_b32 m0, s77
	v_lshl_add_u64 v[224:225], s[54:55], 0, v[154:155]
	global_load_lds_dwordx4 v[222:223], off
	v_lshl_add_u64 v[222:223], s[78:79], 0, v[152:153]
	s_add_i32 m0, s77, 0x2000
	s_nop 0
	global_load_lds_dwordx4 v[222:223], off
	v_lshl_add_u64 v[222:223], s[54:55], 0, v[158:159]
	s_mov_b32 m0, s63
	s_nop 0
	global_load_lds_dwordx4 v[222:223], off
	s_mov_b32 m0, s64
	s_nop 0
	global_load_lds_dwordx4 v[224:225], off
	s_waitcnt vmcnt(8)
	s_waitcnt lgkmcnt(0)
	s_barrier
; #define PG8_STAGE(bufoff, gbase, voff) do { _Pragma("unroll") for (int _i = 0; _i < 2; ++_i) \
;         __builtin_amdgcn_global_load_lds((const unsigned*)((const char*)(gbase) + (voff)[_i]), (PG8_LAS unsigned*)(lds + (bufoff) + ldsw + _i * 8192), 16, 0, 0); } while (0)
; #define PG8_LDA(dst, b, h) do { _Pragma("unroll") for (int m = 0; m < 4; ++m) _Pragma("unroll") for (int k = 0; k < 2; ++k) dst[m][k] = *(const PG8_LAS bf16x8*)(lds + PG8_SA(b, h) + aoff + m * 2048 + k * 1024); } while (0)
; #define PG8_LDB(dst, b, h) do { _Pragma("unroll") for (int n = 0; n < 2; ++n) _Pragma("unroll") for (int k = 0; k < 2; ++k) dst[n][k] = *(const PG8_LAS bf16x8*)(lds + PG8_SB(b, h) + boff + n * 2048 + k * 1024); } while (0)
; #define PG8_MMA(ai, bj, At, Bt) do { __builtin_amdgcn_s_setprio(1); _Pragma("unroll") for (int m = 0; m < 4; ++m) _Pragma("unroll") for (int n = 0; n < 2; ++n) _Pragma("unroll") for (int k = 0; k < 2; ++k) \
;         acc[ai][bj][m][n] = __builtin_amdgcn_mfma_f32_16x16x32_bf16(Bt[n][k], At[m][k], acc[ai][bj][m][n], 0, 0, 0); __builtin_amdgcn_s_setprio(0); } while (0)
; #define PG8_WAIT_V(n) asm volatile("s_waitcnt vmcnt(" #n ")" ::: "memory")
; template <class Epi, class Sched, bool ALIGN_EPI = false, bool SP2 = false>
; __device__ __forceinline__ void gemm_phase(PG8_LAS unsigned char* lds, const Gemm g, const Sched& S, const Epi& E) {
;     ...
;             PG8_LDB(B0, 0, 0); PG8_LDB(B1, 0, 1); PG8_SCHED; PG8_LDA(At, 0, 0); PG8_STAGE(PG8_SA(1, 1), a1 + hstep, voffA);
;             PG8_WAIT_V(8); PG8_WAIT_L(0); PG8_BAR; PG8_MMA(0, 0, At, B0); PG8_MMA(0, 1, At, B1); PG8_BAR; PG8_SCHED;
;             PG8_LDA(At, 0, 1); PG8_STAGE(PG8_SB(0, 0), b2, voffB); PG8_STAGE(PG8_SB(0, 1), b2 + hstep, voffB); PG8_STAGE(PG8_SA(0, 0), a2, voffA);
;             PG8_WAIT_V(8); PG8_WAIT_L(0); PG8_BAR; PG8_MMA(1, 0, At, B0); PG8_MMA(1, 1, At, B1); PG8_BAR; PG8_SCHED;
;             PG8_LDB(B0, 1, 0); PG8_LDB(B1, 1, 1); PG8_SCHED; PG8_LDA(At, 1, 0); PG8_STAGE(PG8_SA(0, 1), a2 + hstep, voffA);
;             PG8_WAIT_V(8); PG8_WAIT_L(0); PG8_BAR; PG8_MMA(0, 0, At, B0); PG8_MMA(0, 1, At, B1); PG8_BAR; PG8_SCHED;
;             PG8_LDA(At, 1, 1); PG8_STAGE(PG8_SB(1, 0), b3, voffB); PG8_STAGE(PG8_SB(1, 1), b3 + hstep, voffB); PG8_STAGE(PG8_SA(1, 0), a3, voffA);
;             PG8_WAIT_V(8); PG8_WAIT_L(0); PG8_BAR; PG8_MMA(1, 0, At, B0); PG8_MMA(1, 1, At, B1); PG8_BAR; PG8_SCHED;
	s_setprio 1
	v_mfma_f32_16x16x32_bf16 v[60:63], v[128:131], v[184:187], 0
	v_mfma_f32_16x16x32_bf16 v[56:59], v[136:139], v[184:187], 0
	v_mfma_f32_16x16x32_bf16 v[48:51], v[128:131], v[194:197], 0
	v_mfma_f32_16x16x32_bf16 v[40:43], v[136:139], v[194:197], 0
	v_mfma_f32_16x16x32_bf16 v[32:35], v[128:131], v[202:205], 0
	v_mfma_f32_16x16x32_bf16 v[24:27], v[136:139], v[202:205], 0
	v_mfma_f32_16x16x32_bf16 v[16:19], v[128:131], v[210:213], 0
	v_mfma_f32_16x16x32_bf16 v[8:11], v[136:139], v[210:213], 0
	v_mfma_f32_16x16x32_bf16 v[60:63], v[132:135], v[188:191], v[60:63]
	v_mfma_f32_16x16x32_bf16 v[56:59], v[140:143], v[188:191], v[56:59]
	v_mfma_f32_16x16x32_bf16 v[48:51], v[132:135], v[198:201], v[48:51]
	v_mfma_f32_16x16x32_bf16 v[40:43], v[140:143], v[198:201], v[40:43]
	v_mfma_f32_16x16x32_bf16 v[32:35], v[132:135], v[206:209], v[32:35]
	v_mfma_f32_16x16x32_bf16 v[24:27], v[140:143], v[206:209], v[24:27]
	v_mfma_f32_16x16x32_bf16 v[16:19], v[132:135], v[218:221], v[16:19]
	v_mfma_f32_16x16x32_bf16 v[8:11], v[140:143], v[218:221], v[8:11]
	v_mfma_f32_16x16x32_bf16 v[52:55], v[144:147], v[184:187], 0
	v_mfma_f32_16x16x32_bf16 v[44:47], v[168:171], v[184:187], 0
	v_mfma_f32_16x16x32_bf16 v[36:39], v[144:147], v[194:197], 0
	v_mfma_f32_16x16x32_bf16 v[28:31], v[168:171], v[194:197], 0
	v_mfma_f32_16x16x32_bf16 v[20:23], v[144:147], v[202:205], 0
	v_mfma_f32_16x16x32_bf16 v[12:15], v[168:171], v[202:205], 0
	v_mfma_f32_16x16x32_bf16 v[4:7], v[144:147], v[210:213], 0
	v_mfma_f32_16x16x32_bf16 v[0:3], v[168:171], v[210:213], 0
	v_mfma_f32_16x16x32_bf16 v[52:55], v[148:151], v[188:191], v[52:55]
	v_mfma_f32_16x16x32_bf16 v[44:47], v[172:175], v[188:191], v[44:47]
	v_mfma_f32_16x16x32_bf16 v[36:39], v[148:151], v[198:201], v[36:39]
	v_mfma_f32_16x16x32_bf16 v[28:31], v[172:175], v[198:201], v[28:31]
	v_mfma_f32_16x16x32_bf16 v[20:23], v[148:151], v[206:209], v[20:23]
	v_mfma_f32_16x16x32_bf16 v[12:15], v[172:175], v[206:209], v[12:15]
	v_mfma_f32_16x16x32_bf16 v[4:7], v[148:151], v[218:221], v[4:7]
	v_mfma_f32_16x16x32_bf16 v[0:3], v[172:175], v[218:221], v[0:3]
	s_setprio 0
	s_barrier
	s_add_i32 s77, 0, 0x18000
	s_add_i32 s78, 0, 0x1c000
	v_add_u32_e32 v140, s77, v179
	v_add_u32_e32 v172, s78, v179
	ds_read_b128 v[128:131], v140
	ds_read_b128 v[132:135], v140 offset:1024
	ds_read_b128 v[136:139], v140 offset:2048
	ds_read_b128 v[140:143], v140 offset:3072
	ds_read_b128 v[144:147], v172
	ds_read_b128 v[148:151], v172 offset:1024
	ds_read_b128 v[168:171], v172 offset:2048
	ds_read_b128 v[172:175], v172 offset:3072
	s_add_u32 s54, s54, 0x40000
	s_addc_u32 s55, s55, 0
	s_mov_b32 m0, s65
	v_lshl_add_u64 v[226:227], s[54:55], 0, v[158:159]
	ds_read_b128 v[184:187], v183 offset:32768
	ds_read_b128 v[188:191], v183 offset:33792
	ds_read_b128 v[194:197], v183 offset:34816
	ds_read_b128 v[198:201], v183 offset:35840
	ds_read_b128 v[202:205], v183 offset:36864
	ds_read_b128 v[206:209], v183 offset:37888
	ds_read_b128 v[210:213], v183 offset:38912
	ds_read_b128 v[218:221], v183 offset:39936
	global_load_lds_dwordx4 v[226:227], off
	v_lshl_add_u64 v[226:227], s[54:55], 0, v[154:155]
	s_mov_b32 m0, s66
	s_nop 0
	global_load_lds_dwordx4 v[226:227], off
	s_waitcnt vmcnt(8)
	s_waitcnt lgkmcnt(0)
	s_barrier
	s_setprio 1
	v_mfma_f32_16x16x32_bf16 v[124:127], v[128:131], v[184:187], v[124:127]
	v_mfma_f32_16x16x32_bf16 v[120:123], v[136:139], v[184:187], v[120:123]
	v_mfma_f32_16x16x32_bf16 v[108:111], v[128:131], v[194:197], v[108:111]
	v_mfma_f32_16x16x32_bf16 v[104:107], v[136:139], v[194:197], v[104:107]
	v_mfma_f32_16x16x32_bf16 v[96:99], v[128:131], v[202:205], v[96:99]
	v_mfma_f32_16x16x32_bf16 v[88:91], v[136:139], v[202:205], v[88:91]
	v_mfma_f32_16x16x32_bf16 v[80:83], v[128:131], v[210:213], v[80:83]
	v_mfma_f32_16x16x32_bf16 v[72:75], v[136:139], v[210:213], v[72:75]
	v_mfma_f32_16x16x32_bf16 v[124:127], v[132:135], v[188:191], v[124:127]
	v_mfma_f32_16x16x32_bf16 v[120:123], v[140:143], v[188:191], v[120:123]
	v_mfma_f32_16x16x32_bf16 v[108:111], v[132:135], v[198:201], v[108:111]
	v_mfma_f32_16x16x32_bf16 v[104:107], v[140:143], v[198:201], v[104:107]
	v_mfma_f32_16x16x32_bf16 v[96:99], v[132:135], v[206:209], v[96:99]
	v_mfma_f32_16x16x32_bf16 v[88:91], v[140:143], v[206:209], v[88:91]
	v_mfma_f32_16x16x32_bf16 v[80:83], v[132:135], v[218:221], v[80:83]
	v_mfma_f32_16x16x32_bf16 v[72:75], v[140:143], v[218:221], v[72:75]
	v_mfma_f32_16x16x32_bf16 v[116:119], v[144:147], v[184:187], v[116:119]
	v_mfma_f32_16x16x32_bf16 v[112:115], v[168:171], v[184:187], v[112:115]
	v_mfma_f32_16x16x32_bf16 v[100:103], v[144:147], v[194:197], v[100:103]
	v_mfma_f32_16x16x32_bf16 v[92:95], v[168:171], v[194:197], v[92:95]
	v_mfma_f32_16x16x32_bf16 v[84:87], v[144:147], v[202:205], v[84:87]
	v_mfma_f32_16x16x32_bf16 v[76:79], v[168:171], v[202:205], v[76:79]
	v_mfma_f32_16x16x32_bf16 v[68:71], v[144:147], v[210:213], v[68:71]
	v_mfma_f32_16x16x32_bf16 v[64:67], v[168:171], v[210:213], v[64:67]
	v_mfma_f32_16x16x32_bf16 v[116:119], v[148:151], v[188:191], v[116:119]
	v_mfma_f32_16x16x32_bf16 v[112:115], v[172:175], v[188:191], v[112:115]
	v_mfma_f32_16x16x32_bf16 v[100:103], v[148:151], v[198:201], v[100:103]
	v_mfma_f32_16x16x32_bf16 v[92:95], v[172:175], v[198:201], v[92:95]
	v_mfma_f32_16x16x32_bf16 v[84:87], v[148:151], v[206:209], v[84:87]
	v_mfma_f32_16x16x32_bf16 v[76:79], v[172:175], v[206:209], v[76:79]
	v_mfma_f32_16x16x32_bf16 v[68:71], v[148:151], v[218:221], v[68:71]
	v_mfma_f32_16x16x32_bf16 v[64:67], v[172:175], v[218:221], v[64:67]
	s_setprio 0
	s_barrier
; #define PG8_STAGE(bufoff, gbase, voff) do { _Pragma("unroll") for (int _i = 0; _i < 2; ++_i) \
;         __builtin_amdgcn_global_load_lds((const unsigned*)((const char*)(gbase) + (voff)[_i]), (PG8_LAS unsigned*)(lds + (bufoff) + ldsw + _i * 8192), 16, 0, 0); } while (0)
; #define PG8_LDA(dst, b, h) do { _Pragma("unroll") for (int m = 0; m < 4; ++m) _Pragma("unroll") for (int k = 0; k < 2; ++k) dst[m][k] = *(const PG8_LAS bf16x8*)(lds + PG8_SA(b, h) + aoff + m * 2048 + k * 1024); } while (0)
; #define PG8_LDB(dst, b, h) do { _Pragma("unroll") for (int n = 0; n < 2; ++n) _Pragma("unroll") for (int k = 0; k < 2; ++k) dst[n][k] = *(const PG8_LAS bf16x8*)(lds + PG8_SB(b, h) + boff + n * 2048 + k * 1024); } while (0)
; template <class Epi, class Sched, bool ALIGN_EPI = false, bool SP2 = false>
; __device__ __forceinline__ void gemm_phase(PG8_LAS unsigned char* lds, const Gemm g, const Sched& S, const Epi& E) {
;     ...
;         for (int t = 0; t < nt; t += 2) {
;             const bool last = (t == nt - 2);
;             const char* a1 = cA + (size_t)(t + 1) * kstep;
;             const char* a2 = last ? nA : cA + (size_t)(t + 2) * kstep; const char* b2 = last ? nB : cB + (size_t)(t + 2) * kstep;
;             const char* a3 = a2 + kstep; const char* b3 = b2 + kstep;
;             if (last && has_next) S.a_ready(nxt);
;             if constexpr (SP2) {
;             PG8_LDB(B0, 0, 0); PG8_LDB(B1, 0, 1); PG8_SCHED; PG8_LDA(At, 0, 0); PG8_STAGE(PG8_SA(1, 1), a1 + hstep, voffA);
;             PG8_WAIT_V(8); PG8_WAIT_L(0); PG8_BAR; PG8_MMA(0, 0, At, B0); PG8_MMA(0, 1, At, B1); PG8_BAR; PG8_SCHED;
;             PG8_LDA(At, 0, 1); PG8_STAGE(PG8_SB(0, 0), b2, voffB); PG8_STAGE(PG8_SB(0, 1), b2 + hstep, voffB); PG8_STAGE(PG8_SA(0, 0), a2, voffA);
;             PG8_WAIT_V(8); PG8_WAIT_L(0); PG8_BAR; PG8_MMA(1, 0, At, B0); PG8_MMA(1, 1, At, B1); PG8_BAR; PG8_SCHED;
;             PG8_LDB(B0, 1, 0); PG8_LDB(B1, 1, 1); PG8_SCHED; PG8_LDA(At, 1, 0); PG8_STAGE(PG8_SA(0, 1), a2 + hstep, voffA);
;             PG8_WAIT_V(8); PG8_WAIT_L(0); PG8_BAR; PG8_MMA(0, 0, At, B0); PG8_MMA(0, 1, At, B1); PG8_BAR; PG8_SCHED;
;             PG8_LDA(At, 1, 1); PG8_STAGE(PG8_SB(1, 0), b3, voffB); PG8_STAGE(PG8_SB(1, 1), b3 + hstep, voffB); PG8_STAGE(PG8_SA(1, 0), a3, voffA);
;             PG8_WAIT_V(8); PG8_WAIT_L(0); PG8_BAR; PG8_MMA(1, 0, At, B0); PG8_MMA(1, 1, At, B1); PG8_BAR; PG8_SCHED;
	s_add_i32 s54, s77, s62
	v_lshl_add_u64 v[176:177], v[176:177], 0, s[26:27]
	s_mov_b32 m0, s54
	ds_read_b128 v[184:187], v183 offset:49152
	ds_read_b128 v[188:191], v183 offset:50176
	ds_read_b128 v[194:197], v183 offset:51200
	ds_read_b128 v[198:201], v183 offset:52224
	ds_read_b128 v[202:205], v183 offset:53248
	ds_read_b128 v[206:209], v183 offset:54272
	ds_read_b128 v[210:213], v183 offset:55296
	ds_read_b128 v[218:221], v183 offset:56320
	global_load_lds_dwordx4 v[176:177], off
	s_add_i32 m0, s54, 0x2000
	s_add_u32 s52, s52, 0x40080
	v_lshl_add_u64 v[176:177], v[214:215], 0, s[26:27]
	s_addc_u32 s53, s53, 0
	s_add_i32 s54, s78, s62
	global_load_lds_dwordx4 v[176:177], off
	v_lshl_add_u64 v[176:177], s[52:53], 0, v[156:157]
	s_mov_b32 m0, s54
	s_nop 0
	global_load_lds_dwordx4 v[176:177], off
	v_lshl_add_u64 v[176:177], s[52:53], 0, v[152:153]
	s_add_i32 m0, s54, 0x2000
	s_nop 0
	global_load_lds_dwordx4 v[176:177], off
	v_lshl_add_u64 v[176:177], v[222:223], 0, s[26:27]
	s_mov_b32 m0, s68
	s_nop 0
	global_load_lds_dwordx4 v[176:177], off
	v_lshl_add_u64 v[176:177], v[224:225], 0, s[26:27]
	s_mov_b32 m0, s69
	s_nop 0
	global_load_lds_dwordx4 v[176:177], off
	s_waitcnt vmcnt(8)
	s_waitcnt lgkmcnt(0)
	s_barrier
	s_setprio 1
	v_mfma_f32_16x16x32_bf16 v[60:63], v[128:131], v[184:187], v[60:63]
	v_mfma_f32_16x16x32_bf16 v[56:59], v[136:139], v[184:187], v[56:59]
	v_mfma_f32_16x16x32_bf16 v[48:51], v[128:131], v[194:197], v[48:51]
	v_mfma_f32_16x16x32_bf16 v[40:43], v[136:139], v[194:197], v[40:43]
	v_mfma_f32_16x16x32_bf16 v[32:35], v[128:131], v[202:205], v[32:35]
	v_mfma_f32_16x16x32_bf16 v[24:27], v[136:139], v[202:205], v[24:27]
	v_mfma_f32_16x16x32_bf16 v[16:19], v[128:131], v[210:213], v[16:19]
	v_mfma_f32_16x16x32_bf16 v[8:11], v[136:139], v[210:213], v[8:11]
	v_mfma_f32_16x16x32_bf16 v[60:63], v[132:135], v[188:191], v[60:63]
	v_mfma_f32_16x16x32_bf16 v[56:59], v[140:143], v[188:191], v[56:59]
	v_mfma_f32_16x16x32_bf16 v[48:51], v[132:135], v[198:201], v[48:51]
	v_mfma_f32_16x16x32_bf16 v[40:43], v[140:143], v[198:201], v[40:43]
	v_mfma_f32_16x16x32_bf16 v[32:35], v[132:135], v[206:209], v[32:35]
	v_mfma_f32_16x16x32_bf16 v[24:27], v[140:143], v[206:209], v[24:27]
	v_mfma_f32_16x16x32_bf16 v[16:19], v[132:135], v[218:221], v[16:19]
	v_mfma_f32_16x16x32_bf16 v[8:11], v[140:143], v[218:221], v[8:11]
	v_mfma_f32_16x16x32_bf16 v[52:55], v[144:147], v[184:187], v[52:55]
	v_mfma_f32_16x16x32_bf16 v[44:47], v[168:171], v[184:187], v[44:47]
	v_mfma_f32_16x16x32_bf16 v[36:39], v[144:147], v[194:197], v[36:39]
	v_mfma_f32_16x16x32_bf16 v[28:31], v[168:171], v[194:197], v[28:31]
	v_mfma_f32_16x16x32_bf16 v[20:23], v[144:147], v[202:205], v[20:23]
	v_mfma_f32_16x16x32_bf16 v[12:15], v[168:171], v[202:205], v[12:15]
	v_mfma_f32_16x16x32_bf16 v[4:7], v[144:147], v[210:213], v[4:7]
	v_mfma_f32_16x16x32_bf16 v[0:3], v[168:171], v[210:213], v[0:3]
	v_mfma_f32_16x16x32_bf16 v[52:55], v[148:151], v[188:191], v[52:55]
	v_mfma_f32_16x16x32_bf16 v[44:47], v[172:175], v[188:191], v[44:47]
	v_mfma_f32_16x16x32_bf16 v[36:39], v[148:151], v[198:201], v[36:39]
	v_mfma_f32_16x16x32_bf16 v[28:31], v[172:175], v[198:201], v[28:31]
	v_mfma_f32_16x16x32_bf16 v[20:23], v[148:151], v[206:209], v[20:23]
	v_mfma_f32_16x16x32_bf16 v[12:15], v[172:175], v[206:209], v[12:15]
	v_mfma_f32_16x16x32_bf16 v[4:7], v[148:151], v[218:221], v[4:7]
	v_mfma_f32_16x16x32_bf16 v[0:3], v[172:175], v[218:221], v[0:3]
	s_setprio 0
	s_barrier
	s_add_i32 s76, s76, 2
	s_add_u32 s50, s50, 0x100
	s_addc_u32 s51, s51, 0
	s_add_u32 s74, s74, 0x100
	s_addc_u32 s75, s75, 0
	s_cmp_gt_u32 s76, 13
.LBB0_553:
	ds_read_b128 v[128:131], v181
	ds_read_b128 v[132:135], v181 offset:1024
	ds_read_b128 v[136:139], v181 offset:2048
	ds_read_b128 v[140:143], v181 offset:3072
	ds_read_b128 v[144:147], v182
	ds_read_b128 v[148:151], v182 offset:1024
	ds_read_b128 v[168:171], v182 offset:2048
	ds_read_b128 v[172:175], v182 offset:3072
	s_add_u32 s52, s50, 0xfffc0080
	s_addc_u32 s53, s51, -1
	s_cmp_eq_u32 s76, 12
	s_cselect_b32 s55, s35, s53
	s_cselect_b32 s54, s72, s52
	s_cselect_b32 s53, s31, s75
	s_cselect_b32 s52, s73, s74
	v_lshl_add_u64 v[176:177], s[50:51], 0, v[160:161]
	s_add_i32 m0, s63, 0xc000
	ds_read_b128 v[184:187], v183
	ds_read_b128 v[188:191], v183 offset:1024
	ds_read_b128 v[194:197], v183 offset:2048
	ds_read_b128 v[198:201], v183 offset:3072
	ds_read_b128 v[202:205], v183 offset:4096
	ds_read_b128 v[206:209], v183 offset:5120
	ds_read_b128 v[210:213], v183 offset:6144
	ds_read_b128 v[218:221], v183 offset:7168
	global_load_lds_dwordx4 v[176:177], off
	v_lshl_add_u64 v[176:177], s[50:51], 0, v[162:163]
	s_add_i32 m0, s63, 0xe000
	s_nop 0
	global_load_lds_dwordx4 v[176:177], off
	s_waitcnt vmcnt(8)
	s_waitcnt lgkmcnt(0)
	s_barrier
; #define PG8_STAGE(bufoff, gbase, voff) do { _Pragma("unroll") for (int _i = 0; _i < 2; ++_i) \
;         __builtin_amdgcn_global_load_lds((const unsigned*)((const char*)(gbase) + (voff)[_i]), (PG8_LAS unsigned*)(lds + (bufoff) + ldsw + _i * 8192), 16, 0, 0); } while (0)
; #define PG8_LDA(dst, b, h) do { _Pragma("unroll") for (int m = 0; m < 4; ++m) _Pragma("unroll") for (int k = 0; k < 2; ++k) dst[m][k] = *(const PG8_LAS bf16x8*)(lds + PG8_SA(b, h) + aoff + m * 2048 + k * 1024); } while (0)
; #define PG8_LDB(dst, b, h) do { _Pragma("unroll") for (int n = 0; n < 2; ++n) _Pragma("unroll") for (int k = 0; k < 2; ++k) dst[n][k] = *(const PG8_LAS bf16x8*)(lds + PG8_SB(b, h) + boff + n * 2048 + k * 1024); } while (0)
; #define PG8_MMA(ai, bj, At, Bt) do { __builtin_amdgcn_s_setprio(1); _Pragma("unroll") for (int m = 0; m < 4; ++m) _Pragma("unroll") for (int n = 0; n < 2; ++n) _Pragma("unroll") for (int k = 0; k < 2; ++k) \
;         acc[ai][bj][m][n] = __builtin_amdgcn_mfma_f32_16x16x32_bf16(Bt[n][k], At[m][k], acc[ai][bj][m][n], 0, 0, 0); __builtin_amdgcn_s_setprio(0); } while (0)
; #define PG8_WAIT_V(n) asm volatile("s_waitcnt vmcnt(" #n ")" ::: "memory")
; template <class Epi, class Sched, bool ALIGN_EPI = false, bool SP2 = false>
; __device__ __forceinline__ void gemm_phase(PG8_LAS unsigned char* lds, const Gemm g, const Sched& S, const Epi& E) {
;     ...
;             PG8_LDB(B0, 0, 0); PG8_LDB(B1, 0, 1); PG8_SCHED; PG8_LDA(At, 0, 0); PG8_STAGE(PG8_SA(1, 1), a1 + hstep, voffA);
;             PG8_WAIT_V(8); PG8_WAIT_L(0); PG8_BAR; PG8_MMA(0, 0, At, B0); PG8_MMA(0, 1, At, B1); PG8_BAR; PG8_SCHED;
;             PG8_LDA(At, 0, 1); PG8_STAGE(PG8_SB(0, 0), b2, voffB); PG8_STAGE(PG8_SB(0, 1), b2 + hstep, voffB); PG8_STAGE(PG8_SA(0, 0), a2, voffA);
;             PG8_WAIT_V(8); PG8_WAIT_L(0); PG8_BAR; PG8_MMA(1, 0, At, B0); PG8_MMA(1, 1, At, B1); PG8_BAR; PG8_SCHED;
;             PG8_LDB(B0, 1, 0); PG8_LDB(B1, 1, 1); PG8_SCHED; PG8_LDA(At, 1, 0); PG8_STAGE(PG8_SA(0, 1), a2 + hstep, voffA);
;             PG8_WAIT_V(8); PG8_WAIT_L(0); PG8_BAR; PG8_MMA(0, 0, At, B0); PG8_MMA(0, 1, At, B1); PG8_BAR; PG8_SCHED;
;             PG8_LDA(At, 1, 1); PG8_STAGE(PG8_SB(1, 0), b3, voffB); PG8_STAGE(PG8_SB(1, 1), b3 + hstep, voffB); PG8_STAGE(PG8_SA(1, 0), a3, voffA);
;             PG8_WAIT_V(8); PG8_WAIT_L(0); PG8_BAR; PG8_MMA(1, 0, At, B0); PG8_MMA(1, 1, At, B1); PG8_BAR; PG8_SCHED;
	s_setprio 1
	v_mfma_f32_16x16x32_bf16 v[124:127], v[128:131], v[184:187], v[124:127]
	v_mfma_f32_16x16x32_bf16 v[120:123], v[136:139], v[184:187], v[120:123]
	v_mfma_f32_16x16x32_bf16 v[108:111], v[128:131], v[194:197], v[108:111]
	v_mfma_f32_16x16x32_bf16 v[104:107], v[136:139], v[194:197], v[104:107]
	v_mfma_f32_16x16x32_bf16 v[96:99], v[128:131], v[202:205], v[96:99]
	v_mfma_f32_16x16x32_bf16 v[88:91], v[136:139], v[202:205], v[88:91]
	v_mfma_f32_16x16x32_bf16 v[80:83], v[128:131], v[210:213], v[80:83]
	v_mfma_f32_16x16x32_bf16 v[72:75], v[136:139], v[210:213], v[72:75]
	v_mfma_f32_16x16x32_bf16 v[124:127], v[132:135], v[188:191], v[124:127]
	v_mfma_f32_16x16x32_bf16 v[120:123], v[140:143], v[188:191], v[120:123]
	v_mfma_f32_16x16x32_bf16 v[108:111], v[132:135], v[198:201], v[108:111]
	v_mfma_f32_16x16x32_bf16 v[104:107], v[140:143], v[198:201], v[104:107]
	v_mfma_f32_16x16x32_bf16 v[96:99], v[132:135], v[206:209], v[96:99]
	v_mfma_f32_16x16x32_bf16 v[88:91], v[140:143], v[206:209], v[88:91]
	v_mfma_f32_16x16x32_bf16 v[80:83], v[132:135], v[218:221], v[80:83]
	v_mfma_f32_16x16x32_bf16 v[72:75], v[140:143], v[218:221], v[72:75]
	v_mfma_f32_16x16x32_bf16 v[116:119], v[144:147], v[184:187], v[116:119]
	v_mfma_f32_16x16x32_bf16 v[112:115], v[168:171], v[184:187], v[112:115]
	v_mfma_f32_16x16x32_bf16 v[100:103], v[144:147], v[194:197], v[100:103]
	v_mfma_f32_16x16x32_bf16 v[92:95], v[168:171], v[194:197], v[92:95]
	v_mfma_f32_16x16x32_bf16 v[84:87], v[144:147], v[202:205], v[84:87]
	v_mfma_f32_16x16x32_bf16 v[76:79], v[168:171], v[202:205], v[76:79]
	v_mfma_f32_16x16x32_bf16 v[68:71], v[144:147], v[210:213], v[68:71]
	v_mfma_f32_16x16x32_bf16 v[64:67], v[168:171], v[210:213], v[64:67]
	v_mfma_f32_16x16x32_bf16 v[116:119], v[148:151], v[188:191], v[116:119]
	v_mfma_f32_16x16x32_bf16 v[112:115], v[172:175], v[188:191], v[112:115]
	v_mfma_f32_16x16x32_bf16 v[100:103], v[148:151], v[198:201], v[100:103]
	v_mfma_f32_16x16x32_bf16 v[92:95], v[172:175], v[198:201], v[92:95]
	v_mfma_f32_16x16x32_bf16 v[84:87], v[148:151], v[206:209], v[84:87]
	v_mfma_f32_16x16x32_bf16 v[76:79], v[172:175], v[206:209], v[76:79]
	v_mfma_f32_16x16x32_bf16 v[68:71], v[148:151], v[218:221], v[68:71]
	v_mfma_f32_16x16x32_bf16 v[64:67], v[172:175], v[218:221], v[64:67]
	s_setprio 0
	s_barrier
	s_add_i32 s77, s70, s62
	v_lshl_add_u64 v[176:177], s[52:53], 0, v[156:157]
	s_mov_b32 m0, s77
	ds_read_b128 v[184:187], v183 offset:16384
	ds_read_b128 v[188:191], v183 offset:17408
	ds_read_b128 v[194:197], v183 offset:18432
	ds_read_b128 v[198:201], v183 offset:19456
	ds_read_b128 v[202:205], v183 offset:20480
	ds_read_b128 v[206:209], v183 offset:21504
	ds_read_b128 v[210:213], v183 offset:22528
	ds_read_b128 v[218:221], v183 offset:23552
	global_load_lds_dwordx4 v[176:177], off
	s_add_i32 m0, s77, 0x2000
	s_add_u32 s78, s52, 0x40000
	v_lshl_add_u64 v[214:215], s[52:53], 0, v[152:153]
	s_addc_u32 s79, s53, 0
	s_add_i32 s77, s71, s62
	global_load_lds_dwordx4 v[214:215], off
	v_lshl_add_u64 v[222:223], s[78:79], 0, v[156:157]
	s_mov_b32 m0, s77
	v_lshl_add_u64 v[224:225], s[54:55], 0, v[154:155]
	global_load_lds_dwordx4 v[222:223], off
	v_lshl_add_u64 v[222:223], s[78:79], 0, v[152:153]
	s_add_i32 m0, s77, 0x2000
	s_nop 0
	global_load_lds_dwordx4 v[222:223], off
	v_lshl_add_u64 v[222:223], s[54:55], 0, v[158:159]
	s_mov_b32 m0, s63
	s_nop 0
	global_load_lds_dwordx4 v[222:223], off
	s_mov_b32 m0, s64
	s_nop 0
	global_load_lds_dwordx4 v[224:225], off
	s_waitcnt vmcnt(8)
	s_waitcnt lgkmcnt(0)
	s_barrier
	s_setprio 1
	v_mfma_f32_16x16x32_bf16 v[60:63], v[128:131], v[184:187], v[60:63]
	v_mfma_f32_16x16x32_bf16 v[56:59], v[136:139], v[184:187], v[56:59]
	v_mfma_f32_16x16x32_bf16 v[48:51], v[128:131], v[194:197], v[48:51]
	v_mfma_f32_16x16x32_bf16 v[40:43], v[136:139], v[194:197], v[40:43]
	v_mfma_f32_16x16x32_bf16 v[32:35], v[128:131], v[202:205], v[32:35]
	v_mfma_f32_16x16x32_bf16 v[24:27], v[136:139], v[202:205], v[24:27]
	v_mfma_f32_16x16x32_bf16 v[16:19], v[128:131], v[210:213], v[16:19]
	v_mfma_f32_16x16x32_bf16 v[8:11], v[136:139], v[210:213], v[8:11]
	v_mfma_f32_16x16x32_bf16 v[60:63], v[132:135], v[188:191], v[60:63]
	v_mfma_f32_16x16x32_bf16 v[56:59], v[140:143], v[188:191], v[56:59]
	v_mfma_f32_16x16x32_bf16 v[48:51], v[132:135], v[198:201], v[48:51]
	v_mfma_f32_16x16x32_bf16 v[40:43], v[140:143], v[198:201], v[40:43]
	v_mfma_f32_16x16x32_bf16 v[32:35], v[132:135], v[206:209], v[32:35]
	v_mfma_f32_16x16x32_bf16 v[24:27], v[140:143], v[206:209], v[24:27]
	v_mfma_f32_16x16x32_bf16 v[16:19], v[132:135], v[218:221], v[16:19]
	v_mfma_f32_16x16x32_bf16 v[8:11], v[140:143], v[218:221], v[8:11]
	v_mfma_f32_16x16x32_bf16 v[52:55], v[144:147], v[184:187], v[52:55]
	v_mfma_f32_16x16x32_bf16 v[44:47], v[168:171], v[184:187], v[44:47]
	v_mfma_f32_16x16x32_bf16 v[36:39], v[144:147], v[194:197], v[36:39]
	v_mfma_f32_16x16x32_bf16 v[28:31], v[168:171], v[194:197], v[28:31]
	v_mfma_f32_16x16x32_bf16 v[20:23], v[144:147], v[202:205], v[20:23]
	v_mfma_f32_16x16x32_bf16 v[12:15], v[168:171], v[202:205], v[12:15]
	v_mfma_f32_16x16x32_bf16 v[4:7], v[144:147], v[210:213], v[4:7]
	v_mfma_f32_16x16x32_bf16 v[0:3], v[168:171], v[210:213], v[0:3]
	v_mfma_f32_16x16x32_bf16 v[52:55], v[148:151], v[188:191], v[52:55]
	v_mfma_f32_16x16x32_bf16 v[44:47], v[172:175], v[188:191], v[44:47]
	v_mfma_f32_16x16x32_bf16 v[36:39], v[148:151], v[198:201], v[36:39]
	v_mfma_f32_16x16x32_bf16 v[28:31], v[172:175], v[198:201], v[28:31]
	v_mfma_f32_16x16x32_bf16 v[20:23], v[148:151], v[206:209], v[20:23]
	v_mfma_f32_16x16x32_bf16 v[12:15], v[172:175], v[206:209], v[12:15]
	v_mfma_f32_16x16x32_bf16 v[4:7], v[148:151], v[218:221], v[4:7]
	v_mfma_f32_16x16x32_bf16 v[0:3], v[172:175], v[218:221], v[0:3]
	s_setprio 0
	s_barrier
; #define PG8_STAGE(bufoff, gbase, voff) do { _Pragma("unroll") for (int _i = 0; _i < 2; ++_i) \
;         __builtin_amdgcn_global_load_lds((const unsigned*)((const char*)(gbase) + (voff)[_i]), (PG8_LAS unsigned*)(lds + (bufoff) + ldsw + _i * 8192), 16, 0, 0); } while (0)
; #define PG8_LDA(dst, b, h) do { _Pragma("unroll") for (int m = 0; m < 4; ++m) _Pragma("unroll") for (int k = 0; k < 2; ++k) dst[m][k] = *(const PG8_LAS bf16x8*)(lds + PG8_SA(b, h) + aoff + m * 2048 + k * 1024); } while (0)
; #define PG8_LDB(dst, b, h) do { _Pragma("unroll") for (int n = 0; n < 2; ++n) _Pragma("unroll") for (int k = 0; k < 2; ++k) dst[n][k] = *(const PG8_LAS bf16x8*)(lds + PG8_SB(b, h) + boff + n * 2048 + k * 1024); } while (0)
; #define PG8_MMA(ai, bj, At, Bt) do { __builtin_amdgcn_s_setprio(1); _Pragma("unroll") for (int m = 0; m < 4; ++m) _Pragma("unroll") for (int n = 0; n < 2; ++n) _Pragma("unroll") for (int k = 0; k < 2; ++k) \
;         acc[ai][bj][m][n] = __builtin_amdgcn_mfma_f32_16x16x32_bf16(Bt[n][k], At[m][k], acc[ai][bj][m][n], 0, 0, 0); __builtin_amdgcn_s_setprio(0); } while (0)
; #define PG8_WAIT_V(n) asm volatile("s_waitcnt vmcnt(" #n ")" ::: "memory")
; #define PG8_WAIT_L(n) asm volatile("s_waitcnt lgkmcnt(" #n ")" ::: "memory")
; #define PG8_BAR __builtin_amdgcn_s_barrier()
; #define PG8_SCHED __builtin_amdgcn_sched_barrier(0)
; template <class Epi, class Sched, bool ALIGN_EPI = false, bool SP2 = false>
; __device__ __forceinline__ void gemm_phase(PG8_LAS unsigned char* lds, const Gemm g, const Sched& S, const Epi& E) {
;     ...
;             PG8_LDB(B0, 1, 0); PG8_LDB(B1, 1, 1); PG8_SCHED; PG8_LDA(At, 1, 0); PG8_STAGE(PG8_SA(0, 1), a2 + hstep, voffA);
;             PG8_WAIT_V(8); PG8_WAIT_L(0); PG8_BAR; PG8_MMA(0, 0, At, B0); PG8_MMA(0, 1, At, B1); PG8_BAR; PG8_SCHED;
;             PG8_LDA(At, 1, 1); PG8_STAGE(PG8_SB(1, 0), b3, voffB); PG8_STAGE(PG8_SB(1, 1), b3 + hstep, voffB); PG8_STAGE(PG8_SA(1, 0), a3, voffA);
;             PG8_WAIT_V(8); PG8_WAIT_L(0); PG8_BAR; PG8_MMA(1, 0, At, B0); PG8_MMA(1, 1, At, B1); PG8_BAR; PG8_SCHED;
	s_add_i32 s77, 0, 0x18000
	s_add_i32 s78, 0, 0x1c000
	v_add_u32_e32 v140, s77, v179
	v_add_u32_e32 v172, s78, v179
	ds_read_b128 v[128:131], v140
	ds_read_b128 v[132:135], v140 offset:1024
	ds_read_b128 v[136:139], v140 offset:2048
	ds_read_b128 v[140:143], v140 offset:3072
	ds_read_b128 v[144:147], v172
	ds_read_b128 v[148:151], v172 offset:1024
	ds_read_b128 v[168:171], v172 offset:2048
	ds_read_b128 v[172:175], v172 offset:3072
	s_add_u32 s54, s54, 0x40000
	s_addc_u32 s55, s55, 0
	s_mov_b32 m0, s65
	v_lshl_add_u64 v[226:227], s[54:55], 0, v[158:159]
	ds_read_b128 v[184:187], v183 offset:32768
	ds_read_b128 v[188:191], v183 offset:33792
	ds_read_b128 v[194:197], v183 offset:34816
	ds_read_b128 v[198:201], v183 offset:35840
	ds_read_b128 v[202:205], v183 offset:36864
	ds_read_b128 v[206:209], v183 offset:37888
	ds_read_b128 v[210:213], v183 offset:38912
	ds_read_b128 v[218:221], v183 offset:39936
	global_load_lds_dwordx4 v[226:227], off
	v_lshl_add_u64 v[226:227], s[54:55], 0, v[154:155]
	s_mov_b32 m0, s66
	s_nop 0
	global_load_lds_dwordx4 v[226:227], off
	s_waitcnt vmcnt(8)
	s_waitcnt lgkmcnt(0)
	s_barrier
	s_setprio 1
	v_mfma_f32_16x16x32_bf16 v[124:127], v[128:131], v[184:187], v[124:127]
	v_mfma_f32_16x16x32_bf16 v[120:123], v[136:139], v[184:187], v[120:123]
	v_mfma_f32_16x16x32_bf16 v[108:111], v[128:131], v[194:197], v[108:111]
	v_mfma_f32_16x16x32_bf16 v[104:107], v[136:139], v[194:197], v[104:107]
	v_mfma_f32_16x16x32_bf16 v[96:99], v[128:131], v[202:205], v[96:99]
	v_mfma_f32_16x16x32_bf16 v[88:91], v[136:139], v[202:205], v[88:91]
	v_mfma_f32_16x16x32_bf16 v[80:83], v[128:131], v[210:213], v[80:83]
	v_mfma_f32_16x16x32_bf16 v[72:75], v[136:139], v[210:213], v[72:75]
	v_mfma_f32_16x16x32_bf16 v[124:127], v[132:135], v[188:191], v[124:127]
	v_mfma_f32_16x16x32_bf16 v[120:123], v[140:143], v[188:191], v[120:123]
	v_mfma_f32_16x16x32_bf16 v[108:111], v[132:135], v[198:201], v[108:111]
	v_mfma_f32_16x16x32_bf16 v[104:107], v[140:143], v[198:201], v[104:107]
	v_mfma_f32_16x16x32_bf16 v[96:99], v[132:135], v[206:209], v[96:99]
	v_mfma_f32_16x16x32_bf16 v[88:91], v[140:143], v[206:209], v[88:91]
	v_mfma_f32_16x16x32_bf16 v[80:83], v[132:135], v[218:221], v[80:83]
	v_mfma_f32_16x16x32_bf16 v[72:75], v[140:143], v[218:221], v[72:75]
	v_mfma_f32_16x16x32_bf16 v[116:119], v[144:147], v[184:187], v[116:119]
	v_mfma_f32_16x16x32_bf16 v[112:115], v[168:171], v[184:187], v[112:115]
	v_mfma_f32_16x16x32_bf16 v[100:103], v[144:147], v[194:197], v[100:103]
	v_mfma_f32_16x16x32_bf16 v[92:95], v[168:171], v[194:197], v[92:95]
	v_mfma_f32_16x16x32_bf16 v[84:87], v[144:147], v[202:205], v[84:87]
	v_mfma_f32_16x16x32_bf16 v[76:79], v[168:171], v[202:205], v[76:79]
	v_mfma_f32_16x16x32_bf16 v[68:71], v[144:147], v[210:213], v[68:71]
	v_mfma_f32_16x16x32_bf16 v[64:67], v[168:171], v[210:213], v[64:67]
	v_mfma_f32_16x16x32_bf16 v[116:119], v[148:151], v[188:191], v[116:119]
	v_mfma_f32_16x16x32_bf16 v[112:115], v[172:175], v[188:191], v[112:115]
	v_mfma_f32_16x16x32_bf16 v[100:103], v[148:151], v[198:201], v[100:103]
	v_mfma_f32_16x16x32_bf16 v[92:95], v[172:175], v[198:201], v[92:95]
	v_mfma_f32_16x16x32_bf16 v[84:87], v[148:151], v[206:209], v[84:87]
	v_mfma_f32_16x16x32_bf16 v[76:79], v[172:175], v[206:209], v[76:79]
	v_mfma_f32_16x16x32_bf16 v[68:71], v[148:151], v[218:221], v[68:71]
	v_mfma_f32_16x16x32_bf16 v[64:67], v[172:175], v[218:221], v[64:67]
	s_setprio 0
	s_barrier
; #define PG8_STAGE(bufoff, gbase, voff) do { _Pragma("unroll") for (int _i = 0; _i < 2; ++_i) \
;         __builtin_amdgcn_global_load_lds((const unsigned*)((const char*)(gbase) + (voff)[_i]), (PG8_LAS unsigned*)(lds + (bufoff) + ldsw + _i * 8192), 16, 0, 0); } while (0)
; #define PG8_LDA(dst, b, h) do { _Pragma("unroll") for (int m = 0; m < 4; ++m) _Pragma("unroll") for (int k = 0; k < 2; ++k) dst[m][k] = *(const PG8_LAS bf16x8*)(lds + PG8_SA(b, h) + aoff + m * 2048 + k * 1024); } while (0)
; #define PG8_LDB(dst, b, h) do { _Pragma("unroll") for (int n = 0; n < 2; ++n) _Pragma("unroll") for (int k = 0; k < 2; ++k) dst[n][k] = *(const PG8_LAS bf16x8*)(lds + PG8_SB(b, h) + boff + n * 2048 + k * 1024); } while (0)
; template <class Epi, class Sched, bool ALIGN_EPI = false, bool SP2 = false>
; __device__ __forceinline__ void gemm_phase(PG8_LAS unsigned char* lds, const Gemm g, const Sched& S, const Epi& E) {
;     ...
;         for (int t = 0; t < nt; t += 2) {
;             const bool last = (t == nt - 2);
;             const char* a1 = cA + (size_t)(t + 1) * kstep;
;             const char* a2 = last ? nA : cA + (size_t)(t + 2) * kstep; const char* b2 = last ? nB : cB + (size_t)(t + 2) * kstep;
;             const char* a3 = a2 + kstep; const char* b3 = b2 + kstep;
;             if (last && has_next) S.a_ready(nxt);
;             if constexpr (SP2) {
;             PG8_LDB(B0, 0, 0); PG8_LDB(B1, 0, 1); PG8_SCHED; PG8_LDA(At, 0, 0); PG8_STAGE(PG8_SA(1, 1), a1 + hstep, voffA);
;             PG8_WAIT_V(8); PG8_WAIT_L(0); PG8_BAR; PG8_MMA(0, 0, At, B0); PG8_MMA(0, 1, At, B1); PG8_BAR; PG8_SCHED;
;             PG8_LDA(At, 0, 1); PG8_STAGE(PG8_SB(0, 0), b2, voffB); PG8_STAGE(PG8_SB(0, 1), b2 + hstep, voffB); PG8_STAGE(PG8_SA(0, 0), a2, voffA);
;             PG8_WAIT_V(8); PG8_WAIT_L(0); PG8_BAR; PG8_MMA(1, 0, At, B0); PG8_MMA(1, 1, At, B1); PG8_BAR; PG8_SCHED;
;             PG8_LDB(B0, 1, 0); PG8_LDB(B1, 1, 1); PG8_SCHED; PG8_LDA(At, 1, 0); PG8_STAGE(PG8_SA(0, 1), a2 + hstep, voffA);
;             PG8_WAIT_V(8); PG8_WAIT_L(0); PG8_BAR; PG8_MMA(0, 0, At, B0); PG8_MMA(0, 1, At, B1); PG8_BAR; PG8_SCHED;
;             PG8_LDA(At, 1, 1); PG8_STAGE(PG8_SB(1, 0), b3, voffB); PG8_STAGE(PG8_SB(1, 1), b3 + hstep, voffB); PG8_STAGE(PG8_SA(1, 0), a3, voffA);
;             PG8_WAIT_V(8); PG8_WAIT_L(0); PG8_BAR; PG8_MMA(1, 0, At, B0); PG8_MMA(1, 1, At, B1); PG8_BAR; PG8_SCHED;
	s_add_i32 s54, s77, s62
	v_lshl_add_u64 v[176:177], v[176:177], 0, s[26:27]
	s_mov_b32 m0, s54
	ds_read_b128 v[184:187], v183 offset:49152
	ds_read_b128 v[188:191], v183 offset:50176
	ds_read_b128 v[194:197], v183 offset:51200
	ds_read_b128 v[198:201], v183 offset:52224
	ds_read_b128 v[202:205], v183 offset:53248
	ds_read_b128 v[206:209], v183 offset:54272
	ds_read_b128 v[210:213], v183 offset:55296
	ds_read_b128 v[218:221], v183 offset:56320
	global_load_lds_dwordx4 v[176:177], off
	s_add_i32 m0, s54, 0x2000
	s_add_u32 s52, s52, 0x40080
	v_lshl_add_u64 v[176:177], v[214:215], 0, s[26:27]
	s_addc_u32 s53, s53, 0
	s_add_i32 s54, s78, s62
	global_load_lds_dwordx4 v[176:177], off
	v_lshl_add_u64 v[176:177], s[52:53], 0, v[156:157]
	s_mov_b32 m0, s54
	s_nop 0
	global_load_lds_dwordx4 v[176:177], off
	v_lshl_add_u64 v[176:177], s[52:53], 0, v[152:153]
	s_add_i32 m0, s54, 0x2000
	s_nop 0
	global_load_lds_dwordx4 v[176:177], off
	v_lshl_add_u64 v[176:177], v[222:223], 0, s[26:27]
	s_mov_b32 m0, s68
	s_nop 0
	global_load_lds_dwordx4 v[176:177], off
	v_lshl_add_u64 v[176:177], v[224:225], 0, s[26:27]
	s_mov_b32 m0, s69
	s_nop 0
	global_load_lds_dwordx4 v[176:177], off
	s_waitcnt vmcnt(8)
	s_waitcnt lgkmcnt(0)
	s_barrier
	s_setprio 1
	v_mfma_f32_16x16x32_bf16 v[60:63], v[128:131], v[184:187], v[60:63]
	v_mfma_f32_16x16x32_bf16 v[56:59], v[136:139], v[184:187], v[56:59]
	v_mfma_f32_16x16x32_bf16 v[48:51], v[128:131], v[194:197], v[48:51]
	v_mfma_f32_16x16x32_bf16 v[40:43], v[136:139], v[194:197], v[40:43]
	v_mfma_f32_16x16x32_bf16 v[32:35], v[128:131], v[202:205], v[32:35]
	v_mfma_f32_16x16x32_bf16 v[24:27], v[136:139], v[202:205], v[24:27]
	v_mfma_f32_16x16x32_bf16 v[16:19], v[128:131], v[210:213], v[16:19]
	v_mfma_f32_16x16x32_bf16 v[8:11], v[136:139], v[210:213], v[8:11]
	v_mfma_f32_16x16x32_bf16 v[60:63], v[132:135], v[188:191], v[60:63]
	v_mfma_f32_16x16x32_bf16 v[56:59], v[140:143], v[188:191], v[56:59]
	v_mfma_f32_16x16x32_bf16 v[48:51], v[132:135], v[198:201], v[48:51]
	v_mfma_f32_16x16x32_bf16 v[40:43], v[140:143], v[198:201], v[40:43]
	v_mfma_f32_16x16x32_bf16 v[32:35], v[132:135], v[206:209], v[32:35]
	v_mfma_f32_16x16x32_bf16 v[24:27], v[140:143], v[206:209], v[24:27]
	v_mfma_f32_16x16x32_bf16 v[16:19], v[132:135], v[218:221], v[16:19]
	v_mfma_f32_16x16x32_bf16 v[8:11], v[140:143], v[218:221], v[8:11]
	v_mfma_f32_16x16x32_bf16 v[52:55], v[144:147], v[184:187], v[52:55]
	v_mfma_f32_16x16x32_bf16 v[44:47], v[168:171], v[184:187], v[44:47]
	v_mfma_f32_16x16x32_bf16 v[36:39], v[144:147], v[194:197], v[36:39]
	v_mfma_f32_16x16x32_bf16 v[28:31], v[168:171], v[194:197], v[28:31]
	v_mfma_f32_16x16x32_bf16 v[20:23], v[144:147], v[202:205], v[20:23]
	v_mfma_f32_16x16x32_bf16 v[12:15], v[168:171], v[202:205], v[12:15]
	v_mfma_f32_16x16x32_bf16 v[4:7], v[144:147], v[210:213], v[4:7]
	v_mfma_f32_16x16x32_bf16 v[0:3], v[168:171], v[210:213], v[0:3]
	v_mfma_f32_16x16x32_bf16 v[52:55], v[148:151], v[188:191], v[52:55]
	v_mfma_f32_16x16x32_bf16 v[44:47], v[172:175], v[188:191], v[44:47]
	v_mfma_f32_16x16x32_bf16 v[36:39], v[148:151], v[198:201], v[36:39]
	v_mfma_f32_16x16x32_bf16 v[28:31], v[172:175], v[198:201], v[28:31]
	v_mfma_f32_16x16x32_bf16 v[20:23], v[148:151], v[206:209], v[20:23]
	v_mfma_f32_16x16x32_bf16 v[12:15], v[172:175], v[206:209], v[12:15]
	v_mfma_f32_16x16x32_bf16 v[4:7], v[148:151], v[218:221], v[4:7]
	v_mfma_f32_16x16x32_bf16 v[0:3], v[172:175], v[218:221], v[0:3]
	s_setprio 0
	s_barrier
	s_add_i32 s76, s76, 2
	s_add_u32 s50, s50, 0x100
	s_addc_u32 s51, s51, 0
	s_add_u32 s74, s74, 0x100
	s_addc_u32 s75, s75, 0
	s_cmp_gt_u32 s76, 13
	s_cbranch_scc0 .LBB0_553
	s_and_b64 vcc, exec, s[28:29]
	s_cbranch_vccz .LBB0_556
	s_barrier

; #define PG8_WAIT_V(n) asm volatile("s_waitcnt vmcnt(" #n ")" ::: "memory")
; #define PG8_BAR __builtin_amdgcn_s_barrier()
; template <class Epi, class Sched, bool ALIGN_EPI = false, bool SP2 = false>
; __device__ __forceinline__ void gemm_phase(PG8_LAS unsigned char* lds, const Gemm g, const Sched& S, const Epi& E) {
;     int tid_ = threadIdx.x; asm volatile("" : "+v"(tid_));
;     const int tid = tid_, wid = __builtin_amdgcn_readfirstlane(tid >> 6), lane = tid & 63, wr = wid >> 2, wc = wid & 3, fr = lane & 15, fq = lane >> 4;
;     const int K = g.K, nt = K / BK;
;     unsigned voffA[2], voffB[2];
; #pragma unroll
;     for (int i = 0; i < 2; ++i) { int R, C; stage_rc(tid * 16 + i * 8192, R, C); const int Rb = Epi::PERM ? ((R & ~31) + perm32(R & 31)) : R;
;         voffA[i] = (unsigned)(R * K + C) * 2u; voffB[i] = (unsigned)(Rb * K + C) * 2u; }
;     const size_t kstep = (size_t)(BK * 2);
;     const size_t hstep = (size_t)HALF * K * 2;
;     const size_t tstep = 2 * hstep;
;     const unsigned ldsw = (unsigned)wid * 1024u;
;     const int aoff = lds_byte(wr * 64 + fr, fq * 8), boff = lds_byte(wc * 32 + fr, fq * 8);
;     ...
;     Unit cur, nxt; int ui = 0;
;     if (!S.next(0, cur)) return;
;     f32x4 acc[2][2][4][2];
; #pragma unroll
;     for (int a = 0; a < 2; ++a)
; #pragma unroll
;         for (int b = 0; b < 2; ++b)
; #pragma unroll
;             for (int m = 0; m < 4; ++m)
; #pragma unroll
;                 for (int n = 0; n < 2; ++n) acc[a][b][m][n] = (f32x4){0.f, 0.f, 0.f, 0.f};
;     bf16x8 At[4][2], B0[2][2], B1[2][2];
;     const char* cA = (const char*)g.A + (size_t)cur.pm * tstep; const char* cB = (const char*)g.Bt + (size_t)cur.pn * tstep;
;     S.a_ready(cur);
;     if constexpr (SP2) {
;         PG8_STAGE(PG8_SB(0, 0), cB, voffB); PG8_STAGE(PG8_SB(0, 1), cB + hstep, voffB); PG8_STAGE(PG8_SA(0, 0), cA, voffA); PG8_STAGE(PG8_SA(0, 1), cA + hstep, voffA);
;         if (wr == 1) PG8_BAR;
;         PG8_WAIT_V(2); PG8_BAR;
;         PG8_STAGE(PG8_SB(1, 0), cB + kstep, voffB); PG8_STAGE(PG8_SA(1, 0), cA + kstep, voffA); PG8_STAGE(PG8_SB(1, 1), cB + hstep + kstep, voffB);
;         PG8_WAIT_V(6); PG8_BAR;
;     } else {
;         PG8_STAGE(PG8_SB(0, 0), cB, voffB); PG8_STAGE(PG8_SA(0, 0), cA, voffA); PG8_STAGE(PG8_SB(0, 1), cB + hstep, voffB); PG8_STAGE(PG8_SA(0, 1), cA + hstep, voffA);
;         if (wr == 1) PG8_BAR;
.LBB0_560:
	v_mov_b32_e32 v14, v216
	s_nop 0
	s_nop 0
	v_cndmask_b32_e64 v0, 0, 1, s[48:49]
	v_cmp_ne_u32_e64 s[38:39], 1, v0
	s_andn2_b64 vcc, exec, s[48:49]
	v_readfirstlane_b32 s22, v14
	s_cbranch_vccnz .LBB0_580
	v_lshlrev_b32_e32 v0, 4, v14
	v_add_u32_e32 v1, 0x2000, v0
	v_ashrrev_i32_e32 v2, 31, v1
	v_lshrrev_b32_e32 v2, 22, v2
	v_add_u32_e32 v2, v1, v2
	v_ashrrev_i32_e32 v8, 10, v2
	v_mul_i32_i24_e32 v2, 0x400, v8
	v_sub_u32_e32 v1, v1, v2
	v_lshrrev_b32_e32 v2, 4, v1
	v_bitop3_b32 v1, v2, v1, 32 bitop3:0x6c
	v_ashrrev_i32_e32 v2, 31, v1
	s_ashr_i32 s23, s22, 6
	v_lshrrev_b32_e32 v2, 26, v2
	s_ashr_i32 s24, s22, 8
	s_lshl_b32 s13, s23, 10
	v_add_u32_e32 v2, v1, v2
	v_lshlrev_b32_e32 v3, 3, v8
	s_add_u32 s47, s20, 0x17800000
	v_ashrrev_i32_e32 v9, 6, v2
	v_and_b32_e32 v3, -16, v3
	s_addc_u32 s52, s21, 0
	v_add_u32_e32 v3, v9, v3
	s_add_u32 s53, s18, 0x2a00000
	v_and_b32_e32 v4, 3, v9
	s_mov_b32 s18, 0x1fffe0
	v_lshrrev_b32_e32 v5, 2, v3
	v_lshlrev_b32_e32 v6, 1, v3
	v_and_b32_e32 v2, 0xc0, v2
	v_and_or_b32 v4, v3, s18, v4
	v_and_b32_e32 v5, 4, v5
	v_and_b32_e32 v6, 24, v6
	v_sub_u32_e32 v1, v1, v2
	v_mov_b32_e32 v2, 1
	v_or3_b32 v4, v4, v5, v6
	v_lshlrev_b32_e32 v5, 5, v8
	v_ashrrev_i16_sdwa v1, v2, sext(v1) dst_sel:DWORD dst_unused:UNUSED_PAD src0_sel:DWORD src1_sel:BYTE_0
	v_and_b32_e32 v5, 32, v5
	v_bfe_i32 v10, v1, 0, 16
	v_add_lshl_u32 v1, v5, v10, 1
	v_lshl_add_u32 v184, v4, 11, v1
	v_lshl_add_u32 v186, v3, 11, v1
	v_bfe_i32 v1, v14, 27, 1
	v_lshrrev_b32_e32 v1, 22, v1
	v_add_u32_e32 v1, v0, v1
	v_and_b32_e32 v1, 0xfffffc00, v1
	v_sub_u32_e32 v0, v0, v1
	v_lshrrev_b32_e32 v1, 4, v0
	v_ashrrev_i32_e32 v3, 31, v14
	v_bitop3_b32 v0, v1, v0, 32 bitop3:0x6c
	v_lshrrev_b32_e32 v3, 26, v3
	v_ashrrev_i32_e32 v1, 31, v0
	v_add_u32_e32 v3, v14, v3
	v_lshrrev_b32_e32 v1, 26, v1
	v_ashrrev_i32_e32 v12, 6, v3
	v_add_u32_e32 v1, v0, v1
	v_lshlrev_b32_e32 v3, 3, v12
	v_ashrrev_i32_e32 v11, 6, v1
	v_and_b32_e32 v3, -16, v3
	s_addc_u32 s54, s19, 0
	v_add_u32_e32 v3, v11, v3
	v_and_b32_e32 v4, 3, v11
	v_and_or_b32 v4, v3, s18, v4
	s_and_b64 s[18:19], s[42:43], exec
	s_cselect_b32 s18, s58, s57
	s_add_i32 s18, s18, s56
	s_ashr_i32 s19, s18, 31
	s_lshr_b32 s19, s19, 27
	s_add_i32 s19, s18, s19
	s_ashr_i32 s20, s19, 5
	s_and_b32 s19, s19, 0xffe0
	s_sub_i32 s18, s18, s19
	s_bfe_i32 s19, s18, 0x80000
	s_bfe_u32 s19, s19, 0x2000d
	s_add_i32 s19, s18, s19
	s_lshl_b32 s21, s20, 2
	s_bfe_i32 s20, s19, 0x80000
	s_and_b32 s19, s19, 0xfc
	s_sub_i32 s18, s18, s19
	s_sext_i32_i16 s20, s20
	s_sext_i32_i8 s18, s18
	v_lshrrev_b32_e32 v5, 2, v3
	v_lshlrev_b32_e32 v6, 1, v3
	v_and_b32_e32 v1, 0xc0, v1
	s_lshr_b32 s20, s20, 2
	s_add_i32 s34, s21, s18
	v_and_b32_e32 v5, 4, v5
	v_and_b32_e32 v6, 24, v6
	v_sub_u32_e32 v0, v0, v1
	s_ashr_i32 s35, s34, 31
	s_bfe_i64 s[26:27], s[20:21], 0x100000
	v_or3_b32 v4, v4, v5, v6
	v_lshlrev_b32_e32 v5, 5, v12
	v_ashrrev_i16_sdwa v0, v2, sext(v0) dst_sel:DWORD dst_unused:UNUSED_PAD src0_sel:DWORD src1_sel:BYTE_0
	s_lshl_b64 s[18:19], s[34:35], 19
	s_lshl_b64 s[26:27], s[26:27], 19
	v_and_b32_e32 v5, 32, v5
	v_bfe_i32 v13, v0, 0, 16
	s_add_u32 s44, s53, s26
	v_add_lshl_u32 v0, v5, v13, 1
	s_addc_u32 s45, s54, s27
	s_add_i32 s55, s13, 0
	v_lshl_add_u32 v188, v4, 11, v0
	s_add_i32 m0, s55, 0x10000
	v_lshl_add_u32 v190, v3, 11, v0
	global_load_lds_dwordx4 v188, s[44:45]
	s_add_i32 m0, s55, 0x12000
	s_add_u32 s26, s44, 0x40000
	global_load_lds_dwordx4 v184, s[44:45]
	s_addc_u32 s27, s45, 0
	s_add_i32 m0, s55, 0x14000
	v_mov_b32_e32 v189, 0
	global_load_lds_dwordx4 v188, s[26:27]
	s_add_i32 m0, s55, 0x16000
	s_add_u32 s36, s47, s18
	s_addc_u32 s37, s52, s19
	s_add_i32 s60, s55, 0x2000
	global_load_lds_dwordx4 v184, s[26:27]
	s_mov_b32 m0, s55
	s_add_u32 s18, s36, 0x40000
	global_load_lds_dwordx4 v190, s[36:37]
	s_mov_b32 m0, s60
	s_addc_u32 s19, s37, 0
	s_add_i32 s61, s55, 0x4000
	global_load_lds_dwordx4 v186, s[36:37]
	s_mov_b32 m0, s61
	s_add_i32 s62, s55, 0x6000
	global_load_lds_dwordx4 v190, s[18:19]
	s_mov_b32 m0, s62
	v_mov_b32_e32 v185, v189
	global_load_lds_dwordx4 v186, s[18:19]
	v_mov_b32_e32 v191, v189
	v_mov_b32_e32 v187, v189
	s_cmp_eq_u32 s24, 1
	s_mov_b32 s63, 0
	v_lshl_add_u64 v[6:7], s[44:45], 0, v[188:189]
	v_lshl_add_u64 v[4:5], s[44:45], 0, v[184:185]
	v_lshl_add_u64 v[0:1], s[36:37], 0, v[190:191]
	s_cselect_b64 s[18:19], -1, 0
	s_cmp_lg_u32 s24, 1
	v_lshl_add_u64 v[2:3], s[36:37], 0, v[186:187]
	s_cbranch_scc1 .LBB0_563
	s_barrier

; #define PG8_STAGE(bufoff, gbase, voff) do { _Pragma("unroll") for (int _i = 0; _i < 2; ++_i) \
;         __builtin_amdgcn_global_load_lds((const unsigned*)((const char*)(gbase) + (voff)[_i]), (PG8_LAS unsigned*)(lds + (bufoff) + ldsw + _i * 8192), 16, 0, 0); } while (0)
; #define PG8_LDA(dst, b, h) do { _Pragma("unroll") for (int m = 0; m < 4; ++m) _Pragma("unroll") for (int k = 0; k < 2; ++k) dst[m][k] = *(const PG8_LAS bf16x8*)(lds + PG8_SA(b, h) + aoff + m * 2048 + k * 1024); } while (0)
; #define PG8_LDB(dst, b, h) do { _Pragma("unroll") for (int n = 0; n < 2; ++n) _Pragma("unroll") for (int k = 0; k < 2; ++k) dst[n][k] = *(const PG8_LAS bf16x8*)(lds + PG8_SB(b, h) + boff + n * 2048 + k * 1024); } while (0)
; #define PG8_WAIT_V(n) asm volatile("s_waitcnt vmcnt(" #n ")" ::: "memory")
; #define PG8_WAIT_L(n) asm volatile("s_waitcnt lgkmcnt(" #n ")" ::: "memory")
; #define PG8_BAR __builtin_amdgcn_s_barrier()
; #define PG8_SCHED __builtin_amdgcn_sched_barrier(0)
; template <class Epi, class Sched, bool ALIGN_EPI = false, bool SP2 = false>
; __device__ __forceinline__ void gemm_phase(PG8_LAS unsigned char* lds, const Gemm g, const Sched& S, const Epi& E) {
;     ...
;         const bool has_next = S.next(ui + 1, nxt);
;         const char* nA = has_next ? (const char*)g.A + (size_t)nxt.pm * tstep : cA; const char* nB = has_next ? (const char*)g.Bt + (size_t)nxt.pn * tstep : cB;
;         for (int t = 0; t < nt; t += 2) {
;             const bool last = (t == nt - 2);
;             const char* a1 = cA + (size_t)(t + 1) * kstep;
;             const char* a2 = last ? nA : cA + (size_t)(t + 2) * kstep; const char* b2 = last ? nB : cB + (size_t)(t + 2) * kstep;
;             const char* a3 = a2 + kstep; const char* b3 = b2 + kstep;
;             if (last && has_next) S.a_ready(nxt);
;             if constexpr (SP2) {
;             PG8_LDB(B0, 0, 0); PG8_LDB(B1, 0, 1); PG8_SCHED; PG8_LDA(At, 0, 0); PG8_STAGE(PG8_SA(1, 1), a1 + hstep, voffA);
;             PG8_WAIT_V(8); PG8_WAIT_L(0); PG8_BAR; PG8_MMA(0, 0, At, B0); PG8_MMA(0, 1, At, B1); PG8_BAR; PG8_SCHED;
;             PG8_LDA(At, 0, 1); PG8_STAGE(PG8_SB(0, 0), b2, voffB); PG8_STAGE(PG8_SB(0, 1), b2 + hstep, voffB); PG8_STAGE(PG8_SA(0, 0), a2, voffA);
;             PG8_WAIT_V(8); PG8_WAIT_L(0); PG8_BAR; PG8_MMA(1, 0, At, B0); PG8_MMA(1, 1, At, B1); PG8_BAR; PG8_SCHED;
.LBB0_572:
	s_ashr_i32 s27, s26, 31
	s_lshl_b64 s[28:29], s[26:27], 19
	s_add_u32 s28, s47, s28
	s_addc_u32 s29, s52, s29
	s_and_b64 s[30:31], s[40:41], exec
	s_cselect_b32 s27, s29, s37
	s_cselect_b32 s68, s28, s36
	s_ashr_i32 s25, s24, 31
	s_lshl_b64 s[30:31], s[24:25], 19
	s_add_u32 s30, s53, s30
	s_addc_u32 s31, s54, s31
	s_and_b64 s[50:51], s[40:41], exec
	s_cselect_b32 s25, s31, s45
	s_cselect_b32 s69, s30, s44
	s_add_u32 s36, s36, 0x40080
	s_addc_u32 s37, s37, 0
	s_add_u32 s70, s44, 0x100
	s_addc_u32 s71, s45, 0
	s_mov_b32 s72, -2
	ds_read_b128 v[128:131], v220
	ds_read_b128 v[132:135], v220 offset:1024
	ds_read_b128 v[136:139], v220 offset:2048
	ds_read_b128 v[140:143], v220 offset:3072
	ds_read_b128 v[144:147], v221
	ds_read_b128 v[148:151], v221 offset:1024
	ds_read_b128 v[152:155], v221 offset:2048
	ds_read_b128 v[156:159], v221 offset:3072
	s_add_u32 s44, s36, 0xfffc0080
	s_addc_u32 s45, s37, -1
	s_cmp_eq_u32 s72, 12
	s_cselect_b32 s51, s27, s45
	s_cselect_b32 s50, s68, s44
	s_cselect_b32 s45, s25, s71
	s_cselect_b32 s44, s69, s70
	v_lshl_add_u64 v[210:211], s[36:37], 0, v[194:195]
	s_add_i32 m0, s55, 0xc000
	ds_read_b128 v[160:163], v222
	ds_read_b128 v[164:167], v222 offset:1024
	ds_read_b128 v[168:171], v222 offset:2048
	ds_read_b128 v[172:175], v222 offset:3072
	ds_read_b128 v[176:179], v222 offset:4096
	ds_read_b128 v[180:183], v222 offset:5120
	ds_read_b128 v[202:205], v222 offset:6144
	ds_read_b128 v[206:209], v222 offset:7168
	global_load_lds_dwordx4 v[210:211], off
	v_lshl_add_u64 v[210:211], s[36:37], 0, v[196:197]
	s_add_i32 m0, s55, 0xe000
	s_nop 0
	global_load_lds_dwordx4 v[210:211], off
	s_waitcnt vmcnt(8)
	s_waitcnt lgkmcnt(0)
	s_barrier
	s_setprio 1
	v_mfma_f32_16x16x32_bf16 v[124:127], v[128:131], v[160:163], 0
	v_mfma_f32_16x16x32_bf16 v[120:123], v[136:139], v[160:163], 0
	v_mfma_f32_16x16x32_bf16 v[108:111], v[128:131], v[168:171], 0
	v_mfma_f32_16x16x32_bf16 v[104:107], v[136:139], v[168:171], 0
	v_mfma_f32_16x16x32_bf16 v[92:95], v[128:131], v[176:179], 0
	v_mfma_f32_16x16x32_bf16 v[88:91], v[136:139], v[176:179], 0
	v_mfma_f32_16x16x32_bf16 v[76:79], v[128:131], v[202:205], 0
	v_mfma_f32_16x16x32_bf16 v[72:75], v[136:139], v[202:205], 0
	v_mfma_f32_16x16x32_bf16 v[124:127], v[132:135], v[164:167], v[124:127]
	v_mfma_f32_16x16x32_bf16 v[120:123], v[140:143], v[164:167], v[120:123]
	v_mfma_f32_16x16x32_bf16 v[108:111], v[132:135], v[172:175], v[108:111]
	v_mfma_f32_16x16x32_bf16 v[104:107], v[140:143], v[172:175], v[104:107]
	v_mfma_f32_16x16x32_bf16 v[92:95], v[132:135], v[180:183], v[92:95]
	v_mfma_f32_16x16x32_bf16 v[88:91], v[140:143], v[180:183], v[88:91]
	v_mfma_f32_16x16x32_bf16 v[76:79], v[132:135], v[206:209], v[76:79]
	v_mfma_f32_16x16x32_bf16 v[72:75], v[140:143], v[206:209], v[72:75]
	v_mfma_f32_16x16x32_bf16 v[116:119], v[144:147], v[160:163], 0
	v_mfma_f32_16x16x32_bf16 v[112:115], v[152:155], v[160:163], 0
	v_mfma_f32_16x16x32_bf16 v[100:103], v[144:147], v[168:171], 0
	v_mfma_f32_16x16x32_bf16 v[96:99], v[152:155], v[168:171], 0
	v_mfma_f32_16x16x32_bf16 v[84:87], v[144:147], v[176:179], 0
	v_mfma_f32_16x16x32_bf16 v[80:83], v[152:155], v[176:179], 0
	v_mfma_f32_16x16x32_bf16 v[68:71], v[144:147], v[202:205], 0
	v_mfma_f32_16x16x32_bf16 v[64:67], v[152:155], v[202:205], 0
	v_mfma_f32_16x16x32_bf16 v[116:119], v[148:151], v[164:167], v[116:119]
	v_mfma_f32_16x16x32_bf16 v[112:115], v[156:159], v[164:167], v[112:115]
	v_mfma_f32_16x16x32_bf16 v[100:103], v[148:151], v[172:175], v[100:103]
	v_mfma_f32_16x16x32_bf16 v[96:99], v[156:159], v[172:175], v[96:99]
	v_mfma_f32_16x16x32_bf16 v[84:87], v[148:151], v[180:183], v[84:87]
	v_mfma_f32_16x16x32_bf16 v[80:83], v[156:159], v[180:183], v[80:83]
	v_mfma_f32_16x16x32_bf16 v[68:71], v[148:151], v[206:209], v[68:71]
	v_mfma_f32_16x16x32_bf16 v[64:67], v[156:159], v[206:209], v[64:67]
	s_setprio 0
	s_barrier
	s_add_i32 s73, s66, s13
	v_lshl_add_u64 v[210:211], s[44:45], 0, v[188:189]
	s_mov_b32 m0, s73
	ds_read_b128 v[160:163], v222 offset:16384
	ds_read_b128 v[164:167], v222 offset:17408
	ds_read_b128 v[168:171], v222 offset:18432
	ds_read_b128 v[172:175], v222 offset:19456
	ds_read_b128 v[176:179], v222 offset:20480
	ds_read_b128 v[180:183], v222 offset:21504
	ds_read_b128 v[202:205], v222 offset:22528
	ds_read_b128 v[206:209], v222 offset:23552
	global_load_lds_dwordx4 v[210:211], off
	s_add_i32 m0, s73, 0x2000
	s_add_u32 s74, s44, 0x40000
	v_lshl_add_u64 v[212:213], s[44:45], 0, v[184:185]
	s_addc_u32 s75, s45, 0
	s_add_i32 s73, s67, s13
	global_load_lds_dwordx4 v[212:213], off
	v_lshl_add_u64 v[214:215], s[74:75], 0, v[188:189]
	s_mov_b32 m0, s73
	v_lshl_add_u64 v[224:225], s[50:51], 0, v[186:187]
	global_load_lds_dwordx4 v[214:215], off
	v_lshl_add_u64 v[214:215], s[74:75], 0, v[184:185]
	s_add_i32 m0, s73, 0x2000
	s_nop 0
	global_load_lds_dwordx4 v[214:215], off
	v_lshl_add_u64 v[214:215], s[50:51], 0, v[190:191]
	s_mov_b32 m0, s55
	s_nop 0
	global_load_lds_dwordx4 v[214:215], off
	s_mov_b32 m0, s60
	s_nop 0
	global_load_lds_dwordx4 v[224:225], off
	s_waitcnt vmcnt(8)
	s_waitcnt lgkmcnt(0)
	s_barrier
; #define PG8_STAGE(bufoff, gbase, voff) do { _Pragma("unroll") for (int _i = 0; _i < 2; ++_i) \
;         __builtin_amdgcn_global_load_lds((const unsigned*)((const char*)(gbase) + (voff)[_i]), (PG8_LAS unsigned*)(lds + (bufoff) + ldsw + _i * 8192), 16, 0, 0); } while (0)
; #define PG8_LDA(dst, b, h) do { _Pragma("unroll") for (int m = 0; m < 4; ++m) _Pragma("unroll") for (int k = 0; k < 2; ++k) dst[m][k] = *(const PG8_LAS bf16x8*)(lds + PG8_SA(b, h) + aoff + m * 2048 + k * 1024); } while (0)
; #define PG8_LDB(dst, b, h) do { _Pragma("unroll") for (int n = 0; n < 2; ++n) _Pragma("unroll") for (int k = 0; k < 2; ++k) dst[n][k] = *(const PG8_LAS bf16x8*)(lds + PG8_SB(b, h) + boff + n * 2048 + k * 1024); } while (0)
; #define PG8_MMA(ai, bj, At, Bt) do { __builtin_amdgcn_s_setprio(1); _Pragma("unroll") for (int m = 0; m < 4; ++m) _Pragma("unroll") for (int n = 0; n < 2; ++n) _Pragma("unroll") for (int k = 0; k < 2; ++k) \
;         acc[ai][bj][m][n] = __builtin_amdgcn_mfma_f32_16x16x32_bf16(Bt[n][k], At[m][k], acc[ai][bj][m][n], 0, 0, 0); __builtin_amdgcn_s_setprio(0); } while (0)
; #define PG8_WAIT_V(n) asm volatile("s_waitcnt vmcnt(" #n ")" ::: "memory")
; template <class Epi, class Sched, bool ALIGN_EPI = false, bool SP2 = false>
; __device__ __forceinline__ void gemm_phase(PG8_LAS unsigned char* lds, const Gemm g, const Sched& S, const Epi& E) {
;     ...
;             PG8_LDB(B0, 0, 0); PG8_LDB(B1, 0, 1); PG8_SCHED; PG8_LDA(At, 0, 0); PG8_STAGE(PG8_SA(1, 1), a1 + hstep, voffA);
;             PG8_WAIT_V(8); PG8_WAIT_L(0); PG8_BAR; PG8_MMA(0, 0, At, B0); PG8_MMA(0, 1, At, B1); PG8_BAR; PG8_SCHED;
;             PG8_LDA(At, 0, 1); PG8_STAGE(PG8_SB(0, 0), b2, voffB); PG8_STAGE(PG8_SB(0, 1), b2 + hstep, voffB); PG8_STAGE(PG8_SA(0, 0), a2, voffA);
;             PG8_WAIT_V(8); PG8_WAIT_L(0); PG8_BAR; PG8_MMA(1, 0, At, B0); PG8_MMA(1, 1, At, B1); PG8_BAR; PG8_SCHED;
;             PG8_LDB(B0, 1, 0); PG8_LDB(B1, 1, 1); PG8_SCHED; PG8_LDA(At, 1, 0); PG8_STAGE(PG8_SA(0, 1), a2 + hstep, voffA);
;             PG8_WAIT_V(8); PG8_WAIT_L(0); PG8_BAR; PG8_MMA(0, 0, At, B0); PG8_MMA(0, 1, At, B1); PG8_BAR; PG8_SCHED;
;             PG8_LDA(At, 1, 1); PG8_STAGE(PG8_SB(1, 0), b3, voffB); PG8_STAGE(PG8_SB(1, 1), b3 + hstep, voffB); PG8_STAGE(PG8_SA(1, 0), a3, voffA);
;             PG8_WAIT_V(8); PG8_WAIT_L(0); PG8_BAR; PG8_MMA(1, 0, At, B0); PG8_MMA(1, 1, At, B1); PG8_BAR; PG8_SCHED;
	s_setprio 1
	v_mfma_f32_16x16x32_bf16 v[60:63], v[128:131], v[160:163], 0
	v_mfma_f32_16x16x32_bf16 v[56:59], v[136:139], v[160:163], 0
	v_mfma_f32_16x16x32_bf16 v[44:47], v[128:131], v[168:171], 0
	v_mfma_f32_16x16x32_bf16 v[40:43], v[136:139], v[168:171], 0
	v_mfma_f32_16x16x32_bf16 v[28:31], v[128:131], v[176:179], 0
	v_mfma_f32_16x16x32_bf16 v[24:27], v[136:139], v[176:179], 0
	v_mfma_f32_16x16x32_bf16 v[12:15], v[128:131], v[202:205], 0
	v_mfma_f32_16x16x32_bf16 v[8:11], v[136:139], v[202:205], 0
	v_mfma_f32_16x16x32_bf16 v[60:63], v[132:135], v[164:167], v[60:63]
	v_mfma_f32_16x16x32_bf16 v[56:59], v[140:143], v[164:167], v[56:59]
	v_mfma_f32_16x16x32_bf16 v[44:47], v[132:135], v[172:175], v[44:47]
	v_mfma_f32_16x16x32_bf16 v[40:43], v[140:143], v[172:175], v[40:43]
	v_mfma_f32_16x16x32_bf16 v[28:31], v[132:135], v[180:183], v[28:31]
	v_mfma_f32_16x16x32_bf16 v[24:27], v[140:143], v[180:183], v[24:27]
	v_mfma_f32_16x16x32_bf16 v[12:15], v[132:135], v[206:209], v[12:15]
	v_mfma_f32_16x16x32_bf16 v[8:11], v[140:143], v[206:209], v[8:11]
	v_mfma_f32_16x16x32_bf16 v[52:55], v[144:147], v[160:163], 0
	v_mfma_f32_16x16x32_bf16 v[48:51], v[152:155], v[160:163], 0
	v_mfma_f32_16x16x32_bf16 v[36:39], v[144:147], v[168:171], 0
	v_mfma_f32_16x16x32_bf16 v[32:35], v[152:155], v[168:171], 0
	v_mfma_f32_16x16x32_bf16 v[20:23], v[144:147], v[176:179], 0
	v_mfma_f32_16x16x32_bf16 v[16:19], v[152:155], v[176:179], 0
	v_mfma_f32_16x16x32_bf16 v[4:7], v[144:147], v[202:205], 0
	v_mfma_f32_16x16x32_bf16 v[0:3], v[152:155], v[202:205], 0
	v_mfma_f32_16x16x32_bf16 v[52:55], v[148:151], v[164:167], v[52:55]
	v_mfma_f32_16x16x32_bf16 v[48:51], v[156:159], v[164:167], v[48:51]
	v_mfma_f32_16x16x32_bf16 v[36:39], v[148:151], v[172:175], v[36:39]
	v_mfma_f32_16x16x32_bf16 v[32:35], v[156:159], v[172:175], v[32:35]
	v_mfma_f32_16x16x32_bf16 v[20:23], v[148:151], v[180:183], v[20:23]
	v_mfma_f32_16x16x32_bf16 v[16:19], v[156:159], v[180:183], v[16:19]
	v_mfma_f32_16x16x32_bf16 v[4:7], v[148:151], v[206:209], v[4:7]
	v_mfma_f32_16x16x32_bf16 v[0:3], v[156:159], v[206:209], v[0:3]
	s_setprio 0
	s_barrier
	s_add_i32 s73, 0, 0x18000
	s_add_i32 s74, 0, 0x1c000
	v_add_u32_e32 v140, s73, v218
	v_add_u32_e32 v156, s74, v218
	ds_read_b128 v[128:131], v140
	ds_read_b128 v[132:135], v140 offset:1024
	ds_read_b128 v[136:139], v140 offset:2048
	ds_read_b128 v[140:143], v140 offset:3072
	ds_read_b128 v[144:147], v156
	ds_read_b128 v[148:151], v156 offset:1024
	ds_read_b128 v[152:155], v156 offset:2048
	ds_read_b128 v[156:159], v156 offset:3072
	s_add_u32 s50, s50, 0x40000
	s_addc_u32 s51, s51, 0
	s_mov_b32 m0, s61
	v_lshl_add_u64 v[226:227], s[50:51], 0, v[190:191]
	ds_read_b128 v[160:163], v222 offset:32768
	ds_read_b128 v[164:167], v222 offset:33792
	ds_read_b128 v[168:171], v222 offset:34816
	ds_read_b128 v[172:175], v222 offset:35840
	ds_read_b128 v[176:179], v222 offset:36864
	ds_read_b128 v[180:183], v222 offset:37888
	ds_read_b128 v[202:205], v222 offset:38912
	ds_read_b128 v[206:209], v222 offset:39936
	global_load_lds_dwordx4 v[226:227], off
	v_lshl_add_u64 v[226:227], s[50:51], 0, v[186:187]
	s_mov_b32 m0, s62
	s_nop 0
	global_load_lds_dwordx4 v[226:227], off
	s_waitcnt vmcnt(8)
	s_waitcnt lgkmcnt(0)
	s_barrier
	s_setprio 1
	v_mfma_f32_16x16x32_bf16 v[124:127], v[128:131], v[160:163], v[124:127]
	v_mfma_f32_16x16x32_bf16 v[120:123], v[136:139], v[160:163], v[120:123]
	v_mfma_f32_16x16x32_bf16 v[108:111], v[128:131], v[168:171], v[108:111]
	v_mfma_f32_16x16x32_bf16 v[104:107], v[136:139], v[168:171], v[104:107]
	v_mfma_f32_16x16x32_bf16 v[92:95], v[128:131], v[176:179], v[92:95]
	v_mfma_f32_16x16x32_bf16 v[88:91], v[136:139], v[176:179], v[88:91]
	v_mfma_f32_16x16x32_bf16 v[76:79], v[128:131], v[202:205], v[76:79]
	v_mfma_f32_16x16x32_bf16 v[72:75], v[136:139], v[202:205], v[72:75]
	v_mfma_f32_16x16x32_bf16 v[124:127], v[132:135], v[164:167], v[124:127]
	v_mfma_f32_16x16x32_bf16 v[120:123], v[140:143], v[164:167], v[120:123]
	v_mfma_f32_16x16x32_bf16 v[108:111], v[132:135], v[172:175], v[108:111]
	v_mfma_f32_16x16x32_bf16 v[104:107], v[140:143], v[172:175], v[104:107]
	v_mfma_f32_16x16x32_bf16 v[92:95], v[132:135], v[180:183], v[92:95]
	v_mfma_f32_16x16x32_bf16 v[88:91], v[140:143], v[180:183], v[88:91]
	v_mfma_f32_16x16x32_bf16 v[76:79], v[132:135], v[206:209], v[76:79]
	v_mfma_f32_16x16x32_bf16 v[72:75], v[140:143], v[206:209], v[72:75]
	v_mfma_f32_16x16x32_bf16 v[116:119], v[144:147], v[160:163], v[116:119]
	v_mfma_f32_16x16x32_bf16 v[112:115], v[152:155], v[160:163], v[112:115]
	v_mfma_f32_16x16x32_bf16 v[100:103], v[144:147], v[168:171], v[100:103]
	v_mfma_f32_16x16x32_bf16 v[96:99], v[152:155], v[168:171], v[96:99]
	v_mfma_f32_16x16x32_bf16 v[84:87], v[144:147], v[176:179], v[84:87]
	v_mfma_f32_16x16x32_bf16 v[80:83], v[152:155], v[176:179], v[80:83]
	v_mfma_f32_16x16x32_bf16 v[68:71], v[144:147], v[202:205], v[68:71]
	v_mfma_f32_16x16x32_bf16 v[64:67], v[152:155], v[202:205], v[64:67]
	v_mfma_f32_16x16x32_bf16 v[116:119], v[148:151], v[164:167], v[116:119]
	v_mfma_f32_16x16x32_bf16 v[112:115], v[156:159], v[164:167], v[112:115]
	v_mfma_f32_16x16x32_bf16 v[100:103], v[148:151], v[172:175], v[100:103]
	v_mfma_f32_16x16x32_bf16 v[96:99], v[156:159], v[172:175], v[96:99]
	v_mfma_f32_16x16x32_bf16 v[84:87], v[148:151], v[180:183], v[84:87]
	v_mfma_f32_16x16x32_bf16 v[80:83], v[156:159], v[180:183], v[80:83]
	v_mfma_f32_16x16x32_bf16 v[68:71], v[148:151], v[206:209], v[68:71]
	v_mfma_f32_16x16x32_bf16 v[64:67], v[156:159], v[206:209], v[64:67]
	s_setprio 0
	s_barrier
; #define PG8_STAGE(bufoff, gbase, voff) do { _Pragma("unroll") for (int _i = 0; _i < 2; ++_i) \
;         __builtin_amdgcn_global_load_lds((const unsigned*)((const char*)(gbase) + (voff)[_i]), (PG8_LAS unsigned*)(lds + (bufoff) + ldsw + _i * 8192), 16, 0, 0); } while (0)
; #define PG8_LDA(dst, b, h) do { _Pragma("unroll") for (int m = 0; m < 4; ++m) _Pragma("unroll") for (int k = 0; k < 2; ++k) dst[m][k] = *(const PG8_LAS bf16x8*)(lds + PG8_SA(b, h) + aoff + m * 2048 + k * 1024); } while (0)
; #define PG8_LDB(dst, b, h) do { _Pragma("unroll") for (int n = 0; n < 2; ++n) _Pragma("unroll") for (int k = 0; k < 2; ++k) dst[n][k] = *(const PG8_LAS bf16x8*)(lds + PG8_SB(b, h) + boff + n * 2048 + k * 1024); } while (0)
; template <class Epi, class Sched, bool ALIGN_EPI = false, bool SP2 = false>
; __device__ __forceinline__ void gemm_phase(PG8_LAS unsigned char* lds, const Gemm g, const Sched& S, const Epi& E) {
;     ...
;         for (int t = 0; t < nt; t += 2) {
;             const bool last = (t == nt - 2);
;             const char* a1 = cA + (size_t)(t + 1) * kstep;
;             const char* a2 = last ? nA : cA + (size_t)(t + 2) * kstep; const char* b2 = last ? nB : cB + (size_t)(t + 2) * kstep;
;             const char* a3 = a2 + kstep; const char* b3 = b2 + kstep;
;             if (last && has_next) S.a_ready(nxt);
;             if constexpr (SP2) {
;             PG8_LDB(B0, 0, 0); PG8_LDB(B1, 0, 1); PG8_SCHED; PG8_LDA(At, 0, 0); PG8_STAGE(PG8_SA(1, 1), a1 + hstep, voffA);
;             PG8_WAIT_V(8); PG8_WAIT_L(0); PG8_BAR; PG8_MMA(0, 0, At, B0); PG8_MMA(0, 1, At, B1); PG8_BAR; PG8_SCHED;
;             PG8_LDA(At, 0, 1); PG8_STAGE(PG8_SB(0, 0), b2, voffB); PG8_STAGE(PG8_SB(0, 1), b2 + hstep, voffB); PG8_STAGE(PG8_SA(0, 0), a2, voffA);
;             PG8_WAIT_V(8); PG8_WAIT_L(0); PG8_BAR; PG8_MMA(1, 0, At, B0); PG8_MMA(1, 1, At, B1); PG8_BAR; PG8_SCHED;
;             PG8_LDB(B0, 1, 0); PG8_LDB(B1, 1, 1); PG8_SCHED; PG8_LDA(At, 1, 0); PG8_STAGE(PG8_SA(0, 1), a2 + hstep, voffA);
;             PG8_WAIT_V(8); PG8_WAIT_L(0); PG8_BAR; PG8_MMA(0, 0, At, B0); PG8_MMA(0, 1, At, B1); PG8_BAR; PG8_SCHED;
;             PG8_LDA(At, 1, 1); PG8_STAGE(PG8_SB(1, 0), b3, voffB); PG8_STAGE(PG8_SB(1, 1), b3 + hstep, voffB); PG8_STAGE(PG8_SA(1, 0), a3, voffA);
;             PG8_WAIT_V(8); PG8_WAIT_L(0); PG8_BAR; PG8_MMA(1, 0, At, B0); PG8_MMA(1, 1, At, B1); PG8_BAR; PG8_SCHED;
	s_add_i32 s50, s73, s13
	v_lshl_add_u64 v[210:211], v[210:211], 0, s[20:21]
	s_mov_b32 m0, s50
	ds_read_b128 v[160:163], v222 offset:49152
	ds_read_b128 v[164:167], v222 offset:50176
	ds_read_b128 v[168:171], v222 offset:51200
	ds_read_b128 v[172:175], v222 offset:52224
	ds_read_b128 v[176:179], v222 offset:53248
	ds_read_b128 v[180:183], v222 offset:54272
	ds_read_b128 v[202:205], v222 offset:55296
	ds_read_b128 v[206:209], v222 offset:56320
	global_load_lds_dwordx4 v[210:211], off
	s_add_i32 m0, s50, 0x2000
	s_add_u32 s44, s44, 0x40080
	v_lshl_add_u64 v[210:211], v[212:213], 0, s[20:21]
	s_addc_u32 s45, s45, 0
	s_add_i32 s50, s74, s13
	global_load_lds_dwordx4 v[210:211], off
	v_lshl_add_u64 v[210:211], s[44:45], 0, v[188:189]
	s_mov_b32 m0, s50
	s_nop 0
	global_load_lds_dwordx4 v[210:211], off
	v_lshl_add_u64 v[210:211], s[44:45], 0, v[184:185]
	s_add_i32 m0, s50, 0x2000
	s_nop 0
	global_load_lds_dwordx4 v[210:211], off
	v_lshl_add_u64 v[210:211], v[214:215], 0, s[20:21]
	s_mov_b32 m0, s64
	s_nop 0
	global_load_lds_dwordx4 v[210:211], off
	v_lshl_add_u64 v[210:211], v[224:225], 0, s[20:21]
	s_mov_b32 m0, s65
	s_nop 0
	global_load_lds_dwordx4 v[210:211], off
	s_waitcnt vmcnt(8)
	s_waitcnt lgkmcnt(0)
	s_barrier
	s_setprio 1
	v_mfma_f32_16x16x32_bf16 v[60:63], v[128:131], v[160:163], v[60:63]
	v_mfma_f32_16x16x32_bf16 v[56:59], v[136:139], v[160:163], v[56:59]
	v_mfma_f32_16x16x32_bf16 v[44:47], v[128:131], v[168:171], v[44:47]
	v_mfma_f32_16x16x32_bf16 v[40:43], v[136:139], v[168:171], v[40:43]
	v_mfma_f32_16x16x32_bf16 v[28:31], v[128:131], v[176:179], v[28:31]
	v_mfma_f32_16x16x32_bf16 v[24:27], v[136:139], v[176:179], v[24:27]
	v_mfma_f32_16x16x32_bf16 v[12:15], v[128:131], v[202:205], v[12:15]
	v_mfma_f32_16x16x32_bf16 v[8:11], v[136:139], v[202:205], v[8:11]
	v_mfma_f32_16x16x32_bf16 v[60:63], v[132:135], v[164:167], v[60:63]
	v_mfma_f32_16x16x32_bf16 v[56:59], v[140:143], v[164:167], v[56:59]
	v_mfma_f32_16x16x32_bf16 v[44:47], v[132:135], v[172:175], v[44:47]
	v_mfma_f32_16x16x32_bf16 v[40:43], v[140:143], v[172:175], v[40:43]
	v_mfma_f32_16x16x32_bf16 v[28:31], v[132:135], v[180:183], v[28:31]
	v_mfma_f32_16x16x32_bf16 v[24:27], v[140:143], v[180:183], v[24:27]
	v_mfma_f32_16x16x32_bf16 v[12:15], v[132:135], v[206:209], v[12:15]
	v_mfma_f32_16x16x32_bf16 v[8:11], v[140:143], v[206:209], v[8:11]
	v_mfma_f32_16x16x32_bf16 v[52:55], v[144:147], v[160:163], v[52:55]
	v_mfma_f32_16x16x32_bf16 v[48:51], v[152:155], v[160:163], v[48:51]
	v_mfma_f32_16x16x32_bf16 v[36:39], v[144:147], v[168:171], v[36:39]
	v_mfma_f32_16x16x32_bf16 v[32:35], v[152:155], v[168:171], v[32:35]
	v_mfma_f32_16x16x32_bf16 v[20:23], v[144:147], v[176:179], v[20:23]
	v_mfma_f32_16x16x32_bf16 v[16:19], v[152:155], v[176:179], v[16:19]
	v_mfma_f32_16x16x32_bf16 v[4:7], v[144:147], v[202:205], v[4:7]
	v_mfma_f32_16x16x32_bf16 v[0:3], v[152:155], v[202:205], v[0:3]
	v_mfma_f32_16x16x32_bf16 v[52:55], v[148:151], v[164:167], v[52:55]
	v_mfma_f32_16x16x32_bf16 v[48:51], v[156:159], v[164:167], v[48:51]
	v_mfma_f32_16x16x32_bf16 v[36:39], v[148:151], v[172:175], v[36:39]
	v_mfma_f32_16x16x32_bf16 v[32:35], v[156:159], v[172:175], v[32:35]
	v_mfma_f32_16x16x32_bf16 v[20:23], v[148:151], v[180:183], v[20:23]
	v_mfma_f32_16x16x32_bf16 v[16:19], v[156:159], v[180:183], v[16:19]
	v_mfma_f32_16x16x32_bf16 v[4:7], v[148:151], v[206:209], v[4:7]
	v_mfma_f32_16x16x32_bf16 v[0:3], v[156:159], v[206:209], v[0:3]
	s_setprio 0
	s_barrier
	s_add_i32 s72, s72, 2
	s_add_u32 s36, s36, 0x100
	s_addc_u32 s37, s37, 0
	s_add_u32 s70, s70, 0x100
	s_addc_u32 s71, s71, 0
	s_cmp_gt_u32 s72, 13
.LBB0_573:
	ds_read_b128 v[128:131], v220
	ds_read_b128 v[132:135], v220 offset:1024
	ds_read_b128 v[136:139], v220 offset:2048
	ds_read_b128 v[140:143], v220 offset:3072
	ds_read_b128 v[144:147], v221
	ds_read_b128 v[148:151], v221 offset:1024
	ds_read_b128 v[152:155], v221 offset:2048
	ds_read_b128 v[156:159], v221 offset:3072
	s_add_u32 s44, s36, 0xfffc0080
	s_addc_u32 s45, s37, -1
	s_cmp_eq_u32 s72, 12
	s_cselect_b32 s51, s27, s45
	s_cselect_b32 s50, s68, s44
	s_cselect_b32 s45, s25, s71
	s_cselect_b32 s44, s69, s70
	v_lshl_add_u64 v[210:211], s[36:37], 0, v[194:195]
	s_add_i32 m0, s55, 0xc000
	ds_read_b128 v[160:163], v222
	ds_read_b128 v[164:167], v222 offset:1024
	ds_read_b128 v[168:171], v222 offset:2048
	ds_read_b128 v[172:175], v222 offset:3072
	ds_read_b128 v[176:179], v222 offset:4096
	ds_read_b128 v[180:183], v222 offset:5120
	ds_read_b128 v[202:205], v222 offset:6144
	ds_read_b128 v[206:209], v222 offset:7168
	global_load_lds_dwordx4 v[210:211], off
	v_lshl_add_u64 v[210:211], s[36:37], 0, v[196:197]
	s_add_i32 m0, s55, 0xe000
	s_nop 0
	global_load_lds_dwordx4 v[210:211], off
	s_waitcnt vmcnt(8)
	s_waitcnt lgkmcnt(0)
	s_barrier
; #define PG8_STAGE(bufoff, gbase, voff) do { _Pragma("unroll") for (int _i = 0; _i < 2; ++_i) \
;         __builtin_amdgcn_global_load_lds((const unsigned*)((const char*)(gbase) + (voff)[_i]), (PG8_LAS unsigned*)(lds + (bufoff) + ldsw + _i * 8192), 16, 0, 0); } while (0)
; #define PG8_LDA(dst, b, h) do { _Pragma("unroll") for (int m = 0; m < 4; ++m) _Pragma("unroll") for (int k = 0; k < 2; ++k) dst[m][k] = *(const PG8_LAS bf16x8*)(lds + PG8_SA(b, h) + aoff + m * 2048 + k * 1024); } while (0)
; #define PG8_LDB(dst, b, h) do { _Pragma("unroll") for (int n = 0; n < 2; ++n) _Pragma("unroll") for (int k = 0; k < 2; ++k) dst[n][k] = *(const PG8_LAS bf16x8*)(lds + PG8_SB(b, h) + boff + n * 2048 + k * 1024); } while (0)
; #define PG8_MMA(ai, bj, At, Bt) do { __builtin_amdgcn_s_setprio(1); _Pragma("unroll") for (int m = 0; m < 4; ++m) _Pragma("unroll") for (int n = 0; n < 2; ++n) _Pragma("unroll") for (int k = 0; k < 2; ++k) \
;         acc[ai][bj][m][n] = __builtin_amdgcn_mfma_f32_16x16x32_bf16(Bt[n][k], At[m][k], acc[ai][bj][m][n], 0, 0, 0); __builtin_amdgcn_s_setprio(0); } while (0)
; #define PG8_WAIT_V(n) asm volatile("s_waitcnt vmcnt(" #n ")" ::: "memory")
; template <class Epi, class Sched, bool ALIGN_EPI = false, bool SP2 = false>
; __device__ __forceinline__ void gemm_phase(PG8_LAS unsigned char* lds, const Gemm g, const Sched& S, const Epi& E) {
;     ...
;             PG8_LDB(B0, 0, 0); PG8_LDB(B1, 0, 1); PG8_SCHED; PG8_LDA(At, 0, 0); PG8_STAGE(PG8_SA(1, 1), a1 + hstep, voffA);
;             PG8_WAIT_V(8); PG8_WAIT_L(0); PG8_BAR; PG8_MMA(0, 0, At, B0); PG8_MMA(0, 1, At, B1); PG8_BAR; PG8_SCHED;
;             PG8_LDA(At, 0, 1); PG8_STAGE(PG8_SB(0, 0), b2, voffB); PG8_STAGE(PG8_SB(0, 1), b2 + hstep, voffB); PG8_STAGE(PG8_SA(0, 0), a2, voffA);
;             PG8_WAIT_V(8); PG8_WAIT_L(0); PG8_BAR; PG8_MMA(1, 0, At, B0); PG8_MMA(1, 1, At, B1); PG8_BAR; PG8_SCHED;
;             PG8_LDB(B0, 1, 0); PG8_LDB(B1, 1, 1); PG8_SCHED; PG8_LDA(At, 1, 0); PG8_STAGE(PG8_SA(0, 1), a2 + hstep, voffA);
;             PG8_WAIT_V(8); PG8_WAIT_L(0); PG8_BAR; PG8_MMA(0, 0, At, B0); PG8_MMA(0, 1, At, B1); PG8_BAR; PG8_SCHED;
;             PG8_LDA(At, 1, 1); PG8_STAGE(PG8_SB(1, 0), b3, voffB); PG8_STAGE(PG8_SB(1, 1), b3 + hstep, voffB); PG8_STAGE(PG8_SA(1, 0), a3, voffA);
;             PG8_WAIT_V(8); PG8_WAIT_L(0); PG8_BAR; PG8_MMA(1, 0, At, B0); PG8_MMA(1, 1, At, B1); PG8_BAR; PG8_SCHED;
	s_setprio 1
	v_mfma_f32_16x16x32_bf16 v[124:127], v[128:131], v[160:163], v[124:127]
	v_mfma_f32_16x16x32_bf16 v[120:123], v[136:139], v[160:163], v[120:123]
	v_mfma_f32_16x16x32_bf16 v[108:111], v[128:131], v[168:171], v[108:111]
	v_mfma_f32_16x16x32_bf16 v[104:107], v[136:139], v[168:171], v[104:107]
	v_mfma_f32_16x16x32_bf16 v[92:95], v[128:131], v[176:179], v[92:95]
	v_mfma_f32_16x16x32_bf16 v[88:91], v[136:139], v[176:179], v[88:91]
	v_mfma_f32_16x16x32_bf16 v[76:79], v[128:131], v[202:205], v[76:79]
	v_mfma_f32_16x16x32_bf16 v[72:75], v[136:139], v[202:205], v[72:75]
	v_mfma_f32_16x16x32_bf16 v[124:127], v[132:135], v[164:167], v[124:127]
	v_mfma_f32_16x16x32_bf16 v[120:123], v[140:143], v[164:167], v[120:123]
	v_mfma_f32_16x16x32_bf16 v[108:111], v[132:135], v[172:175], v[108:111]
	v_mfma_f32_16x16x32_bf16 v[104:107], v[140:143], v[172:175], v[104:107]
	v_mfma_f32_16x16x32_bf16 v[92:95], v[132:135], v[180:183], v[92:95]
	v_mfma_f32_16x16x32_bf16 v[88:91], v[140:143], v[180:183], v[88:91]
	v_mfma_f32_16x16x32_bf16 v[76:79], v[132:135], v[206:209], v[76:79]
	v_mfma_f32_16x16x32_bf16 v[72:75], v[140:143], v[206:209], v[72:75]
	v_mfma_f32_16x16x32_bf16 v[116:119], v[144:147], v[160:163], v[116:119]
	v_mfma_f32_16x16x32_bf16 v[112:115], v[152:155], v[160:163], v[112:115]
	v_mfma_f32_16x16x32_bf16 v[100:103], v[144:147], v[168:171], v[100:103]
	v_mfma_f32_16x16x32_bf16 v[96:99], v[152:155], v[168:171], v[96:99]
	v_mfma_f32_16x16x32_bf16 v[84:87], v[144:147], v[176:179], v[84:87]
	v_mfma_f32_16x16x32_bf16 v[80:83], v[152:155], v[176:179], v[80:83]
	v_mfma_f32_16x16x32_bf16 v[68:71], v[144:147], v[202:205], v[68:71]
	v_mfma_f32_16x16x32_bf16 v[64:67], v[152:155], v[202:205], v[64:67]
	v_mfma_f32_16x16x32_bf16 v[116:119], v[148:151], v[164:167], v[116:119]
	v_mfma_f32_16x16x32_bf16 v[112:115], v[156:159], v[164:167], v[112:115]
	v_mfma_f32_16x16x32_bf16 v[100:103], v[148:151], v[172:175], v[100:103]
	v_mfma_f32_16x16x32_bf16 v[96:99], v[156:159], v[172:175], v[96:99]
	v_mfma_f32_16x16x32_bf16 v[84:87], v[148:151], v[180:183], v[84:87]
	v_mfma_f32_16x16x32_bf16 v[80:83], v[156:159], v[180:183], v[80:83]
	v_mfma_f32_16x16x32_bf16 v[68:71], v[148:151], v[206:209], v[68:71]
	v_mfma_f32_16x16x32_bf16 v[64:67], v[156:159], v[206:209], v[64:67]
	s_setprio 0
	s_barrier
	s_add_i32 s73, s66, s13
	v_lshl_add_u64 v[210:211], s[44:45], 0, v[188:189]
	s_mov_b32 m0, s73
	ds_read_b128 v[160:163], v222 offset:16384
	ds_read_b128 v[164:167], v222 offset:17408
	ds_read_b128 v[168:171], v222 offset:18432
	ds_read_b128 v[172:175], v222 offset:19456
	ds_read_b128 v[176:179], v222 offset:20480
	ds_read_b128 v[180:183], v222 offset:21504
	ds_read_b128 v[202:205], v222 offset:22528
	ds_read_b128 v[206:209], v222 offset:23552
	global_load_lds_dwordx4 v[210:211], off
	s_add_i32 m0, s73, 0x2000
	s_add_u32 s74, s44, 0x40000
	v_lshl_add_u64 v[212:213], s[44:45], 0, v[184:185]
	s_addc_u32 s75, s45, 0
	s_add_i32 s73, s67, s13
	global_load_lds_dwordx4 v[212:213], off
	v_lshl_add_u64 v[214:215], s[74:75], 0, v[188:189]
	s_mov_b32 m0, s73
	v_lshl_add_u64 v[224:225], s[50:51], 0, v[186:187]
	global_load_lds_dwordx4 v[214:215], off
	v_lshl_add_u64 v[214:215], s[74:75], 0, v[184:185]
	s_add_i32 m0, s73, 0x2000
	s_nop 0
	global_load_lds_dwordx4 v[214:215], off
	v_lshl_add_u64 v[214:215], s[50:51], 0, v[190:191]
	s_mov_b32 m0, s55
	s_nop 0
	global_load_lds_dwordx4 v[214:215], off
	s_mov_b32 m0, s60
	s_nop 0
	global_load_lds_dwordx4 v[224:225], off
	s_waitcnt vmcnt(8)
	s_waitcnt lgkmcnt(0)
	s_barrier
	s_setprio 1
	v_mfma_f32_16x16x32_bf16 v[60:63], v[128:131], v[160:163], v[60:63]
	v_mfma_f32_16x16x32_bf16 v[56:59], v[136:139], v[160:163], v[56:59]
	v_mfma_f32_16x16x32_bf16 v[44:47], v[128:131], v[168:171], v[44:47]
	v_mfma_f32_16x16x32_bf16 v[40:43], v[136:139], v[168:171], v[40:43]
	v_mfma_f32_16x16x32_bf16 v[28:31], v[128:131], v[176:179], v[28:31]
	v_mfma_f32_16x16x32_bf16 v[24:27], v[136:139], v[176:179], v[24:27]
	v_mfma_f32_16x16x32_bf16 v[12:15], v[128:131], v[202:205], v[12:15]
	v_mfma_f32_16x16x32_bf16 v[8:11], v[136:139], v[202:205], v[8:11]
	v_mfma_f32_16x16x32_bf16 v[60:63], v[132:135], v[164:167], v[60:63]
	v_mfma_f32_16x16x32_bf16 v[56:59], v[140:143], v[164:167], v[56:59]
	v_mfma_f32_16x16x32_bf16 v[44:47], v[132:135], v[172:175], v[44:47]
	v_mfma_f32_16x16x32_bf16 v[40:43], v[140:143], v[172:175], v[40:43]
	v_mfma_f32_16x16x32_bf16 v[28:31], v[132:135], v[180:183], v[28:31]
	v_mfma_f32_16x16x32_bf16 v[24:27], v[140:143], v[180:183], v[24:27]
	v_mfma_f32_16x16x32_bf16 v[12:15], v[132:135], v[206:209], v[12:15]
	v_mfma_f32_16x16x32_bf16 v[8:11], v[140:143], v[206:209], v[8:11]
	v_mfma_f32_16x16x32_bf16 v[52:55], v[144:147], v[160:163], v[52:55]
	v_mfma_f32_16x16x32_bf16 v[48:51], v[152:155], v[160:163], v[48:51]
	v_mfma_f32_16x16x32_bf16 v[36:39], v[144:147], v[168:171], v[36:39]
	v_mfma_f32_16x16x32_bf16 v[32:35], v[152:155], v[168:171], v[32:35]
	v_mfma_f32_16x16x32_bf16 v[20:23], v[144:147], v[176:179], v[20:23]
	v_mfma_f32_16x16x32_bf16 v[16:19], v[152:155], v[176:179], v[16:19]
	v_mfma_f32_16x16x32_bf16 v[4:7], v[144:147], v[202:205], v[4:7]
	v_mfma_f32_16x16x32_bf16 v[0:3], v[152:155], v[202:205], v[0:3]
	v_mfma_f32_16x16x32_bf16 v[52:55], v[148:151], v[164:167], v[52:55]
	v_mfma_f32_16x16x32_bf16 v[48:51], v[156:159], v[164:167], v[48:51]
	v_mfma_f32_16x16x32_bf16 v[36:39], v[148:151], v[172:175], v[36:39]
	v_mfma_f32_16x16x32_bf16 v[32:35], v[156:159], v[172:175], v[32:35]
	v_mfma_f32_16x16x32_bf16 v[20:23], v[148:151], v[180:183], v[20:23]
	v_mfma_f32_16x16x32_bf16 v[16:19], v[156:159], v[180:183], v[16:19]
	v_mfma_f32_16x16x32_bf16 v[4:7], v[148:151], v[206:209], v[4:7]
	v_mfma_f32_16x16x32_bf16 v[0:3], v[156:159], v[206:209], v[0:3]
	s_setprio 0
	s_barrier
; #define PG8_STAGE(bufoff, gbase, voff) do { _Pragma("unroll") for (int _i = 0; _i < 2; ++_i) \
;         __builtin_amdgcn_global_load_lds((const unsigned*)((const char*)(gbase) + (voff)[_i]), (PG8_LAS unsigned*)(lds + (bufoff) + ldsw + _i * 8192), 16, 0, 0); } while (0)
; #define PG8_LDA(dst, b, h) do { _Pragma("unroll") for (int m = 0; m < 4; ++m) _Pragma("unroll") for (int k = 0; k < 2; ++k) dst[m][k] = *(const PG8_LAS bf16x8*)(lds + PG8_SA(b, h) + aoff + m * 2048 + k * 1024); } while (0)
; #define PG8_LDB(dst, b, h) do { _Pragma("unroll") for (int n = 0; n < 2; ++n) _Pragma("unroll") for (int k = 0; k < 2; ++k) dst[n][k] = *(const PG8_LAS bf16x8*)(lds + PG8_SB(b, h) + boff + n * 2048 + k * 1024); } while (0)
; #define PG8_MMA(ai, bj, At, Bt) do { __builtin_amdgcn_s_setprio(1); _Pragma("unroll") for (int m = 0; m < 4; ++m) _Pragma("unroll") for (int n = 0; n < 2; ++n) _Pragma("unroll") for (int k = 0; k < 2; ++k) \
;         acc[ai][bj][m][n] = __builtin_amdgcn_mfma_f32_16x16x32_bf16(Bt[n][k], At[m][k], acc[ai][bj][m][n], 0, 0, 0); __builtin_amdgcn_s_setprio(0); } while (0)
; #define PG8_WAIT_V(n) asm volatile("s_waitcnt vmcnt(" #n ")" ::: "memory")
; #define PG8_WAIT_L(n) asm volatile("s_waitcnt lgkmcnt(" #n ")" ::: "memory")
; #define PG8_BAR __builtin_amdgcn_s_barrier()
; #define PG8_SCHED __builtin_amdgcn_sched_barrier(0)
; template <class Epi, class Sched, bool ALIGN_EPI = false, bool SP2 = false>
; __device__ __forceinline__ void gemm_phase(PG8_LAS unsigned char* lds, const Gemm g, const Sched& S, const Epi& E) {
;     ...
;             PG8_LDB(B0, 1, 0); PG8_LDB(B1, 1, 1); PG8_SCHED; PG8_LDA(At, 1, 0); PG8_STAGE(PG8_SA(0, 1), a2 + hstep, voffA);
;             PG8_WAIT_V(8); PG8_WAIT_L(0); PG8_BAR; PG8_MMA(0, 0, At, B0); PG8_MMA(0, 1, At, B1); PG8_BAR; PG8_SCHED;
;             PG8_LDA(At, 1, 1); PG8_STAGE(PG8_SB(1, 0), b3, voffB); PG8_STAGE(PG8_SB(1, 1), b3 + hstep, voffB); PG8_STAGE(PG8_SA(1, 0), a3, voffA);
;             PG8_WAIT_V(8); PG8_WAIT_L(0); PG8_BAR; PG8_MMA(1, 0, At, B0); PG8_MMA(1, 1, At, B1); PG8_BAR; PG8_SCHED;
	s_add_i32 s73, 0, 0x18000
	s_add_i32 s74, 0, 0x1c000
	v_add_u32_e32 v140, s73, v218
	v_add_u32_e32 v156, s74, v218
	ds_read_b128 v[128:131], v140
	ds_read_b128 v[132:135], v140 offset:1024
	ds_read_b128 v[136:139], v140 offset:2048
	ds_read_b128 v[140:143], v140 offset:3072
	ds_read_b128 v[144:147], v156
	ds_read_b128 v[148:151], v156 offset:1024
	ds_read_b128 v[152:155], v156 offset:2048
	ds_read_b128 v[156:159], v156 offset:3072
	s_add_u32 s50, s50, 0x40000
	s_addc_u32 s51, s51, 0
	s_mov_b32 m0, s61
	v_lshl_add_u64 v[226:227], s[50:51], 0, v[190:191]
	ds_read_b128 v[160:163], v222 offset:32768
	ds_read_b128 v[164:167], v222 offset:33792
	ds_read_b128 v[168:171], v222 offset:34816
	ds_read_b128 v[172:175], v222 offset:35840
	ds_read_b128 v[176:179], v222 offset:36864
	ds_read_b128 v[180:183], v222 offset:37888
	ds_read_b128 v[202:205], v222 offset:38912
	ds_read_b128 v[206:209], v222 offset:39936
	global_load_lds_dwordx4 v[226:227], off
	v_lshl_add_u64 v[226:227], s[50:51], 0, v[186:187]
	s_mov_b32 m0, s62
	s_nop 0
	global_load_lds_dwordx4 v[226:227], off
	s_waitcnt vmcnt(8)
	s_waitcnt lgkmcnt(0)
	s_barrier
	s_setprio 1
	v_mfma_f32_16x16x32_bf16 v[124:127], v[128:131], v[160:163], v[124:127]
	v_mfma_f32_16x16x32_bf16 v[120:123], v[136:139], v[160:163], v[120:123]
	v_mfma_f32_16x16x32_bf16 v[108:111], v[128:131], v[168:171], v[108:111]
	v_mfma_f32_16x16x32_bf16 v[104:107], v[136:139], v[168:171], v[104:107]
	v_mfma_f32_16x16x32_bf16 v[92:95], v[128:131], v[176:179], v[92:95]
	v_mfma_f32_16x16x32_bf16 v[88:91], v[136:139], v[176:179], v[88:91]
	v_mfma_f32_16x16x32_bf16 v[76:79], v[128:131], v[202:205], v[76:79]
	v_mfma_f32_16x16x32_bf16 v[72:75], v[136:139], v[202:205], v[72:75]
	v_mfma_f32_16x16x32_bf16 v[124:127], v[132:135], v[164:167], v[124:127]
	v_mfma_f32_16x16x32_bf16 v[120:123], v[140:143], v[164:167], v[120:123]
	v_mfma_f32_16x16x32_bf16 v[108:111], v[132:135], v[172:175], v[108:111]
	v_mfma_f32_16x16x32_bf16 v[104:107], v[140:143], v[172:175], v[104:107]
	v_mfma_f32_16x16x32_bf16 v[92:95], v[132:135], v[180:183], v[92:95]
	v_mfma_f32_16x16x32_bf16 v[88:91], v[140:143], v[180:183], v[88:91]
	v_mfma_f32_16x16x32_bf16 v[76:79], v[132:135], v[206:209], v[76:79]
	v_mfma_f32_16x16x32_bf16 v[72:75], v[140:143], v[206:209], v[72:75]
	v_mfma_f32_16x16x32_bf16 v[116:119], v[144:147], v[160:163], v[116:119]
	v_mfma_f32_16x16x32_bf16 v[112:115], v[152:155], v[160:163], v[112:115]
	v_mfma_f32_16x16x32_bf16 v[100:103], v[144:147], v[168:171], v[100:103]
	v_mfma_f32_16x16x32_bf16 v[96:99], v[152:155], v[168:171], v[96:99]
	v_mfma_f32_16x16x32_bf16 v[84:87], v[144:147], v[176:179], v[84:87]
	v_mfma_f32_16x16x32_bf16 v[80:83], v[152:155], v[176:179], v[80:83]
	v_mfma_f32_16x16x32_bf16 v[68:71], v[144:147], v[202:205], v[68:71]
	v_mfma_f32_16x16x32_bf16 v[64:67], v[152:155], v[202:205], v[64:67]
	v_mfma_f32_16x16x32_bf16 v[116:119], v[148:151], v[164:167], v[116:119]
	v_mfma_f32_16x16x32_bf16 v[112:115], v[156:159], v[164:167], v[112:115]
	v_mfma_f32_16x16x32_bf16 v[100:103], v[148:151], v[172:175], v[100:103]
	v_mfma_f32_16x16x32_bf16 v[96:99], v[156:159], v[172:175], v[96:99]
	v_mfma_f32_16x16x32_bf16 v[84:87], v[148:151], v[180:183], v[84:87]
	v_mfma_f32_16x16x32_bf16 v[80:83], v[156:159], v[180:183], v[80:83]
	v_mfma_f32_16x16x32_bf16 v[68:71], v[148:151], v[206:209], v[68:71]
	v_mfma_f32_16x16x32_bf16 v[64:67], v[156:159], v[206:209], v[64:67]
	s_setprio 0
	s_barrier
; #define PG8_STAGE(bufoff, gbase, voff) do { _Pragma("unroll") for (int _i = 0; _i < 2; ++_i) \
;         __builtin_amdgcn_global_load_lds((const unsigned*)((const char*)(gbase) + (voff)[_i]), (PG8_LAS unsigned*)(lds + (bufoff) + ldsw + _i * 8192), 16, 0, 0); } while (0)
; #define PG8_LDA(dst, b, h) do { _Pragma("unroll") for (int m = 0; m < 4; ++m) _Pragma("unroll") for (int k = 0; k < 2; ++k) dst[m][k] = *(const PG8_LAS bf16x8*)(lds + PG8_SA(b, h) + aoff + m * 2048 + k * 1024); } while (0)
; #define PG8_LDB(dst, b, h) do { _Pragma("unroll") for (int n = 0; n < 2; ++n) _Pragma("unroll") for (int k = 0; k < 2; ++k) dst[n][k] = *(const PG8_LAS bf16x8*)(lds + PG8_SB(b, h) + boff + n * 2048 + k * 1024); } while (0)
; template <class Epi, class Sched, bool ALIGN_EPI = false, bool SP2 = false>
; __device__ __forceinline__ void gemm_phase(PG8_LAS unsigned char* lds, const Gemm g, const Sched& S, const Epi& E) {
;     ...
;         for (int t = 0; t < nt; t += 2) {
;             const bool last = (t == nt - 2);
;             const char* a1 = cA + (size_t)(t + 1) * kstep;
;             const char* a2 = last ? nA : cA + (size_t)(t + 2) * kstep; const char* b2 = last ? nB : cB + (size_t)(t + 2) * kstep;
;             const char* a3 = a2 + kstep; const char* b3 = b2 + kstep;
;             if (last && has_next) S.a_ready(nxt);
;             if constexpr (SP2) {
;             PG8_LDB(B0, 0, 0); PG8_LDB(B1, 0, 1); PG8_SCHED; PG8_LDA(At, 0, 0); PG8_STAGE(PG8_SA(1, 1), a1 + hstep, voffA);
;             PG8_WAIT_V(8); PG8_WAIT_L(0); PG8_BAR; PG8_MMA(0, 0, At, B0); PG8_MMA(0, 1, At, B1); PG8_BAR; PG8_SCHED;
;             PG8_LDA(At, 0, 1); PG8_STAGE(PG8_SB(0, 0), b2, voffB); PG8_STAGE(PG8_SB(0, 1), b2 + hstep, voffB); PG8_STAGE(PG8_SA(0, 0), a2, voffA);
;             PG8_WAIT_V(8); PG8_WAIT_L(0); PG8_BAR; PG8_MMA(1, 0, At, B0); PG8_MMA(1, 1, At, B1); PG8_BAR; PG8_SCHED;
;             PG8_LDB(B0, 1, 0); PG8_LDB(B1, 1, 1); PG8_SCHED; PG8_LDA(At, 1, 0); PG8_STAGE(PG8_SA(0, 1), a2 + hstep, voffA);
;             PG8_WAIT_V(8); PG8_WAIT_L(0); PG8_BAR; PG8_MMA(0, 0, At, B0); PG8_MMA(0, 1, At, B1); PG8_BAR; PG8_SCHED;
;             PG8_LDA(At, 1, 1); PG8_STAGE(PG8_SB(1, 0), b3, voffB); PG8_STAGE(PG8_SB(1, 1), b3 + hstep, voffB); PG8_STAGE(PG8_SA(1, 0), a3, voffA);
;             PG8_WAIT_V(8); PG8_WAIT_L(0); PG8_BAR; PG8_MMA(1, 0, At, B0); PG8_MMA(1, 1, At, B1); PG8_BAR; PG8_SCHED;
	s_add_i32 s50, s73, s13
	v_lshl_add_u64 v[210:211], v[210:211], 0, s[20:21]
	s_mov_b32 m0, s50
	ds_read_b128 v[160:163], v222 offset:49152
	ds_read_b128 v[164:167], v222 offset:50176
	ds_read_b128 v[168:171], v222 offset:51200
	ds_read_b128 v[172:175], v222 offset:52224
	ds_read_b128 v[176:179], v222 offset:53248
	ds_read_b128 v[180:183], v222 offset:54272
	ds_read_b128 v[202:205], v222 offset:55296
	ds_read_b128 v[206:209], v222 offset:56320
	global_load_lds_dwordx4 v[210:211], off
	s_add_i32 m0, s50, 0x2000
	s_add_u32 s44, s44, 0x40080
	v_lshl_add_u64 v[210:211], v[212:213], 0, s[20:21]
	s_addc_u32 s45, s45, 0
	s_add_i32 s50, s74, s13
	global_load_lds_dwordx4 v[210:211], off
	v_lshl_add_u64 v[210:211], s[44:45], 0, v[188:189]
	s_mov_b32 m0, s50
	s_nop 0
	global_load_lds_dwordx4 v[210:211], off
	v_lshl_add_u64 v[210:211], s[44:45], 0, v[184:185]
	s_add_i32 m0, s50, 0x2000
	s_nop 0
	global_load_lds_dwordx4 v[210:211], off
	v_lshl_add_u64 v[210:211], v[214:215], 0, s[20:21]
	s_mov_b32 m0, s64
	s_nop 0
	global_load_lds_dwordx4 v[210:211], off
	v_lshl_add_u64 v[210:211], v[224:225], 0, s[20:21]
	s_mov_b32 m0, s65
	s_nop 0
	global_load_lds_dwordx4 v[210:211], off
	s_waitcnt vmcnt(8)
	s_waitcnt lgkmcnt(0)
	s_barrier
	s_setprio 1
	v_mfma_f32_16x16x32_bf16 v[60:63], v[128:131], v[160:163], v[60:63]
	v_mfma_f32_16x16x32_bf16 v[56:59], v[136:139], v[160:163], v[56:59]
	v_mfma_f32_16x16x32_bf16 v[44:47], v[128:131], v[168:171], v[44:47]
	v_mfma_f32_16x16x32_bf16 v[40:43], v[136:139], v[168:171], v[40:43]
	v_mfma_f32_16x16x32_bf16 v[28:31], v[128:131], v[176:179], v[28:31]
	v_mfma_f32_16x16x32_bf16 v[24:27], v[136:139], v[176:179], v[24:27]
	v_mfma_f32_16x16x32_bf16 v[12:15], v[128:131], v[202:205], v[12:15]
	v_mfma_f32_16x16x32_bf16 v[8:11], v[136:139], v[202:205], v[8:11]
	v_mfma_f32_16x16x32_bf16 v[60:63], v[132:135], v[164:167], v[60:63]
	v_mfma_f32_16x16x32_bf16 v[56:59], v[140:143], v[164:167], v[56:59]
	v_mfma_f32_16x16x32_bf16 v[44:47], v[132:135], v[172:175], v[44:47]
	v_mfma_f32_16x16x32_bf16 v[40:43], v[140:143], v[172:175], v[40:43]
	v_mfma_f32_16x16x32_bf16 v[28:31], v[132:135], v[180:183], v[28:31]
	v_mfma_f32_16x16x32_bf16 v[24:27], v[140:143], v[180:183], v[24:27]
	v_mfma_f32_16x16x32_bf16 v[12:15], v[132:135], v[206:209], v[12:15]
	v_mfma_f32_16x16x32_bf16 v[8:11], v[140:143], v[206:209], v[8:11]
	v_mfma_f32_16x16x32_bf16 v[52:55], v[144:147], v[160:163], v[52:55]
	v_mfma_f32_16x16x32_bf16 v[48:51], v[152:155], v[160:163], v[48:51]
	v_mfma_f32_16x16x32_bf16 v[36:39], v[144:147], v[168:171], v[36:39]
	v_mfma_f32_16x16x32_bf16 v[32:35], v[152:155], v[168:171], v[32:35]
	v_mfma_f32_16x16x32_bf16 v[20:23], v[144:147], v[176:179], v[20:23]
	v_mfma_f32_16x16x32_bf16 v[16:19], v[152:155], v[176:179], v[16:19]
	v_mfma_f32_16x16x32_bf16 v[4:7], v[144:147], v[202:205], v[4:7]
	v_mfma_f32_16x16x32_bf16 v[0:3], v[152:155], v[202:205], v[0:3]
	v_mfma_f32_16x16x32_bf16 v[52:55], v[148:151], v[164:167], v[52:55]
	v_mfma_f32_16x16x32_bf16 v[48:51], v[156:159], v[164:167], v[48:51]
	v_mfma_f32_16x16x32_bf16 v[36:39], v[148:151], v[172:175], v[36:39]
	v_mfma_f32_16x16x32_bf16 v[32:35], v[156:159], v[172:175], v[32:35]
	v_mfma_f32_16x16x32_bf16 v[20:23], v[148:151], v[180:183], v[20:23]
	v_mfma_f32_16x16x32_bf16 v[16:19], v[156:159], v[180:183], v[16:19]
	v_mfma_f32_16x16x32_bf16 v[4:7], v[148:151], v[206:209], v[4:7]
	v_mfma_f32_16x16x32_bf16 v[0:3], v[156:159], v[206:209], v[0:3]
	s_setprio 0
	s_barrier
	s_add_i32 s72, s72, 2
	s_add_u32 s36, s36, 0x100
	s_addc_u32 s37, s37, 0
	s_add_u32 s70, s70, 0x100
	s_addc_u32 s71, s71, 0
	s_cmp_gt_u32 s72, 13
	s_cbranch_scc0 .LBB0_573
	s_and_b64 vcc, exec, s[22:23]
	s_cbranch_vccz .LBB0_576
	s_barrier

; #define PG8_WAIT_V(n) asm volatile("s_waitcnt vmcnt(" #n ")" ::: "memory")
; #define PG8_BAR __builtin_amdgcn_s_barrier()
; __device__ __forceinline__ unsigned xb_add(unsigned* p, unsigned v) { return __hip_atomic_fetch_add(p, v, __ATOMIC_RELAXED, __HIP_MEMORY_SCOPE_AGENT); }
; template <class Epi, class Sched, bool ALIGN_EPI = false, bool SP2 = false>
; __device__ __forceinline__ void gemm_phase(PG8_LAS unsigned char* lds, const Gemm g, const Sched& S, const Epi& E) {
;     ...
;     PG8_WAIT_V(0);
;     if constexpr (!ALIGN_EPI) { if (wr == 0) PG8_BAR; }
;     PG8_BAR;
; __device__ __forceinline__ void xcd_barrier(const XcdBarrier& b) {
;     asm volatile("s_waitcnt vmcnt(0)" ::: "memory");
;     __syncthreads();
;     if (threadIdx.x == 0) {
;         unsigned* bar = b.bar;
;         __builtin_amdgcn_s_waitcnt(0);
;         unsigned nloc = b.st[0], nx = b.st[1];
;         if (nloc == 0u) { xcd_barrier_complete(bar, b.x, nloc, nx); b.st[0] = nloc; b.st[1] = nx; }
;         const unsigned old = xb_add(&bar[XB_XSUB(b.x)], 1u);
;         const unsigned gen = old / nloc;
;         if (old + 1u == (gen + 1u) * nloc) {
.LBB0_580:
	s_nop 0
	s_nop 0
	s_nop 0
	s_nop 0
	s_waitcnt vmcnt(0)
	s_barrier
	s_mov_b64 s[14:15], exec
	v_readlane_b32 s16, v254, 0
	v_readlane_b32 s17, v254, 1
	v_readlane_b32 s22, v254, 43
	s_and_b64 s[16:17], s[14:15], s[16:17]
	v_readlane_b32 s23, v254, 44
	s_mov_b64 exec, s[16:17]
	s_cbranch_execz .LBB0_632
	s_add_i32 s13, 0, 0x23f20
	v_mov_b32_e32 v0, s13
	s_waitcnt vmcnt(0) expcnt(0) lgkmcnt(0)
	ds_read_b32 v2, v0
	s_add_i32 s13, 0, 0x23f24
	v_mov_b32_e32 v0, s13
	ds_read_b32 v0, v0
	s_waitcnt lgkmcnt(1)
	v_cmp_ne_u32_e32 vcc, 0, v2
	s_cbranch_vccnz .LBB0_596
	s_mov_b32 s13, 1
	v_mov_b32_e32 v16, 0
	s_branch .LBB0_584

; #define PG8_STAGE(bufoff, gbase, voff) do { _Pragma("unroll") for (int _i = 0; _i < 2; ++_i) \
;         __builtin_amdgcn_global_load_lds((const unsigned*)((const char*)(gbase) + (voff)[_i]), (PG8_LAS unsigned*)(lds + (bufoff) + ldsw + _i * 8192), 16, 0, 0); } while (0)
; #define PG8_LDA(dst, b, h) do { _Pragma("unroll") for (int m = 0; m < 4; ++m) _Pragma("unroll") for (int k = 0; k < 2; ++k) dst[m][k] = *(const PG8_LAS bf16x8*)(lds + PG8_SA(b, h) + aoff + m * 2048 + k * 1024); } while (0)
; #define PG8_LDB(dst, b, h) do { _Pragma("unroll") for (int n = 0; n < 2; ++n) _Pragma("unroll") for (int k = 0; k < 2; ++k) dst[n][k] = *(const PG8_LAS bf16x8*)(lds + PG8_SB(b, h) + boff + n * 2048 + k * 1024); } while (0)
; #define PG8_WAIT_V(n) asm volatile("s_waitcnt vmcnt(" #n ")" ::: "memory")
; #define PG8_WAIT_L(n) asm volatile("s_waitcnt lgkmcnt(" #n ")" ::: "memory")
; #define PG8_BAR __builtin_amdgcn_s_barrier()
; #define PG8_SCHED __builtin_amdgcn_sched_barrier(0)
; template <class Epi, class Sched, bool ALIGN_EPI = false, bool SP2 = false>
; __device__ __forceinline__ void gemm_phase(PG8_LAS unsigned char* lds, const Gemm g, const Sched& S, const Epi& E) {
;     ...
;         const bool has_next = S.next(ui + 1, nxt);
;         const char* nA = has_next ? (const char*)g.A + (size_t)nxt.pm * tstep : cA; const char* nB = has_next ? (const char*)g.Bt + (size_t)nxt.pn * tstep : cB;
;         for (int t = 0; t < nt; t += 2) {
;             const bool last = (t == nt - 2);
;             const char* a1 = cA + (size_t)(t + 1) * kstep;
;             const char* a2 = last ? nA : cA + (size_t)(t + 2) * kstep; const char* b2 = last ? nB : cB + (size_t)(t + 2) * kstep;
;             const char* a3 = a2 + kstep; const char* b3 = b2 + kstep;
;             if (last && has_next) S.a_ready(nxt);
;             if constexpr (SP2) {
;             PG8_LDB(B0, 0, 0); PG8_LDB(B1, 0, 1); PG8_SCHED; PG8_LDA(At, 0, 0); PG8_STAGE(PG8_SA(1, 1), a1 + hstep, voffA);
;             PG8_WAIT_V(8); PG8_WAIT_L(0); PG8_BAR; PG8_MMA(0, 0, At, B0); PG8_MMA(0, 1, At, B1); PG8_BAR; PG8_SCHED;
;             PG8_LDA(At, 0, 1); PG8_STAGE(PG8_SB(0, 0), b2, voffB); PG8_STAGE(PG8_SB(0, 1), b2 + hstep, voffB); PG8_STAGE(PG8_SA(0, 0), a2, voffA);
;             PG8_WAIT_V(8); PG8_WAIT_L(0); PG8_BAR; PG8_MMA(1, 0, At, B0); PG8_MMA(1, 1, At, B1); PG8_BAR; PG8_SCHED;
.LBB0_644:
	s_ashr_i32 s27, s26, 31
	s_lshl_b64 s[28:29], s[26:27], 20
	s_add_u32 s28, s13, s28
	s_addc_u32 s29, s47, s29
	s_and_b64 s[30:31], s[38:39], exec
	s_cselect_b32 s27, s29, s37
	s_cselect_b32 s70, s28, s36
	s_ashr_i32 s25, s24, 31
	s_lshl_b64 s[30:31], s[24:25], 20
	s_add_u32 s30, s52, s30
	s_addc_u32 s31, s53, s31
	s_and_b64 s[44:45], s[38:39], exec
	s_cselect_b32 s25, s31, s41
	s_cselect_b32 s71, s30, s40
	s_add_u32 s72, s40, 0x100
	s_addc_u32 s73, s41, 0
	s_mov_b32 s74, -2
	ds_read_b128 v[92:95], v196
	ds_read_b128 v[100:103], v196 offset:1024
	ds_read_b128 v[108:111], v196 offset:2048
	ds_read_b128 v[116:119], v196 offset:3072
	ds_read_b128 v[144:147], v197
	ds_read_b128 v[148:151], v197 offset:1024
	ds_read_b128 v[152:155], v197 offset:2048
	ds_read_b128 v[156:159], v197 offset:3072
	s_add_u32 s40, s36, 0x100
	s_addc_u32 s41, s37, 0
	s_cmp_eq_u32 s74, 28
	s_cselect_b32 s51, s27, s41
	s_cselect_b32 s50, s70, s40
	s_cselect_b32 s45, s25, s73
	s_cselect_b32 s44, s71, s72
	v_lshl_add_u64 v[212:213], s[36:37], 0, v[176:177]
	s_add_i32 m0, s55, 0xc000
	ds_read_b128 v[160:163], v198
	ds_read_b128 v[164:167], v198 offset:1024
	ds_read_b128 v[168:171], v198 offset:2048
	ds_read_b128 v[184:187], v198 offset:3072
	ds_read_b128 v[188:191], v198 offset:4096
	ds_read_b128 v[200:203], v198 offset:5120
	ds_read_b128 v[204:207], v198 offset:6144
	ds_read_b128 v[208:211], v198 offset:7168
	global_load_lds_dwordx4 v[212:213], off
	v_lshl_add_u64 v[212:213], s[36:37], 0, v[178:179]
	s_add_i32 m0, s55, 0xe000
	s_nop 0
	global_load_lds_dwordx4 v[212:213], off
	s_waitcnt vmcnt(8)
	s_waitcnt lgkmcnt(0)
	s_barrier
	s_setprio 1
	v_mfma_f32_16x16x32_bf16 v[140:143], v[92:95], v[160:163], 0
	v_mfma_f32_16x16x32_bf16 v[136:139], v[108:111], v[160:163], 0
	v_mfma_f32_16x16x32_bf16 v[132:135], v[92:95], v[168:171], 0
	v_mfma_f32_16x16x32_bf16 v[120:123], v[108:111], v[168:171], 0
	v_mfma_f32_16x16x32_bf16 v[112:115], v[92:95], v[188:191], 0
	v_mfma_f32_16x16x32_bf16 v[88:91], v[108:111], v[188:191], 0
	v_mfma_f32_16x16x32_bf16 v[76:79], v[92:95], v[204:207], 0
	v_mfma_f32_16x16x32_bf16 v[72:75], v[108:111], v[204:207], 0
	v_mfma_f32_16x16x32_bf16 v[140:143], v[100:103], v[164:167], v[140:143]
	v_mfma_f32_16x16x32_bf16 v[136:139], v[116:119], v[164:167], v[136:139]
	v_mfma_f32_16x16x32_bf16 v[132:135], v[100:103], v[184:187], v[132:135]
	v_mfma_f32_16x16x32_bf16 v[120:123], v[116:119], v[184:187], v[120:123]
	v_mfma_f32_16x16x32_bf16 v[112:115], v[100:103], v[200:203], v[112:115]
	v_mfma_f32_16x16x32_bf16 v[88:91], v[116:119], v[200:203], v[88:91]
	v_mfma_f32_16x16x32_bf16 v[76:79], v[100:103], v[208:211], v[76:79]
	v_mfma_f32_16x16x32_bf16 v[72:75], v[116:119], v[208:211], v[72:75]
	v_mfma_f32_16x16x32_bf16 v[128:131], v[144:147], v[160:163], 0
	v_mfma_f32_16x16x32_bf16 v[124:127], v[152:155], v[160:163], 0
	v_mfma_f32_16x16x32_bf16 v[104:107], v[144:147], v[168:171], 0
	v_mfma_f32_16x16x32_bf16 v[96:99], v[152:155], v[168:171], 0
	v_mfma_f32_16x16x32_bf16 v[84:87], v[144:147], v[188:191], 0
	v_mfma_f32_16x16x32_bf16 v[80:83], v[152:155], v[188:191], 0
	v_mfma_f32_16x16x32_bf16 v[68:71], v[144:147], v[204:207], 0
	v_mfma_f32_16x16x32_bf16 v[64:67], v[152:155], v[204:207], 0
	v_mfma_f32_16x16x32_bf16 v[128:131], v[148:151], v[164:167], v[128:131]
	v_mfma_f32_16x16x32_bf16 v[124:127], v[156:159], v[164:167], v[124:127]
	v_mfma_f32_16x16x32_bf16 v[104:107], v[148:151], v[184:187], v[104:107]
	v_mfma_f32_16x16x32_bf16 v[96:99], v[156:159], v[184:187], v[96:99]
	v_mfma_f32_16x16x32_bf16 v[84:87], v[148:151], v[200:203], v[84:87]
	v_mfma_f32_16x16x32_bf16 v[80:83], v[156:159], v[200:203], v[80:83]
	v_mfma_f32_16x16x32_bf16 v[68:71], v[148:151], v[208:211], v[68:71]
	v_mfma_f32_16x16x32_bf16 v[64:67], v[156:159], v[208:211], v[64:67]
	s_setprio 0
	s_barrier
	s_add_i32 s36, s68, s54
	v_lshl_add_u64 v[212:213], s[44:45], 0, v[174:175]
	s_mov_b32 m0, s36
	ds_read_b128 v[160:163], v198 offset:16384
	ds_read_b128 v[164:167], v198 offset:17408
	ds_read_b128 v[168:171], v198 offset:18432
	ds_read_b128 v[184:187], v198 offset:19456
	ds_read_b128 v[188:191], v198 offset:20480
	ds_read_b128 v[200:203], v198 offset:21504
	ds_read_b128 v[204:207], v198 offset:22528
	ds_read_b128 v[208:211], v198 offset:23552
	global_load_lds_dwordx4 v[212:213], off
	s_add_i32 m0, s36, 0x2000
	s_add_u32 s36, s44, 0x80000
	v_lshl_add_u64 v[214:215], s[44:45], 0, v[172:173]
	s_addc_u32 s37, s45, 0
	s_add_i32 s75, s69, s54
	global_load_lds_dwordx4 v[214:215], off
	v_lshl_add_u64 v[218:219], s[36:37], 0, v[174:175]
	s_mov_b32 m0, s75
	v_lshl_add_u64 v[220:221], s[50:51], 0, v[172:173]
	global_load_lds_dwordx4 v[218:219], off
	v_lshl_add_u64 v[218:219], s[36:37], 0, v[172:173]
	s_add_i32 m0, s75, 0x2000
	s_nop 0
	global_load_lds_dwordx4 v[218:219], off
	v_lshl_add_u64 v[218:219], s[50:51], 0, v[174:175]
	s_mov_b32 m0, s55
	s_nop 0
	global_load_lds_dwordx4 v[218:219], off
	s_mov_b32 m0, s60
	s_nop 0
	global_load_lds_dwordx4 v[220:221], off
	s_waitcnt vmcnt(8)
	s_waitcnt lgkmcnt(0)
	s_barrier
; #define PG8_STAGE(bufoff, gbase, voff) do { _Pragma("unroll") for (int _i = 0; _i < 2; ++_i) \
;         __builtin_amdgcn_global_load_lds((const unsigned*)((const char*)(gbase) + (voff)[_i]), (PG8_LAS unsigned*)(lds + (bufoff) + ldsw + _i * 8192), 16, 0, 0); } while (0)
; #define PG8_LDA(dst, b, h) do { _Pragma("unroll") for (int m = 0; m < 4; ++m) _Pragma("unroll") for (int k = 0; k < 2; ++k) dst[m][k] = *(const PG8_LAS bf16x8*)(lds + PG8_SA(b, h) + aoff + m * 2048 + k * 1024); } while (0)
; #define PG8_LDB(dst, b, h) do { _Pragma("unroll") for (int n = 0; n < 2; ++n) _Pragma("unroll") for (int k = 0; k < 2; ++k) dst[n][k] = *(const PG8_LAS bf16x8*)(lds + PG8_SB(b, h) + boff + n * 2048 + k * 1024); } while (0)
; #define PG8_MMA(ai, bj, At, Bt) do { __builtin_amdgcn_s_setprio(1); _Pragma("unroll") for (int m = 0; m < 4; ++m) _Pragma("unroll") for (int n = 0; n < 2; ++n) _Pragma("unroll") for (int k = 0; k < 2; ++k) \
;         acc[ai][bj][m][n] = __builtin_amdgcn_mfma_f32_16x16x32_bf16(Bt[n][k], At[m][k], acc[ai][bj][m][n], 0, 0, 0); __builtin_amdgcn_s_setprio(0); } while (0)
; #define PG8_WAIT_V(n) asm volatile("s_waitcnt vmcnt(" #n ")" ::: "memory")
; template <class Epi, class Sched, bool ALIGN_EPI = false, bool SP2 = false>
; __device__ __forceinline__ void gemm_phase(PG8_LAS unsigned char* lds, const Gemm g, const Sched& S, const Epi& E) {
;     ...
;             PG8_LDB(B0, 0, 0); PG8_LDB(B1, 0, 1); PG8_SCHED; PG8_LDA(At, 0, 0); PG8_STAGE(PG8_SA(1, 1), a1 + hstep, voffA);
;             PG8_WAIT_V(8); PG8_WAIT_L(0); PG8_BAR; PG8_MMA(0, 0, At, B0); PG8_MMA(0, 1, At, B1); PG8_BAR; PG8_SCHED;
;             PG8_LDA(At, 0, 1); PG8_STAGE(PG8_SB(0, 0), b2, voffB); PG8_STAGE(PG8_SB(0, 1), b2 + hstep, voffB); PG8_STAGE(PG8_SA(0, 0), a2, voffA);
;             PG8_WAIT_V(8); PG8_WAIT_L(0); PG8_BAR; PG8_MMA(1, 0, At, B0); PG8_MMA(1, 1, At, B1); PG8_BAR; PG8_SCHED;
;             PG8_LDB(B0, 1, 0); PG8_LDB(B1, 1, 1); PG8_SCHED; PG8_LDA(At, 1, 0); PG8_STAGE(PG8_SA(0, 1), a2 + hstep, voffA);
;             PG8_WAIT_V(8); PG8_WAIT_L(0); PG8_BAR; PG8_MMA(0, 0, At, B0); PG8_MMA(0, 1, At, B1); PG8_BAR; PG8_SCHED;
;             PG8_LDA(At, 1, 1); PG8_STAGE(PG8_SB(1, 0), b3, voffB); PG8_STAGE(PG8_SB(1, 1), b3 + hstep, voffB); PG8_STAGE(PG8_SA(1, 0), a3, voffA);
;             PG8_WAIT_V(8); PG8_WAIT_L(0); PG8_BAR; PG8_MMA(1, 0, At, B0); PG8_MMA(1, 1, At, B1); PG8_BAR; PG8_SCHED;
	s_setprio 1
	v_mfma_f32_16x16x32_bf16 v[60:63], v[92:95], v[160:163], 0
	v_mfma_f32_16x16x32_bf16 v[56:59], v[108:111], v[160:163], 0
	v_mfma_f32_16x16x32_bf16 v[52:55], v[92:95], v[168:171], 0
	v_mfma_f32_16x16x32_bf16 v[40:43], v[108:111], v[168:171], 0
	v_mfma_f32_16x16x32_bf16 v[36:39], v[92:95], v[188:191], 0
	v_mfma_f32_16x16x32_bf16 v[24:27], v[108:111], v[188:191], 0
	v_mfma_f32_16x16x32_bf16 v[12:15], v[92:95], v[204:207], 0
	v_mfma_f32_16x16x32_bf16 v[8:11], v[108:111], v[204:207], 0
	v_mfma_f32_16x16x32_bf16 v[60:63], v[100:103], v[164:167], v[60:63]
	v_mfma_f32_16x16x32_bf16 v[56:59], v[116:119], v[164:167], v[56:59]
	v_mfma_f32_16x16x32_bf16 v[52:55], v[100:103], v[184:187], v[52:55]
	v_mfma_f32_16x16x32_bf16 v[40:43], v[116:119], v[184:187], v[40:43]
	v_mfma_f32_16x16x32_bf16 v[36:39], v[100:103], v[200:203], v[36:39]
	v_mfma_f32_16x16x32_bf16 v[24:27], v[116:119], v[200:203], v[24:27]
	v_mfma_f32_16x16x32_bf16 v[12:15], v[100:103], v[208:211], v[12:15]
	v_mfma_f32_16x16x32_bf16 v[8:11], v[116:119], v[208:211], v[8:11]
	v_mfma_f32_16x16x32_bf16 v[48:51], v[144:147], v[160:163], 0
	v_mfma_f32_16x16x32_bf16 v[44:47], v[152:155], v[160:163], 0
	v_mfma_f32_16x16x32_bf16 v[32:35], v[144:147], v[168:171], 0
	v_mfma_f32_16x16x32_bf16 v[28:31], v[152:155], v[168:171], 0
	v_mfma_f32_16x16x32_bf16 v[20:23], v[144:147], v[188:191], 0
	v_mfma_f32_16x16x32_bf16 v[16:19], v[152:155], v[188:191], 0
	v_mfma_f32_16x16x32_bf16 v[4:7], v[144:147], v[204:207], 0
	v_mfma_f32_16x16x32_bf16 v[0:3], v[152:155], v[204:207], 0
	v_mfma_f32_16x16x32_bf16 v[48:51], v[148:151], v[164:167], v[48:51]
	v_mfma_f32_16x16x32_bf16 v[44:47], v[156:159], v[164:167], v[44:47]
	v_mfma_f32_16x16x32_bf16 v[32:35], v[148:151], v[184:187], v[32:35]
	v_mfma_f32_16x16x32_bf16 v[28:31], v[156:159], v[184:187], v[28:31]
	v_mfma_f32_16x16x32_bf16 v[20:23], v[148:151], v[200:203], v[20:23]
	v_mfma_f32_16x16x32_bf16 v[16:19], v[156:159], v[200:203], v[16:19]
	v_mfma_f32_16x16x32_bf16 v[4:7], v[148:151], v[208:211], v[4:7]
	v_mfma_f32_16x16x32_bf16 v[0:3], v[156:159], v[208:211], v[0:3]
	s_setprio 0
	s_barrier
	s_add_i32 s75, 0, 0x18000
	s_add_i32 s76, 0, 0x1c000
	v_add_u32_e32 v116, s75, v194
	v_add_u32_e32 v156, s76, v194
	ds_read_b128 v[92:95], v116
	ds_read_b128 v[100:103], v116 offset:1024
	ds_read_b128 v[108:111], v116 offset:2048
	ds_read_b128 v[116:119], v116 offset:3072
	ds_read_b128 v[144:147], v156
	ds_read_b128 v[148:151], v156 offset:1024
	ds_read_b128 v[152:155], v156 offset:2048
	ds_read_b128 v[156:159], v156 offset:3072
	s_add_u32 s36, s50, 0x80000
	s_addc_u32 s37, s51, 0
	s_mov_b32 m0, s61
	v_lshl_add_u64 v[222:223], s[36:37], 0, v[174:175]
	ds_read_b128 v[160:163], v198 offset:32768
	ds_read_b128 v[164:167], v198 offset:33792
	ds_read_b128 v[168:171], v198 offset:34816
	ds_read_b128 v[184:187], v198 offset:35840
	ds_read_b128 v[188:191], v198 offset:36864
	ds_read_b128 v[200:203], v198 offset:37888
	ds_read_b128 v[204:207], v198 offset:38912
	ds_read_b128 v[208:211], v198 offset:39936
	global_load_lds_dwordx4 v[222:223], off
	v_lshl_add_u64 v[222:223], s[36:37], 0, v[172:173]
	s_mov_b32 m0, s62
	s_nop 0
	global_load_lds_dwordx4 v[222:223], off
	s_waitcnt vmcnt(8)
	s_waitcnt lgkmcnt(0)
	s_barrier
	s_setprio 1
	v_mfma_f32_16x16x32_bf16 v[140:143], v[92:95], v[160:163], v[140:143]
	v_mfma_f32_16x16x32_bf16 v[136:139], v[108:111], v[160:163], v[136:139]
	v_mfma_f32_16x16x32_bf16 v[132:135], v[92:95], v[168:171], v[132:135]
	v_mfma_f32_16x16x32_bf16 v[120:123], v[108:111], v[168:171], v[120:123]
	v_mfma_f32_16x16x32_bf16 v[112:115], v[92:95], v[188:191], v[112:115]
	v_mfma_f32_16x16x32_bf16 v[88:91], v[108:111], v[188:191], v[88:91]
	v_mfma_f32_16x16x32_bf16 v[76:79], v[92:95], v[204:207], v[76:79]
	v_mfma_f32_16x16x32_bf16 v[72:75], v[108:111], v[204:207], v[72:75]
	v_mfma_f32_16x16x32_bf16 v[140:143], v[100:103], v[164:167], v[140:143]
	v_mfma_f32_16x16x32_bf16 v[136:139], v[116:119], v[164:167], v[136:139]
	v_mfma_f32_16x16x32_bf16 v[132:135], v[100:103], v[184:187], v[132:135]
	v_mfma_f32_16x16x32_bf16 v[120:123], v[116:119], v[184:187], v[120:123]
	v_mfma_f32_16x16x32_bf16 v[112:115], v[100:103], v[200:203], v[112:115]
	v_mfma_f32_16x16x32_bf16 v[88:91], v[116:119], v[200:203], v[88:91]
	v_mfma_f32_16x16x32_bf16 v[76:79], v[100:103], v[208:211], v[76:79]
	v_mfma_f32_16x16x32_bf16 v[72:75], v[116:119], v[208:211], v[72:75]
	v_mfma_f32_16x16x32_bf16 v[128:131], v[144:147], v[160:163], v[128:131]
	v_mfma_f32_16x16x32_bf16 v[124:127], v[152:155], v[160:163], v[124:127]
	v_mfma_f32_16x16x32_bf16 v[104:107], v[144:147], v[168:171], v[104:107]
	v_mfma_f32_16x16x32_bf16 v[96:99], v[152:155], v[168:171], v[96:99]
	v_mfma_f32_16x16x32_bf16 v[84:87], v[144:147], v[188:191], v[84:87]
	v_mfma_f32_16x16x32_bf16 v[80:83], v[152:155], v[188:191], v[80:83]
	v_mfma_f32_16x16x32_bf16 v[68:71], v[144:147], v[204:207], v[68:71]
	v_mfma_f32_16x16x32_bf16 v[64:67], v[152:155], v[204:207], v[64:67]
	v_mfma_f32_16x16x32_bf16 v[128:131], v[148:151], v[164:167], v[128:131]
	v_mfma_f32_16x16x32_bf16 v[124:127], v[156:159], v[164:167], v[124:127]
	v_mfma_f32_16x16x32_bf16 v[104:107], v[148:151], v[184:187], v[104:107]
	v_mfma_f32_16x16x32_bf16 v[96:99], v[156:159], v[184:187], v[96:99]
	v_mfma_f32_16x16x32_bf16 v[84:87], v[148:151], v[200:203], v[84:87]
	v_mfma_f32_16x16x32_bf16 v[80:83], v[156:159], v[200:203], v[80:83]
	v_mfma_f32_16x16x32_bf16 v[68:71], v[148:151], v[208:211], v[68:71]
	v_mfma_f32_16x16x32_bf16 v[64:67], v[156:159], v[208:211], v[64:67]
	s_setprio 0
	s_barrier
; #define PG8_STAGE(bufoff, gbase, voff) do { _Pragma("unroll") for (int _i = 0; _i < 2; ++_i) \
;         __builtin_amdgcn_global_load_lds((const unsigned*)((const char*)(gbase) + (voff)[_i]), (PG8_LAS unsigned*)(lds + (bufoff) + ldsw + _i * 8192), 16, 0, 0); } while (0)
; #define PG8_LDA(dst, b, h) do { _Pragma("unroll") for (int m = 0; m < 4; ++m) _Pragma("unroll") for (int k = 0; k < 2; ++k) dst[m][k] = *(const PG8_LAS bf16x8*)(lds + PG8_SA(b, h) + aoff + m * 2048 + k * 1024); } while (0)
; #define PG8_LDB(dst, b, h) do { _Pragma("unroll") for (int n = 0; n < 2; ++n) _Pragma("unroll") for (int k = 0; k < 2; ++k) dst[n][k] = *(const PG8_LAS bf16x8*)(lds + PG8_SB(b, h) + boff + n * 2048 + k * 1024); } while (0)
; template <class Epi, class Sched, bool ALIGN_EPI = false, bool SP2 = false>
; __device__ __forceinline__ void gemm_phase(PG8_LAS unsigned char* lds, const Gemm g, const Sched& S, const Epi& E) {
;     ...
;         for (int t = 0; t < nt; t += 2) {
;             const bool last = (t == nt - 2);
;             const char* a1 = cA + (size_t)(t + 1) * kstep;
;             const char* a2 = last ? nA : cA + (size_t)(t + 2) * kstep; const char* b2 = last ? nB : cB + (size_t)(t + 2) * kstep;
;             const char* a3 = a2 + kstep; const char* b3 = b2 + kstep;
;             if (last && has_next) S.a_ready(nxt);
;             if constexpr (SP2) {
;             PG8_LDB(B0, 0, 0); PG8_LDB(B1, 0, 1); PG8_SCHED; PG8_LDA(At, 0, 0); PG8_STAGE(PG8_SA(1, 1), a1 + hstep, voffA);
;             PG8_WAIT_V(8); PG8_WAIT_L(0); PG8_BAR; PG8_MMA(0, 0, At, B0); PG8_MMA(0, 1, At, B1); PG8_BAR; PG8_SCHED;
;             PG8_LDA(At, 0, 1); PG8_STAGE(PG8_SB(0, 0), b2, voffB); PG8_STAGE(PG8_SB(0, 1), b2 + hstep, voffB); PG8_STAGE(PG8_SA(0, 0), a2, voffA);
;             PG8_WAIT_V(8); PG8_WAIT_L(0); PG8_BAR; PG8_MMA(1, 0, At, B0); PG8_MMA(1, 1, At, B1); PG8_BAR; PG8_SCHED;
;             PG8_LDB(B0, 1, 0); PG8_LDB(B1, 1, 1); PG8_SCHED; PG8_LDA(At, 1, 0); PG8_STAGE(PG8_SA(0, 1), a2 + hstep, voffA);
;             PG8_WAIT_V(8); PG8_WAIT_L(0); PG8_BAR; PG8_MMA(0, 0, At, B0); PG8_MMA(0, 1, At, B1); PG8_BAR; PG8_SCHED;
;             PG8_LDA(At, 1, 1); PG8_STAGE(PG8_SB(1, 0), b3, voffB); PG8_STAGE(PG8_SB(1, 1), b3 + hstep, voffB); PG8_STAGE(PG8_SA(1, 0), a3, voffA);
;             PG8_WAIT_V(8); PG8_WAIT_L(0); PG8_BAR; PG8_MMA(1, 0, At, B0); PG8_MMA(1, 1, At, B1); PG8_BAR; PG8_SCHED;
	s_add_i32 s36, s75, s54
	v_lshl_add_u64 v[212:213], v[212:213], 0, s[20:21]
	s_mov_b32 m0, s36
	ds_read_b128 v[160:163], v198 offset:49152
	ds_read_b128 v[164:167], v198 offset:50176
	ds_read_b128 v[168:171], v198 offset:51200
	ds_read_b128 v[184:187], v198 offset:52224
	ds_read_b128 v[188:191], v198 offset:53248
	ds_read_b128 v[200:203], v198 offset:54272
	ds_read_b128 v[204:207], v198 offset:55296
	ds_read_b128 v[208:211], v198 offset:56320
	global_load_lds_dwordx4 v[212:213], off
	s_add_i32 m0, s36, 0x2000
	s_add_u32 s36, s44, 0x80080
	v_lshl_add_u64 v[212:213], v[214:215], 0, s[20:21]
	s_addc_u32 s37, s45, 0
	s_add_i32 s44, s76, s54
	global_load_lds_dwordx4 v[212:213], off
	v_lshl_add_u64 v[212:213], s[36:37], 0, v[174:175]
	s_mov_b32 m0, s44
	s_nop 0
	global_load_lds_dwordx4 v[212:213], off
	v_lshl_add_u64 v[212:213], s[36:37], 0, v[172:173]
	s_add_i32 m0, s44, 0x2000
	s_nop 0
	global_load_lds_dwordx4 v[212:213], off
	v_lshl_add_u64 v[212:213], v[218:219], 0, s[20:21]
	s_mov_b32 m0, s66
	s_nop 0
	global_load_lds_dwordx4 v[212:213], off
	v_lshl_add_u64 v[212:213], v[220:221], 0, s[20:21]
	s_mov_b32 m0, s67
	s_nop 0
	global_load_lds_dwordx4 v[212:213], off
	s_waitcnt vmcnt(8)
	s_waitcnt lgkmcnt(0)
	s_barrier
	s_setprio 1
	v_mfma_f32_16x16x32_bf16 v[60:63], v[92:95], v[160:163], v[60:63]
	v_mfma_f32_16x16x32_bf16 v[56:59], v[108:111], v[160:163], v[56:59]
	v_mfma_f32_16x16x32_bf16 v[52:55], v[92:95], v[168:171], v[52:55]
	v_mfma_f32_16x16x32_bf16 v[40:43], v[108:111], v[168:171], v[40:43]
	v_mfma_f32_16x16x32_bf16 v[36:39], v[92:95], v[188:191], v[36:39]
	v_mfma_f32_16x16x32_bf16 v[24:27], v[108:111], v[188:191], v[24:27]
	v_mfma_f32_16x16x32_bf16 v[12:15], v[92:95], v[204:207], v[12:15]
	v_mfma_f32_16x16x32_bf16 v[8:11], v[108:111], v[204:207], v[8:11]
	v_mfma_f32_16x16x32_bf16 v[60:63], v[100:103], v[164:167], v[60:63]
	v_mfma_f32_16x16x32_bf16 v[56:59], v[116:119], v[164:167], v[56:59]
	v_mfma_f32_16x16x32_bf16 v[52:55], v[100:103], v[184:187], v[52:55]
	v_mfma_f32_16x16x32_bf16 v[40:43], v[116:119], v[184:187], v[40:43]
	v_mfma_f32_16x16x32_bf16 v[36:39], v[100:103], v[200:203], v[36:39]
	v_mfma_f32_16x16x32_bf16 v[24:27], v[116:119], v[200:203], v[24:27]
	v_mfma_f32_16x16x32_bf16 v[12:15], v[100:103], v[208:211], v[12:15]
	v_mfma_f32_16x16x32_bf16 v[8:11], v[116:119], v[208:211], v[8:11]
	v_mfma_f32_16x16x32_bf16 v[48:51], v[144:147], v[160:163], v[48:51]
	v_mfma_f32_16x16x32_bf16 v[44:47], v[152:155], v[160:163], v[44:47]
	v_mfma_f32_16x16x32_bf16 v[32:35], v[144:147], v[168:171], v[32:35]
	v_mfma_f32_16x16x32_bf16 v[28:31], v[152:155], v[168:171], v[28:31]
	v_mfma_f32_16x16x32_bf16 v[20:23], v[144:147], v[188:191], v[20:23]
	v_mfma_f32_16x16x32_bf16 v[16:19], v[152:155], v[188:191], v[16:19]
	v_mfma_f32_16x16x32_bf16 v[4:7], v[144:147], v[204:207], v[4:7]
	v_mfma_f32_16x16x32_bf16 v[0:3], v[152:155], v[204:207], v[0:3]
	v_mfma_f32_16x16x32_bf16 v[48:51], v[148:151], v[164:167], v[48:51]
	v_mfma_f32_16x16x32_bf16 v[44:47], v[156:159], v[164:167], v[44:47]
	v_mfma_f32_16x16x32_bf16 v[32:35], v[148:151], v[184:187], v[32:35]
	v_mfma_f32_16x16x32_bf16 v[28:31], v[156:159], v[184:187], v[28:31]
	v_mfma_f32_16x16x32_bf16 v[20:23], v[148:151], v[200:203], v[20:23]
	v_mfma_f32_16x16x32_bf16 v[16:19], v[156:159], v[200:203], v[16:19]
	v_mfma_f32_16x16x32_bf16 v[4:7], v[148:151], v[208:211], v[4:7]
	v_mfma_f32_16x16x32_bf16 v[0:3], v[156:159], v[208:211], v[0:3]
	s_setprio 0
	s_barrier
	s_add_i32 s74, s74, 2
	s_add_u32 s72, s72, 0x100
	s_addc_u32 s73, s73, 0
	s_cmp_gt_u32 s74, 29
	s_mov_b64 s[36:37], s[40:41]
.LBB0_645:
	ds_read_b128 v[92:95], v196
	ds_read_b128 v[100:103], v196 offset:1024
	ds_read_b128 v[108:111], v196 offset:2048
	ds_read_b128 v[116:119], v196 offset:3072
	ds_read_b128 v[144:147], v197
	ds_read_b128 v[148:151], v197 offset:1024
	ds_read_b128 v[152:155], v197 offset:2048
	ds_read_b128 v[156:159], v197 offset:3072
	s_add_u32 s40, s36, 0x100
	s_addc_u32 s41, s37, 0
	s_cmp_eq_u32 s74, 28
	s_cselect_b32 s51, s27, s41
	s_cselect_b32 s50, s70, s40
	s_cselect_b32 s45, s25, s73
	s_cselect_b32 s44, s71, s72
	v_lshl_add_u64 v[212:213], s[36:37], 0, v[176:177]
	s_add_i32 m0, s55, 0xc000
	ds_read_b128 v[160:163], v198
	ds_read_b128 v[164:167], v198 offset:1024
	ds_read_b128 v[168:171], v198 offset:2048
	ds_read_b128 v[184:187], v198 offset:3072
	ds_read_b128 v[188:191], v198 offset:4096
	ds_read_b128 v[200:203], v198 offset:5120
	ds_read_b128 v[204:207], v198 offset:6144
	ds_read_b128 v[208:211], v198 offset:7168
	global_load_lds_dwordx4 v[212:213], off
	v_lshl_add_u64 v[212:213], s[36:37], 0, v[178:179]
	s_add_i32 m0, s55, 0xe000
	s_nop 0
	global_load_lds_dwordx4 v[212:213], off
	s_waitcnt vmcnt(8)
	s_waitcnt lgkmcnt(0)
	s_barrier
; #define PG8_STAGE(bufoff, gbase, voff) do { _Pragma("unroll") for (int _i = 0; _i < 2; ++_i) \
;         __builtin_amdgcn_global_load_lds((const unsigned*)((const char*)(gbase) + (voff)[_i]), (PG8_LAS unsigned*)(lds + (bufoff) + ldsw + _i * 8192), 16, 0, 0); } while (0)
; #define PG8_LDA(dst, b, h) do { _Pragma("unroll") for (int m = 0; m < 4; ++m) _Pragma("unroll") for (int k = 0; k < 2; ++k) dst[m][k] = *(const PG8_LAS bf16x8*)(lds + PG8_SA(b, h) + aoff + m * 2048 + k * 1024); } while (0)
; #define PG8_LDB(dst, b, h) do { _Pragma("unroll") for (int n = 0; n < 2; ++n) _Pragma("unroll") for (int k = 0; k < 2; ++k) dst[n][k] = *(const PG8_LAS bf16x8*)(lds + PG8_SB(b, h) + boff + n * 2048 + k * 1024); } while (0)
; #define PG8_MMA(ai, bj, At, Bt) do { __builtin_amdgcn_s_setprio(1); _Pragma("unroll") for (int m = 0; m < 4; ++m) _Pragma("unroll") for (int n = 0; n < 2; ++n) _Pragma("unroll") for (int k = 0; k < 2; ++k) \
;         acc[ai][bj][m][n] = __builtin_amdgcn_mfma_f32_16x16x32_bf16(Bt[n][k], At[m][k], acc[ai][bj][m][n], 0, 0, 0); __builtin_amdgcn_s_setprio(0); } while (0)
; #define PG8_WAIT_V(n) asm volatile("s_waitcnt vmcnt(" #n ")" ::: "memory")
; template <class Epi, class Sched, bool ALIGN_EPI = false, bool SP2 = false>
; __device__ __forceinline__ void gemm_phase(PG8_LAS unsigned char* lds, const Gemm g, const Sched& S, const Epi& E) {
;     ...
;             PG8_LDB(B0, 0, 0); PG8_LDB(B1, 0, 1); PG8_SCHED; PG8_LDA(At, 0, 0); PG8_STAGE(PG8_SA(1, 1), a1 + hstep, voffA);
;             PG8_WAIT_V(8); PG8_WAIT_L(0); PG8_BAR; PG8_MMA(0, 0, At, B0); PG8_MMA(0, 1, At, B1); PG8_BAR; PG8_SCHED;
;             PG8_LDA(At, 0, 1); PG8_STAGE(PG8_SB(0, 0), b2, voffB); PG8_STAGE(PG8_SB(0, 1), b2 + hstep, voffB); PG8_STAGE(PG8_SA(0, 0), a2, voffA);
;             PG8_WAIT_V(8); PG8_WAIT_L(0); PG8_BAR; PG8_MMA(1, 0, At, B0); PG8_MMA(1, 1, At, B1); PG8_BAR; PG8_SCHED;
;             PG8_LDB(B0, 1, 0); PG8_LDB(B1, 1, 1); PG8_SCHED; PG8_LDA(At, 1, 0); PG8_STAGE(PG8_SA(0, 1), a2 + hstep, voffA);
;             PG8_WAIT_V(8); PG8_WAIT_L(0); PG8_BAR; PG8_MMA(0, 0, At, B0); PG8_MMA(0, 1, At, B1); PG8_BAR; PG8_SCHED;
;             PG8_LDA(At, 1, 1); PG8_STAGE(PG8_SB(1, 0), b3, voffB); PG8_STAGE(PG8_SB(1, 1), b3 + hstep, voffB); PG8_STAGE(PG8_SA(1, 0), a3, voffA);
;             PG8_WAIT_V(8); PG8_WAIT_L(0); PG8_BAR; PG8_MMA(1, 0, At, B0); PG8_MMA(1, 1, At, B1); PG8_BAR; PG8_SCHED;
	s_setprio 1
	v_mfma_f32_16x16x32_bf16 v[140:143], v[92:95], v[160:163], v[140:143]
	v_mfma_f32_16x16x32_bf16 v[136:139], v[108:111], v[160:163], v[136:139]
	v_mfma_f32_16x16x32_bf16 v[132:135], v[92:95], v[168:171], v[132:135]
	v_mfma_f32_16x16x32_bf16 v[120:123], v[108:111], v[168:171], v[120:123]
	v_mfma_f32_16x16x32_bf16 v[112:115], v[92:95], v[188:191], v[112:115]
	v_mfma_f32_16x16x32_bf16 v[88:91], v[108:111], v[188:191], v[88:91]
	v_mfma_f32_16x16x32_bf16 v[76:79], v[92:95], v[204:207], v[76:79]
	v_mfma_f32_16x16x32_bf16 v[72:75], v[108:111], v[204:207], v[72:75]
	v_mfma_f32_16x16x32_bf16 v[140:143], v[100:103], v[164:167], v[140:143]
	v_mfma_f32_16x16x32_bf16 v[136:139], v[116:119], v[164:167], v[136:139]
	v_mfma_f32_16x16x32_bf16 v[132:135], v[100:103], v[184:187], v[132:135]
	v_mfma_f32_16x16x32_bf16 v[120:123], v[116:119], v[184:187], v[120:123]
	v_mfma_f32_16x16x32_bf16 v[112:115], v[100:103], v[200:203], v[112:115]
	v_mfma_f32_16x16x32_bf16 v[88:91], v[116:119], v[200:203], v[88:91]
	v_mfma_f32_16x16x32_bf16 v[76:79], v[100:103], v[208:211], v[76:79]
	v_mfma_f32_16x16x32_bf16 v[72:75], v[116:119], v[208:211], v[72:75]
	v_mfma_f32_16x16x32_bf16 v[128:131], v[144:147], v[160:163], v[128:131]
	v_mfma_f32_16x16x32_bf16 v[124:127], v[152:155], v[160:163], v[124:127]
	v_mfma_f32_16x16x32_bf16 v[104:107], v[144:147], v[168:171], v[104:107]
	v_mfma_f32_16x16x32_bf16 v[96:99], v[152:155], v[168:171], v[96:99]
	v_mfma_f32_16x16x32_bf16 v[84:87], v[144:147], v[188:191], v[84:87]
	v_mfma_f32_16x16x32_bf16 v[80:83], v[152:155], v[188:191], v[80:83]
	v_mfma_f32_16x16x32_bf16 v[68:71], v[144:147], v[204:207], v[68:71]
	v_mfma_f32_16x16x32_bf16 v[64:67], v[152:155], v[204:207], v[64:67]
	v_mfma_f32_16x16x32_bf16 v[128:131], v[148:151], v[164:167], v[128:131]
	v_mfma_f32_16x16x32_bf16 v[124:127], v[156:159], v[164:167], v[124:127]
	v_mfma_f32_16x16x32_bf16 v[104:107], v[148:151], v[184:187], v[104:107]
	v_mfma_f32_16x16x32_bf16 v[96:99], v[156:159], v[184:187], v[96:99]
	v_mfma_f32_16x16x32_bf16 v[84:87], v[148:151], v[200:203], v[84:87]
	v_mfma_f32_16x16x32_bf16 v[80:83], v[156:159], v[200:203], v[80:83]
	v_mfma_f32_16x16x32_bf16 v[68:71], v[148:151], v[208:211], v[68:71]
	v_mfma_f32_16x16x32_bf16 v[64:67], v[156:159], v[208:211], v[64:67]
	s_setprio 0
	s_barrier
	s_add_i32 s36, s68, s54
	v_lshl_add_u64 v[212:213], s[44:45], 0, v[174:175]
	s_mov_b32 m0, s36
	ds_read_b128 v[160:163], v198 offset:16384
	ds_read_b128 v[164:167], v198 offset:17408
	ds_read_b128 v[168:171], v198 offset:18432
	ds_read_b128 v[184:187], v198 offset:19456
	ds_read_b128 v[188:191], v198 offset:20480
	ds_read_b128 v[200:203], v198 offset:21504
	ds_read_b128 v[204:207], v198 offset:22528
	ds_read_b128 v[208:211], v198 offset:23552
	global_load_lds_dwordx4 v[212:213], off
	s_add_i32 m0, s36, 0x2000
	s_add_u32 s36, s44, 0x80000
	v_lshl_add_u64 v[214:215], s[44:45], 0, v[172:173]
	s_addc_u32 s37, s45, 0
	s_add_i32 s75, s69, s54
	global_load_lds_dwordx4 v[214:215], off
	v_lshl_add_u64 v[218:219], s[36:37], 0, v[174:175]
	s_mov_b32 m0, s75
	v_lshl_add_u64 v[220:221], s[50:51], 0, v[172:173]
	global_load_lds_dwordx4 v[218:219], off
	v_lshl_add_u64 v[218:219], s[36:37], 0, v[172:173]
	s_add_i32 m0, s75, 0x2000
	s_nop 0
	global_load_lds_dwordx4 v[218:219], off
	v_lshl_add_u64 v[218:219], s[50:51], 0, v[174:175]
	s_mov_b32 m0, s55
	s_nop 0
	global_load_lds_dwordx4 v[218:219], off
	s_mov_b32 m0, s60
	s_nop 0
	global_load_lds_dwordx4 v[220:221], off
	s_waitcnt vmcnt(8)
	s_waitcnt lgkmcnt(0)
	s_barrier
	s_setprio 1
	v_mfma_f32_16x16x32_bf16 v[60:63], v[92:95], v[160:163], v[60:63]
	v_mfma_f32_16x16x32_bf16 v[56:59], v[108:111], v[160:163], v[56:59]
	v_mfma_f32_16x16x32_bf16 v[52:55], v[92:95], v[168:171], v[52:55]
	v_mfma_f32_16x16x32_bf16 v[40:43], v[108:111], v[168:171], v[40:43]
	v_mfma_f32_16x16x32_bf16 v[36:39], v[92:95], v[188:191], v[36:39]
	v_mfma_f32_16x16x32_bf16 v[24:27], v[108:111], v[188:191], v[24:27]
	v_mfma_f32_16x16x32_bf16 v[12:15], v[92:95], v[204:207], v[12:15]
	v_mfma_f32_16x16x32_bf16 v[8:11], v[108:111], v[204:207], v[8:11]
	v_mfma_f32_16x16x32_bf16 v[60:63], v[100:103], v[164:167], v[60:63]
	v_mfma_f32_16x16x32_bf16 v[56:59], v[116:119], v[164:167], v[56:59]
	v_mfma_f32_16x16x32_bf16 v[52:55], v[100:103], v[184:187], v[52:55]
	v_mfma_f32_16x16x32_bf16 v[40:43], v[116:119], v[184:187], v[40:43]
	v_mfma_f32_16x16x32_bf16 v[36:39], v[100:103], v[200:203], v[36:39]
	v_mfma_f32_16x16x32_bf16 v[24:27], v[116:119], v[200:203], v[24:27]
	v_mfma_f32_16x16x32_bf16 v[12:15], v[100:103], v[208:211], v[12:15]
	v_mfma_f32_16x16x32_bf16 v[8:11], v[116:119], v[208:211], v[8:11]
	v_mfma_f32_16x16x32_bf16 v[48:51], v[144:147], v[160:163], v[48:51]
	v_mfma_f32_16x16x32_bf16 v[44:47], v[152:155], v[160:163], v[44:47]
	v_mfma_f32_16x16x32_bf16 v[32:35], v[144:147], v[168:171], v[32:35]
	v_mfma_f32_16x16x32_bf16 v[28:31], v[152:155], v[168:171], v[28:31]
	v_mfma_f32_16x16x32_bf16 v[20:23], v[144:147], v[188:191], v[20:23]
	v_mfma_f32_16x16x32_bf16 v[16:19], v[152:155], v[188:191], v[16:19]
	v_mfma_f32_16x16x32_bf16 v[4:7], v[144:147], v[204:207], v[4:7]
	v_mfma_f32_16x16x32_bf16 v[0:3], v[152:155], v[204:207], v[0:3]
	v_mfma_f32_16x16x32_bf16 v[48:51], v[148:151], v[164:167], v[48:51]
	v_mfma_f32_16x16x32_bf16 v[44:47], v[156:159], v[164:167], v[44:47]
	v_mfma_f32_16x16x32_bf16 v[32:35], v[148:151], v[184:187], v[32:35]
	v_mfma_f32_16x16x32_bf16 v[28:31], v[156:159], v[184:187], v[28:31]
	v_mfma_f32_16x16x32_bf16 v[20:23], v[148:151], v[200:203], v[20:23]
	v_mfma_f32_16x16x32_bf16 v[16:19], v[156:159], v[200:203], v[16:19]
	v_mfma_f32_16x16x32_bf16 v[4:7], v[148:151], v[208:211], v[4:7]
	v_mfma_f32_16x16x32_bf16 v[0:3], v[156:159], v[208:211], v[0:3]
	s_setprio 0
	s_barrier
; #define PG8_STAGE(bufoff, gbase, voff) do { _Pragma("unroll") for (int _i = 0; _i < 2; ++_i) \
;         __builtin_amdgcn_global_load_lds((const unsigned*)((const char*)(gbase) + (voff)[_i]), (PG8_LAS unsigned*)(lds + (bufoff) + ldsw + _i * 8192), 16, 0, 0); } while (0)
; #define PG8_LDA(dst, b, h) do { _Pragma("unroll") for (int m = 0; m < 4; ++m) _Pragma("unroll") for (int k = 0; k < 2; ++k) dst[m][k] = *(const PG8_LAS bf16x8*)(lds + PG8_SA(b, h) + aoff + m * 2048 + k * 1024); } while (0)
; #define PG8_LDB(dst, b, h) do { _Pragma("unroll") for (int n = 0; n < 2; ++n) _Pragma("unroll") for (int k = 0; k < 2; ++k) dst[n][k] = *(const PG8_LAS bf16x8*)(lds + PG8_SB(b, h) + boff + n * 2048 + k * 1024); } while (0)
; #define PG8_MMA(ai, bj, At, Bt) do { __builtin_amdgcn_s_setprio(1); _Pragma("unroll") for (int m = 0; m < 4; ++m) _Pragma("unroll") for (int n = 0; n < 2; ++n) _Pragma("unroll") for (int k = 0; k < 2; ++k) \
;         acc[ai][bj][m][n] = __builtin_amdgcn_mfma_f32_16x16x32_bf16(Bt[n][k], At[m][k], acc[ai][bj][m][n], 0, 0, 0); __builtin_amdgcn_s_setprio(0); } while (0)
; #define PG8_WAIT_V(n) asm volatile("s_waitcnt vmcnt(" #n ")" ::: "memory")
; #define PG8_WAIT_L(n) asm volatile("s_waitcnt lgkmcnt(" #n ")" ::: "memory")
; #define PG8_BAR __builtin_amdgcn_s_barrier()
; #define PG8_SCHED __builtin_amdgcn_sched_barrier(0)
; template <class Epi, class Sched, bool ALIGN_EPI = false, bool SP2 = false>
; __device__ __forceinline__ void gemm_phase(PG8_LAS unsigned char* lds, const Gemm g, const Sched& S, const Epi& E) {
;     ...
;             PG8_LDB(B0, 1, 0); PG8_LDB(B1, 1, 1); PG8_SCHED; PG8_LDA(At, 1, 0); PG8_STAGE(PG8_SA(0, 1), a2 + hstep, voffA);
;             PG8_WAIT_V(8); PG8_WAIT_L(0); PG8_BAR; PG8_MMA(0, 0, At, B0); PG8_MMA(0, 1, At, B1); PG8_BAR; PG8_SCHED;
;             PG8_LDA(At, 1, 1); PG8_STAGE(PG8_SB(1, 0), b3, voffB); PG8_STAGE(PG8_SB(1, 1), b3 + hstep, voffB); PG8_STAGE(PG8_SA(1, 0), a3, voffA);
;             PG8_WAIT_V(8); PG8_WAIT_L(0); PG8_BAR; PG8_MMA(1, 0, At, B0); PG8_MMA(1, 1, At, B1); PG8_BAR; PG8_SCHED;
	s_add_i32 s75, 0, 0x18000
	s_add_i32 s76, 0, 0x1c000
	v_add_u32_e32 v116, s75, v194
	v_add_u32_e32 v156, s76, v194
	ds_read_b128 v[92:95], v116
	ds_read_b128 v[100:103], v116 offset:1024
	ds_read_b128 v[108:111], v116 offset:2048
	ds_read_b128 v[116:119], v116 offset:3072
	ds_read_b128 v[144:147], v156
	ds_read_b128 v[148:151], v156 offset:1024
	ds_read_b128 v[152:155], v156 offset:2048
	ds_read_b128 v[156:159], v156 offset:3072
	s_add_u32 s36, s50, 0x80000
	s_addc_u32 s37, s51, 0
	s_mov_b32 m0, s61
	v_lshl_add_u64 v[222:223], s[36:37], 0, v[174:175]
	ds_read_b128 v[160:163], v198 offset:32768
	ds_read_b128 v[164:167], v198 offset:33792
	ds_read_b128 v[168:171], v198 offset:34816
	ds_read_b128 v[184:187], v198 offset:35840
	ds_read_b128 v[188:191], v198 offset:36864
	ds_read_b128 v[200:203], v198 offset:37888
	ds_read_b128 v[204:207], v198 offset:38912
	ds_read_b128 v[208:211], v198 offset:39936
	global_load_lds_dwordx4 v[222:223], off
	v_lshl_add_u64 v[222:223], s[36:37], 0, v[172:173]
	s_mov_b32 m0, s62
	s_nop 0
	global_load_lds_dwordx4 v[222:223], off
	s_waitcnt vmcnt(8)
	s_waitcnt lgkmcnt(0)
	s_barrier
	s_setprio 1
	v_mfma_f32_16x16x32_bf16 v[140:143], v[92:95], v[160:163], v[140:143]
	v_mfma_f32_16x16x32_bf16 v[136:139], v[108:111], v[160:163], v[136:139]
	v_mfma_f32_16x16x32_bf16 v[132:135], v[92:95], v[168:171], v[132:135]
	v_mfma_f32_16x16x32_bf16 v[120:123], v[108:111], v[168:171], v[120:123]
	v_mfma_f32_16x16x32_bf16 v[112:115], v[92:95], v[188:191], v[112:115]
	v_mfma_f32_16x16x32_bf16 v[88:91], v[108:111], v[188:191], v[88:91]
	v_mfma_f32_16x16x32_bf16 v[76:79], v[92:95], v[204:207], v[76:79]
	v_mfma_f32_16x16x32_bf16 v[72:75], v[108:111], v[204:207], v[72:75]
	v_mfma_f32_16x16x32_bf16 v[140:143], v[100:103], v[164:167], v[140:143]
	v_mfma_f32_16x16x32_bf16 v[136:139], v[116:119], v[164:167], v[136:139]
	v_mfma_f32_16x16x32_bf16 v[132:135], v[100:103], v[184:187], v[132:135]
	v_mfma_f32_16x16x32_bf16 v[120:123], v[116:119], v[184:187], v[120:123]
	v_mfma_f32_16x16x32_bf16 v[112:115], v[100:103], v[200:203], v[112:115]
	v_mfma_f32_16x16x32_bf16 v[88:91], v[116:119], v[200:203], v[88:91]
	v_mfma_f32_16x16x32_bf16 v[76:79], v[100:103], v[208:211], v[76:79]
	v_mfma_f32_16x16x32_bf16 v[72:75], v[116:119], v[208:211], v[72:75]
	v_mfma_f32_16x16x32_bf16 v[128:131], v[144:147], v[160:163], v[128:131]
	v_mfma_f32_16x16x32_bf16 v[124:127], v[152:155], v[160:163], v[124:127]
	v_mfma_f32_16x16x32_bf16 v[104:107], v[144:147], v[168:171], v[104:107]
	v_mfma_f32_16x16x32_bf16 v[96:99], v[152:155], v[168:171], v[96:99]
	v_mfma_f32_16x16x32_bf16 v[84:87], v[144:147], v[188:191], v[84:87]
	v_mfma_f32_16x16x32_bf16 v[80:83], v[152:155], v[188:191], v[80:83]
	v_mfma_f32_16x16x32_bf16 v[68:71], v[144:147], v[204:207], v[68:71]
	v_mfma_f32_16x16x32_bf16 v[64:67], v[152:155], v[204:207], v[64:67]
	v_mfma_f32_16x16x32_bf16 v[128:131], v[148:151], v[164:167], v[128:131]
	v_mfma_f32_16x16x32_bf16 v[124:127], v[156:159], v[164:167], v[124:127]
	v_mfma_f32_16x16x32_bf16 v[104:107], v[148:151], v[184:187], v[104:107]
	v_mfma_f32_16x16x32_bf16 v[96:99], v[156:159], v[184:187], v[96:99]
	v_mfma_f32_16x16x32_bf16 v[84:87], v[148:151], v[200:203], v[84:87]
	v_mfma_f32_16x16x32_bf16 v[80:83], v[156:159], v[200:203], v[80:83]
	v_mfma_f32_16x16x32_bf16 v[68:71], v[148:151], v[208:211], v[68:71]
	v_mfma_f32_16x16x32_bf16 v[64:67], v[156:159], v[208:211], v[64:67]
	s_setprio 0
	s_barrier
; #define PG8_STAGE(bufoff, gbase, voff) do { _Pragma("unroll") for (int _i = 0; _i < 2; ++_i) \
;         __builtin_amdgcn_global_load_lds((const unsigned*)((const char*)(gbase) + (voff)[_i]), (PG8_LAS unsigned*)(lds + (bufoff) + ldsw + _i * 8192), 16, 0, 0); } while (0)
; #define PG8_LDA(dst, b, h) do { _Pragma("unroll") for (int m = 0; m < 4; ++m) _Pragma("unroll") for (int k = 0; k < 2; ++k) dst[m][k] = *(const PG8_LAS bf16x8*)(lds + PG8_SA(b, h) + aoff + m * 2048 + k * 1024); } while (0)
; #define PG8_LDB(dst, b, h) do { _Pragma("unroll") for (int n = 0; n < 2; ++n) _Pragma("unroll") for (int k = 0; k < 2; ++k) dst[n][k] = *(const PG8_LAS bf16x8*)(lds + PG8_SB(b, h) + boff + n * 2048 + k * 1024); } while (0)
; template <class Epi, class Sched, bool ALIGN_EPI = false, bool SP2 = false>
; __device__ __forceinline__ void gemm_phase(PG8_LAS unsigned char* lds, const Gemm g, const Sched& S, const Epi& E) {
;     ...
;         for (int t = 0; t < nt; t += 2) {
;             const bool last = (t == nt - 2);
;             const char* a1 = cA + (size_t)(t + 1) * kstep;
;             const char* a2 = last ? nA : cA + (size_t)(t + 2) * kstep; const char* b2 = last ? nB : cB + (size_t)(t + 2) * kstep;
;             const char* a3 = a2 + kstep; const char* b3 = b2 + kstep;
;             if (last && has_next) S.a_ready(nxt);
;             if constexpr (SP2) {
;             PG8_LDB(B0, 0, 0); PG8_LDB(B1, 0, 1); PG8_SCHED; PG8_LDA(At, 0, 0); PG8_STAGE(PG8_SA(1, 1), a1 + hstep, voffA);
;             PG8_WAIT_V(8); PG8_WAIT_L(0); PG8_BAR; PG8_MMA(0, 0, At, B0); PG8_MMA(0, 1, At, B1); PG8_BAR; PG8_SCHED;
;             PG8_LDA(At, 0, 1); PG8_STAGE(PG8_SB(0, 0), b2, voffB); PG8_STAGE(PG8_SB(0, 1), b2 + hstep, voffB); PG8_STAGE(PG8_SA(0, 0), a2, voffA);
;             PG8_WAIT_V(8); PG8_WAIT_L(0); PG8_BAR; PG8_MMA(1, 0, At, B0); PG8_MMA(1, 1, At, B1); PG8_BAR; PG8_SCHED;
;             PG8_LDB(B0, 1, 0); PG8_LDB(B1, 1, 1); PG8_SCHED; PG8_LDA(At, 1, 0); PG8_STAGE(PG8_SA(0, 1), a2 + hstep, voffA);
;             PG8_WAIT_V(8); PG8_WAIT_L(0); PG8_BAR; PG8_MMA(0, 0, At, B0); PG8_MMA(0, 1, At, B1); PG8_BAR; PG8_SCHED;
;             PG8_LDA(At, 1, 1); PG8_STAGE(PG8_SB(1, 0), b3, voffB); PG8_STAGE(PG8_SB(1, 1), b3 + hstep, voffB); PG8_STAGE(PG8_SA(1, 0), a3, voffA);
;             PG8_WAIT_V(8); PG8_WAIT_L(0); PG8_BAR; PG8_MMA(1, 0, At, B0); PG8_MMA(1, 1, At, B1); PG8_BAR; PG8_SCHED;
	s_add_i32 s36, s75, s54
	v_lshl_add_u64 v[212:213], v[212:213], 0, s[20:21]
	s_mov_b32 m0, s36
	ds_read_b128 v[160:163], v198 offset:49152
	ds_read_b128 v[164:167], v198 offset:50176
	ds_read_b128 v[168:171], v198 offset:51200
	ds_read_b128 v[184:187], v198 offset:52224
	ds_read_b128 v[188:191], v198 offset:53248
	ds_read_b128 v[200:203], v198 offset:54272
	ds_read_b128 v[204:207], v198 offset:55296
	ds_read_b128 v[208:211], v198 offset:56320
	global_load_lds_dwordx4 v[212:213], off
	s_add_i32 m0, s36, 0x2000
	s_add_u32 s36, s44, 0x80080
	v_lshl_add_u64 v[212:213], v[214:215], 0, s[20:21]
	s_addc_u32 s37, s45, 0
	s_add_i32 s44, s76, s54
	global_load_lds_dwordx4 v[212:213], off
	v_lshl_add_u64 v[212:213], s[36:37], 0, v[174:175]
	s_mov_b32 m0, s44
	s_nop 0
	global_load_lds_dwordx4 v[212:213], off
	v_lshl_add_u64 v[212:213], s[36:37], 0, v[172:173]
	s_add_i32 m0, s44, 0x2000
	s_nop 0
	global_load_lds_dwordx4 v[212:213], off
	v_lshl_add_u64 v[212:213], v[218:219], 0, s[20:21]
	s_mov_b32 m0, s66
	s_nop 0
	global_load_lds_dwordx4 v[212:213], off
	v_lshl_add_u64 v[212:213], v[220:221], 0, s[20:21]
	s_mov_b32 m0, s67
	s_nop 0
	global_load_lds_dwordx4 v[212:213], off
	s_waitcnt vmcnt(8)
	s_waitcnt lgkmcnt(0)
	s_barrier
	s_setprio 1
	v_mfma_f32_16x16x32_bf16 v[60:63], v[92:95], v[160:163], v[60:63]
	v_mfma_f32_16x16x32_bf16 v[56:59], v[108:111], v[160:163], v[56:59]
	v_mfma_f32_16x16x32_bf16 v[52:55], v[92:95], v[168:171], v[52:55]
	v_mfma_f32_16x16x32_bf16 v[40:43], v[108:111], v[168:171], v[40:43]
	v_mfma_f32_16x16x32_bf16 v[36:39], v[92:95], v[188:191], v[36:39]
	v_mfma_f32_16x16x32_bf16 v[24:27], v[108:111], v[188:191], v[24:27]
	v_mfma_f32_16x16x32_bf16 v[12:15], v[92:95], v[204:207], v[12:15]
	v_mfma_f32_16x16x32_bf16 v[8:11], v[108:111], v[204:207], v[8:11]
	v_mfma_f32_16x16x32_bf16 v[60:63], v[100:103], v[164:167], v[60:63]
	v_mfma_f32_16x16x32_bf16 v[56:59], v[116:119], v[164:167], v[56:59]
	v_mfma_f32_16x16x32_bf16 v[52:55], v[100:103], v[184:187], v[52:55]
	v_mfma_f32_16x16x32_bf16 v[40:43], v[116:119], v[184:187], v[40:43]
	v_mfma_f32_16x16x32_bf16 v[36:39], v[100:103], v[200:203], v[36:39]
	v_mfma_f32_16x16x32_bf16 v[24:27], v[116:119], v[200:203], v[24:27]
	v_mfma_f32_16x16x32_bf16 v[12:15], v[100:103], v[208:211], v[12:15]
	v_mfma_f32_16x16x32_bf16 v[8:11], v[116:119], v[208:211], v[8:11]
	v_mfma_f32_16x16x32_bf16 v[48:51], v[144:147], v[160:163], v[48:51]
	v_mfma_f32_16x16x32_bf16 v[44:47], v[152:155], v[160:163], v[44:47]
	v_mfma_f32_16x16x32_bf16 v[32:35], v[144:147], v[168:171], v[32:35]
	v_mfma_f32_16x16x32_bf16 v[28:31], v[152:155], v[168:171], v[28:31]
	v_mfma_f32_16x16x32_bf16 v[20:23], v[144:147], v[188:191], v[20:23]
	v_mfma_f32_16x16x32_bf16 v[16:19], v[152:155], v[188:191], v[16:19]
	v_mfma_f32_16x16x32_bf16 v[4:7], v[144:147], v[204:207], v[4:7]
	v_mfma_f32_16x16x32_bf16 v[0:3], v[152:155], v[204:207], v[0:3]
	v_mfma_f32_16x16x32_bf16 v[48:51], v[148:151], v[164:167], v[48:51]
	v_mfma_f32_16x16x32_bf16 v[44:47], v[156:159], v[164:167], v[44:47]
	v_mfma_f32_16x16x32_bf16 v[32:35], v[148:151], v[184:187], v[32:35]
	v_mfma_f32_16x16x32_bf16 v[28:31], v[156:159], v[184:187], v[28:31]
	v_mfma_f32_16x16x32_bf16 v[20:23], v[148:151], v[200:203], v[20:23]
	v_mfma_f32_16x16x32_bf16 v[16:19], v[156:159], v[200:203], v[16:19]
	v_mfma_f32_16x16x32_bf16 v[4:7], v[148:151], v[208:211], v[4:7]
	v_mfma_f32_16x16x32_bf16 v[0:3], v[156:159], v[208:211], v[0:3]
	s_setprio 0
	s_barrier
	s_add_i32 s74, s74, 2
	s_add_u32 s72, s72, 0x100
	s_addc_u32 s73, s73, 0
	s_cmp_gt_u32 s74, 29
	s_mov_b64 s[36:37], s[40:41]
	s_cbranch_scc0 .LBB0_645
	s_and_b64 vcc, exec, s[22:23]
	s_cbranch_vccz .LBB0_648
	s_barrier

; #define PG8_WAIT_V(n) asm volatile("s_waitcnt vmcnt(" #n ")" ::: "memory")
; #define PG8_BAR __builtin_amdgcn_s_barrier()
; template <class Epi, class Sched, bool ALIGN_EPI = false, bool SP2 = false>
; __device__ __forceinline__ void gemm_phase(PG8_LAS unsigned char* lds, const Gemm g, const Sched& S, const Epi& E) {
;     int tid_ = threadIdx.x; asm volatile("" : "+v"(tid_));
;     const int tid = tid_, wid = __builtin_amdgcn_readfirstlane(tid >> 6), lane = tid & 63, wr = wid >> 2, wc = wid & 3, fr = lane & 15, fq = lane >> 4;
;     const int K = g.K, nt = K / BK;
;     unsigned voffA[2], voffB[2];
; #pragma unroll
;     for (int i = 0; i < 2; ++i) { int R, C; stage_rc(tid * 16 + i * 8192, R, C); const int Rb = Epi::PERM ? ((R & ~31) + perm32(R & 31)) : R;
;         voffA[i] = (unsigned)(R * K + C) * 2u; voffB[i] = (unsigned)(Rb * K + C) * 2u; }
;     const size_t kstep = (size_t)(BK * 2);
;     const size_t hstep = (size_t)HALF * K * 2;
;     const size_t tstep = 2 * hstep;
;     const unsigned ldsw = (unsigned)wid * 1024u;
;     const int aoff = lds_byte(wr * 64 + fr, fq * 8), boff = lds_byte(wc * 32 + fr, fq * 8);
;     ...
;     Unit cur, nxt; int ui = 0;
;     if (!S.next(0, cur)) return;
;     f32x4 acc[2][2][4][2];
; #pragma unroll
;     for (int a = 0; a < 2; ++a)
; #pragma unroll
;         for (int b = 0; b < 2; ++b)
; #pragma unroll
;             for (int m = 0; m < 4; ++m)
; #pragma unroll
;                 for (int n = 0; n < 2; ++n) acc[a][b][m][n] = (f32x4){0.f, 0.f, 0.f, 0.f};
;     bf16x8 At[4][2], B0[2][2], B1[2][2];
;     const char* cA = (const char*)g.A + (size_t)cur.pm * tstep; const char* cB = (const char*)g.Bt + (size_t)cur.pn * tstep;
;     S.a_ready(cur);
;     if constexpr (SP2) {
;         PG8_STAGE(PG8_SB(0, 0), cB, voffB); PG8_STAGE(PG8_SB(0, 1), cB + hstep, voffB); PG8_STAGE(PG8_SA(0, 0), cA, voffA); PG8_STAGE(PG8_SA(0, 1), cA + hstep, voffA);
;         if (wr == 1) PG8_BAR;
;         PG8_WAIT_V(2); PG8_BAR;
;         PG8_STAGE(PG8_SB(1, 0), cB + kstep, voffB); PG8_STAGE(PG8_SA(1, 0), cA + kstep, voffA); PG8_STAGE(PG8_SB(1, 1), cB + hstep + kstep, voffB);
;         PG8_WAIT_V(6); PG8_BAR;
;     } else {
;         PG8_STAGE(PG8_SB(0, 0), cB, voffB); PG8_STAGE(PG8_SA(0, 0), cA, voffA); PG8_STAGE(PG8_SB(0, 1), cB + hstep, voffB); PG8_STAGE(PG8_SA(0, 1), cA + hstep, voffA);
;         if (wr == 1) PG8_BAR;
.LBB0_762:
	s_or_b64 exec, exec, s[12:13]
	s_nop 0
	s_nop 0
	s_nop 0
	s_nop 0
	s_nop 0
	s_nop 0
	s_nop 0
	s_nop 0
	s_nop 0
	s_nop 0
	s_nop 0
	s_nop 0
	s_mov_b64 s[14:15], s[0:1]
	s_mov_b64 s[16:17], s[0:1]
	s_mov_b64 s[12:13], s[0:1]
	v_mov_b32_e32 v14, v216
	s_waitcnt lgkmcnt(0)
	s_barrier
	s_cmpk_lt_i32 s2, 0x1000
	s_nop 0
	v_readfirstlane_b32 s18, v14
	s_cbranch_scc0 .LBB0_782
	v_lshlrev_b32_e32 v0, 4, v14
	v_add_u32_e32 v1, 0x2000, v0
	v_ashrrev_i32_e32 v2, 31, v1
	v_lshrrev_b32_e32 v2, 22, v2
	v_add_u32_e32 v2, v1, v2
	v_ashrrev_i32_e32 v8, 10, v2
	v_mul_i32_i24_e32 v2, 0x400, v8
	v_sub_u32_e32 v1, v1, v2
	v_lshrrev_b32_e32 v2, 4, v1
	v_bitop3_b32 v1, v2, v1, 32 bitop3:0x6c
	v_ashrrev_i32_e32 v2, 31, v1
	s_load_dwordx2 s[14:15], s[14:15], 0xc8
	s_nop 0
	s_load_dwordx2 s[16:17], s[16:17], 0xc8
	v_lshrrev_b32_e32 v2, 26, v2
	v_add_u32_e32 v2, v1, v2
	v_lshlrev_b32_e32 v3, 3, v8
	v_ashrrev_i32_e32 v9, 6, v2
	v_and_b32_e32 v3, -16, v3
	v_add_u32_e32 v3, v9, v3
	s_waitcnt lgkmcnt(0)
	s_add_u32 s40, s14, 0x7800000
	v_and_b32_e32 v4, 3, v9
	s_mov_b32 s14, 0xfffe0
	v_lshrrev_b32_e32 v5, 2, v3
	v_lshlrev_b32_e32 v6, 1, v3
	v_and_b32_e32 v2, 0xc0, v2
	v_and_or_b32 v4, v3, s14, v4
	v_and_b32_e32 v5, 4, v5
	v_and_b32_e32 v6, 24, v6
	v_sub_u32_e32 v1, v1, v2
	v_mov_b32_e32 v2, 1
	v_or3_b32 v4, v4, v5, v6
	v_lshlrev_b32_e32 v5, 5, v8
	v_ashrrev_i16_sdwa v1, v2, sext(v1) dst_sel:DWORD dst_unused:UNUSED_PAD src0_sel:DWORD src1_sel:BYTE_0
	v_and_b32_e32 v5, 32, v5
	v_bfe_i32 v10, v1, 0, 16
	v_add_lshl_u32 v1, v5, v10, 1
	s_waitcnt vmcnt(0)
	v_lshl_add_u32 v128, v4, 12, v1
	v_lshl_add_u32 v130, v3, 12, v1
	v_bfe_i32 v1, v14, 27, 1
	v_lshrrev_b32_e32 v1, 22, v1
	v_add_u32_e32 v1, v0, v1
	v_and_b32_e32 v1, 0xfffffc00, v1
	v_sub_u32_e32 v0, v0, v1
	v_lshrrev_b32_e32 v1, 4, v0
	v_ashrrev_i32_e32 v3, 31, v14
	v_bitop3_b32 v0, v1, v0, 32 bitop3:0x6c
	v_lshrrev_b32_e32 v3, 26, v3
	v_ashrrev_i32_e32 v1, 31, v0
	v_add_u32_e32 v3, v14, v3
	s_addc_u32 s41, s15, 0
	v_lshrrev_b32_e32 v1, 26, v1
	v_ashrrev_i32_e32 v12, 6, v3
	s_add_u32 s44, s16, 0x3600000
	v_add_u32_e32 v1, v0, v1
	v_lshlrev_b32_e32 v3, 3, v12
	s_addc_u32 s45, s17, 0
	s_ashr_i32 s19, s18, 6
	v_ashrrev_i32_e32 v11, 6, v1
	v_and_b32_e32 v3, -16, v3
	s_ashr_i32 s20, s18, 8
	s_lshl_b32 s47, s19, 10
	v_add_u32_e32 v3, v11, v3
	v_and_b32_e32 v4, 3, v11
	s_lshl_b32 s17, s59, 9
	v_and_or_b32 v4, v3, s14, v4
	s_mul_i32 s16, s59, 0x201
	s_and_b64 s[14:15], s[42:43], exec
	s_cselect_b32 s14, s16, s17
	s_add_i32 s14, s14, s56
	s_ashr_i32 s15, s14, 31
	s_lshr_b32 s15, s15, 24
	s_add_i32 s15, s14, s15
	s_ashr_i32 s16, s15, 8
	s_and_b32 s15, s15, 0xff00
	s_sub_i32 s15, s14, s15
	s_sext_i32_i16 s14, s15
	s_bfe_u32 s14, s14, 0x3001c
	s_add_i32 s17, s15, s14
	s_sext_i32_i16 s14, s17
	s_and_b32 s17, s17, 0xfff8
	s_sub_i32 s15, s15, s17
	s_lshl_b32 s16, s16, 3
	s_sext_i32_i16 s15, s15
	v_lshrrev_b32_e32 v5, 2, v3
	v_lshlrev_b32_e32 v6, 1, v3
	v_and_b32_e32 v1, 0xc0, v1
	s_lshr_b32 s14, s14, 3
	s_add_i32 s28, s16, s15
	v_and_b32_e32 v5, 4, v5
	v_and_b32_e32 v6, 24, v6
	v_sub_u32_e32 v0, v0, v1
	s_ashr_i32 s29, s28, 31
	s_bfe_i64 s[22:23], s[14:15], 0x100000
	v_or3_b32 v4, v4, v5, v6
	v_lshlrev_b32_e32 v5, 5, v12
	v_ashrrev_i16_sdwa v0, v2, sext(v0) dst_sel:DWORD dst_unused:UNUSED_PAD src0_sel:DWORD src1_sel:BYTE_0
	s_lshl_b64 s[16:17], s[28:29], 20
	s_lshl_b64 s[22:23], s[22:23], 20
	v_and_b32_e32 v5, 32, v5
	v_bfe_i32 v13, v0, 0, 16
	s_add_u32 s34, s44, s22
	v_add_lshl_u32 v0, v5, v13, 1
	s_addc_u32 s35, s45, s23
	s_add_i32 s50, s47, 0
	v_lshl_add_u32 v132, v4, 12, v0
	s_add_i32 m0, s50, 0x10000
	v_lshl_add_u32 v134, v3, 12, v0
	global_load_lds_dwordx4 v132, s[34:35]
	s_add_i32 m0, s50, 0x12000
	s_add_u32 s22, s34, 0x80000
	global_load_lds_dwordx4 v128, s[34:35]
	s_addc_u32 s23, s35, 0
	s_add_i32 m0, s50, 0x14000
	v_mov_b32_e32 v133, 0
	global_load_lds_dwordx4 v132, s[22:23]
	s_add_i32 m0, s50, 0x16000
	s_add_u32 s30, s40, s16
	s_addc_u32 s31, s41, s17
	s_add_i32 s51, s50, 0x2000
	global_load_lds_dwordx4 v128, s[22:23]
	s_mov_b32 m0, s50
	s_add_u32 s16, s30, 0x80000
	global_load_lds_dwordx4 v134, s[30:31]
	s_mov_b32 m0, s51
	s_addc_u32 s17, s31, 0
	s_add_i32 s52, s50, 0x4000
	global_load_lds_dwordx4 v130, s[30:31]
	s_mov_b32 m0, s52
	s_add_i32 s53, s50, 0x6000
	global_load_lds_dwordx4 v134, s[16:17]
	s_mov_b32 m0, s53
	v_mov_b32_e32 v129, v133
	global_load_lds_dwordx4 v130, s[16:17]
	s_load_dwordx2 s[16:17], s[12:13], 0xc8
	v_mov_b32_e32 v135, v133
	v_mov_b32_e32 v131, v133
	s_cmp_eq_u32 s20, 1
	s_mov_b32 s54, 0
	v_lshl_add_u64 v[6:7], s[34:35], 0, v[132:133]
	v_lshl_add_u64 v[4:5], s[34:35], 0, v[128:129]
	v_lshl_add_u64 v[0:1], s[30:31], 0, v[134:135]
	s_cselect_b64 s[12:13], -1, 0
	s_cmp_lg_u32 s20, 1
	v_lshl_add_u64 v[2:3], s[30:31], 0, v[130:131]
	s_cbranch_scc1 .LBB0_765
	s_barrier

; #define PG8_STAGE(bufoff, gbase, voff) do { _Pragma("unroll") for (int _i = 0; _i < 2; ++_i) \
;         __builtin_amdgcn_global_load_lds((const unsigned*)((const char*)(gbase) + (voff)[_i]), (PG8_LAS unsigned*)(lds + (bufoff) + ldsw + _i * 8192), 16, 0, 0); } while (0)
; #define PG8_LDA(dst, b, h) do { _Pragma("unroll") for (int m = 0; m < 4; ++m) _Pragma("unroll") for (int k = 0; k < 2; ++k) dst[m][k] = *(const PG8_LAS bf16x8*)(lds + PG8_SA(b, h) + aoff + m * 2048 + k * 1024); } while (0)
; #define PG8_LDB(dst, b, h) do { _Pragma("unroll") for (int n = 0; n < 2; ++n) _Pragma("unroll") for (int k = 0; k < 2; ++k) dst[n][k] = *(const PG8_LAS bf16x8*)(lds + PG8_SB(b, h) + boff + n * 2048 + k * 1024); } while (0)
; #define PG8_WAIT_V(n) asm volatile("s_waitcnt vmcnt(" #n ")" ::: "memory")
; #define PG8_WAIT_L(n) asm volatile("s_waitcnt lgkmcnt(" #n ")" ::: "memory")
; #define PG8_BAR __builtin_amdgcn_s_barrier()
; #define PG8_SCHED __builtin_amdgcn_sched_barrier(0)
; template <class Epi, class Sched, bool ALIGN_EPI = false, bool SP2 = false>
; __device__ __forceinline__ void gemm_phase(PG8_LAS unsigned char* lds, const Gemm g, const Sched& S, const Epi& E) {
;     ...
;         const bool has_next = S.next(ui + 1, nxt);
;         const char* nA = has_next ? (const char*)g.A + (size_t)nxt.pm * tstep : cA; const char* nB = has_next ? (const char*)g.Bt + (size_t)nxt.pn * tstep : cB;
;         for (int t = 0; t < nt; t += 2) {
;             const bool last = (t == nt - 2);
;             const char* a1 = cA + (size_t)(t + 1) * kstep;
;             const char* a2 = last ? nA : cA + (size_t)(t + 2) * kstep; const char* b2 = last ? nB : cB + (size_t)(t + 2) * kstep;
;             const char* a3 = a2 + kstep; const char* b3 = b2 + kstep;
;             if (last && has_next) S.a_ready(nxt);
;             if constexpr (SP2) {
;             PG8_LDB(B0, 0, 0); PG8_LDB(B1, 0, 1); PG8_SCHED; PG8_LDA(At, 0, 0); PG8_STAGE(PG8_SA(1, 1), a1 + hstep, voffA);
;             PG8_WAIT_V(8); PG8_WAIT_L(0); PG8_BAR; PG8_MMA(0, 0, At, B0); PG8_MMA(0, 1, At, B1); PG8_BAR; PG8_SCHED;
;             PG8_LDA(At, 0, 1); PG8_STAGE(PG8_SB(0, 0), b2, voffB); PG8_STAGE(PG8_SB(0, 1), b2 + hstep, voffB); PG8_STAGE(PG8_SA(0, 0), a2, voffA);
;             PG8_WAIT_V(8); PG8_WAIT_L(0); PG8_BAR; PG8_MMA(1, 0, At, B0); PG8_MMA(1, 1, At, B1); PG8_BAR; PG8_SCHED;
.LBB0_774:
	s_ashr_i32 s23, s22, 31
	s_lshl_b64 s[24:25], s[22:23], 20
	s_add_u32 s24, s40, s24
	s_addc_u32 s25, s41, s25
	s_and_b64 s[26:27], s[38:39], exec
	s_cselect_b32 s23, s25, s31
	s_cselect_b32 s62, s24, s30
	s_ashr_i32 s21, s20, 31
	s_lshl_b64 s[26:27], s[20:21], 20
	s_add_u32 s26, s44, s26
	s_addc_u32 s27, s45, s27
	s_and_b64 s[36:37], s[38:39], exec
	s_cselect_b32 s21, s27, s35
	s_cselect_b32 s63, s26, s34
	s_add_u32 s30, s30, 0x80080
	s_addc_u32 s31, s31, 0
	s_add_u32 s64, s34, 0x100
	s_addc_u32 s65, s35, 0
	s_mov_b32 s66, -2
	ds_read_b128 v[152:155], v149
	ds_read_b128 v[156:159], v149 offset:1024
	ds_read_b128 v[160:163], v149 offset:2048
	ds_read_b128 v[164:167], v149 offset:3072
	ds_read_b128 v[168:171], v150
	ds_read_b128 v[172:175], v150 offset:1024
	ds_read_b128 v[176:179], v150 offset:2048
	ds_read_b128 v[180:183], v150 offset:3072
	s_add_u32 s34, s30, 0xfff80080
	s_addc_u32 s35, s31, -1
	s_cmp_eq_u32 s66, 28
	s_cselect_b32 s37, s23, s35
	s_cselect_b32 s36, s62, s34
	s_cselect_b32 s35, s21, s65
	s_cselect_b32 s34, s63, s64
	v_lshl_add_u64 v[144:145], s[30:31], 0, v[136:137]
	s_add_i32 m0, s50, 0xc000
	ds_read_b128 v[184:187], v151
	ds_read_b128 v[188:191], v151 offset:1024
	ds_read_b128 v[192:195], v151 offset:2048
	ds_read_b128 v[196:199], v151 offset:3072
	ds_read_b128 v[200:203], v151 offset:4096
	ds_read_b128 v[204:207], v151 offset:5120
	ds_read_b128 v[208:211], v151 offset:6144
	ds_read_b128 v[212:215], v151 offset:7168
	global_load_lds_dwordx4 v[144:145], off
	v_lshl_add_u64 v[144:145], s[30:31], 0, v[138:139]
	s_add_i32 m0, s50, 0xe000
	s_nop 0
	global_load_lds_dwordx4 v[144:145], off
	s_waitcnt vmcnt(8)
	s_waitcnt lgkmcnt(0)
	s_barrier
	s_setprio 1
	v_mfma_f32_16x16x32_bf16 v[124:127], v[152:155], v[184:187], 0
	v_mfma_f32_16x16x32_bf16 v[120:123], v[160:163], v[184:187], 0
	v_mfma_f32_16x16x32_bf16 v[108:111], v[152:155], v[192:195], 0
	v_mfma_f32_16x16x32_bf16 v[104:107], v[160:163], v[192:195], 0
	v_mfma_f32_16x16x32_bf16 v[92:95], v[152:155], v[200:203], 0
	v_mfma_f32_16x16x32_bf16 v[88:91], v[160:163], v[200:203], 0
	v_mfma_f32_16x16x32_bf16 v[76:79], v[152:155], v[208:211], 0
	v_mfma_f32_16x16x32_bf16 v[72:75], v[160:163], v[208:211], 0
	v_mfma_f32_16x16x32_bf16 v[124:127], v[156:159], v[188:191], v[124:127]
	v_mfma_f32_16x16x32_bf16 v[120:123], v[164:167], v[188:191], v[120:123]
	v_mfma_f32_16x16x32_bf16 v[108:111], v[156:159], v[196:199], v[108:111]
	v_mfma_f32_16x16x32_bf16 v[104:107], v[164:167], v[196:199], v[104:107]
	v_mfma_f32_16x16x32_bf16 v[92:95], v[156:159], v[204:207], v[92:95]
	v_mfma_f32_16x16x32_bf16 v[88:91], v[164:167], v[204:207], v[88:91]
	v_mfma_f32_16x16x32_bf16 v[76:79], v[156:159], v[212:215], v[76:79]
	v_mfma_f32_16x16x32_bf16 v[72:75], v[164:167], v[212:215], v[72:75]
	v_mfma_f32_16x16x32_bf16 v[116:119], v[168:171], v[184:187], 0
	v_mfma_f32_16x16x32_bf16 v[112:115], v[176:179], v[184:187], 0
	v_mfma_f32_16x16x32_bf16 v[100:103], v[168:171], v[192:195], 0
	v_mfma_f32_16x16x32_bf16 v[96:99], v[176:179], v[192:195], 0
	v_mfma_f32_16x16x32_bf16 v[84:87], v[168:171], v[200:203], 0
	v_mfma_f32_16x16x32_bf16 v[80:83], v[176:179], v[200:203], 0
	v_mfma_f32_16x16x32_bf16 v[68:71], v[168:171], v[208:211], 0
	v_mfma_f32_16x16x32_bf16 v[64:67], v[176:179], v[208:211], 0
	v_mfma_f32_16x16x32_bf16 v[116:119], v[172:175], v[188:191], v[116:119]
	v_mfma_f32_16x16x32_bf16 v[112:115], v[180:183], v[188:191], v[112:115]
	v_mfma_f32_16x16x32_bf16 v[100:103], v[172:175], v[196:199], v[100:103]
	v_mfma_f32_16x16x32_bf16 v[96:99], v[180:183], v[196:199], v[96:99]
	v_mfma_f32_16x16x32_bf16 v[84:87], v[172:175], v[204:207], v[84:87]
	v_mfma_f32_16x16x32_bf16 v[80:83], v[180:183], v[204:207], v[80:83]
	v_mfma_f32_16x16x32_bf16 v[68:71], v[172:175], v[212:215], v[68:71]
	v_mfma_f32_16x16x32_bf16 v[64:67], v[180:183], v[212:215], v[64:67]
	s_setprio 0
	s_barrier
	s_add_i32 s67, s60, s47
	v_lshl_add_u64 v[144:145], s[34:35], 0, v[132:133]
	s_mov_b32 m0, s67
	ds_read_b128 v[184:187], v151 offset:16384
	ds_read_b128 v[188:191], v151 offset:17408
	ds_read_b128 v[192:195], v151 offset:18432
	ds_read_b128 v[196:199], v151 offset:19456
	ds_read_b128 v[200:203], v151 offset:20480
	ds_read_b128 v[204:207], v151 offset:21504
	ds_read_b128 v[208:211], v151 offset:22528
	ds_read_b128 v[212:215], v151 offset:23552
	global_load_lds_dwordx4 v[144:145], off
	s_add_i32 m0, s67, 0x2000
	s_add_u32 s68, s34, 0x80000
	v_lshl_add_u64 v[218:219], s[34:35], 0, v[128:129]
	s_addc_u32 s69, s35, 0
	s_add_i32 s67, s61, s47
	global_load_lds_dwordx4 v[218:219], off
	v_lshl_add_u64 v[220:221], s[68:69], 0, v[132:133]
	s_mov_b32 m0, s67
	v_lshl_add_u64 v[222:223], s[36:37], 0, v[130:131]
	global_load_lds_dwordx4 v[220:221], off
	v_lshl_add_u64 v[220:221], s[68:69], 0, v[128:129]
	s_add_i32 m0, s67, 0x2000
	s_nop 0
	global_load_lds_dwordx4 v[220:221], off
	v_lshl_add_u64 v[220:221], s[36:37], 0, v[134:135]
	s_mov_b32 m0, s50
	s_nop 0
	global_load_lds_dwordx4 v[220:221], off
	s_mov_b32 m0, s51
	s_nop 0
	global_load_lds_dwordx4 v[222:223], off
	s_waitcnt vmcnt(8)
	s_waitcnt lgkmcnt(0)
	s_barrier
; #define PG8_STAGE(bufoff, gbase, voff) do { _Pragma("unroll") for (int _i = 0; _i < 2; ++_i) \
;         __builtin_amdgcn_global_load_lds((const unsigned*)((const char*)(gbase) + (voff)[_i]), (PG8_LAS unsigned*)(lds + (bufoff) + ldsw + _i * 8192), 16, 0, 0); } while (0)
; #define PG8_LDA(dst, b, h) do { _Pragma("unroll") for (int m = 0; m < 4; ++m) _Pragma("unroll") for (int k = 0; k < 2; ++k) dst[m][k] = *(const PG8_LAS bf16x8*)(lds + PG8_SA(b, h) + aoff + m * 2048 + k * 1024); } while (0)
; #define PG8_LDB(dst, b, h) do { _Pragma("unroll") for (int n = 0; n < 2; ++n) _Pragma("unroll") for (int k = 0; k < 2; ++k) dst[n][k] = *(const PG8_LAS bf16x8*)(lds + PG8_SB(b, h) + boff + n * 2048 + k * 1024); } while (0)
; #define PG8_MMA(ai, bj, At, Bt) do { __builtin_amdgcn_s_setprio(1); _Pragma("unroll") for (int m = 0; m < 4; ++m) _Pragma("unroll") for (int n = 0; n < 2; ++n) _Pragma("unroll") for (int k = 0; k < 2; ++k) \
;         acc[ai][bj][m][n] = __builtin_amdgcn_mfma_f32_16x16x32_bf16(Bt[n][k], At[m][k], acc[ai][bj][m][n], 0, 0, 0); __builtin_amdgcn_s_setprio(0); } while (0)
; #define PG8_WAIT_V(n) asm volatile("s_waitcnt vmcnt(" #n ")" ::: "memory")
; template <class Epi, class Sched, bool ALIGN_EPI = false, bool SP2 = false>
; __device__ __forceinline__ void gemm_phase(PG8_LAS unsigned char* lds, const Gemm g, const Sched& S, const Epi& E) {
;     ...
;             PG8_LDB(B0, 0, 0); PG8_LDB(B1, 0, 1); PG8_SCHED; PG8_LDA(At, 0, 0); PG8_STAGE(PG8_SA(1, 1), a1 + hstep, voffA);
;             PG8_WAIT_V(8); PG8_WAIT_L(0); PG8_BAR; PG8_MMA(0, 0, At, B0); PG8_MMA(0, 1, At, B1); PG8_BAR; PG8_SCHED;
;             PG8_LDA(At, 0, 1); PG8_STAGE(PG8_SB(0, 0), b2, voffB); PG8_STAGE(PG8_SB(0, 1), b2 + hstep, voffB); PG8_STAGE(PG8_SA(0, 0), a2, voffA);
;             PG8_WAIT_V(8); PG8_WAIT_L(0); PG8_BAR; PG8_MMA(1, 0, At, B0); PG8_MMA(1, 1, At, B1); PG8_BAR; PG8_SCHED;
;             PG8_LDB(B0, 1, 0); PG8_LDB(B1, 1, 1); PG8_SCHED; PG8_LDA(At, 1, 0); PG8_STAGE(PG8_SA(0, 1), a2 + hstep, voffA);
;             PG8_WAIT_V(8); PG8_WAIT_L(0); PG8_BAR; PG8_MMA(0, 0, At, B0); PG8_MMA(0, 1, At, B1); PG8_BAR; PG8_SCHED;
;             PG8_LDA(At, 1, 1); PG8_STAGE(PG8_SB(1, 0), b3, voffB); PG8_STAGE(PG8_SB(1, 1), b3 + hstep, voffB); PG8_STAGE(PG8_SA(1, 0), a3, voffA);
;             PG8_WAIT_V(8); PG8_WAIT_L(0); PG8_BAR; PG8_MMA(1, 0, At, B0); PG8_MMA(1, 1, At, B1); PG8_BAR; PG8_SCHED;
	s_setprio 1
	v_mfma_f32_16x16x32_bf16 v[60:63], v[152:155], v[184:187], 0
	v_mfma_f32_16x16x32_bf16 v[56:59], v[160:163], v[184:187], 0
	v_mfma_f32_16x16x32_bf16 v[44:47], v[152:155], v[192:195], 0
	v_mfma_f32_16x16x32_bf16 v[40:43], v[160:163], v[192:195], 0
	v_mfma_f32_16x16x32_bf16 v[28:31], v[152:155], v[200:203], 0
	v_mfma_f32_16x16x32_bf16 v[24:27], v[160:163], v[200:203], 0
	v_mfma_f32_16x16x32_bf16 v[12:15], v[152:155], v[208:211], 0
	v_mfma_f32_16x16x32_bf16 v[8:11], v[160:163], v[208:211], 0
	v_mfma_f32_16x16x32_bf16 v[60:63], v[156:159], v[188:191], v[60:63]
	v_mfma_f32_16x16x32_bf16 v[56:59], v[164:167], v[188:191], v[56:59]
	v_mfma_f32_16x16x32_bf16 v[44:47], v[156:159], v[196:199], v[44:47]
	v_mfma_f32_16x16x32_bf16 v[40:43], v[164:167], v[196:199], v[40:43]
	v_mfma_f32_16x16x32_bf16 v[28:31], v[156:159], v[204:207], v[28:31]
	v_mfma_f32_16x16x32_bf16 v[24:27], v[164:167], v[204:207], v[24:27]
	v_mfma_f32_16x16x32_bf16 v[12:15], v[156:159], v[212:215], v[12:15]
	v_mfma_f32_16x16x32_bf16 v[8:11], v[164:167], v[212:215], v[8:11]
	v_mfma_f32_16x16x32_bf16 v[52:55], v[168:171], v[184:187], 0
	v_mfma_f32_16x16x32_bf16 v[48:51], v[176:179], v[184:187], 0
	v_mfma_f32_16x16x32_bf16 v[36:39], v[168:171], v[192:195], 0
	v_mfma_f32_16x16x32_bf16 v[32:35], v[176:179], v[192:195], 0
	v_mfma_f32_16x16x32_bf16 v[20:23], v[168:171], v[200:203], 0
	v_mfma_f32_16x16x32_bf16 v[16:19], v[176:179], v[200:203], 0
	v_mfma_f32_16x16x32_bf16 v[4:7], v[168:171], v[208:211], 0
	v_mfma_f32_16x16x32_bf16 v[0:3], v[176:179], v[208:211], 0
	v_mfma_f32_16x16x32_bf16 v[52:55], v[172:175], v[188:191], v[52:55]
	v_mfma_f32_16x16x32_bf16 v[48:51], v[180:183], v[188:191], v[48:51]
	v_mfma_f32_16x16x32_bf16 v[36:39], v[172:175], v[196:199], v[36:39]
	v_mfma_f32_16x16x32_bf16 v[32:35], v[180:183], v[196:199], v[32:35]
	v_mfma_f32_16x16x32_bf16 v[20:23], v[172:175], v[204:207], v[20:23]
	v_mfma_f32_16x16x32_bf16 v[16:19], v[180:183], v[204:207], v[16:19]
	v_mfma_f32_16x16x32_bf16 v[4:7], v[172:175], v[212:215], v[4:7]
	v_mfma_f32_16x16x32_bf16 v[0:3], v[180:183], v[212:215], v[0:3]
	s_setprio 0
	s_barrier
	s_add_i32 s67, 0, 0x18000
	s_add_i32 s68, 0, 0x1c000
	v_add_u32_e32 v164, s67, v147
	v_add_u32_e32 v180, s68, v147
	ds_read_b128 v[152:155], v164
	ds_read_b128 v[156:159], v164 offset:1024
	ds_read_b128 v[160:163], v164 offset:2048
	ds_read_b128 v[164:167], v164 offset:3072
	ds_read_b128 v[168:171], v180
	ds_read_b128 v[172:175], v180 offset:1024
	ds_read_b128 v[176:179], v180 offset:2048
	ds_read_b128 v[180:183], v180 offset:3072
	s_add_u32 s36, s36, 0x80000
	s_addc_u32 s37, s37, 0
	s_mov_b32 m0, s52
	v_lshl_add_u64 v[224:225], s[36:37], 0, v[134:135]
	ds_read_b128 v[184:187], v151 offset:32768
	ds_read_b128 v[188:191], v151 offset:33792
	ds_read_b128 v[192:195], v151 offset:34816
	ds_read_b128 v[196:199], v151 offset:35840
	ds_read_b128 v[200:203], v151 offset:36864
	ds_read_b128 v[204:207], v151 offset:37888
	ds_read_b128 v[208:211], v151 offset:38912
	ds_read_b128 v[212:215], v151 offset:39936
	global_load_lds_dwordx4 v[224:225], off
	v_lshl_add_u64 v[224:225], s[36:37], 0, v[130:131]
	s_mov_b32 m0, s53
	s_nop 0
	global_load_lds_dwordx4 v[224:225], off
	s_waitcnt vmcnt(8)
	s_waitcnt lgkmcnt(0)
	s_barrier
	s_setprio 1
	v_mfma_f32_16x16x32_bf16 v[124:127], v[152:155], v[184:187], v[124:127]
	v_mfma_f32_16x16x32_bf16 v[120:123], v[160:163], v[184:187], v[120:123]
	v_mfma_f32_16x16x32_bf16 v[108:111], v[152:155], v[192:195], v[108:111]
	v_mfma_f32_16x16x32_bf16 v[104:107], v[160:163], v[192:195], v[104:107]
	v_mfma_f32_16x16x32_bf16 v[92:95], v[152:155], v[200:203], v[92:95]
	v_mfma_f32_16x16x32_bf16 v[88:91], v[160:163], v[200:203], v[88:91]
	v_mfma_f32_16x16x32_bf16 v[76:79], v[152:155], v[208:211], v[76:79]
	v_mfma_f32_16x16x32_bf16 v[72:75], v[160:163], v[208:211], v[72:75]
	v_mfma_f32_16x16x32_bf16 v[124:127], v[156:159], v[188:191], v[124:127]
	v_mfma_f32_16x16x32_bf16 v[120:123], v[164:167], v[188:191], v[120:123]
	v_mfma_f32_16x16x32_bf16 v[108:111], v[156:159], v[196:199], v[108:111]
	v_mfma_f32_16x16x32_bf16 v[104:107], v[164:167], v[196:199], v[104:107]
	v_mfma_f32_16x16x32_bf16 v[92:95], v[156:159], v[204:207], v[92:95]
	v_mfma_f32_16x16x32_bf16 v[88:91], v[164:167], v[204:207], v[88:91]
	v_mfma_f32_16x16x32_bf16 v[76:79], v[156:159], v[212:215], v[76:79]
	v_mfma_f32_16x16x32_bf16 v[72:75], v[164:167], v[212:215], v[72:75]
	v_mfma_f32_16x16x32_bf16 v[116:119], v[168:171], v[184:187], v[116:119]
	v_mfma_f32_16x16x32_bf16 v[112:115], v[176:179], v[184:187], v[112:115]
	v_mfma_f32_16x16x32_bf16 v[100:103], v[168:171], v[192:195], v[100:103]
	v_mfma_f32_16x16x32_bf16 v[96:99], v[176:179], v[192:195], v[96:99]
	v_mfma_f32_16x16x32_bf16 v[84:87], v[168:171], v[200:203], v[84:87]
	v_mfma_f32_16x16x32_bf16 v[80:83], v[176:179], v[200:203], v[80:83]
	v_mfma_f32_16x16x32_bf16 v[68:71], v[168:171], v[208:211], v[68:71]
	v_mfma_f32_16x16x32_bf16 v[64:67], v[176:179], v[208:211], v[64:67]
	v_mfma_f32_16x16x32_bf16 v[116:119], v[172:175], v[188:191], v[116:119]
	v_mfma_f32_16x16x32_bf16 v[112:115], v[180:183], v[188:191], v[112:115]
	v_mfma_f32_16x16x32_bf16 v[100:103], v[172:175], v[196:199], v[100:103]
	v_mfma_f32_16x16x32_bf16 v[96:99], v[180:183], v[196:199], v[96:99]
	v_mfma_f32_16x16x32_bf16 v[84:87], v[172:175], v[204:207], v[84:87]
	v_mfma_f32_16x16x32_bf16 v[80:83], v[180:183], v[204:207], v[80:83]
	v_mfma_f32_16x16x32_bf16 v[68:71], v[172:175], v[212:215], v[68:71]
	v_mfma_f32_16x16x32_bf16 v[64:67], v[180:183], v[212:215], v[64:67]
	s_setprio 0
	s_barrier
; #define PG8_STAGE(bufoff, gbase, voff) do { _Pragma("unroll") for (int _i = 0; _i < 2; ++_i) \
;         __builtin_amdgcn_global_load_lds((const unsigned*)((const char*)(gbase) + (voff)[_i]), (PG8_LAS unsigned*)(lds + (bufoff) + ldsw + _i * 8192), 16, 0, 0); } while (0)
; #define PG8_LDA(dst, b, h) do { _Pragma("unroll") for (int m = 0; m < 4; ++m) _Pragma("unroll") for (int k = 0; k < 2; ++k) dst[m][k] = *(const PG8_LAS bf16x8*)(lds + PG8_SA(b, h) + aoff + m * 2048 + k * 1024); } while (0)
; #define PG8_LDB(dst, b, h) do { _Pragma("unroll") for (int n = 0; n < 2; ++n) _Pragma("unroll") for (int k = 0; k < 2; ++k) dst[n][k] = *(const PG8_LAS bf16x8*)(lds + PG8_SB(b, h) + boff + n * 2048 + k * 1024); } while (0)
; template <class Epi, class Sched, bool ALIGN_EPI = false, bool SP2 = false>
; __device__ __forceinline__ void gemm_phase(PG8_LAS unsigned char* lds, const Gemm g, const Sched& S, const Epi& E) {
;     ...
;         for (int t = 0; t < nt; t += 2) {
;             const bool last = (t == nt - 2);
;             const char* a1 = cA + (size_t)(t + 1) * kstep;
;             const char* a2 = last ? nA : cA + (size_t)(t + 2) * kstep; const char* b2 = last ? nB : cB + (size_t)(t + 2) * kstep;
;             const char* a3 = a2 + kstep; const char* b3 = b2 + kstep;
;             if (last && has_next) S.a_ready(nxt);
;             if constexpr (SP2) {
;             PG8_LDB(B0, 0, 0); PG8_LDB(B1, 0, 1); PG8_SCHED; PG8_LDA(At, 0, 0); PG8_STAGE(PG8_SA(1, 1), a1 + hstep, voffA);
;             PG8_WAIT_V(8); PG8_WAIT_L(0); PG8_BAR; PG8_MMA(0, 0, At, B0); PG8_MMA(0, 1, At, B1); PG8_BAR; PG8_SCHED;
;             PG8_LDA(At, 0, 1); PG8_STAGE(PG8_SB(0, 0), b2, voffB); PG8_STAGE(PG8_SB(0, 1), b2 + hstep, voffB); PG8_STAGE(PG8_SA(0, 0), a2, voffA);
;             PG8_WAIT_V(8); PG8_WAIT_L(0); PG8_BAR; PG8_MMA(1, 0, At, B0); PG8_MMA(1, 1, At, B1); PG8_BAR; PG8_SCHED;
;             PG8_LDB(B0, 1, 0); PG8_LDB(B1, 1, 1); PG8_SCHED; PG8_LDA(At, 1, 0); PG8_STAGE(PG8_SA(0, 1), a2 + hstep, voffA);
;             PG8_WAIT_V(8); PG8_WAIT_L(0); PG8_BAR; PG8_MMA(0, 0, At, B0); PG8_MMA(0, 1, At, B1); PG8_BAR; PG8_SCHED;
;             PG8_LDA(At, 1, 1); PG8_STAGE(PG8_SB(1, 0), b3, voffB); PG8_STAGE(PG8_SB(1, 1), b3 + hstep, voffB); PG8_STAGE(PG8_SA(1, 0), a3, voffA);
;             PG8_WAIT_V(8); PG8_WAIT_L(0); PG8_BAR; PG8_MMA(1, 0, At, B0); PG8_MMA(1, 1, At, B1); PG8_BAR; PG8_SCHED;
	s_add_i32 s36, s67, s47
	v_lshl_add_u64 v[144:145], v[144:145], 0, s[16:17]
	s_mov_b32 m0, s36
	ds_read_b128 v[184:187], v151 offset:49152
	ds_read_b128 v[188:191], v151 offset:50176
	ds_read_b128 v[192:195], v151 offset:51200
	ds_read_b128 v[196:199], v151 offset:52224
	ds_read_b128 v[200:203], v151 offset:53248
	ds_read_b128 v[204:207], v151 offset:54272
	ds_read_b128 v[208:211], v151 offset:55296
	ds_read_b128 v[212:215], v151 offset:56320
	global_load_lds_dwordx4 v[144:145], off
	s_add_i32 m0, s36, 0x2000
	s_add_u32 s34, s34, 0x80080
	v_lshl_add_u64 v[144:145], v[218:219], 0, s[16:17]
	s_addc_u32 s35, s35, 0
	s_add_i32 s36, s68, s47
	global_load_lds_dwordx4 v[144:145], off
	v_lshl_add_u64 v[144:145], s[34:35], 0, v[132:133]
	s_mov_b32 m0, s36
	s_nop 0
	global_load_lds_dwordx4 v[144:145], off
	v_lshl_add_u64 v[144:145], s[34:35], 0, v[128:129]
	s_add_i32 m0, s36, 0x2000
	s_nop 0
	global_load_lds_dwordx4 v[144:145], off
	v_lshl_add_u64 v[144:145], v[220:221], 0, s[16:17]
	s_mov_b32 m0, s55
	s_nop 0
	global_load_lds_dwordx4 v[144:145], off
	v_lshl_add_u64 v[144:145], v[222:223], 0, s[16:17]
	s_mov_b32 m0, s59
	s_nop 0
	global_load_lds_dwordx4 v[144:145], off
	s_waitcnt vmcnt(8)
	s_waitcnt lgkmcnt(0)
	s_barrier
	s_setprio 1
	v_mfma_f32_16x16x32_bf16 v[60:63], v[152:155], v[184:187], v[60:63]
	v_mfma_f32_16x16x32_bf16 v[56:59], v[160:163], v[184:187], v[56:59]
	v_mfma_f32_16x16x32_bf16 v[44:47], v[152:155], v[192:195], v[44:47]
	v_mfma_f32_16x16x32_bf16 v[40:43], v[160:163], v[192:195], v[40:43]
	v_mfma_f32_16x16x32_bf16 v[28:31], v[152:155], v[200:203], v[28:31]
	v_mfma_f32_16x16x32_bf16 v[24:27], v[160:163], v[200:203], v[24:27]
	v_mfma_f32_16x16x32_bf16 v[12:15], v[152:155], v[208:211], v[12:15]
	v_mfma_f32_16x16x32_bf16 v[8:11], v[160:163], v[208:211], v[8:11]
	v_mfma_f32_16x16x32_bf16 v[60:63], v[156:159], v[188:191], v[60:63]
	v_mfma_f32_16x16x32_bf16 v[56:59], v[164:167], v[188:191], v[56:59]
	v_mfma_f32_16x16x32_bf16 v[44:47], v[156:159], v[196:199], v[44:47]
	v_mfma_f32_16x16x32_bf16 v[40:43], v[164:167], v[196:199], v[40:43]
	v_mfma_f32_16x16x32_bf16 v[28:31], v[156:159], v[204:207], v[28:31]
	v_mfma_f32_16x16x32_bf16 v[24:27], v[164:167], v[204:207], v[24:27]
	v_mfma_f32_16x16x32_bf16 v[12:15], v[156:159], v[212:215], v[12:15]
	v_mfma_f32_16x16x32_bf16 v[8:11], v[164:167], v[212:215], v[8:11]
	v_mfma_f32_16x16x32_bf16 v[52:55], v[168:171], v[184:187], v[52:55]
	v_mfma_f32_16x16x32_bf16 v[48:51], v[176:179], v[184:187], v[48:51]
	v_mfma_f32_16x16x32_bf16 v[36:39], v[168:171], v[192:195], v[36:39]
	v_mfma_f32_16x16x32_bf16 v[32:35], v[176:179], v[192:195], v[32:35]
	v_mfma_f32_16x16x32_bf16 v[20:23], v[168:171], v[200:203], v[20:23]
	v_mfma_f32_16x16x32_bf16 v[16:19], v[176:179], v[200:203], v[16:19]
	v_mfma_f32_16x16x32_bf16 v[4:7], v[168:171], v[208:211], v[4:7]
	v_mfma_f32_16x16x32_bf16 v[0:3], v[176:179], v[208:211], v[0:3]
	v_mfma_f32_16x16x32_bf16 v[52:55], v[172:175], v[188:191], v[52:55]
	v_mfma_f32_16x16x32_bf16 v[48:51], v[180:183], v[188:191], v[48:51]
	v_mfma_f32_16x16x32_bf16 v[36:39], v[172:175], v[196:199], v[36:39]
	v_mfma_f32_16x16x32_bf16 v[32:35], v[180:183], v[196:199], v[32:35]
	v_mfma_f32_16x16x32_bf16 v[20:23], v[172:175], v[204:207], v[20:23]
	v_mfma_f32_16x16x32_bf16 v[16:19], v[180:183], v[204:207], v[16:19]
	v_mfma_f32_16x16x32_bf16 v[4:7], v[172:175], v[212:215], v[4:7]
	v_mfma_f32_16x16x32_bf16 v[0:3], v[180:183], v[212:215], v[0:3]
	s_setprio 0
	s_barrier
	s_add_i32 s66, s66, 2
	s_add_u32 s30, s30, 0x100
	s_addc_u32 s31, s31, 0
	s_add_u32 s64, s64, 0x100
	s_addc_u32 s65, s65, 0
	s_cmp_gt_u32 s66, 29
.LBB0_775:
	ds_read_b128 v[152:155], v149
	ds_read_b128 v[156:159], v149 offset:1024
	ds_read_b128 v[160:163], v149 offset:2048
	ds_read_b128 v[164:167], v149 offset:3072
	ds_read_b128 v[168:171], v150
	ds_read_b128 v[172:175], v150 offset:1024
	ds_read_b128 v[176:179], v150 offset:2048
	ds_read_b128 v[180:183], v150 offset:3072
	s_add_u32 s34, s30, 0xfff80080
	s_addc_u32 s35, s31, -1
	s_cmp_eq_u32 s66, 28
	s_cselect_b32 s37, s23, s35
	s_cselect_b32 s36, s62, s34
	s_cselect_b32 s35, s21, s65
	s_cselect_b32 s34, s63, s64
	v_lshl_add_u64 v[144:145], s[30:31], 0, v[136:137]
	s_add_i32 m0, s50, 0xc000
	ds_read_b128 v[184:187], v151
	ds_read_b128 v[188:191], v151 offset:1024
	ds_read_b128 v[192:195], v151 offset:2048
	ds_read_b128 v[196:199], v151 offset:3072
	ds_read_b128 v[200:203], v151 offset:4096
	ds_read_b128 v[204:207], v151 offset:5120
	ds_read_b128 v[208:211], v151 offset:6144
	ds_read_b128 v[212:215], v151 offset:7168
	global_load_lds_dwordx4 v[144:145], off
	v_lshl_add_u64 v[144:145], s[30:31], 0, v[138:139]
	s_add_i32 m0, s50, 0xe000
	s_nop 0
	global_load_lds_dwordx4 v[144:145], off
	s_waitcnt vmcnt(8)
	s_waitcnt lgkmcnt(0)
	s_barrier
; #define PG8_STAGE(bufoff, gbase, voff) do { _Pragma("unroll") for (int _i = 0; _i < 2; ++_i) \
;         __builtin_amdgcn_global_load_lds((const unsigned*)((const char*)(gbase) + (voff)[_i]), (PG8_LAS unsigned*)(lds + (bufoff) + ldsw + _i * 8192), 16, 0, 0); } while (0)
; #define PG8_LDA(dst, b, h) do { _Pragma("unroll") for (int m = 0; m < 4; ++m) _Pragma("unroll") for (int k = 0; k < 2; ++k) dst[m][k] = *(const PG8_LAS bf16x8*)(lds + PG8_SA(b, h) + aoff + m * 2048 + k * 1024); } while (0)
; #define PG8_LDB(dst, b, h) do { _Pragma("unroll") for (int n = 0; n < 2; ++n) _Pragma("unroll") for (int k = 0; k < 2; ++k) dst[n][k] = *(const PG8_LAS bf16x8*)(lds + PG8_SB(b, h) + boff + n * 2048 + k * 1024); } while (0)
; #define PG8_MMA(ai, bj, At, Bt) do { __builtin_amdgcn_s_setprio(1); _Pragma("unroll") for (int m = 0; m < 4; ++m) _Pragma("unroll") for (int n = 0; n < 2; ++n) _Pragma("unroll") for (int k = 0; k < 2; ++k) \
;         acc[ai][bj][m][n] = __builtin_amdgcn_mfma_f32_16x16x32_bf16(Bt[n][k], At[m][k], acc[ai][bj][m][n], 0, 0, 0); __builtin_amdgcn_s_setprio(0); } while (0)
; #define PG8_WAIT_V(n) asm volatile("s_waitcnt vmcnt(" #n ")" ::: "memory")
; template <class Epi, class Sched, bool ALIGN_EPI = false, bool SP2 = false>
; __device__ __forceinline__ void gemm_phase(PG8_LAS unsigned char* lds, const Gemm g, const Sched& S, const Epi& E) {
;     ...
;             PG8_LDB(B0, 0, 0); PG8_LDB(B1, 0, 1); PG8_SCHED; PG8_LDA(At, 0, 0); PG8_STAGE(PG8_SA(1, 1), a1 + hstep, voffA);
;             PG8_WAIT_V(8); PG8_WAIT_L(0); PG8_BAR; PG8_MMA(0, 0, At, B0); PG8_MMA(0, 1, At, B1); PG8_BAR; PG8_SCHED;
;             PG8_LDA(At, 0, 1); PG8_STAGE(PG8_SB(0, 0), b2, voffB); PG8_STAGE(PG8_SB(0, 1), b2 + hstep, voffB); PG8_STAGE(PG8_SA(0, 0), a2, voffA);
;             PG8_WAIT_V(8); PG8_WAIT_L(0); PG8_BAR; PG8_MMA(1, 0, At, B0); PG8_MMA(1, 1, At, B1); PG8_BAR; PG8_SCHED;
;             PG8_LDB(B0, 1, 0); PG8_LDB(B1, 1, 1); PG8_SCHED; PG8_LDA(At, 1, 0); PG8_STAGE(PG8_SA(0, 1), a2 + hstep, voffA);
;             PG8_WAIT_V(8); PG8_WAIT_L(0); PG8_BAR; PG8_MMA(0, 0, At, B0); PG8_MMA(0, 1, At, B1); PG8_BAR; PG8_SCHED;
;             PG8_LDA(At, 1, 1); PG8_STAGE(PG8_SB(1, 0), b3, voffB); PG8_STAGE(PG8_SB(1, 1), b3 + hstep, voffB); PG8_STAGE(PG8_SA(1, 0), a3, voffA);
;             PG8_WAIT_V(8); PG8_WAIT_L(0); PG8_BAR; PG8_MMA(1, 0, At, B0); PG8_MMA(1, 1, At, B1); PG8_BAR; PG8_SCHED;
	s_setprio 1
	v_mfma_f32_16x16x32_bf16 v[124:127], v[152:155], v[184:187], v[124:127]
	v_mfma_f32_16x16x32_bf16 v[120:123], v[160:163], v[184:187], v[120:123]
	v_mfma_f32_16x16x32_bf16 v[108:111], v[152:155], v[192:195], v[108:111]
	v_mfma_f32_16x16x32_bf16 v[104:107], v[160:163], v[192:195], v[104:107]
	v_mfma_f32_16x16x32_bf16 v[92:95], v[152:155], v[200:203], v[92:95]
	v_mfma_f32_16x16x32_bf16 v[88:91], v[160:163], v[200:203], v[88:91]
	v_mfma_f32_16x16x32_bf16 v[76:79], v[152:155], v[208:211], v[76:79]
	v_mfma_f32_16x16x32_bf16 v[72:75], v[160:163], v[208:211], v[72:75]
	v_mfma_f32_16x16x32_bf16 v[124:127], v[156:159], v[188:191], v[124:127]
	v_mfma_f32_16x16x32_bf16 v[120:123], v[164:167], v[188:191], v[120:123]
	v_mfma_f32_16x16x32_bf16 v[108:111], v[156:159], v[196:199], v[108:111]
	v_mfma_f32_16x16x32_bf16 v[104:107], v[164:167], v[196:199], v[104:107]
	v_mfma_f32_16x16x32_bf16 v[92:95], v[156:159], v[204:207], v[92:95]
	v_mfma_f32_16x16x32_bf16 v[88:91], v[164:167], v[204:207], v[88:91]
	v_mfma_f32_16x16x32_bf16 v[76:79], v[156:159], v[212:215], v[76:79]
	v_mfma_f32_16x16x32_bf16 v[72:75], v[164:167], v[212:215], v[72:75]
	v_mfma_f32_16x16x32_bf16 v[116:119], v[168:171], v[184:187], v[116:119]
	v_mfma_f32_16x16x32_bf16 v[112:115], v[176:179], v[184:187], v[112:115]
	v_mfma_f32_16x16x32_bf16 v[100:103], v[168:171], v[192:195], v[100:103]
	v_mfma_f32_16x16x32_bf16 v[96:99], v[176:179], v[192:195], v[96:99]
	v_mfma_f32_16x16x32_bf16 v[84:87], v[168:171], v[200:203], v[84:87]
	v_mfma_f32_16x16x32_bf16 v[80:83], v[176:179], v[200:203], v[80:83]
	v_mfma_f32_16x16x32_bf16 v[68:71], v[168:171], v[208:211], v[68:71]
	v_mfma_f32_16x16x32_bf16 v[64:67], v[176:179], v[208:211], v[64:67]
	v_mfma_f32_16x16x32_bf16 v[116:119], v[172:175], v[188:191], v[116:119]
	v_mfma_f32_16x16x32_bf16 v[112:115], v[180:183], v[188:191], v[112:115]
	v_mfma_f32_16x16x32_bf16 v[100:103], v[172:175], v[196:199], v[100:103]
	v_mfma_f32_16x16x32_bf16 v[96:99], v[180:183], v[196:199], v[96:99]
	v_mfma_f32_16x16x32_bf16 v[84:87], v[172:175], v[204:207], v[84:87]
	v_mfma_f32_16x16x32_bf16 v[80:83], v[180:183], v[204:207], v[80:83]
	v_mfma_f32_16x16x32_bf16 v[68:71], v[172:175], v[212:215], v[68:71]
	v_mfma_f32_16x16x32_bf16 v[64:67], v[180:183], v[212:215], v[64:67]
	s_setprio 0
	s_barrier
	s_add_i32 s67, s60, s47
	v_lshl_add_u64 v[144:145], s[34:35], 0, v[132:133]
	s_mov_b32 m0, s67
	ds_read_b128 v[184:187], v151 offset:16384
	ds_read_b128 v[188:191], v151 offset:17408
	ds_read_b128 v[192:195], v151 offset:18432
	ds_read_b128 v[196:199], v151 offset:19456
	ds_read_b128 v[200:203], v151 offset:20480
	ds_read_b128 v[204:207], v151 offset:21504
	ds_read_b128 v[208:211], v151 offset:22528
	ds_read_b128 v[212:215], v151 offset:23552
	global_load_lds_dwordx4 v[144:145], off
	s_add_i32 m0, s67, 0x2000
	s_add_u32 s68, s34, 0x80000
	v_lshl_add_u64 v[218:219], s[34:35], 0, v[128:129]
	s_addc_u32 s69, s35, 0
	s_add_i32 s67, s61, s47
	global_load_lds_dwordx4 v[218:219], off
	v_lshl_add_u64 v[220:221], s[68:69], 0, v[132:133]
	s_mov_b32 m0, s67
	v_lshl_add_u64 v[222:223], s[36:37], 0, v[130:131]
	global_load_lds_dwordx4 v[220:221], off
	v_lshl_add_u64 v[220:221], s[68:69], 0, v[128:129]
	s_add_i32 m0, s67, 0x2000
	s_nop 0
	global_load_lds_dwordx4 v[220:221], off
	v_lshl_add_u64 v[220:221], s[36:37], 0, v[134:135]
	s_mov_b32 m0, s50
	s_nop 0
	global_load_lds_dwordx4 v[220:221], off
	s_mov_b32 m0, s51
	s_nop 0
	global_load_lds_dwordx4 v[222:223], off
	s_waitcnt vmcnt(8)
	s_waitcnt lgkmcnt(0)
	s_barrier
	s_setprio 1
	v_mfma_f32_16x16x32_bf16 v[60:63], v[152:155], v[184:187], v[60:63]
	v_mfma_f32_16x16x32_bf16 v[56:59], v[160:163], v[184:187], v[56:59]
	v_mfma_f32_16x16x32_bf16 v[44:47], v[152:155], v[192:195], v[44:47]
	v_mfma_f32_16x16x32_bf16 v[40:43], v[160:163], v[192:195], v[40:43]
	v_mfma_f32_16x16x32_bf16 v[28:31], v[152:155], v[200:203], v[28:31]
	v_mfma_f32_16x16x32_bf16 v[24:27], v[160:163], v[200:203], v[24:27]
	v_mfma_f32_16x16x32_bf16 v[12:15], v[152:155], v[208:211], v[12:15]
	v_mfma_f32_16x16x32_bf16 v[8:11], v[160:163], v[208:211], v[8:11]
	v_mfma_f32_16x16x32_bf16 v[60:63], v[156:159], v[188:191], v[60:63]
	v_mfma_f32_16x16x32_bf16 v[56:59], v[164:167], v[188:191], v[56:59]
	v_mfma_f32_16x16x32_bf16 v[44:47], v[156:159], v[196:199], v[44:47]
	v_mfma_f32_16x16x32_bf16 v[40:43], v[164:167], v[196:199], v[40:43]
	v_mfma_f32_16x16x32_bf16 v[28:31], v[156:159], v[204:207], v[28:31]
	v_mfma_f32_16x16x32_bf16 v[24:27], v[164:167], v[204:207], v[24:27]
	v_mfma_f32_16x16x32_bf16 v[12:15], v[156:159], v[212:215], v[12:15]
	v_mfma_f32_16x16x32_bf16 v[8:11], v[164:167], v[212:215], v[8:11]
	v_mfma_f32_16x16x32_bf16 v[52:55], v[168:171], v[184:187], v[52:55]
	v_mfma_f32_16x16x32_bf16 v[48:51], v[176:179], v[184:187], v[48:51]
	v_mfma_f32_16x16x32_bf16 v[36:39], v[168:171], v[192:195], v[36:39]
	v_mfma_f32_16x16x32_bf16 v[32:35], v[176:179], v[192:195], v[32:35]
	v_mfma_f32_16x16x32_bf16 v[20:23], v[168:171], v[200:203], v[20:23]
	v_mfma_f32_16x16x32_bf16 v[16:19], v[176:179], v[200:203], v[16:19]
	v_mfma_f32_16x16x32_bf16 v[4:7], v[168:171], v[208:211], v[4:7]
	v_mfma_f32_16x16x32_bf16 v[0:3], v[176:179], v[208:211], v[0:3]
	v_mfma_f32_16x16x32_bf16 v[52:55], v[172:175], v[188:191], v[52:55]
	v_mfma_f32_16x16x32_bf16 v[48:51], v[180:183], v[188:191], v[48:51]
	v_mfma_f32_16x16x32_bf16 v[36:39], v[172:175], v[196:199], v[36:39]
	v_mfma_f32_16x16x32_bf16 v[32:35], v[180:183], v[196:199], v[32:35]
	v_mfma_f32_16x16x32_bf16 v[20:23], v[172:175], v[204:207], v[20:23]
	v_mfma_f32_16x16x32_bf16 v[16:19], v[180:183], v[204:207], v[16:19]
	v_mfma_f32_16x16x32_bf16 v[4:7], v[172:175], v[212:215], v[4:7]
	v_mfma_f32_16x16x32_bf16 v[0:3], v[180:183], v[212:215], v[0:3]
	s_setprio 0
	s_barrier
; #define PG8_STAGE(bufoff, gbase, voff) do { _Pragma("unroll") for (int _i = 0; _i < 2; ++_i) \
;         __builtin_amdgcn_global_load_lds((const unsigned*)((const char*)(gbase) + (voff)[_i]), (PG8_LAS unsigned*)(lds + (bufoff) + ldsw + _i * 8192), 16, 0, 0); } while (0)
; #define PG8_LDA(dst, b, h) do { _Pragma("unroll") for (int m = 0; m < 4; ++m) _Pragma("unroll") for (int k = 0; k < 2; ++k) dst[m][k] = *(const PG8_LAS bf16x8*)(lds + PG8_SA(b, h) + aoff + m * 2048 + k * 1024); } while (0)
; #define PG8_LDB(dst, b, h) do { _Pragma("unroll") for (int n = 0; n < 2; ++n) _Pragma("unroll") for (int k = 0; k < 2; ++k) dst[n][k] = *(const PG8_LAS bf16x8*)(lds + PG8_SB(b, h) + boff + n * 2048 + k * 1024); } while (0)
; #define PG8_MMA(ai, bj, At, Bt) do { __builtin_amdgcn_s_setprio(1); _Pragma("unroll") for (int m = 0; m < 4; ++m) _Pragma("unroll") for (int n = 0; n < 2; ++n) _Pragma("unroll") for (int k = 0; k < 2; ++k) \
;         acc[ai][bj][m][n] = __builtin_amdgcn_mfma_f32_16x16x32_bf16(Bt[n][k], At[m][k], acc[ai][bj][m][n], 0, 0, 0); __builtin_amdgcn_s_setprio(0); } while (0)
; #define PG8_WAIT_V(n) asm volatile("s_waitcnt vmcnt(" #n ")" ::: "memory")
; #define PG8_WAIT_L(n) asm volatile("s_waitcnt lgkmcnt(" #n ")" ::: "memory")
; #define PG8_BAR __builtin_amdgcn_s_barrier()
; #define PG8_SCHED __builtin_amdgcn_sched_barrier(0)
; template <class Epi, class Sched, bool ALIGN_EPI = false, bool SP2 = false>
; __device__ __forceinline__ void gemm_phase(PG8_LAS unsigned char* lds, const Gemm g, const Sched& S, const Epi& E) {
;     ...
;             PG8_LDB(B0, 1, 0); PG8_LDB(B1, 1, 1); PG8_SCHED; PG8_LDA(At, 1, 0); PG8_STAGE(PG8_SA(0, 1), a2 + hstep, voffA);
;             PG8_WAIT_V(8); PG8_WAIT_L(0); PG8_BAR; PG8_MMA(0, 0, At, B0); PG8_MMA(0, 1, At, B1); PG8_BAR; PG8_SCHED;
	s_add_i32 s67, 0, 0x18000
	s_add_i32 s68, 0, 0x1c000
	v_add_u32_e32 v164, s67, v147
	v_add_u32_e32 v180, s68, v147
	ds_read_b128 v[152:155], v164
	ds_read_b128 v[156:159], v164 offset:1024
	ds_read_b128 v[160:163], v164 offset:2048
	ds_read_b128 v[164:167], v164 offset:3072
	ds_read_b128 v[168:171], v180
	ds_read_b128 v[172:175], v180 offset:1024
	ds_read_b128 v[176:179], v180 offset:2048
	ds_read_b128 v[180:183], v180 offset:3072
	s_add_u32 s36, s36, 0x80000
	s_addc_u32 s37, s37, 0
	s_mov_b32 m0, s52
	v_lshl_add_u64 v[224:225], s[36:37], 0, v[134:135]
	ds_read_b128 v[184:187], v151 offset:32768
	ds_read_b128 v[188:191], v151 offset:33792
	ds_read_b128 v[192:195], v151 offset:34816
	ds_read_b128 v[196:199], v151 offset:35840
	ds_read_b128 v[200:203], v151 offset:36864
	ds_read_b128 v[204:207], v151 offset:37888
	ds_read_b128 v[208:211], v151 offset:38912
	ds_read_b128 v[212:215], v151 offset:39936
	global_load_lds_dwordx4 v[224:225], off
	v_lshl_add_u64 v[224:225], s[36:37], 0, v[130:131]
	s_mov_b32 m0, s53
	s_nop 0
	global_load_lds_dwordx4 v[224:225], off
	s_waitcnt vmcnt(8)
	s_waitcnt lgkmcnt(0)
	s_barrier
	s_setprio 1
	v_mfma_f32_16x16x32_bf16 v[124:127], v[152:155], v[184:187], v[124:127]
	v_mfma_f32_16x16x32_bf16 v[120:123], v[160:163], v[184:187], v[120:123]
	v_mfma_f32_16x16x32_bf16 v[108:111], v[152:155], v[192:195], v[108:111]
	v_mfma_f32_16x16x32_bf16 v[104:107], v[160:163], v[192:195], v[104:107]
	v_mfma_f32_16x16x32_bf16 v[92:95], v[152:155], v[200:203], v[92:95]
	v_mfma_f32_16x16x32_bf16 v[88:91], v[160:163], v[200:203], v[88:91]
	v_mfma_f32_16x16x32_bf16 v[76:79], v[152:155], v[208:211], v[76:79]
	v_mfma_f32_16x16x32_bf16 v[72:75], v[160:163], v[208:211], v[72:75]
	v_mfma_f32_16x16x32_bf16 v[124:127], v[156:159], v[188:191], v[124:127]
	v_mfma_f32_16x16x32_bf16 v[120:123], v[164:167], v[188:191], v[120:123]
	v_mfma_f32_16x16x32_bf16 v[108:111], v[156:159], v[196:199], v[108:111]
	v_mfma_f32_16x16x32_bf16 v[104:107], v[164:167], v[196:199], v[104:107]
	v_mfma_f32_16x16x32_bf16 v[92:95], v[156:159], v[204:207], v[92:95]
	v_mfma_f32_16x16x32_bf16 v[88:91], v[164:167], v[204:207], v[88:91]
	v_mfma_f32_16x16x32_bf16 v[76:79], v[156:159], v[212:215], v[76:79]
	v_mfma_f32_16x16x32_bf16 v[72:75], v[164:167], v[212:215], v[72:75]
	v_mfma_f32_16x16x32_bf16 v[116:119], v[168:171], v[184:187], v[116:119]
	v_mfma_f32_16x16x32_bf16 v[112:115], v[176:179], v[184:187], v[112:115]
	v_mfma_f32_16x16x32_bf16 v[100:103], v[168:171], v[192:195], v[100:103]
	v_mfma_f32_16x16x32_bf16 v[96:99], v[176:179], v[192:195], v[96:99]
	v_mfma_f32_16x16x32_bf16 v[84:87], v[168:171], v[200:203], v[84:87]
	v_mfma_f32_16x16x32_bf16 v[80:83], v[176:179], v[200:203], v[80:83]
	v_mfma_f32_16x16x32_bf16 v[68:71], v[168:171], v[208:211], v[68:71]
	v_mfma_f32_16x16x32_bf16 v[64:67], v[176:179], v[208:211], v[64:67]
	v_mfma_f32_16x16x32_bf16 v[116:119], v[172:175], v[188:191], v[116:119]
	v_mfma_f32_16x16x32_bf16 v[112:115], v[180:183], v[188:191], v[112:115]
	v_mfma_f32_16x16x32_bf16 v[100:103], v[172:175], v[196:199], v[100:103]
	v_mfma_f32_16x16x32_bf16 v[96:99], v[180:183], v[196:199], v[96:99]
	v_mfma_f32_16x16x32_bf16 v[84:87], v[172:175], v[204:207], v[84:87]
	v_mfma_f32_16x16x32_bf16 v[80:83], v[180:183], v[204:207], v[80:83]
	v_mfma_f32_16x16x32_bf16 v[68:71], v[172:175], v[212:215], v[68:71]
	v_mfma_f32_16x16x32_bf16 v[64:67], v[180:183], v[212:215], v[64:67]
	s_setprio 0
	s_barrier
; #define PG8_STAGE(bufoff, gbase, voff) do { _Pragma("unroll") for (int _i = 0; _i < 2; ++_i) \
;         __builtin_amdgcn_global_load_lds((const unsigned*)((const char*)(gbase) + (voff)[_i]), (PG8_LAS unsigned*)(lds + (bufoff) + ldsw + _i * 8192), 16, 0, 0); } while (0)
; #define PG8_LDA(dst, b, h) do { _Pragma("unroll") for (int m = 0; m < 4; ++m) _Pragma("unroll") for (int k = 0; k < 2; ++k) dst[m][k] = *(const PG8_LAS bf16x8*)(lds + PG8_SA(b, h) + aoff + m * 2048 + k * 1024); } while (0)
; #define PG8_MMA(ai, bj, At, Bt) do { __builtin_amdgcn_s_setprio(1); _Pragma("unroll") for (int m = 0; m < 4; ++m) _Pragma("unroll") for (int n = 0; n < 2; ++n) _Pragma("unroll") for (int k = 0; k < 2; ++k) \
;         acc[ai][bj][m][n] = __builtin_amdgcn_mfma_f32_16x16x32_bf16(Bt[n][k], At[m][k], acc[ai][bj][m][n], 0, 0, 0); __builtin_amdgcn_s_setprio(0); } while (0)
; #define PG8_WAIT_V(n) asm volatile("s_waitcnt vmcnt(" #n ")" ::: "memory")
; #define PG8_WAIT_L(n) asm volatile("s_waitcnt lgkmcnt(" #n ")" ::: "memory")
; #define PG8_BAR __builtin_amdgcn_s_barrier()
; #define PG8_SCHED __builtin_amdgcn_sched_barrier(0)
; template <class Epi, class Sched, bool ALIGN_EPI = false, bool SP2 = false>
; __device__ __forceinline__ void gemm_phase(PG8_LAS unsigned char* lds, const Gemm g, const Sched& S, const Epi& E) {
;     ...
;             PG8_LDA(At, 1, 1); PG8_STAGE(PG8_SB(1, 0), b3, voffB); PG8_STAGE(PG8_SB(1, 1), b3 + hstep, voffB); PG8_STAGE(PG8_SA(1, 0), a3, voffA);
;             PG8_WAIT_V(8); PG8_WAIT_L(0); PG8_BAR; PG8_MMA(1, 0, At, B0); PG8_MMA(1, 1, At, B1); PG8_BAR; PG8_SCHED;
;     ...
;         if constexpr (ALIGN_EPI) { if (wr == 0) PG8_BAR; }
	s_add_i32 s36, s67, s47
	v_lshl_add_u64 v[144:145], v[144:145], 0, s[16:17]
	s_mov_b32 m0, s36
	ds_read_b128 v[184:187], v151 offset:49152
	ds_read_b128 v[188:191], v151 offset:50176
	ds_read_b128 v[192:195], v151 offset:51200
	ds_read_b128 v[196:199], v151 offset:52224
	ds_read_b128 v[200:203], v151 offset:53248
	ds_read_b128 v[204:207], v151 offset:54272
	ds_read_b128 v[208:211], v151 offset:55296
	ds_read_b128 v[212:215], v151 offset:56320
	global_load_lds_dwordx4 v[144:145], off
	s_add_i32 m0, s36, 0x2000
	s_add_u32 s34, s34, 0x80080
	v_lshl_add_u64 v[144:145], v[218:219], 0, s[16:17]
	s_addc_u32 s35, s35, 0
	s_add_i32 s36, s68, s47
	global_load_lds_dwordx4 v[144:145], off
	v_lshl_add_u64 v[144:145], s[34:35], 0, v[132:133]
	s_mov_b32 m0, s36
	s_nop 0
	global_load_lds_dwordx4 v[144:145], off
	v_lshl_add_u64 v[144:145], s[34:35], 0, v[128:129]
	s_add_i32 m0, s36, 0x2000
	s_nop 0
	global_load_lds_dwordx4 v[144:145], off
	v_lshl_add_u64 v[144:145], v[220:221], 0, s[16:17]
	s_mov_b32 m0, s55
	s_nop 0
	global_load_lds_dwordx4 v[144:145], off
	v_lshl_add_u64 v[144:145], v[222:223], 0, s[16:17]
	s_mov_b32 m0, s59
	s_nop 0
	global_load_lds_dwordx4 v[144:145], off
	s_waitcnt vmcnt(8)
	s_waitcnt lgkmcnt(0)
	s_barrier
	s_setprio 1
	v_mfma_f32_16x16x32_bf16 v[60:63], v[152:155], v[184:187], v[60:63]
	v_mfma_f32_16x16x32_bf16 v[56:59], v[160:163], v[184:187], v[56:59]
	v_mfma_f32_16x16x32_bf16 v[44:47], v[152:155], v[192:195], v[44:47]
	v_mfma_f32_16x16x32_bf16 v[40:43], v[160:163], v[192:195], v[40:43]
	v_mfma_f32_16x16x32_bf16 v[28:31], v[152:155], v[200:203], v[28:31]
	v_mfma_f32_16x16x32_bf16 v[24:27], v[160:163], v[200:203], v[24:27]
	v_mfma_f32_16x16x32_bf16 v[12:15], v[152:155], v[208:211], v[12:15]
	v_mfma_f32_16x16x32_bf16 v[8:11], v[160:163], v[208:211], v[8:11]
	v_mfma_f32_16x16x32_bf16 v[60:63], v[156:159], v[188:191], v[60:63]
	v_mfma_f32_16x16x32_bf16 v[56:59], v[164:167], v[188:191], v[56:59]
	v_mfma_f32_16x16x32_bf16 v[44:47], v[156:159], v[196:199], v[44:47]
	v_mfma_f32_16x16x32_bf16 v[40:43], v[164:167], v[196:199], v[40:43]
	v_mfma_f32_16x16x32_bf16 v[28:31], v[156:159], v[204:207], v[28:31]
	v_mfma_f32_16x16x32_bf16 v[24:27], v[164:167], v[204:207], v[24:27]
	v_mfma_f32_16x16x32_bf16 v[12:15], v[156:159], v[212:215], v[12:15]
	v_mfma_f32_16x16x32_bf16 v[8:11], v[164:167], v[212:215], v[8:11]
	v_mfma_f32_16x16x32_bf16 v[52:55], v[168:171], v[184:187], v[52:55]
	v_mfma_f32_16x16x32_bf16 v[48:51], v[176:179], v[184:187], v[48:51]
	v_mfma_f32_16x16x32_bf16 v[36:39], v[168:171], v[192:195], v[36:39]
	v_mfma_f32_16x16x32_bf16 v[32:35], v[176:179], v[192:195], v[32:35]
	v_mfma_f32_16x16x32_bf16 v[20:23], v[168:171], v[200:203], v[20:23]
	v_mfma_f32_16x16x32_bf16 v[16:19], v[176:179], v[200:203], v[16:19]
	v_mfma_f32_16x16x32_bf16 v[4:7], v[168:171], v[208:211], v[4:7]
	v_mfma_f32_16x16x32_bf16 v[0:3], v[176:179], v[208:211], v[0:3]
	v_mfma_f32_16x16x32_bf16 v[52:55], v[172:175], v[188:191], v[52:55]
	v_mfma_f32_16x16x32_bf16 v[48:51], v[180:183], v[188:191], v[48:51]
	v_mfma_f32_16x16x32_bf16 v[36:39], v[172:175], v[196:199], v[36:39]
	v_mfma_f32_16x16x32_bf16 v[32:35], v[180:183], v[196:199], v[32:35]
	v_mfma_f32_16x16x32_bf16 v[20:23], v[172:175], v[204:207], v[20:23]
	v_mfma_f32_16x16x32_bf16 v[16:19], v[180:183], v[204:207], v[16:19]
	v_mfma_f32_16x16x32_bf16 v[4:7], v[172:175], v[212:215], v[4:7]
	v_mfma_f32_16x16x32_bf16 v[0:3], v[180:183], v[212:215], v[0:3]
	s_setprio 0
	s_barrier
	s_add_i32 s66, s66, 2
	s_add_u32 s30, s30, 0x100
	s_addc_u32 s31, s31, 0
	s_add_u32 s64, s64, 0x100
	s_addc_u32 s65, s65, 0
	s_cmp_gt_u32 s66, 29
	s_cbranch_scc0 .LBB0_775
	s_and_b64 vcc, exec, s[18:19]
	s_cbranch_vccz .LBB0_778
	s_barrier

; __device__ __forceinline__ unsigned xb_ld(unsigned* p)              { return __hip_atomic_load(p, __ATOMIC_RELAXED, __HIP_MEMORY_SCOPE_AGENT); }
; __device__ __forceinline__ unsigned xb_add(unsigned* p, unsigned v) { return __hip_atomic_fetch_add(p, v, __ATOMIC_RELAXED, __HIP_MEMORY_SCOPE_AGENT); }
; #define XB_SPIN(cond, bar) do { unsigned _sp = 0; while (cond) { __builtin_amdgcn_s_sleep(1); \
;     if ((++_sp & 255u) == 0u) { if (xb_ld(&(bar)[XB_TMO])) break; if (_sp > XB_SPIN_CAP) { atomicAdd(&(bar)[XB_TMO], 1u); break; } } } } while (0)
; __device__ __forceinline__ void xcd_barrier(const XcdBarrier& b) {
;     ...
;         if (old + 1u == (gen + 1u) * nloc) {
;             __builtin_amdgcn_fence(__ATOMIC_RELEASE, "agent");
;             asm volatile("s_waitcnt vmcnt(0)" ::: "memory");
;             const unsigned og = xb_add(&bar[XB_TOP], 1u);
;             const unsigned tg = og / nx;
;             if (og + 1u == (tg + 1u) * nx) xb_add(&bar[XB_TOPGEN], 1u);
;             else XB_SPIN(xb_ld(&bar[XB_TOPGEN]) == tg, bar);
;             __builtin_amdgcn_fence(__ATOMIC_ACQUIRE, "agent");
;             xb_add(&bar[XB_XGEN(b.x)], 1u);
.LBB0_829:
	s_or_b64 exec, exec, s[4:5]
	s_nop 0
	s_nop 0
	s_nop 0
	s_nop 0
	s_nop 0
	s_and_saveexec_b64 s[4:5], s[6:7]
	s_cbranch_execz .LBB0_831
	v_mov_b32_e32 v2, 1
	global_atomic_add v[0:1], v2, off

; #define PG8_STAGE(bufoff, gbase, voff) do { _Pragma("unroll") for (int _i = 0; _i < 2; ++_i) \
;         __builtin_amdgcn_global_load_lds((const unsigned*)((const char*)(gbase) + (voff)[_i]), (PG8_LAS unsigned*)(lds + (bufoff) + ldsw + _i * 8192), 16, 0, 0); } while (0)
; #define PG8_LDA(dst, b, h) do { _Pragma("unroll") for (int m = 0; m < 4; ++m) _Pragma("unroll") for (int k = 0; k < 2; ++k) dst[m][k] = *(const PG8_LAS bf16x8*)(lds + PG8_SA(b, h) + aoff + m * 2048 + k * 1024); } while (0)
; #define PG8_LDB(dst, b, h) do { _Pragma("unroll") for (int n = 0; n < 2; ++n) _Pragma("unroll") for (int k = 0; k < 2; ++k) dst[n][k] = *(const PG8_LAS bf16x8*)(lds + PG8_SB(b, h) + boff + n * 2048 + k * 1024); } while (0)
; #define PG8_WAIT_V(n) asm volatile("s_waitcnt vmcnt(" #n ")" ::: "memory")
; #define PG8_WAIT_L(n) asm volatile("s_waitcnt lgkmcnt(" #n ")" ::: "memory")
; #define PG8_BAR __builtin_amdgcn_s_barrier()
; #define PG8_SCHED __builtin_amdgcn_sched_barrier(0)
; template <class Epi, class Sched, bool ALIGN_EPI = false, bool SP2 = false>
; __device__ __forceinline__ void gemm_phase(PG8_LAS unsigned char* lds, const Gemm g, const Sched& S, const Epi& E) {
;     ...
;         const bool has_next = S.next(ui + 1, nxt);
;         const char* nA = has_next ? (const char*)g.A + (size_t)nxt.pm * tstep : cA; const char* nB = has_next ? (const char*)g.Bt + (size_t)nxt.pn * tstep : cB;
;         for (int t = 0; t < nt; t += 2) {
;             const bool last = (t == nt - 2);
;             const char* a1 = cA + (size_t)(t + 1) * kstep;
;             const char* a2 = last ? nA : cA + (size_t)(t + 2) * kstep; const char* b2 = last ? nB : cB + (size_t)(t + 2) * kstep;
;             const char* a3 = a2 + kstep; const char* b3 = b2 + kstep;
;             if (last && has_next) S.a_ready(nxt);
;             if constexpr (SP2) {
;             PG8_LDB(B0, 0, 0); PG8_LDB(B1, 0, 1); PG8_SCHED; PG8_LDA(At, 0, 0); PG8_STAGE(PG8_SA(1, 1), a1 + hstep, voffA);
;             PG8_WAIT_V(8); PG8_WAIT_L(0); PG8_BAR; PG8_MMA(0, 0, At, B0); PG8_MMA(0, 1, At, B1); PG8_BAR; PG8_SCHED;
;             PG8_LDA(At, 0, 1); PG8_STAGE(PG8_SB(0, 0), b2, voffB); PG8_STAGE(PG8_SB(0, 1), b2 + hstep, voffB); PG8_STAGE(PG8_SA(0, 0), a2, voffA);
;             PG8_WAIT_V(8); PG8_WAIT_L(0); PG8_BAR; PG8_MMA(1, 0, At, B0); PG8_MMA(1, 1, At, B1); PG8_BAR; PG8_SCHED;
.LBB0_846:
	s_ashr_i32 s23, s22, 31
	s_lshl_b64 s[24:25], s[22:23], 22
	s_add_u32 s24, s40, s24
	s_addc_u32 s25, s41, s25
	s_and_b64 s[26:27], s[0:1], exec
	s_cselect_b32 s23, s25, s31
	s_cselect_b32 s57, s24, s30
	s_ashr_i32 s21, s20, 31
	s_lshl_b64 s[26:27], s[20:21], 22
	s_add_u32 s26, s44, s26
	s_addc_u32 s27, s45, s27
	s_and_b64 s[36:37], s[0:1], exec
	s_cselect_b32 s21, s27, s35
	s_cselect_b32 s58, s26, s34
	s_add_u32 s59, s34, 0x100
	s_addc_u32 s60, s35, 0
	s_mov_b32 s61, -2
	ds_read_b128 v[72:75], v165
	ds_read_b128 v[84:87], v165 offset:1024
	ds_read_b128 v[92:95], v165 offset:2048
	ds_read_b128 v[108:111], v165 offset:3072
	ds_read_b128 v[156:159], v166
	ds_read_b128 v[168:171], v166 offset:1024
	ds_read_b128 v[172:175], v166 offset:2048
	ds_read_b128 v[176:179], v166 offset:3072
	s_add_u32 s34, s30, 0x100
	s_addc_u32 s35, s31, 0
	s_cmpk_eq_i32 s61, 0x7c
	s_cselect_b32 s39, s23, s35
	s_cselect_b32 s38, s57, s34
	s_cselect_b32 s37, s21, s60
	s_cselect_b32 s36, s58, s59
	v_lshl_add_u64 v[160:161], s[30:31], 0, v[148:149]
	s_add_i32 m0, s42, 0xc000
	ds_read_b128 v[180:183], v167
	ds_read_b128 v[184:187], v167 offset:1024
	ds_read_b128 v[188:191], v167 offset:2048
	ds_read_b128 v[192:195], v167 offset:3072
	ds_read_b128 v[196:199], v167 offset:4096
	ds_read_b128 v[200:203], v167 offset:5120
	ds_read_b128 v[204:207], v167 offset:6144
	ds_read_b128 v[208:211], v167 offset:7168
	global_load_lds_dwordx4 v[160:161], off
	v_lshl_add_u64 v[160:161], s[30:31], 0, v[150:151]
	s_add_i32 m0, s42, 0xe000
	s_nop 0
	global_load_lds_dwordx4 v[160:161], off
	s_waitcnt vmcnt(8)
	s_waitcnt lgkmcnt(0)
	s_barrier
	s_setprio 1
	v_mfma_f32_16x16x32_bf16 v[140:143], v[72:75], v[180:183], 0
	v_mfma_f32_16x16x32_bf16 v[136:139], v[92:95], v[180:183], 0
	v_mfma_f32_16x16x32_bf16 v[132:135], v[72:75], v[188:191], 0
	v_mfma_f32_16x16x32_bf16 v[128:131], v[92:95], v[188:191], 0
	v_mfma_f32_16x16x32_bf16 v[120:123], v[72:75], v[196:199], 0
	v_mfma_f32_16x16x32_bf16 v[112:115], v[92:95], v[196:199], 0
	v_mfma_f32_16x16x32_bf16 v[100:103], v[72:75], v[204:207], 0
	v_mfma_f32_16x16x32_bf16 v[88:91], v[92:95], v[204:207], 0
	v_mfma_f32_16x16x32_bf16 v[140:143], v[84:87], v[184:187], v[140:143]
	v_mfma_f32_16x16x32_bf16 v[136:139], v[108:111], v[184:187], v[136:139]
	v_mfma_f32_16x16x32_bf16 v[132:135], v[84:87], v[192:195], v[132:135]
	v_mfma_f32_16x16x32_bf16 v[128:131], v[108:111], v[192:195], v[128:131]
	v_mfma_f32_16x16x32_bf16 v[120:123], v[84:87], v[200:203], v[120:123]
	v_mfma_f32_16x16x32_bf16 v[112:115], v[108:111], v[200:203], v[112:115]
	v_mfma_f32_16x16x32_bf16 v[100:103], v[84:87], v[208:211], v[100:103]
	v_mfma_f32_16x16x32_bf16 v[88:91], v[108:111], v[208:211], v[88:91]
	v_mfma_f32_16x16x32_bf16 v[124:127], v[156:159], v[180:183], 0
	v_mfma_f32_16x16x32_bf16 v[116:119], v[172:175], v[180:183], 0
	v_mfma_f32_16x16x32_bf16 v[104:107], v[156:159], v[188:191], 0
	v_mfma_f32_16x16x32_bf16 v[96:99], v[172:175], v[188:191], 0
	v_mfma_f32_16x16x32_bf16 v[80:83], v[156:159], v[196:199], 0
	v_mfma_f32_16x16x32_bf16 v[76:79], v[172:175], v[196:199], 0
	v_mfma_f32_16x16x32_bf16 v[68:71], v[156:159], v[204:207], 0
	v_mfma_f32_16x16x32_bf16 v[64:67], v[172:175], v[204:207], 0
	v_mfma_f32_16x16x32_bf16 v[124:127], v[168:171], v[184:187], v[124:127]
	v_mfma_f32_16x16x32_bf16 v[116:119], v[176:179], v[184:187], v[116:119]
	v_mfma_f32_16x16x32_bf16 v[104:107], v[168:171], v[192:195], v[104:107]
	v_mfma_f32_16x16x32_bf16 v[96:99], v[176:179], v[192:195], v[96:99]
	v_mfma_f32_16x16x32_bf16 v[80:83], v[168:171], v[200:203], v[80:83]
	v_mfma_f32_16x16x32_bf16 v[76:79], v[176:179], v[200:203], v[76:79]
	v_mfma_f32_16x16x32_bf16 v[68:71], v[168:171], v[208:211], v[68:71]
	v_mfma_f32_16x16x32_bf16 v[64:67], v[176:179], v[208:211], v[64:67]
	s_setprio 0
	s_barrier
	s_add_i32 s30, s55, s47
	v_lshl_add_u64 v[160:161], s[36:37], 0, v[146:147]
	s_mov_b32 m0, s30
	ds_read_b128 v[180:183], v167 offset:16384
	ds_read_b128 v[184:187], v167 offset:17408
	ds_read_b128 v[188:191], v167 offset:18432
	ds_read_b128 v[192:195], v167 offset:19456
	ds_read_b128 v[196:199], v167 offset:20480
	ds_read_b128 v[200:203], v167 offset:21504
	ds_read_b128 v[204:207], v167 offset:22528
	ds_read_b128 v[208:211], v167 offset:23552
	global_load_lds_dwordx4 v[160:161], off
	s_add_i32 m0, s30, 0x2000
	s_add_u32 s30, s36, 0x200000
	v_lshl_add_u64 v[212:213], s[36:37], 0, v[144:145]
	s_addc_u32 s31, s37, 0
	s_add_i32 s62, s56, s47
	global_load_lds_dwordx4 v[212:213], off
	v_lshl_add_u64 v[214:215], s[30:31], 0, v[146:147]
	s_mov_b32 m0, s62
	v_lshl_add_u64 v[216:217], s[38:39], 0, v[144:145]
	global_load_lds_dwordx4 v[214:215], off
	v_lshl_add_u64 v[214:215], s[30:31], 0, v[144:145]
	s_add_i32 m0, s62, 0x2000
	s_nop 0
	global_load_lds_dwordx4 v[214:215], off
	v_lshl_add_u64 v[214:215], s[38:39], 0, v[146:147]
	s_mov_b32 m0, s42
	s_nop 0
	global_load_lds_dwordx4 v[214:215], off
	s_mov_b32 m0, s43
	s_nop 0
	global_load_lds_dwordx4 v[216:217], off
	s_waitcnt vmcnt(8)
	s_waitcnt lgkmcnt(0)
	s_barrier
; #define PG8_STAGE(bufoff, gbase, voff) do { _Pragma("unroll") for (int _i = 0; _i < 2; ++_i) \
;         __builtin_amdgcn_global_load_lds((const unsigned*)((const char*)(gbase) + (voff)[_i]), (PG8_LAS unsigned*)(lds + (bufoff) + ldsw + _i * 8192), 16, 0, 0); } while (0)
; #define PG8_LDA(dst, b, h) do { _Pragma("unroll") for (int m = 0; m < 4; ++m) _Pragma("unroll") for (int k = 0; k < 2; ++k) dst[m][k] = *(const PG8_LAS bf16x8*)(lds + PG8_SA(b, h) + aoff + m * 2048 + k * 1024); } while (0)
; #define PG8_LDB(dst, b, h) do { _Pragma("unroll") for (int n = 0; n < 2; ++n) _Pragma("unroll") for (int k = 0; k < 2; ++k) dst[n][k] = *(const PG8_LAS bf16x8*)(lds + PG8_SB(b, h) + boff + n * 2048 + k * 1024); } while (0)
; #define PG8_MMA(ai, bj, At, Bt) do { __builtin_amdgcn_s_setprio(1); _Pragma("unroll") for (int m = 0; m < 4; ++m) _Pragma("unroll") for (int n = 0; n < 2; ++n) _Pragma("unroll") for (int k = 0; k < 2; ++k) \
;         acc[ai][bj][m][n] = __builtin_amdgcn_mfma_f32_16x16x32_bf16(Bt[n][k], At[m][k], acc[ai][bj][m][n], 0, 0, 0); __builtin_amdgcn_s_setprio(0); } while (0)
; #define PG8_WAIT_V(n) asm volatile("s_waitcnt vmcnt(" #n ")" ::: "memory")
; #define PG8_WAIT_L(n) asm volatile("s_waitcnt lgkmcnt(" #n ")" ::: "memory")
; #define PG8_BAR __builtin_amdgcn_s_barrier()
; #define PG8_SCHED __builtin_amdgcn_sched_barrier(0)
; template <class Epi, class Sched, bool ALIGN_EPI = false, bool SP2 = false>
; __device__ __forceinline__ void gemm_phase(PG8_LAS unsigned char* lds, const Gemm g, const Sched& S, const Epi& E) {
;     ...
;             PG8_WAIT_V(8); PG8_WAIT_L(0); PG8_BAR; PG8_MMA(1, 0, At, B0); PG8_MMA(1, 1, At, B1); PG8_BAR; PG8_SCHED;
;             PG8_LDB(B0, 1, 0); PG8_LDB(B1, 1, 1); PG8_SCHED; PG8_LDA(At, 1, 0); PG8_STAGE(PG8_SA(0, 1), a2 + hstep, voffA);
;             PG8_WAIT_V(8); PG8_WAIT_L(0); PG8_BAR; PG8_MMA(0, 0, At, B0); PG8_MMA(0, 1, At, B1); PG8_BAR; PG8_SCHED;
	s_setprio 1
	v_mfma_f32_16x16x32_bf16 v[60:63], v[72:75], v[180:183], 0
	v_mfma_f32_16x16x32_bf16 v[56:59], v[92:95], v[180:183], 0
	v_mfma_f32_16x16x32_bf16 v[52:55], v[72:75], v[188:191], 0
	v_mfma_f32_16x16x32_bf16 v[44:47], v[92:95], v[188:191], 0
	v_mfma_f32_16x16x32_bf16 v[36:39], v[72:75], v[196:199], 0
	v_mfma_f32_16x16x32_bf16 v[28:31], v[92:95], v[196:199], 0
	v_mfma_f32_16x16x32_bf16 v[20:23], v[72:75], v[204:207], 0
	v_mfma_f32_16x16x32_bf16 v[12:15], v[92:95], v[204:207], 0
	v_mfma_f32_16x16x32_bf16 v[60:63], v[84:87], v[184:187], v[60:63]
	v_mfma_f32_16x16x32_bf16 v[56:59], v[108:111], v[184:187], v[56:59]
	v_mfma_f32_16x16x32_bf16 v[52:55], v[84:87], v[192:195], v[52:55]
	v_mfma_f32_16x16x32_bf16 v[44:47], v[108:111], v[192:195], v[44:47]
	v_mfma_f32_16x16x32_bf16 v[36:39], v[84:87], v[200:203], v[36:39]
	v_mfma_f32_16x16x32_bf16 v[28:31], v[108:111], v[200:203], v[28:31]
	v_mfma_f32_16x16x32_bf16 v[20:23], v[84:87], v[208:211], v[20:23]
	v_mfma_f32_16x16x32_bf16 v[12:15], v[108:111], v[208:211], v[12:15]
	v_mfma_f32_16x16x32_bf16 v[48:51], v[156:159], v[180:183], 0
	v_mfma_f32_16x16x32_bf16 v[40:43], v[172:175], v[180:183], 0
	v_mfma_f32_16x16x32_bf16 v[32:35], v[156:159], v[188:191], 0
	v_mfma_f32_16x16x32_bf16 v[24:27], v[172:175], v[188:191], 0
	v_mfma_f32_16x16x32_bf16 v[16:19], v[156:159], v[196:199], 0
	v_mfma_f32_16x16x32_bf16 v[8:11], v[172:175], v[196:199], 0
	v_mfma_f32_16x16x32_bf16 v[4:7], v[156:159], v[204:207], 0
	v_mfma_f32_16x16x32_bf16 v[0:3], v[172:175], v[204:207], 0
	v_mfma_f32_16x16x32_bf16 v[48:51], v[168:171], v[184:187], v[48:51]
	v_mfma_f32_16x16x32_bf16 v[40:43], v[176:179], v[184:187], v[40:43]
	v_mfma_f32_16x16x32_bf16 v[32:35], v[168:171], v[192:195], v[32:35]
	v_mfma_f32_16x16x32_bf16 v[24:27], v[176:179], v[192:195], v[24:27]
	v_mfma_f32_16x16x32_bf16 v[16:19], v[168:171], v[200:203], v[16:19]
	v_mfma_f32_16x16x32_bf16 v[8:11], v[176:179], v[200:203], v[8:11]
	v_mfma_f32_16x16x32_bf16 v[4:7], v[168:171], v[208:211], v[4:7]
	v_mfma_f32_16x16x32_bf16 v[0:3], v[176:179], v[208:211], v[0:3]
	s_setprio 0
	s_barrier
	s_add_i32 s62, 0, 0x18000
	s_add_i32 s63, 0, 0x1c000
	v_add_u32_e32 v108, s62, v163
	v_add_u32_e32 v176, s63, v163
	ds_read_b128 v[72:75], v108
	ds_read_b128 v[84:87], v108 offset:1024
	ds_read_b128 v[92:95], v108 offset:2048
	ds_read_b128 v[108:111], v108 offset:3072
	ds_read_b128 v[156:159], v176
	ds_read_b128 v[168:171], v176 offset:1024
	ds_read_b128 v[172:175], v176 offset:2048
	ds_read_b128 v[176:179], v176 offset:3072
	s_add_u32 s30, s38, 0x200000
	s_addc_u32 s31, s39, 0
	s_mov_b32 m0, s48
	v_lshl_add_u64 v[218:219], s[30:31], 0, v[146:147]
	ds_read_b128 v[180:183], v167 offset:32768
	ds_read_b128 v[184:187], v167 offset:33792
	ds_read_b128 v[188:191], v167 offset:34816
	ds_read_b128 v[192:195], v167 offset:35840
	ds_read_b128 v[196:199], v167 offset:36864
	ds_read_b128 v[200:203], v167 offset:37888
	ds_read_b128 v[204:207], v167 offset:38912
	ds_read_b128 v[208:211], v167 offset:39936
	global_load_lds_dwordx4 v[218:219], off
	v_lshl_add_u64 v[218:219], s[30:31], 0, v[144:145]
	s_mov_b32 m0, s49
	s_nop 0
	global_load_lds_dwordx4 v[218:219], off
	s_waitcnt vmcnt(8)
	s_waitcnt lgkmcnt(0)
	s_barrier
	s_setprio 1
	v_mfma_f32_16x16x32_bf16 v[140:143], v[72:75], v[180:183], v[140:143]
	v_mfma_f32_16x16x32_bf16 v[136:139], v[92:95], v[180:183], v[136:139]
	v_mfma_f32_16x16x32_bf16 v[132:135], v[72:75], v[188:191], v[132:135]
	v_mfma_f32_16x16x32_bf16 v[128:131], v[92:95], v[188:191], v[128:131]
	v_mfma_f32_16x16x32_bf16 v[120:123], v[72:75], v[196:199], v[120:123]
	v_mfma_f32_16x16x32_bf16 v[112:115], v[92:95], v[196:199], v[112:115]
	v_mfma_f32_16x16x32_bf16 v[100:103], v[72:75], v[204:207], v[100:103]
	v_mfma_f32_16x16x32_bf16 v[88:91], v[92:95], v[204:207], v[88:91]
	v_mfma_f32_16x16x32_bf16 v[140:143], v[84:87], v[184:187], v[140:143]
	v_mfma_f32_16x16x32_bf16 v[136:139], v[108:111], v[184:187], v[136:139]
	v_mfma_f32_16x16x32_bf16 v[132:135], v[84:87], v[192:195], v[132:135]
	v_mfma_f32_16x16x32_bf16 v[128:131], v[108:111], v[192:195], v[128:131]
	v_mfma_f32_16x16x32_bf16 v[120:123], v[84:87], v[200:203], v[120:123]
	v_mfma_f32_16x16x32_bf16 v[112:115], v[108:111], v[200:203], v[112:115]
	v_mfma_f32_16x16x32_bf16 v[100:103], v[84:87], v[208:211], v[100:103]
	v_mfma_f32_16x16x32_bf16 v[88:91], v[108:111], v[208:211], v[88:91]
	v_mfma_f32_16x16x32_bf16 v[124:127], v[156:159], v[180:183], v[124:127]
	v_mfma_f32_16x16x32_bf16 v[116:119], v[172:175], v[180:183], v[116:119]
	v_mfma_f32_16x16x32_bf16 v[104:107], v[156:159], v[188:191], v[104:107]
	v_mfma_f32_16x16x32_bf16 v[96:99], v[172:175], v[188:191], v[96:99]
	v_mfma_f32_16x16x32_bf16 v[80:83], v[156:159], v[196:199], v[80:83]
	v_mfma_f32_16x16x32_bf16 v[76:79], v[172:175], v[196:199], v[76:79]
	v_mfma_f32_16x16x32_bf16 v[68:71], v[156:159], v[204:207], v[68:71]
	v_mfma_f32_16x16x32_bf16 v[64:67], v[172:175], v[204:207], v[64:67]
	v_mfma_f32_16x16x32_bf16 v[124:127], v[168:171], v[184:187], v[124:127]
	v_mfma_f32_16x16x32_bf16 v[116:119], v[176:179], v[184:187], v[116:119]
	v_mfma_f32_16x16x32_bf16 v[104:107], v[168:171], v[192:195], v[104:107]
	v_mfma_f32_16x16x32_bf16 v[96:99], v[176:179], v[192:195], v[96:99]
	v_mfma_f32_16x16x32_bf16 v[80:83], v[168:171], v[200:203], v[80:83]
	v_mfma_f32_16x16x32_bf16 v[76:79], v[176:179], v[200:203], v[76:79]
	v_mfma_f32_16x16x32_bf16 v[68:71], v[168:171], v[208:211], v[68:71]
	v_mfma_f32_16x16x32_bf16 v[64:67], v[176:179], v[208:211], v[64:67]
	s_setprio 0
	s_barrier
; #define PG8_STAGE(bufoff, gbase, voff) do { _Pragma("unroll") for (int _i = 0; _i < 2; ++_i) \
;         __builtin_amdgcn_global_load_lds((const unsigned*)((const char*)(gbase) + (voff)[_i]), (PG8_LAS unsigned*)(lds + (bufoff) + ldsw + _i * 8192), 16, 0, 0); } while (0)
; #define PG8_LDA(dst, b, h) do { _Pragma("unroll") for (int m = 0; m < 4; ++m) _Pragma("unroll") for (int k = 0; k < 2; ++k) dst[m][k] = *(const PG8_LAS bf16x8*)(lds + PG8_SA(b, h) + aoff + m * 2048 + k * 1024); } while (0)
; #define PG8_LDB(dst, b, h) do { _Pragma("unroll") for (int n = 0; n < 2; ++n) _Pragma("unroll") for (int k = 0; k < 2; ++k) dst[n][k] = *(const PG8_LAS bf16x8*)(lds + PG8_SB(b, h) + boff + n * 2048 + k * 1024); } while (0)
; #define PG8_MMA(ai, bj, At, Bt) do { __builtin_amdgcn_s_setprio(1); _Pragma("unroll") for (int m = 0; m < 4; ++m) _Pragma("unroll") for (int n = 0; n < 2; ++n) _Pragma("unroll") for (int k = 0; k < 2; ++k) \
;         acc[ai][bj][m][n] = __builtin_amdgcn_mfma_f32_16x16x32_bf16(Bt[n][k], At[m][k], acc[ai][bj][m][n], 0, 0, 0); __builtin_amdgcn_s_setprio(0); } while (0)
; #define PG8_WAIT_V(n) asm volatile("s_waitcnt vmcnt(" #n ")" ::: "memory")
; #define PG8_WAIT_L(n) asm volatile("s_waitcnt lgkmcnt(" #n ")" ::: "memory")
; #define PG8_BAR __builtin_amdgcn_s_barrier()
; #define PG8_SCHED __builtin_amdgcn_sched_barrier(0)
; template <class Epi, class Sched, bool ALIGN_EPI = false, bool SP2 = false>
; __device__ __forceinline__ void gemm_phase(PG8_LAS unsigned char* lds, const Gemm g, const Sched& S, const Epi& E) {
;     ...
;             PG8_LDB(B0, 0, 0); PG8_LDB(B1, 0, 1); PG8_SCHED; PG8_LDA(At, 0, 0); PG8_STAGE(PG8_SA(1, 1), a1 + hstep, voffA);
;             PG8_WAIT_V(8); PG8_WAIT_L(0); PG8_BAR; PG8_MMA(0, 0, At, B0); PG8_MMA(0, 1, At, B1); PG8_BAR; PG8_SCHED;
;     ...
;             PG8_LDA(At, 1, 1); PG8_STAGE(PG8_SB(1, 0), b3, voffB); PG8_STAGE(PG8_SB(1, 1), b3 + hstep, voffB); PG8_STAGE(PG8_SA(1, 0), a3, voffA);
;             PG8_WAIT_V(8); PG8_WAIT_L(0); PG8_BAR; PG8_MMA(1, 0, At, B0); PG8_MMA(1, 1, At, B1); PG8_BAR; PG8_SCHED;
	s_add_i32 s30, s62, s47
	v_lshl_add_u64 v[160:161], v[160:161], 0, s[8:9]
	s_mov_b32 m0, s30
	ds_read_b128 v[180:183], v167 offset:49152
	ds_read_b128 v[184:187], v167 offset:50176
	ds_read_b128 v[188:191], v167 offset:51200
	ds_read_b128 v[192:195], v167 offset:52224
	ds_read_b128 v[196:199], v167 offset:53248
	ds_read_b128 v[200:203], v167 offset:54272
	ds_read_b128 v[204:207], v167 offset:55296
	ds_read_b128 v[208:211], v167 offset:56320
	global_load_lds_dwordx4 v[160:161], off
	s_add_i32 m0, s30, 0x2000
	s_add_u32 s30, s36, 0x200080
	v_lshl_add_u64 v[160:161], v[212:213], 0, s[8:9]
	s_addc_u32 s31, s37, 0
	s_add_i32 s36, s63, s47
	global_load_lds_dwordx4 v[160:161], off
	v_lshl_add_u64 v[160:161], s[30:31], 0, v[146:147]
	s_mov_b32 m0, s36
	s_nop 0
	global_load_lds_dwordx4 v[160:161], off
	v_lshl_add_u64 v[160:161], s[30:31], 0, v[144:145]
	s_add_i32 m0, s36, 0x2000
	s_nop 0
	global_load_lds_dwordx4 v[160:161], off
	v_lshl_add_u64 v[160:161], v[214:215], 0, s[8:9]
	s_mov_b32 m0, s53
	s_nop 0
	global_load_lds_dwordx4 v[160:161], off
	v_lshl_add_u64 v[160:161], v[216:217], 0, s[8:9]
	s_mov_b32 m0, s54
	s_nop 0
	global_load_lds_dwordx4 v[160:161], off
	s_waitcnt vmcnt(8)
	s_waitcnt lgkmcnt(0)
	s_barrier
	s_setprio 1
	v_mfma_f32_16x16x32_bf16 v[60:63], v[72:75], v[180:183], v[60:63]
	v_mfma_f32_16x16x32_bf16 v[56:59], v[92:95], v[180:183], v[56:59]
	v_mfma_f32_16x16x32_bf16 v[52:55], v[72:75], v[188:191], v[52:55]
	v_mfma_f32_16x16x32_bf16 v[44:47], v[92:95], v[188:191], v[44:47]
	v_mfma_f32_16x16x32_bf16 v[36:39], v[72:75], v[196:199], v[36:39]
	v_mfma_f32_16x16x32_bf16 v[28:31], v[92:95], v[196:199], v[28:31]
	v_mfma_f32_16x16x32_bf16 v[20:23], v[72:75], v[204:207], v[20:23]
	v_mfma_f32_16x16x32_bf16 v[12:15], v[92:95], v[204:207], v[12:15]
	v_mfma_f32_16x16x32_bf16 v[60:63], v[84:87], v[184:187], v[60:63]
	v_mfma_f32_16x16x32_bf16 v[56:59], v[108:111], v[184:187], v[56:59]
	v_mfma_f32_16x16x32_bf16 v[52:55], v[84:87], v[192:195], v[52:55]
	v_mfma_f32_16x16x32_bf16 v[44:47], v[108:111], v[192:195], v[44:47]
	v_mfma_f32_16x16x32_bf16 v[36:39], v[84:87], v[200:203], v[36:39]
	v_mfma_f32_16x16x32_bf16 v[28:31], v[108:111], v[200:203], v[28:31]
	v_mfma_f32_16x16x32_bf16 v[20:23], v[84:87], v[208:211], v[20:23]
	v_mfma_f32_16x16x32_bf16 v[12:15], v[108:111], v[208:211], v[12:15]
	v_mfma_f32_16x16x32_bf16 v[48:51], v[156:159], v[180:183], v[48:51]
	v_mfma_f32_16x16x32_bf16 v[40:43], v[172:175], v[180:183], v[40:43]
	v_mfma_f32_16x16x32_bf16 v[32:35], v[156:159], v[188:191], v[32:35]
	v_mfma_f32_16x16x32_bf16 v[24:27], v[172:175], v[188:191], v[24:27]
	v_mfma_f32_16x16x32_bf16 v[16:19], v[156:159], v[196:199], v[16:19]
	v_mfma_f32_16x16x32_bf16 v[8:11], v[172:175], v[196:199], v[8:11]
	v_mfma_f32_16x16x32_bf16 v[4:7], v[156:159], v[204:207], v[4:7]
	v_mfma_f32_16x16x32_bf16 v[0:3], v[172:175], v[204:207], v[0:3]
	v_mfma_f32_16x16x32_bf16 v[48:51], v[168:171], v[184:187], v[48:51]
	v_mfma_f32_16x16x32_bf16 v[40:43], v[176:179], v[184:187], v[40:43]
	v_mfma_f32_16x16x32_bf16 v[32:35], v[168:171], v[192:195], v[32:35]
	v_mfma_f32_16x16x32_bf16 v[24:27], v[176:179], v[192:195], v[24:27]
	v_mfma_f32_16x16x32_bf16 v[16:19], v[168:171], v[200:203], v[16:19]
	v_mfma_f32_16x16x32_bf16 v[8:11], v[176:179], v[200:203], v[8:11]
	v_mfma_f32_16x16x32_bf16 v[4:7], v[168:171], v[208:211], v[4:7]
	v_mfma_f32_16x16x32_bf16 v[0:3], v[176:179], v[208:211], v[0:3]
	s_setprio 0
	s_barrier
	s_add_i32 s61, s61, 2
	s_add_u32 s59, s59, 0x100
	s_addc_u32 s60, s60, 0
	s_cmpk_gt_u32 s61, 0x7d
	s_mov_b64 s[30:31], s[34:35]
.LBB0_847:
	ds_read_b128 v[72:75], v165
	ds_read_b128 v[84:87], v165 offset:1024
	ds_read_b128 v[92:95], v165 offset:2048
	ds_read_b128 v[108:111], v165 offset:3072
	ds_read_b128 v[156:159], v166
	ds_read_b128 v[168:171], v166 offset:1024
	ds_read_b128 v[172:175], v166 offset:2048
	ds_read_b128 v[176:179], v166 offset:3072
	s_add_u32 s34, s30, 0x100
	s_addc_u32 s35, s31, 0
	s_cmpk_eq_i32 s61, 0x7c
	s_cselect_b32 s39, s23, s35
	s_cselect_b32 s38, s57, s34
	s_cselect_b32 s37, s21, s60
	s_cselect_b32 s36, s58, s59
	v_lshl_add_u64 v[160:161], s[30:31], 0, v[148:149]
	s_add_i32 m0, s42, 0xc000
	ds_read_b128 v[180:183], v167
	ds_read_b128 v[184:187], v167 offset:1024
	ds_read_b128 v[188:191], v167 offset:2048
	ds_read_b128 v[192:195], v167 offset:3072
	ds_read_b128 v[196:199], v167 offset:4096
	ds_read_b128 v[200:203], v167 offset:5120
	ds_read_b128 v[204:207], v167 offset:6144
	ds_read_b128 v[208:211], v167 offset:7168
	global_load_lds_dwordx4 v[160:161], off
	v_lshl_add_u64 v[160:161], s[30:31], 0, v[150:151]
	s_add_i32 m0, s42, 0xe000
	s_nop 0
	global_load_lds_dwordx4 v[160:161], off
	s_waitcnt vmcnt(8)
	s_waitcnt lgkmcnt(0)
	s_barrier
; #define PG8_STAGE(bufoff, gbase, voff) do { _Pragma("unroll") for (int _i = 0; _i < 2; ++_i) \
;         __builtin_amdgcn_global_load_lds((const unsigned*)((const char*)(gbase) + (voff)[_i]), (PG8_LAS unsigned*)(lds + (bufoff) + ldsw + _i * 8192), 16, 0, 0); } while (0)
; #define PG8_LDA(dst, b, h) do { _Pragma("unroll") for (int m = 0; m < 4; ++m) _Pragma("unroll") for (int k = 0; k < 2; ++k) dst[m][k] = *(const PG8_LAS bf16x8*)(lds + PG8_SA(b, h) + aoff + m * 2048 + k * 1024); } while (0)
; #define PG8_MMA(ai, bj, At, Bt) do { __builtin_amdgcn_s_setprio(1); _Pragma("unroll") for (int m = 0; m < 4; ++m) _Pragma("unroll") for (int n = 0; n < 2; ++n) _Pragma("unroll") for (int k = 0; k < 2; ++k) \
;         acc[ai][bj][m][n] = __builtin_amdgcn_mfma_f32_16x16x32_bf16(Bt[n][k], At[m][k], acc[ai][bj][m][n], 0, 0, 0); __builtin_amdgcn_s_setprio(0); } while (0)
; #define PG8_WAIT_V(n) asm volatile("s_waitcnt vmcnt(" #n ")" ::: "memory")
; #define PG8_WAIT_L(n) asm volatile("s_waitcnt lgkmcnt(" #n ")" ::: "memory")
; #define PG8_BAR __builtin_amdgcn_s_barrier()
; #define PG8_SCHED __builtin_amdgcn_sched_barrier(0)
; template <class Epi, class Sched, bool ALIGN_EPI = false, bool SP2 = false>
; __device__ __forceinline__ void gemm_phase(PG8_LAS unsigned char* lds, const Gemm g, const Sched& S, const Epi& E) {
;     ...
;             PG8_WAIT_V(8); PG8_WAIT_L(0); PG8_BAR; PG8_MMA(0, 0, At, B0); PG8_MMA(0, 1, At, B1); PG8_BAR; PG8_SCHED;
;             PG8_LDA(At, 0, 1); PG8_STAGE(PG8_SB(0, 0), b2, voffB); PG8_STAGE(PG8_SB(0, 1), b2 + hstep, voffB); PG8_STAGE(PG8_SA(0, 0), a2, voffA);
;             PG8_WAIT_V(8); PG8_WAIT_L(0); PG8_BAR; PG8_MMA(1, 0, At, B0); PG8_MMA(1, 1, At, B1); PG8_BAR; PG8_SCHED;
	s_setprio 1
	v_mfma_f32_16x16x32_bf16 v[140:143], v[72:75], v[180:183], v[140:143]
	v_mfma_f32_16x16x32_bf16 v[136:139], v[92:95], v[180:183], v[136:139]
	v_mfma_f32_16x16x32_bf16 v[132:135], v[72:75], v[188:191], v[132:135]
	v_mfma_f32_16x16x32_bf16 v[128:131], v[92:95], v[188:191], v[128:131]
	v_mfma_f32_16x16x32_bf16 v[120:123], v[72:75], v[196:199], v[120:123]
	v_mfma_f32_16x16x32_bf16 v[112:115], v[92:95], v[196:199], v[112:115]
	v_mfma_f32_16x16x32_bf16 v[100:103], v[72:75], v[204:207], v[100:103]
	v_mfma_f32_16x16x32_bf16 v[88:91], v[92:95], v[204:207], v[88:91]
	v_mfma_f32_16x16x32_bf16 v[140:143], v[84:87], v[184:187], v[140:143]
	v_mfma_f32_16x16x32_bf16 v[136:139], v[108:111], v[184:187], v[136:139]
	v_mfma_f32_16x16x32_bf16 v[132:135], v[84:87], v[192:195], v[132:135]
	v_mfma_f32_16x16x32_bf16 v[128:131], v[108:111], v[192:195], v[128:131]
	v_mfma_f32_16x16x32_bf16 v[120:123], v[84:87], v[200:203], v[120:123]
	v_mfma_f32_16x16x32_bf16 v[112:115], v[108:111], v[200:203], v[112:115]
	v_mfma_f32_16x16x32_bf16 v[100:103], v[84:87], v[208:211], v[100:103]
	v_mfma_f32_16x16x32_bf16 v[88:91], v[108:111], v[208:211], v[88:91]
	v_mfma_f32_16x16x32_bf16 v[124:127], v[156:159], v[180:183], v[124:127]
	v_mfma_f32_16x16x32_bf16 v[116:119], v[172:175], v[180:183], v[116:119]
	v_mfma_f32_16x16x32_bf16 v[104:107], v[156:159], v[188:191], v[104:107]
	v_mfma_f32_16x16x32_bf16 v[96:99], v[172:175], v[188:191], v[96:99]
	v_mfma_f32_16x16x32_bf16 v[80:83], v[156:159], v[196:199], v[80:83]
	v_mfma_f32_16x16x32_bf16 v[76:79], v[172:175], v[196:199], v[76:79]
	v_mfma_f32_16x16x32_bf16 v[68:71], v[156:159], v[204:207], v[68:71]
	v_mfma_f32_16x16x32_bf16 v[64:67], v[172:175], v[204:207], v[64:67]
	v_mfma_f32_16x16x32_bf16 v[124:127], v[168:171], v[184:187], v[124:127]
	v_mfma_f32_16x16x32_bf16 v[116:119], v[176:179], v[184:187], v[116:119]
	v_mfma_f32_16x16x32_bf16 v[104:107], v[168:171], v[192:195], v[104:107]
	v_mfma_f32_16x16x32_bf16 v[96:99], v[176:179], v[192:195], v[96:99]
	v_mfma_f32_16x16x32_bf16 v[80:83], v[168:171], v[200:203], v[80:83]
	v_mfma_f32_16x16x32_bf16 v[76:79], v[176:179], v[200:203], v[76:79]
	v_mfma_f32_16x16x32_bf16 v[68:71], v[168:171], v[208:211], v[68:71]
	v_mfma_f32_16x16x32_bf16 v[64:67], v[176:179], v[208:211], v[64:67]
	s_setprio 0
	s_barrier
	s_add_i32 s30, s55, s47
	v_lshl_add_u64 v[160:161], s[36:37], 0, v[146:147]
	s_mov_b32 m0, s30
	ds_read_b128 v[180:183], v167 offset:16384
	ds_read_b128 v[184:187], v167 offset:17408
	ds_read_b128 v[188:191], v167 offset:18432
	ds_read_b128 v[192:195], v167 offset:19456
	ds_read_b128 v[196:199], v167 offset:20480
	ds_read_b128 v[200:203], v167 offset:21504
	ds_read_b128 v[204:207], v167 offset:22528
	ds_read_b128 v[208:211], v167 offset:23552
	global_load_lds_dwordx4 v[160:161], off
	s_add_i32 m0, s30, 0x2000
	s_add_u32 s30, s36, 0x200000
	v_lshl_add_u64 v[212:213], s[36:37], 0, v[144:145]
	s_addc_u32 s31, s37, 0
	s_add_i32 s62, s56, s47
	global_load_lds_dwordx4 v[212:213], off
	v_lshl_add_u64 v[214:215], s[30:31], 0, v[146:147]
	s_mov_b32 m0, s62
	v_lshl_add_u64 v[216:217], s[38:39], 0, v[144:145]
	global_load_lds_dwordx4 v[214:215], off
	v_lshl_add_u64 v[214:215], s[30:31], 0, v[144:145]
	s_add_i32 m0, s62, 0x2000
	s_nop 0
	global_load_lds_dwordx4 v[214:215], off
	v_lshl_add_u64 v[214:215], s[38:39], 0, v[146:147]
	s_mov_b32 m0, s42
	s_nop 0
	global_load_lds_dwordx4 v[214:215], off
	s_mov_b32 m0, s43
	s_nop 0
	global_load_lds_dwordx4 v[216:217], off
	s_waitcnt vmcnt(8)
	s_waitcnt lgkmcnt(0)
	s_barrier
	s_setprio 1
	v_mfma_f32_16x16x32_bf16 v[60:63], v[72:75], v[180:183], v[60:63]
	v_mfma_f32_16x16x32_bf16 v[56:59], v[92:95], v[180:183], v[56:59]
	v_mfma_f32_16x16x32_bf16 v[52:55], v[72:75], v[188:191], v[52:55]
	v_mfma_f32_16x16x32_bf16 v[44:47], v[92:95], v[188:191], v[44:47]
	v_mfma_f32_16x16x32_bf16 v[36:39], v[72:75], v[196:199], v[36:39]
	v_mfma_f32_16x16x32_bf16 v[28:31], v[92:95], v[196:199], v[28:31]
	v_mfma_f32_16x16x32_bf16 v[20:23], v[72:75], v[204:207], v[20:23]
	v_mfma_f32_16x16x32_bf16 v[12:15], v[92:95], v[204:207], v[12:15]
	v_mfma_f32_16x16x32_bf16 v[60:63], v[84:87], v[184:187], v[60:63]
	v_mfma_f32_16x16x32_bf16 v[56:59], v[108:111], v[184:187], v[56:59]
	v_mfma_f32_16x16x32_bf16 v[52:55], v[84:87], v[192:195], v[52:55]
	v_mfma_f32_16x16x32_bf16 v[44:47], v[108:111], v[192:195], v[44:47]
	v_mfma_f32_16x16x32_bf16 v[36:39], v[84:87], v[200:203], v[36:39]
	v_mfma_f32_16x16x32_bf16 v[28:31], v[108:111], v[200:203], v[28:31]
	v_mfma_f32_16x16x32_bf16 v[20:23], v[84:87], v[208:211], v[20:23]
	v_mfma_f32_16x16x32_bf16 v[12:15], v[108:111], v[208:211], v[12:15]
	v_mfma_f32_16x16x32_bf16 v[48:51], v[156:159], v[180:183], v[48:51]
	v_mfma_f32_16x16x32_bf16 v[40:43], v[172:175], v[180:183], v[40:43]
	v_mfma_f32_16x16x32_bf16 v[32:35], v[156:159], v[188:191], v[32:35]
	v_mfma_f32_16x16x32_bf16 v[24:27], v[172:175], v[188:191], v[24:27]
	v_mfma_f32_16x16x32_bf16 v[16:19], v[156:159], v[196:199], v[16:19]
	v_mfma_f32_16x16x32_bf16 v[8:11], v[172:175], v[196:199], v[8:11]
	v_mfma_f32_16x16x32_bf16 v[4:7], v[156:159], v[204:207], v[4:7]
	v_mfma_f32_16x16x32_bf16 v[0:3], v[172:175], v[204:207], v[0:3]
	v_mfma_f32_16x16x32_bf16 v[48:51], v[168:171], v[184:187], v[48:51]
	v_mfma_f32_16x16x32_bf16 v[40:43], v[176:179], v[184:187], v[40:43]
	v_mfma_f32_16x16x32_bf16 v[32:35], v[168:171], v[192:195], v[32:35]
	v_mfma_f32_16x16x32_bf16 v[24:27], v[176:179], v[192:195], v[24:27]
	v_mfma_f32_16x16x32_bf16 v[16:19], v[168:171], v[200:203], v[16:19]
	v_mfma_f32_16x16x32_bf16 v[8:11], v[176:179], v[200:203], v[8:11]
	v_mfma_f32_16x16x32_bf16 v[4:7], v[168:171], v[208:211], v[4:7]
	v_mfma_f32_16x16x32_bf16 v[0:3], v[176:179], v[208:211], v[0:3]
	s_setprio 0
	s_barrier
; #define PG8_STAGE(bufoff, gbase, voff) do { _Pragma("unroll") for (int _i = 0; _i < 2; ++_i) \
;         __builtin_amdgcn_global_load_lds((const unsigned*)((const char*)(gbase) + (voff)[_i]), (PG8_LAS unsigned*)(lds + (bufoff) + ldsw + _i * 8192), 16, 0, 0); } while (0)
; #define PG8_LDA(dst, b, h) do { _Pragma("unroll") for (int m = 0; m < 4; ++m) _Pragma("unroll") for (int k = 0; k < 2; ++k) dst[m][k] = *(const PG8_LAS bf16x8*)(lds + PG8_SA(b, h) + aoff + m * 2048 + k * 1024); } while (0)
; #define PG8_LDB(dst, b, h) do { _Pragma("unroll") for (int n = 0; n < 2; ++n) _Pragma("unroll") for (int k = 0; k < 2; ++k) dst[n][k] = *(const PG8_LAS bf16x8*)(lds + PG8_SB(b, h) + boff + n * 2048 + k * 1024); } while (0)
; #define PG8_MMA(ai, bj, At, Bt) do { __builtin_amdgcn_s_setprio(1); _Pragma("unroll") for (int m = 0; m < 4; ++m) _Pragma("unroll") for (int n = 0; n < 2; ++n) _Pragma("unroll") for (int k = 0; k < 2; ++k) \
;         acc[ai][bj][m][n] = __builtin_amdgcn_mfma_f32_16x16x32_bf16(Bt[n][k], At[m][k], acc[ai][bj][m][n], 0, 0, 0); __builtin_amdgcn_s_setprio(0); } while (0)
; #define PG8_WAIT_V(n) asm volatile("s_waitcnt vmcnt(" #n ")" ::: "memory")
; #define PG8_WAIT_L(n) asm volatile("s_waitcnt lgkmcnt(" #n ")" ::: "memory")
; #define PG8_BAR __builtin_amdgcn_s_barrier()
; #define PG8_SCHED __builtin_amdgcn_sched_barrier(0)
; template <class Epi, class Sched, bool ALIGN_EPI = false, bool SP2 = false>
; __device__ __forceinline__ void gemm_phase(PG8_LAS unsigned char* lds, const Gemm g, const Sched& S, const Epi& E) {
;     ...
;             PG8_LDB(B0, 1, 0); PG8_LDB(B1, 1, 1); PG8_SCHED; PG8_LDA(At, 1, 0); PG8_STAGE(PG8_SA(0, 1), a2 + hstep, voffA);
;             PG8_WAIT_V(8); PG8_WAIT_L(0); PG8_BAR; PG8_MMA(0, 0, At, B0); PG8_MMA(0, 1, At, B1); PG8_BAR; PG8_SCHED;
	s_add_i32 s62, 0, 0x18000
	s_add_i32 s63, 0, 0x1c000
	v_add_u32_e32 v108, s62, v163
	v_add_u32_e32 v176, s63, v163
	ds_read_b128 v[72:75], v108
	ds_read_b128 v[84:87], v108 offset:1024
	ds_read_b128 v[92:95], v108 offset:2048
	ds_read_b128 v[108:111], v108 offset:3072
	ds_read_b128 v[156:159], v176
	ds_read_b128 v[168:171], v176 offset:1024
	ds_read_b128 v[172:175], v176 offset:2048
	ds_read_b128 v[176:179], v176 offset:3072
	s_add_u32 s30, s38, 0x200000
	s_addc_u32 s31, s39, 0
	s_mov_b32 m0, s48
	v_lshl_add_u64 v[218:219], s[30:31], 0, v[146:147]
	ds_read_b128 v[180:183], v167 offset:32768
	ds_read_b128 v[184:187], v167 offset:33792
	ds_read_b128 v[188:191], v167 offset:34816
	ds_read_b128 v[192:195], v167 offset:35840
	ds_read_b128 v[196:199], v167 offset:36864
	ds_read_b128 v[200:203], v167 offset:37888
	ds_read_b128 v[204:207], v167 offset:38912
	ds_read_b128 v[208:211], v167 offset:39936
	global_load_lds_dwordx4 v[218:219], off
	v_lshl_add_u64 v[218:219], s[30:31], 0, v[144:145]
	s_mov_b32 m0, s49
	s_nop 0
	global_load_lds_dwordx4 v[218:219], off
	s_waitcnt vmcnt(8)
	s_waitcnt lgkmcnt(0)
	s_barrier
	s_setprio 1
	v_mfma_f32_16x16x32_bf16 v[140:143], v[72:75], v[180:183], v[140:143]
	v_mfma_f32_16x16x32_bf16 v[136:139], v[92:95], v[180:183], v[136:139]
	v_mfma_f32_16x16x32_bf16 v[132:135], v[72:75], v[188:191], v[132:135]
	v_mfma_f32_16x16x32_bf16 v[128:131], v[92:95], v[188:191], v[128:131]
	v_mfma_f32_16x16x32_bf16 v[120:123], v[72:75], v[196:199], v[120:123]
	v_mfma_f32_16x16x32_bf16 v[112:115], v[92:95], v[196:199], v[112:115]
	v_mfma_f32_16x16x32_bf16 v[100:103], v[72:75], v[204:207], v[100:103]
	v_mfma_f32_16x16x32_bf16 v[88:91], v[92:95], v[204:207], v[88:91]
	v_mfma_f32_16x16x32_bf16 v[140:143], v[84:87], v[184:187], v[140:143]
	v_mfma_f32_16x16x32_bf16 v[136:139], v[108:111], v[184:187], v[136:139]
	v_mfma_f32_16x16x32_bf16 v[132:135], v[84:87], v[192:195], v[132:135]
	v_mfma_f32_16x16x32_bf16 v[128:131], v[108:111], v[192:195], v[128:131]
	v_mfma_f32_16x16x32_bf16 v[120:123], v[84:87], v[200:203], v[120:123]
	v_mfma_f32_16x16x32_bf16 v[112:115], v[108:111], v[200:203], v[112:115]
	v_mfma_f32_16x16x32_bf16 v[100:103], v[84:87], v[208:211], v[100:103]
	v_mfma_f32_16x16x32_bf16 v[88:91], v[108:111], v[208:211], v[88:91]
	v_mfma_f32_16x16x32_bf16 v[124:127], v[156:159], v[180:183], v[124:127]
	v_mfma_f32_16x16x32_bf16 v[116:119], v[172:175], v[180:183], v[116:119]
	v_mfma_f32_16x16x32_bf16 v[104:107], v[156:159], v[188:191], v[104:107]
	v_mfma_f32_16x16x32_bf16 v[96:99], v[172:175], v[188:191], v[96:99]
	v_mfma_f32_16x16x32_bf16 v[80:83], v[156:159], v[196:199], v[80:83]
	v_mfma_f32_16x16x32_bf16 v[76:79], v[172:175], v[196:199], v[76:79]
	v_mfma_f32_16x16x32_bf16 v[68:71], v[156:159], v[204:207], v[68:71]
	v_mfma_f32_16x16x32_bf16 v[64:67], v[172:175], v[204:207], v[64:67]
	v_mfma_f32_16x16x32_bf16 v[124:127], v[168:171], v[184:187], v[124:127]
	v_mfma_f32_16x16x32_bf16 v[116:119], v[176:179], v[184:187], v[116:119]
	v_mfma_f32_16x16x32_bf16 v[104:107], v[168:171], v[192:195], v[104:107]
	v_mfma_f32_16x16x32_bf16 v[96:99], v[176:179], v[192:195], v[96:99]
	v_mfma_f32_16x16x32_bf16 v[80:83], v[168:171], v[200:203], v[80:83]
	v_mfma_f32_16x16x32_bf16 v[76:79], v[176:179], v[200:203], v[76:79]
	v_mfma_f32_16x16x32_bf16 v[68:71], v[168:171], v[208:211], v[68:71]
	v_mfma_f32_16x16x32_bf16 v[64:67], v[176:179], v[208:211], v[64:67]
	s_setprio 0
	s_barrier
; #define PG8_STAGE(bufoff, gbase, voff) do { _Pragma("unroll") for (int _i = 0; _i < 2; ++_i) \
;         __builtin_amdgcn_global_load_lds((const unsigned*)((const char*)(gbase) + (voff)[_i]), (PG8_LAS unsigned*)(lds + (bufoff) + ldsw + _i * 8192), 16, 0, 0); } while (0)
; #define PG8_LDA(dst, b, h) do { _Pragma("unroll") for (int m = 0; m < 4; ++m) _Pragma("unroll") for (int k = 0; k < 2; ++k) dst[m][k] = *(const PG8_LAS bf16x8*)(lds + PG8_SA(b, h) + aoff + m * 2048 + k * 1024); } while (0)
; #define PG8_MMA(ai, bj, At, Bt) do { __builtin_amdgcn_s_setprio(1); _Pragma("unroll") for (int m = 0; m < 4; ++m) _Pragma("unroll") for (int n = 0; n < 2; ++n) _Pragma("unroll") for (int k = 0; k < 2; ++k) \
;         acc[ai][bj][m][n] = __builtin_amdgcn_mfma_f32_16x16x32_bf16(Bt[n][k], At[m][k], acc[ai][bj][m][n], 0, 0, 0); __builtin_amdgcn_s_setprio(0); } while (0)
; #define PG8_WAIT_V(n) asm volatile("s_waitcnt vmcnt(" #n ")" ::: "memory")
; #define PG8_WAIT_L(n) asm volatile("s_waitcnt lgkmcnt(" #n ")" ::: "memory")
; #define PG8_BAR __builtin_amdgcn_s_barrier()
; #define PG8_SCHED __builtin_amdgcn_sched_barrier(0)
; template <class Epi, class Sched, bool ALIGN_EPI = false, bool SP2 = false>
; __device__ __forceinline__ void gemm_phase(PG8_LAS unsigned char* lds, const Gemm g, const Sched& S, const Epi& E) {
;     ...
;             PG8_LDA(At, 1, 1); PG8_STAGE(PG8_SB(1, 0), b3, voffB); PG8_STAGE(PG8_SB(1, 1), b3 + hstep, voffB); PG8_STAGE(PG8_SA(1, 0), a3, voffA);
;             PG8_WAIT_V(8); PG8_WAIT_L(0); PG8_BAR; PG8_MMA(1, 0, At, B0); PG8_MMA(1, 1, At, B1); PG8_BAR; PG8_SCHED;
;     ...
;         if constexpr (ALIGN_EPI) { if (wr == 0) PG8_BAR; }
	s_add_i32 s30, s62, s47
	v_lshl_add_u64 v[160:161], v[160:161], 0, s[8:9]
	s_mov_b32 m0, s30
	ds_read_b128 v[180:183], v167 offset:49152
	ds_read_b128 v[184:187], v167 offset:50176
	ds_read_b128 v[188:191], v167 offset:51200
	ds_read_b128 v[192:195], v167 offset:52224
	ds_read_b128 v[196:199], v167 offset:53248
	ds_read_b128 v[200:203], v167 offset:54272
	ds_read_b128 v[204:207], v167 offset:55296
	ds_read_b128 v[208:211], v167 offset:56320
	global_load_lds_dwordx4 v[160:161], off
	s_add_i32 m0, s30, 0x2000
	s_add_u32 s30, s36, 0x200080
	v_lshl_add_u64 v[160:161], v[212:213], 0, s[8:9]
	s_addc_u32 s31, s37, 0
	s_add_i32 s36, s63, s47
	global_load_lds_dwordx4 v[160:161], off
	v_lshl_add_u64 v[160:161], s[30:31], 0, v[146:147]
	s_mov_b32 m0, s36
	s_nop 0
	global_load_lds_dwordx4 v[160:161], off
	v_lshl_add_u64 v[160:161], s[30:31], 0, v[144:145]
	s_add_i32 m0, s36, 0x2000
	s_nop 0
	global_load_lds_dwordx4 v[160:161], off
	v_lshl_add_u64 v[160:161], v[214:215], 0, s[8:9]
	s_mov_b32 m0, s53
	s_nop 0
	global_load_lds_dwordx4 v[160:161], off
	v_lshl_add_u64 v[160:161], v[216:217], 0, s[8:9]
	s_mov_b32 m0, s54
	s_nop 0
	global_load_lds_dwordx4 v[160:161], off
	s_waitcnt vmcnt(8)
	s_waitcnt lgkmcnt(0)
	s_barrier
	s_setprio 1
	v_mfma_f32_16x16x32_bf16 v[60:63], v[72:75], v[180:183], v[60:63]
	v_mfma_f32_16x16x32_bf16 v[56:59], v[92:95], v[180:183], v[56:59]
	v_mfma_f32_16x16x32_bf16 v[52:55], v[72:75], v[188:191], v[52:55]
	v_mfma_f32_16x16x32_bf16 v[44:47], v[92:95], v[188:191], v[44:47]
	v_mfma_f32_16x16x32_bf16 v[36:39], v[72:75], v[196:199], v[36:39]
	v_mfma_f32_16x16x32_bf16 v[28:31], v[92:95], v[196:199], v[28:31]
	v_mfma_f32_16x16x32_bf16 v[20:23], v[72:75], v[204:207], v[20:23]
	v_mfma_f32_16x16x32_bf16 v[12:15], v[92:95], v[204:207], v[12:15]
	v_mfma_f32_16x16x32_bf16 v[60:63], v[84:87], v[184:187], v[60:63]
	v_mfma_f32_16x16x32_bf16 v[56:59], v[108:111], v[184:187], v[56:59]
	v_mfma_f32_16x16x32_bf16 v[52:55], v[84:87], v[192:195], v[52:55]
	v_mfma_f32_16x16x32_bf16 v[44:47], v[108:111], v[192:195], v[44:47]
	v_mfma_f32_16x16x32_bf16 v[36:39], v[84:87], v[200:203], v[36:39]
	v_mfma_f32_16x16x32_bf16 v[28:31], v[108:111], v[200:203], v[28:31]
	v_mfma_f32_16x16x32_bf16 v[20:23], v[84:87], v[208:211], v[20:23]
	v_mfma_f32_16x16x32_bf16 v[12:15], v[108:111], v[208:211], v[12:15]
	v_mfma_f32_16x16x32_bf16 v[48:51], v[156:159], v[180:183], v[48:51]
	v_mfma_f32_16x16x32_bf16 v[40:43], v[172:175], v[180:183], v[40:43]
	v_mfma_f32_16x16x32_bf16 v[32:35], v[156:159], v[188:191], v[32:35]
	v_mfma_f32_16x16x32_bf16 v[24:27], v[172:175], v[188:191], v[24:27]
	v_mfma_f32_16x16x32_bf16 v[16:19], v[156:159], v[196:199], v[16:19]
	v_mfma_f32_16x16x32_bf16 v[8:11], v[172:175], v[196:199], v[8:11]
	v_mfma_f32_16x16x32_bf16 v[4:7], v[156:159], v[204:207], v[4:7]
	v_mfma_f32_16x16x32_bf16 v[0:3], v[172:175], v[204:207], v[0:3]
	v_mfma_f32_16x16x32_bf16 v[48:51], v[168:171], v[184:187], v[48:51]
	v_mfma_f32_16x16x32_bf16 v[40:43], v[176:179], v[184:187], v[40:43]
	v_mfma_f32_16x16x32_bf16 v[32:35], v[168:171], v[192:195], v[32:35]
	v_mfma_f32_16x16x32_bf16 v[24:27], v[176:179], v[192:195], v[24:27]
	v_mfma_f32_16x16x32_bf16 v[16:19], v[168:171], v[200:203], v[16:19]
	v_mfma_f32_16x16x32_bf16 v[8:11], v[176:179], v[200:203], v[8:11]
	v_mfma_f32_16x16x32_bf16 v[4:7], v[168:171], v[208:211], v[4:7]
	v_mfma_f32_16x16x32_bf16 v[0:3], v[176:179], v[208:211], v[0:3]
	s_setprio 0
	s_barrier
	s_add_i32 s61, s61, 2
	s_add_u32 s59, s59, 0x100
	s_addc_u32 s60, s60, 0
	s_cmpk_gt_u32 s61, 0x7d
	s_mov_b64 s[30:31], s[34:35]
	s_cbranch_scc0 .LBB0_847
	s_and_b64 vcc, exec, s[10:11]
	s_cbranch_vccz .LBB0_850
	s_barrier
